# merge adjacent vmcnt/lgkmcnt waits into one s_waitcnt (GEMM loops, attention)
# baseline (speedup 1.0000x reference)
; __device__ __forceinline__ unsigned xb_ld(unsigned* p)              { return __hip_atomic_load(p, __ATOMIC_RELAXED, __HIP_MEMORY_SCOPE_AGENT); }
; __device__ __forceinline__ unsigned xb_add(unsigned* p, unsigned v) { return __hip_atomic_fetch_add(p, v, __ATOMIC_RELAXED, __HIP_MEMORY_SCOPE_AGENT); }
; #define XB_SPIN(cond, bar) do { unsigned _sp = 0; while (cond) { __builtin_amdgcn_s_sleep(1); \
;     if ((++_sp & 255u) == 0u) { if (xb_ld(&(bar)[XB_TMO])) break; if (_sp > XB_SPIN_CAP) { atomicAdd(&(bar)[XB_TMO], 1u); break; } } } } while (0)
; __device__ __forceinline__ void xcd_barrier(const XcdBarrier& b) {
;     ...
;         const unsigned old = xb_add(&bar[XB_XSUB(b.x)], 1u);
;         const unsigned gen = old / nloc;
;         if (old + 1u == (gen + 1u) * nloc) {
;             __builtin_amdgcn_fence(__ATOMIC_RELEASE, "agent");
;             asm volatile("s_waitcnt vmcnt(0)" ::: "memory");
;             const unsigned og = xb_add(&bar[XB_TOP], 1u);
;             const unsigned tg = og / nx;
;             if (og + 1u == (tg + 1u) * nx) xb_add(&bar[XB_TOPGEN], 1u);
;             else XB_SPIN(xb_ld(&bar[XB_TOPGEN]) == tg, bar);
.LBB0_202:
	s_andn2_saveexec_b64 s[10:11], s[10:11]
	s_cbranch_execz .LBB0_239
	s_mov_b64 s[10:11], exec
	buffer_wbl2 sc1
	s_waitcnt vmcnt(0) lgkmcnt(0)
	v_mbcnt_lo_u32_b32 v1, s10, 0
	v_mbcnt_hi_u32_b32 v1, s11, v1
	v_cmp_eq_u32_e32 vcc, 0, v1
	s_and_saveexec_b64 s[12:13], vcc
	s_cbranch_execz .LBB0_205
	s_bcnt1_i32_b64 s3, s[10:11]
	v_readlane_b32 s10, v251, 0
	v_mov_b32_e32 v2, 0x83000
	v_mov_b32_e32 v3, s3
	v_readlane_b32 s11, v251, 1
	s_nop 4
	global_atomic_add v2, v2, v3, s[10:11] offset:1024 sc0

; __device__ __forceinline__ unsigned xb_ld(unsigned* p)              { return __hip_atomic_load(p, __ATOMIC_RELAXED, __HIP_MEMORY_SCOPE_AGENT); }
; __device__ __forceinline__ unsigned xb_add(unsigned* p, unsigned v) { return __hip_atomic_fetch_add(p, v, __ATOMIC_RELAXED, __HIP_MEMORY_SCOPE_AGENT); }
; #define XB_SPIN(cond, bar) do { unsigned _sp = 0; while (cond) { __builtin_amdgcn_s_sleep(1); \
;     if ((++_sp & 255u) == 0u) { if (xb_ld(&(bar)[XB_TMO])) break; if (_sp > XB_SPIN_CAP) { atomicAdd(&(bar)[XB_TMO], 1u); break; } } } } while (0)
; __device__ __forceinline__ void xcd_barrier(const XcdBarrier& b) {
;     ...
;         const unsigned old = xb_add(&bar[XB_XSUB(b.x)], 1u);
;         const unsigned gen = old / nloc;
;         if (old + 1u == (gen + 1u) * nloc) {
;             __builtin_amdgcn_fence(__ATOMIC_RELEASE, "agent");
;             asm volatile("s_waitcnt vmcnt(0)" ::: "memory");
;             const unsigned og = xb_add(&bar[XB_TOP], 1u);
;             const unsigned tg = og / nx;
;             if (og + 1u == (tg + 1u) * nx) xb_add(&bar[XB_TOPGEN], 1u);
;             else XB_SPIN(xb_ld(&bar[XB_TOPGEN]) == tg, bar);
.LBB0_220:
	s_mov_b64 s[10:11], exec
	buffer_wbl2 sc1
	s_waitcnt vmcnt(0) lgkmcnt(0)
	v_mbcnt_lo_u32_b32 v1, s10, 0
	v_mbcnt_hi_u32_b32 v1, s11, v1
	v_cmp_eq_u32_e32 vcc, 0, v1
	s_and_saveexec_b64 s[12:13], vcc
	s_cbranch_execz .LBB0_222
	s_bcnt1_i32_b64 s3, s[10:11]
	v_readlane_b32 s10, v251, 0
	v_mov_b32_e32 v2, 0x83000
	v_mov_b32_e32 v3, s3
	v_readlane_b32 s11, v251, 1
	s_nop 4
	global_atomic_add v2, v2, v3, s[10:11] offset:1024 sc0

; #define PG8_STAGE(bufoff, gbase, voff) do { _Pragma("unroll") for (int _i = 0; _i < 2; ++_i) \
;         __builtin_amdgcn_global_load_lds((const unsigned*)((const char*)(gbase) + (voff)[_i]), (PG8_LAS unsigned*)(lds + (bufoff) + ldsw + _i * 8192), 16, 0, 0); } while (0)
; #define PG8_LDA(dst, b, h) do { _Pragma("unroll") for (int m = 0; m < 4; ++m) _Pragma("unroll") for (int k = 0; k < 2; ++k) dst[m][k] = *(const PG8_LAS bf16x8*)(lds + PG8_SA(b, h) + aoff + m * 2048 + k * 1024); } while (0)
; #define PG8_LDB(dst, b, h) do { _Pragma("unroll") for (int n = 0; n < 2; ++n) _Pragma("unroll") for (int k = 0; k < 2; ++k) dst[n][k] = *(const PG8_LAS bf16x8*)(lds + PG8_SB(b, h) + boff + n * 2048 + k * 1024); } while (0)
; #define PG8_MMA(ai, bj, At, Bt) do { __builtin_amdgcn_s_setprio(1); _Pragma("unroll") for (int m = 0; m < 4; ++m) _Pragma("unroll") for (int n = 0; n < 2; ++n) _Pragma("unroll") for (int k = 0; k < 2; ++k) \
;         acc[ai][bj][m][n] = __builtin_amdgcn_mfma_f32_16x16x32_bf16(Bt[n][k], At[m][k], acc[ai][bj][m][n], 0, 0, 0); __builtin_amdgcn_s_setprio(0); } while (0)
; #define PG8_WAIT_V(n) asm volatile("s_waitcnt vmcnt(" #n ")" ::: "memory")
; #define PG8_BAR __builtin_amdgcn_s_barrier()
; template <class Epi, class Sched, bool ALIGN_EPI = false, bool SP2 = false>
; __device__ __forceinline__ void gemm_phase(PG8_LAS unsigned char* lds, const Gemm g, const Sched& S, const Epi& E) {
;     ...
;         for (int t = 0; t < nt; t += 2) {
;             const bool last = (t == nt - 2);
;             const char* a1 = cA + (size_t)(t + 1) * kstep;
;             const char* a2 = last ? nA : cA + (size_t)(t + 2) * kstep; const char* b2 = last ? nB : cB + (size_t)(t + 2) * kstep;
;             const char* a3 = a2 + kstep; const char* b3 = b2 + kstep;
;             if (last && has_next) S.a_ready(nxt);
;             if constexpr (SP2) {
;             PG8_LDB(B0, 0, 0); PG8_LDB(B1, 0, 1); PG8_SCHED; PG8_LDA(At, 0, 0); PG8_STAGE(PG8_SA(1, 1), a1 + hstepA, voffA);
;             PG8_WAIT_V(8); PG8_WAIT_L(0); PG8_BAR; PG8_MMA(0, 0, At, B0); PG8_MMA(0, 1, At, B1); PG8_BAR; PG8_SCHED;
;             PG8_LDA(At, 0, 1); PG8_STAGE(PG8_SB(0, 0), b2, voffB); PG8_STAGE(PG8_SB(0, 1), b2 + hstep, voffB); PG8_STAGE(PG8_SA(0, 0), a2, voffA);
;             PG8_WAIT_V(8); PG8_WAIT_L(0); PG8_BAR; PG8_MMA(1, 0, At, B0); PG8_MMA(1, 1, At, B1); PG8_BAR; PG8_SCHED;
.LBB0_258:
	ds_read_b128 v[164:167], v161
	ds_read_b128 v[168:171], v161 offset:1024
	ds_read_b128 v[172:175], v161 offset:2048
	ds_read_b128 v[176:179], v161 offset:3072
	ds_read_b128 v[180:183], v162
	ds_read_b128 v[184:187], v162 offset:1024
	ds_read_b128 v[190:193], v162 offset:2048
	ds_read_b128 v[194:197], v162 offset:3072
	s_add_i32 s65, s36, 2
	s_add_u32 s66, s10, 0xfffc0080
	s_addc_u32 s37, s11, -1
	s_cmp_eq_u32 s56, s36
	s_cselect_b32 s36, s64, s66
	s_cselect_b32 s37, s29, s37
	s_cselect_b32 s67, s31, s39
	s_cselect_b32 s66, s30, s38
	s_add_i32 m0, s48, 0xc000
	ds_read_b128 v[198:201], v163
	ds_read_b128 v[202:205], v163 offset:1024
	ds_read_b128 v[206:209], v163 offset:2048
	ds_read_b128 v[210:213], v163 offset:3072
	ds_read_b128 v[214:217], v163 offset:4096
	ds_read_b128 v[218:221], v163 offset:5120
	ds_read_b128 v[222:225], v163 offset:6144
	global_load_lds_dwordx4 v138, s[10:11]
	s_add_i32 m0, s48, 0xe000
	ds_read_b128 v[226:229], v163 offset:7168
	global_load_lds_dwordx4 v142, s[10:11]
	s_waitcnt vmcnt(8) lgkmcnt(0)
	s_barrier
	s_setprio 1
	v_mfma_f32_16x16x32_bf16 v[124:127], v[164:167], v[198:201], v[124:127]
	v_mfma_f32_16x16x32_bf16 v[120:123], v[172:175], v[198:201], v[120:123]
	v_mfma_f32_16x16x32_bf16 v[108:111], v[164:167], v[206:209], v[108:111]
	v_mfma_f32_16x16x32_bf16 v[104:107], v[172:175], v[206:209], v[104:107]
	v_mfma_f32_16x16x32_bf16 v[92:95], v[164:167], v[214:217], v[92:95]
	v_mfma_f32_16x16x32_bf16 v[88:91], v[172:175], v[214:217], v[88:91]
	v_mfma_f32_16x16x32_bf16 v[76:79], v[164:167], v[222:225], v[76:79]
	v_mfma_f32_16x16x32_bf16 v[72:75], v[172:175], v[222:225], v[72:75]
	v_mfma_f32_16x16x32_bf16 v[124:127], v[168:171], v[202:205], v[124:127]
	v_mfma_f32_16x16x32_bf16 v[120:123], v[176:179], v[202:205], v[120:123]
	v_mfma_f32_16x16x32_bf16 v[108:111], v[168:171], v[210:213], v[108:111]
	v_mfma_f32_16x16x32_bf16 v[104:107], v[176:179], v[210:213], v[104:107]
	v_mfma_f32_16x16x32_bf16 v[92:95], v[168:171], v[218:221], v[92:95]
	v_mfma_f32_16x16x32_bf16 v[88:91], v[176:179], v[218:221], v[88:91]
	v_mfma_f32_16x16x32_bf16 v[76:79], v[168:171], v[226:229], v[76:79]
	v_mfma_f32_16x16x32_bf16 v[72:75], v[176:179], v[226:229], v[72:75]
	v_mfma_f32_16x16x32_bf16 v[116:119], v[180:183], v[198:201], v[116:119]
	v_mfma_f32_16x16x32_bf16 v[112:115], v[190:193], v[198:201], v[112:115]
	v_mfma_f32_16x16x32_bf16 v[100:103], v[180:183], v[206:209], v[100:103]
	v_mfma_f32_16x16x32_bf16 v[96:99], v[190:193], v[206:209], v[96:99]
	v_mfma_f32_16x16x32_bf16 v[84:87], v[180:183], v[214:217], v[84:87]
	v_mfma_f32_16x16x32_bf16 v[80:83], v[190:193], v[214:217], v[80:83]
	v_mfma_f32_16x16x32_bf16 v[68:71], v[180:183], v[222:225], v[68:71]
	v_mfma_f32_16x16x32_bf16 v[64:67], v[190:193], v[222:225], v[64:67]
	v_mfma_f32_16x16x32_bf16 v[116:119], v[184:187], v[202:205], v[116:119]
	v_mfma_f32_16x16x32_bf16 v[112:115], v[194:197], v[202:205], v[112:115]
	v_mfma_f32_16x16x32_bf16 v[100:103], v[184:187], v[210:213], v[100:103]
	v_mfma_f32_16x16x32_bf16 v[96:99], v[194:197], v[210:213], v[96:99]
	v_mfma_f32_16x16x32_bf16 v[84:87], v[184:187], v[218:221], v[84:87]
	v_mfma_f32_16x16x32_bf16 v[80:83], v[194:197], v[218:221], v[80:83]
	v_mfma_f32_16x16x32_bf16 v[68:71], v[184:187], v[226:229], v[68:71]
	v_mfma_f32_16x16x32_bf16 v[64:67], v[194:197], v[226:229], v[64:67]
	s_setprio 0
	s_barrier
	s_add_i32 s68, s57, s47
	s_mov_b32 m0, s68
	ds_read_b128 v[198:201], v163 offset:16384
	ds_read_b128 v[202:205], v163 offset:17408
	ds_read_b128 v[206:209], v163 offset:18432
	ds_read_b128 v[210:213], v163 offset:19456
	global_load_lds_dwordx4 v136, s[66:67]
	s_add_i32 m0, s68, 0x2000
	s_mov_b64 s[100:101], s[66:67]
	s_add_i32 s68, s58, s47
	global_load_lds_dwordx4 v134, s[66:67]
	s_add_u32 s66, s66, s16
	s_addc_u32 s67, s67, s17
	s_mov_b32 m0, s68
	ds_read_b128 v[226:229], v163 offset:23552
	global_load_lds_dwordx4 v136, s[66:67]
	s_add_i32 m0, s68, 0x2000
	ds_read_b128 v[222:225], v163 offset:22528
	global_load_lds_dwordx4 v134, s[66:67]
	s_mov_b32 m0, s48
	ds_read_b128 v[218:221], v163 offset:21504
	global_load_lds_dwordx4 v128, s[36:37]
	s_mov_b32 m0, s49
	ds_read_b128 v[214:217], v163 offset:20480
	global_load_lds_dwordx4 v130, s[36:37]
	s_waitcnt vmcnt(8) lgkmcnt(0)
	s_barrier
	s_setprio 1
	v_mfma_f32_16x16x32_bf16 v[60:63], v[164:167], v[198:201], v[60:63]
	v_mfma_f32_16x16x32_bf16 v[56:59], v[172:175], v[198:201], v[56:59]
	v_mfma_f32_16x16x32_bf16 v[44:47], v[164:167], v[206:209], v[44:47]
	v_mfma_f32_16x16x32_bf16 v[40:43], v[172:175], v[206:209], v[40:43]
	v_mfma_f32_16x16x32_bf16 v[28:31], v[164:167], v[214:217], v[28:31]
	v_mfma_f32_16x16x32_bf16 v[24:27], v[172:175], v[214:217], v[24:27]
	v_mfma_f32_16x16x32_bf16 v[12:15], v[164:167], v[222:225], v[12:15]
	v_mfma_f32_16x16x32_bf16 v[8:11], v[172:175], v[222:225], v[8:11]
	v_mfma_f32_16x16x32_bf16 v[60:63], v[168:171], v[202:205], v[60:63]
	v_mfma_f32_16x16x32_bf16 v[56:59], v[176:179], v[202:205], v[56:59]
	v_mfma_f32_16x16x32_bf16 v[44:47], v[168:171], v[210:213], v[44:47]
	v_mfma_f32_16x16x32_bf16 v[40:43], v[176:179], v[210:213], v[40:43]
	v_mfma_f32_16x16x32_bf16 v[28:31], v[168:171], v[218:221], v[28:31]
	v_mfma_f32_16x16x32_bf16 v[24:27], v[176:179], v[218:221], v[24:27]
	v_mfma_f32_16x16x32_bf16 v[12:15], v[168:171], v[226:229], v[12:15]
	v_mfma_f32_16x16x32_bf16 v[8:11], v[176:179], v[226:229], v[8:11]
	v_mfma_f32_16x16x32_bf16 v[52:55], v[180:183], v[198:201], v[52:55]
	v_mfma_f32_16x16x32_bf16 v[48:51], v[190:193], v[198:201], v[48:51]
	v_mfma_f32_16x16x32_bf16 v[36:39], v[180:183], v[206:209], v[36:39]
	v_mfma_f32_16x16x32_bf16 v[32:35], v[190:193], v[206:209], v[32:35]
	v_mfma_f32_16x16x32_bf16 v[20:23], v[180:183], v[214:217], v[20:23]
	v_mfma_f32_16x16x32_bf16 v[16:19], v[190:193], v[214:217], v[16:19]
	v_mfma_f32_16x16x32_bf16 v[4:7], v[180:183], v[222:225], v[4:7]
	v_mfma_f32_16x16x32_bf16 v[0:3], v[190:193], v[222:225], v[0:3]
	v_mfma_f32_16x16x32_bf16 v[52:55], v[184:187], v[202:205], v[52:55]
	v_mfma_f32_16x16x32_bf16 v[48:51], v[194:197], v[202:205], v[48:51]
	v_mfma_f32_16x16x32_bf16 v[36:39], v[184:187], v[210:213], v[36:39]
	v_mfma_f32_16x16x32_bf16 v[32:35], v[194:197], v[210:213], v[32:35]
	v_mfma_f32_16x16x32_bf16 v[20:23], v[184:187], v[218:221], v[20:23]
	v_mfma_f32_16x16x32_bf16 v[16:19], v[194:197], v[218:221], v[16:19]
	v_mfma_f32_16x16x32_bf16 v[4:7], v[184:187], v[226:229], v[4:7]
	v_mfma_f32_16x16x32_bf16 v[0:3], v[194:197], v[226:229], v[0:3]
	s_setprio 0
	s_barrier
; #define PG8_STAGE(bufoff, gbase, voff) do { _Pragma("unroll") for (int _i = 0; _i < 2; ++_i) \
;         __builtin_amdgcn_global_load_lds((const unsigned*)((const char*)(gbase) + (voff)[_i]), (PG8_LAS unsigned*)(lds + (bufoff) + ldsw + _i * 8192), 16, 0, 0); } while (0)
; #define PG8_LDA(dst, b, h) do { _Pragma("unroll") for (int m = 0; m < 4; ++m) _Pragma("unroll") for (int k = 0; k < 2; ++k) dst[m][k] = *(const PG8_LAS bf16x8*)(lds + PG8_SA(b, h) + aoff + m * 2048 + k * 1024); } while (0)
; #define PG8_LDB(dst, b, h) do { _Pragma("unroll") for (int n = 0; n < 2; ++n) _Pragma("unroll") for (int k = 0; k < 2; ++k) dst[n][k] = *(const PG8_LAS bf16x8*)(lds + PG8_SB(b, h) + boff + n * 2048 + k * 1024); } while (0)
; #define PG8_MMA(ai, bj, At, Bt) do { __builtin_amdgcn_s_setprio(1); _Pragma("unroll") for (int m = 0; m < 4; ++m) _Pragma("unroll") for (int n = 0; n < 2; ++n) _Pragma("unroll") for (int k = 0; k < 2; ++k) \
;         acc[ai][bj][m][n] = __builtin_amdgcn_mfma_f32_16x16x32_bf16(Bt[n][k], At[m][k], acc[ai][bj][m][n], 0, 0, 0); __builtin_amdgcn_s_setprio(0); } while (0)
; #define PG8_WAIT_V(n) asm volatile("s_waitcnt vmcnt(" #n ")" ::: "memory")
; #define PG8_WAIT_L(n) asm volatile("s_waitcnt lgkmcnt(" #n ")" ::: "memory")
; #define PG8_BAR __builtin_amdgcn_s_barrier()
; template <class Epi, class Sched, bool ALIGN_EPI = false, bool SP2 = false>
; __device__ __forceinline__ void gemm_phase(PG8_LAS unsigned char* lds, const Gemm g, const Sched& S, const Epi& E) {
;     ...
;         for (int t = 0; t < nt; t += 2) {
;             const bool last = (t == nt - 2);
;             const char* a1 = cA + (size_t)(t + 1) * kstep;
;             const char* a2 = last ? nA : cA + (size_t)(t + 2) * kstep; const char* b2 = last ? nB : cB + (size_t)(t + 2) * kstep;
;             const char* a3 = a2 + kstep; const char* b3 = b2 + kstep;
;     ...
;             PG8_LDB(B0, 1, 0); PG8_LDB(B1, 1, 1); PG8_SCHED; PG8_LDA(At, 1, 0); PG8_STAGE(PG8_SA(0, 1), a2 + hstepA, voffA);
;             PG8_WAIT_V(8); PG8_WAIT_L(0); PG8_BAR; PG8_MMA(0, 0, At, B0); PG8_MMA(0, 1, At, B1); PG8_BAR; PG8_SCHED;
;             PG8_LDA(At, 1, 1); PG8_STAGE(PG8_SB(1, 0), b3, voffB); PG8_STAGE(PG8_SB(1, 1), b3 + hstep, voffB); PG8_STAGE(PG8_SA(1, 0), a3, voffA);
;             PG8_WAIT_V(8); PG8_WAIT_L(0); PG8_BAR; PG8_MMA(1, 0, At, B0); PG8_MMA(1, 1, At, B1); PG8_BAR; PG8_SCHED;
	s_add_i32 s66, 0, 0x18000
	s_add_i32 s67, 0, 0x1c000
	v_add_u32_e32 v176, s66, v159
	v_add_u32_e32 v189, s67, v159
	ds_read_b128 v[164:167], v176
	ds_read_b128 v[168:171], v176 offset:1024
	ds_read_b128 v[172:175], v176 offset:2048
	ds_read_b128 v[176:179], v176 offset:3072
	ds_read_b128 v[180:183], v189
	ds_read_b128 v[184:187], v189 offset:1024
	ds_read_b128 v[190:193], v189 offset:2048
	ds_read_b128 v[194:197], v189 offset:3072
	s_mov_b64 vcc, s[36:37]
	s_add_u32 s36, s36, 0x40000
	s_addc_u32 s37, s37, 0
	s_mov_b32 m0, s50
	ds_read_b128 v[198:201], v163 offset:32768
	ds_read_b128 v[202:205], v163 offset:33792
	ds_read_b128 v[206:209], v163 offset:34816
	ds_read_b128 v[210:213], v163 offset:35840
	ds_read_b128 v[214:217], v163 offset:36864
	ds_read_b128 v[218:221], v163 offset:37888
	ds_read_b128 v[222:225], v163 offset:38912
	global_load_lds_dwordx4 v128, s[36:37]
	s_mov_b32 m0, s51
	ds_read_b128 v[226:229], v163 offset:39936
	global_load_lds_dwordx4 v130, s[36:37]
	s_waitcnt vmcnt(8) lgkmcnt(0)
	s_barrier
	s_setprio 1
	v_mfma_f32_16x16x32_bf16 v[124:127], v[164:167], v[198:201], v[124:127]
	v_mfma_f32_16x16x32_bf16 v[120:123], v[172:175], v[198:201], v[120:123]
	v_mfma_f32_16x16x32_bf16 v[108:111], v[164:167], v[206:209], v[108:111]
	v_mfma_f32_16x16x32_bf16 v[104:107], v[172:175], v[206:209], v[104:107]
	v_mfma_f32_16x16x32_bf16 v[92:95], v[164:167], v[214:217], v[92:95]
	v_mfma_f32_16x16x32_bf16 v[88:91], v[172:175], v[214:217], v[88:91]
	v_mfma_f32_16x16x32_bf16 v[76:79], v[164:167], v[222:225], v[76:79]
	v_mfma_f32_16x16x32_bf16 v[72:75], v[172:175], v[222:225], v[72:75]
	v_mfma_f32_16x16x32_bf16 v[124:127], v[168:171], v[202:205], v[124:127]
	v_mfma_f32_16x16x32_bf16 v[120:123], v[176:179], v[202:205], v[120:123]
	v_mfma_f32_16x16x32_bf16 v[108:111], v[168:171], v[210:213], v[108:111]
	v_mfma_f32_16x16x32_bf16 v[104:107], v[176:179], v[210:213], v[104:107]
	v_mfma_f32_16x16x32_bf16 v[92:95], v[168:171], v[218:221], v[92:95]
	v_mfma_f32_16x16x32_bf16 v[88:91], v[176:179], v[218:221], v[88:91]
	v_mfma_f32_16x16x32_bf16 v[76:79], v[168:171], v[226:229], v[76:79]
	v_mfma_f32_16x16x32_bf16 v[72:75], v[176:179], v[226:229], v[72:75]
	v_mfma_f32_16x16x32_bf16 v[116:119], v[180:183], v[198:201], v[116:119]
	v_mfma_f32_16x16x32_bf16 v[112:115], v[190:193], v[198:201], v[112:115]
	v_mfma_f32_16x16x32_bf16 v[100:103], v[180:183], v[206:209], v[100:103]
	v_mfma_f32_16x16x32_bf16 v[96:99], v[190:193], v[206:209], v[96:99]
	v_mfma_f32_16x16x32_bf16 v[84:87], v[180:183], v[214:217], v[84:87]
	v_mfma_f32_16x16x32_bf16 v[80:83], v[190:193], v[214:217], v[80:83]
	v_mfma_f32_16x16x32_bf16 v[68:71], v[180:183], v[222:225], v[68:71]
	v_mfma_f32_16x16x32_bf16 v[64:67], v[190:193], v[222:225], v[64:67]
	v_mfma_f32_16x16x32_bf16 v[116:119], v[184:187], v[202:205], v[116:119]
	v_mfma_f32_16x16x32_bf16 v[112:115], v[194:197], v[202:205], v[112:115]
	v_mfma_f32_16x16x32_bf16 v[100:103], v[184:187], v[210:213], v[100:103]
	v_mfma_f32_16x16x32_bf16 v[96:99], v[194:197], v[210:213], v[96:99]
	v_mfma_f32_16x16x32_bf16 v[84:87], v[184:187], v[218:221], v[84:87]
	v_mfma_f32_16x16x32_bf16 v[80:83], v[194:197], v[218:221], v[80:83]
	v_mfma_f32_16x16x32_bf16 v[68:71], v[184:187], v[226:229], v[68:71]
	v_mfma_f32_16x16x32_bf16 v[64:67], v[194:197], v[226:229], v[64:67]
	s_setprio 0
	s_barrier
	s_add_i32 s36, s66, s47
	s_add_i32 m0, s36, 0xffffff80
	ds_read_b128 v[198:201], v163 offset:49152
	ds_read_b128 v[202:205], v163 offset:50176
	ds_read_b128 v[206:209], v163 offset:51200
	ds_read_b128 v[210:213], v163 offset:52224
	global_load_lds_dwordx4 v136, s[100:101] offset:128
	s_add_i32 m0, s36, 0x1f80
	s_add_i32 s36, s67, s47
	global_load_lds_dwordx4 v134, s[100:101] offset:128
	s_add_u32 s100, s100, s16
	s_addc_u32 s101, s101, s17
	s_add_i32 m0, s36, 0xffffff80
	ds_read_b128 v[226:229], v163 offset:56320
	global_load_lds_dwordx4 v136, s[100:101] offset:128
	s_add_i32 m0, s36, 0x1f80
	ds_read_b128 v[222:225], v163 offset:55296
	global_load_lds_dwordx4 v134, s[100:101] offset:128
	s_add_i32 m0, s52, 0xffffff80
	ds_read_b128 v[218:221], v163 offset:54272
	global_load_lds_dwordx4 v128, vcc offset:128
	s_add_i32 m0, s53, 0xffffff80
	ds_read_b128 v[214:217], v163 offset:53248
	global_load_lds_dwordx4 v130, vcc offset:128
	s_waitcnt vmcnt(8) lgkmcnt(0)
	s_barrier
	s_setprio 1
	v_mfma_f32_16x16x32_bf16 v[60:63], v[164:167], v[198:201], v[60:63]
	v_mfma_f32_16x16x32_bf16 v[56:59], v[172:175], v[198:201], v[56:59]
	v_mfma_f32_16x16x32_bf16 v[44:47], v[164:167], v[206:209], v[44:47]
	v_mfma_f32_16x16x32_bf16 v[40:43], v[172:175], v[206:209], v[40:43]
	v_mfma_f32_16x16x32_bf16 v[28:31], v[164:167], v[214:217], v[28:31]
	v_mfma_f32_16x16x32_bf16 v[24:27], v[172:175], v[214:217], v[24:27]
	v_mfma_f32_16x16x32_bf16 v[12:15], v[164:167], v[222:225], v[12:15]
	v_mfma_f32_16x16x32_bf16 v[8:11], v[172:175], v[222:225], v[8:11]
	v_mfma_f32_16x16x32_bf16 v[60:63], v[168:171], v[202:205], v[60:63]
	v_mfma_f32_16x16x32_bf16 v[56:59], v[176:179], v[202:205], v[56:59]
	v_mfma_f32_16x16x32_bf16 v[44:47], v[168:171], v[210:213], v[44:47]
	v_mfma_f32_16x16x32_bf16 v[40:43], v[176:179], v[210:213], v[40:43]
	v_mfma_f32_16x16x32_bf16 v[28:31], v[168:171], v[218:221], v[28:31]
	v_mfma_f32_16x16x32_bf16 v[24:27], v[176:179], v[218:221], v[24:27]
	v_mfma_f32_16x16x32_bf16 v[12:15], v[168:171], v[226:229], v[12:15]
	v_mfma_f32_16x16x32_bf16 v[8:11], v[176:179], v[226:229], v[8:11]
	v_mfma_f32_16x16x32_bf16 v[52:55], v[180:183], v[198:201], v[52:55]
	v_mfma_f32_16x16x32_bf16 v[48:51], v[190:193], v[198:201], v[48:51]
	v_mfma_f32_16x16x32_bf16 v[36:39], v[180:183], v[206:209], v[36:39]
	v_mfma_f32_16x16x32_bf16 v[32:35], v[190:193], v[206:209], v[32:35]
	v_mfma_f32_16x16x32_bf16 v[20:23], v[180:183], v[214:217], v[20:23]
	v_mfma_f32_16x16x32_bf16 v[16:19], v[190:193], v[214:217], v[16:19]
	v_mfma_f32_16x16x32_bf16 v[4:7], v[180:183], v[222:225], v[4:7]
	v_mfma_f32_16x16x32_bf16 v[0:3], v[190:193], v[222:225], v[0:3]
	v_mfma_f32_16x16x32_bf16 v[52:55], v[184:187], v[202:205], v[52:55]
	v_mfma_f32_16x16x32_bf16 v[48:51], v[194:197], v[202:205], v[48:51]
	v_mfma_f32_16x16x32_bf16 v[36:39], v[184:187], v[210:213], v[36:39]
	v_mfma_f32_16x16x32_bf16 v[32:35], v[194:197], v[210:213], v[32:35]
	v_mfma_f32_16x16x32_bf16 v[20:23], v[184:187], v[218:221], v[20:23]
	v_mfma_f32_16x16x32_bf16 v[16:19], v[194:197], v[218:221], v[16:19]
	v_mfma_f32_16x16x32_bf16 v[4:7], v[184:187], v[226:229], v[4:7]
	v_mfma_f32_16x16x32_bf16 v[0:3], v[194:197], v[226:229], v[0:3]
	s_setprio 0
	s_barrier
	s_add_u32 s10, s10, 0x100
	s_addc_u32 s11, s11, 0
	s_add_u32 s38, s38, 0x100
	s_addc_u32 s39, s39, 0
	s_cmp_ge_i32 s65, s54
	s_mov_b32 s36, s65
	s_cbranch_scc0 .LBB0_258

; #define PG8_STAGE(bufoff, gbase, voff) do { _Pragma("unroll") for (int _i = 0; _i < 2; ++_i) \
;         __builtin_amdgcn_global_load_lds((const unsigned*)((const char*)(gbase) + (voff)[_i]), (PG8_LAS unsigned*)(lds + (bufoff) + ldsw + _i * 8192), 16, 0, 0); } while (0)
; #define PG8_LDA(dst, b, h) do { _Pragma("unroll") for (int m = 0; m < 4; ++m) _Pragma("unroll") for (int k = 0; k < 2; ++k) dst[m][k] = *(const PG8_LAS bf16x8*)(lds + PG8_SA(b, h) + aoff + m * 2048 + k * 1024); } while (0)
; #define PG8_LDB(dst, b, h) do { _Pragma("unroll") for (int n = 0; n < 2; ++n) _Pragma("unroll") for (int k = 0; k < 2; ++k) dst[n][k] = *(const PG8_LAS bf16x8*)(lds + PG8_SB(b, h) + boff + n * 2048 + k * 1024); } while (0)
; #define PG8_MMA(ai, bj, At, Bt) do { __builtin_amdgcn_s_setprio(1); _Pragma("unroll") for (int m = 0; m < 4; ++m) _Pragma("unroll") for (int n = 0; n < 2; ++n) _Pragma("unroll") for (int k = 0; k < 2; ++k) \
;         acc[ai][bj][m][n] = __builtin_amdgcn_mfma_f32_16x16x32_bf16(Bt[n][k], At[m][k], acc[ai][bj][m][n], 0, 0, 0); __builtin_amdgcn_s_setprio(0); } while (0)
; #define PG8_WAIT_V(n) asm volatile("s_waitcnt vmcnt(" #n ")" ::: "memory")
; #define PG8_BAR __builtin_amdgcn_s_barrier()
; template <class Epi, class Sched, bool ALIGN_EPI = false, bool SP2 = false>
; __device__ __forceinline__ void gemm_phase(PG8_LAS unsigned char* lds, const Gemm g, const Sched& S, const Epi& E) {
;     ...
;         for (int t = 0; t < nt; t += 2) {
;             const bool last = (t == nt - 2);
;             const char* a1 = cA + (size_t)(t + 1) * kstep;
;             const char* a2 = last ? nA : cA + (size_t)(t + 2) * kstep; const char* b2 = last ? nB : cB + (size_t)(t + 2) * kstep;
;             const char* a3 = a2 + kstep; const char* b3 = b2 + kstep;
;             if (last && has_next) S.a_ready(nxt);
;             if constexpr (SP2) {
;             PG8_LDB(B0, 0, 0); PG8_LDB(B1, 0, 1); PG8_SCHED; PG8_LDA(At, 0, 0); PG8_STAGE(PG8_SA(1, 1), a1 + hstepA, voffA);
;             PG8_WAIT_V(8); PG8_WAIT_L(0); PG8_BAR; PG8_MMA(0, 0, At, B0); PG8_MMA(0, 1, At, B1); PG8_BAR; PG8_SCHED;
;             PG8_LDA(At, 0, 1); PG8_STAGE(PG8_SB(0, 0), b2, voffB); PG8_STAGE(PG8_SB(0, 1), b2 + hstep, voffB); PG8_STAGE(PG8_SA(0, 0), a2, voffA);
;             PG8_WAIT_V(8); PG8_WAIT_L(0); PG8_BAR; PG8_MMA(1, 0, At, B0); PG8_MMA(1, 1, At, B1); PG8_BAR; PG8_SCHED;
.LBB0_282:
	ds_read_b128 v[148:151], v144
	ds_read_b128 v[152:155], v144 offset:1024
	ds_read_b128 v[156:159], v144 offset:2048
	ds_read_b128 v[160:163], v144 offset:3072
	ds_read_b128 v[164:167], v145
	ds_read_b128 v[168:171], v145 offset:1024
	ds_read_b128 v[172:175], v145 offset:2048
	ds_read_b128 v[176:179], v145 offset:3072
	s_add_i32 s61, s34, 2
	s_add_u32 s62, s30, 0xfffc0080
	s_addc_u32 s35, s31, -1
	s_cmp_eq_u32 s52, s34
	s_cselect_b32 s34, s36, s62
	s_cselect_b32 s35, s5, s35
	s_cselect_b32 s63, s27, s60
	s_cselect_b32 s62, s26, s37
	s_add_i32 m0, s33, 0xc000
	ds_read_b128 v[180:183], v146
	ds_read_b128 v[184:187], v146 offset:1024
	ds_read_b128 v[190:193], v146 offset:2048
	ds_read_b128 v[194:197], v146 offset:3072
	ds_read_b128 v[198:201], v146 offset:4096
	ds_read_b128 v[202:205], v146 offset:5120
	ds_read_b128 v[206:209], v146 offset:6144
	global_load_lds_dwordx4 v138, s[30:31]
	s_add_i32 m0, s33, 0xe000
	ds_read_b128 v[210:213], v146 offset:7168
	global_load_lds_dwordx4 v140, s[30:31]
	s_waitcnt vmcnt(8) lgkmcnt(0)
	s_barrier
	s_setprio 1
	v_mfma_f32_16x16x32_bf16 v[124:127], v[148:151], v[180:183], v[124:127]
	v_mfma_f32_16x16x32_bf16 v[120:123], v[156:159], v[180:183], v[120:123]
	v_mfma_f32_16x16x32_bf16 v[108:111], v[148:151], v[190:193], v[108:111]
	v_mfma_f32_16x16x32_bf16 v[104:107], v[156:159], v[190:193], v[104:107]
	v_mfma_f32_16x16x32_bf16 v[92:95], v[148:151], v[198:201], v[92:95]
	v_mfma_f32_16x16x32_bf16 v[88:91], v[156:159], v[198:201], v[88:91]
	v_mfma_f32_16x16x32_bf16 v[76:79], v[148:151], v[206:209], v[76:79]
	v_mfma_f32_16x16x32_bf16 v[72:75], v[156:159], v[206:209], v[72:75]
	v_mfma_f32_16x16x32_bf16 v[124:127], v[152:155], v[184:187], v[124:127]
	v_mfma_f32_16x16x32_bf16 v[120:123], v[160:163], v[184:187], v[120:123]
	v_mfma_f32_16x16x32_bf16 v[108:111], v[152:155], v[194:197], v[108:111]
	v_mfma_f32_16x16x32_bf16 v[104:107], v[160:163], v[194:197], v[104:107]
	v_mfma_f32_16x16x32_bf16 v[92:95], v[152:155], v[202:205], v[92:95]
	v_mfma_f32_16x16x32_bf16 v[88:91], v[160:163], v[202:205], v[88:91]
	v_mfma_f32_16x16x32_bf16 v[76:79], v[152:155], v[210:213], v[76:79]
	v_mfma_f32_16x16x32_bf16 v[72:75], v[160:163], v[210:213], v[72:75]
	v_mfma_f32_16x16x32_bf16 v[116:119], v[164:167], v[180:183], v[116:119]
	v_mfma_f32_16x16x32_bf16 v[112:115], v[172:175], v[180:183], v[112:115]
	v_mfma_f32_16x16x32_bf16 v[100:103], v[164:167], v[190:193], v[100:103]
	v_mfma_f32_16x16x32_bf16 v[96:99], v[172:175], v[190:193], v[96:99]
	v_mfma_f32_16x16x32_bf16 v[84:87], v[164:167], v[198:201], v[84:87]
	v_mfma_f32_16x16x32_bf16 v[80:83], v[172:175], v[198:201], v[80:83]
	v_mfma_f32_16x16x32_bf16 v[68:71], v[164:167], v[206:209], v[68:71]
	v_mfma_f32_16x16x32_bf16 v[64:67], v[172:175], v[206:209], v[64:67]
	v_mfma_f32_16x16x32_bf16 v[116:119], v[168:171], v[184:187], v[116:119]
	v_mfma_f32_16x16x32_bf16 v[112:115], v[176:179], v[184:187], v[112:115]
	v_mfma_f32_16x16x32_bf16 v[100:103], v[168:171], v[194:197], v[100:103]
	v_mfma_f32_16x16x32_bf16 v[96:99], v[176:179], v[194:197], v[96:99]
	v_mfma_f32_16x16x32_bf16 v[84:87], v[168:171], v[202:205], v[84:87]
	v_mfma_f32_16x16x32_bf16 v[80:83], v[176:179], v[202:205], v[80:83]
	v_mfma_f32_16x16x32_bf16 v[68:71], v[168:171], v[210:213], v[68:71]
	v_mfma_f32_16x16x32_bf16 v[64:67], v[176:179], v[210:213], v[64:67]
	s_setprio 0
	s_barrier
	s_add_i32 s64, s53, s44
	s_mov_b32 m0, s64
	ds_read_b128 v[180:183], v146 offset:16384
	ds_read_b128 v[184:187], v146 offset:17408
	ds_read_b128 v[190:193], v146 offset:18432
	ds_read_b128 v[194:197], v146 offset:19456
	global_load_lds_dwordx4 v132, s[62:63]
	s_add_i32 m0, s64, 0x2000
	s_mov_b64 s[100:101], s[62:63]
	s_add_i32 s64, s54, s44
	global_load_lds_dwordx4 v134, s[62:63]
	s_add_u32 s62, s62, s16
	s_addc_u32 s63, s63, s17
	s_mov_b32 m0, s64
	ds_read_b128 v[210:213], v146 offset:23552
	global_load_lds_dwordx4 v132, s[62:63]
	s_add_i32 m0, s64, 0x2000
	ds_read_b128 v[206:209], v146 offset:22528
	global_load_lds_dwordx4 v134, s[62:63]
	s_mov_b32 m0, s33
	ds_read_b128 v[202:205], v146 offset:21504
	global_load_lds_dwordx4 v128, s[34:35]
	s_mov_b32 m0, s43
	ds_read_b128 v[198:201], v146 offset:20480
	global_load_lds_dwordx4 v130, s[34:35]
	s_waitcnt vmcnt(8) lgkmcnt(0)
	s_barrier
	s_setprio 1
	v_mfma_f32_16x16x32_bf16 v[60:63], v[148:151], v[180:183], v[60:63]
	v_mfma_f32_16x16x32_bf16 v[56:59], v[156:159], v[180:183], v[56:59]
	v_mfma_f32_16x16x32_bf16 v[44:47], v[148:151], v[190:193], v[44:47]
	v_mfma_f32_16x16x32_bf16 v[40:43], v[156:159], v[190:193], v[40:43]
	v_mfma_f32_16x16x32_bf16 v[28:31], v[148:151], v[198:201], v[28:31]
	v_mfma_f32_16x16x32_bf16 v[24:27], v[156:159], v[198:201], v[24:27]
	v_mfma_f32_16x16x32_bf16 v[12:15], v[148:151], v[206:209], v[12:15]
	v_mfma_f32_16x16x32_bf16 v[8:11], v[156:159], v[206:209], v[8:11]
	v_mfma_f32_16x16x32_bf16 v[60:63], v[152:155], v[184:187], v[60:63]
	v_mfma_f32_16x16x32_bf16 v[56:59], v[160:163], v[184:187], v[56:59]
	v_mfma_f32_16x16x32_bf16 v[44:47], v[152:155], v[194:197], v[44:47]
	v_mfma_f32_16x16x32_bf16 v[40:43], v[160:163], v[194:197], v[40:43]
	v_mfma_f32_16x16x32_bf16 v[28:31], v[152:155], v[202:205], v[28:31]
	v_mfma_f32_16x16x32_bf16 v[24:27], v[160:163], v[202:205], v[24:27]
	v_mfma_f32_16x16x32_bf16 v[12:15], v[152:155], v[210:213], v[12:15]
	v_mfma_f32_16x16x32_bf16 v[8:11], v[160:163], v[210:213], v[8:11]
	v_mfma_f32_16x16x32_bf16 v[52:55], v[164:167], v[180:183], v[52:55]
	v_mfma_f32_16x16x32_bf16 v[48:51], v[172:175], v[180:183], v[48:51]
	v_mfma_f32_16x16x32_bf16 v[36:39], v[164:167], v[190:193], v[36:39]
	v_mfma_f32_16x16x32_bf16 v[32:35], v[172:175], v[190:193], v[32:35]
	v_mfma_f32_16x16x32_bf16 v[20:23], v[164:167], v[198:201], v[20:23]
	v_mfma_f32_16x16x32_bf16 v[16:19], v[172:175], v[198:201], v[16:19]
	v_mfma_f32_16x16x32_bf16 v[4:7], v[164:167], v[206:209], v[4:7]
	v_mfma_f32_16x16x32_bf16 v[0:3], v[172:175], v[206:209], v[0:3]
	v_mfma_f32_16x16x32_bf16 v[52:55], v[168:171], v[184:187], v[52:55]
	v_mfma_f32_16x16x32_bf16 v[48:51], v[176:179], v[184:187], v[48:51]
	v_mfma_f32_16x16x32_bf16 v[36:39], v[168:171], v[194:197], v[36:39]
	v_mfma_f32_16x16x32_bf16 v[32:35], v[176:179], v[194:197], v[32:35]
	v_mfma_f32_16x16x32_bf16 v[20:23], v[168:171], v[202:205], v[20:23]
	v_mfma_f32_16x16x32_bf16 v[16:19], v[176:179], v[202:205], v[16:19]
	v_mfma_f32_16x16x32_bf16 v[4:7], v[168:171], v[210:213], v[4:7]
	v_mfma_f32_16x16x32_bf16 v[0:3], v[176:179], v[210:213], v[0:3]
	s_setprio 0
	s_barrier
; #define PG8_STAGE(bufoff, gbase, voff) do { _Pragma("unroll") for (int _i = 0; _i < 2; ++_i) \
;         __builtin_amdgcn_global_load_lds((const unsigned*)((const char*)(gbase) + (voff)[_i]), (PG8_LAS unsigned*)(lds + (bufoff) + ldsw + _i * 8192), 16, 0, 0); } while (0)
; #define PG8_LDA(dst, b, h) do { _Pragma("unroll") for (int m = 0; m < 4; ++m) _Pragma("unroll") for (int k = 0; k < 2; ++k) dst[m][k] = *(const PG8_LAS bf16x8*)(lds + PG8_SA(b, h) + aoff + m * 2048 + k * 1024); } while (0)
; #define PG8_LDB(dst, b, h) do { _Pragma("unroll") for (int n = 0; n < 2; ++n) _Pragma("unroll") for (int k = 0; k < 2; ++k) dst[n][k] = *(const PG8_LAS bf16x8*)(lds + PG8_SB(b, h) + boff + n * 2048 + k * 1024); } while (0)
; #define PG8_MMA(ai, bj, At, Bt) do { __builtin_amdgcn_s_setprio(1); _Pragma("unroll") for (int m = 0; m < 4; ++m) _Pragma("unroll") for (int n = 0; n < 2; ++n) _Pragma("unroll") for (int k = 0; k < 2; ++k) \
;         acc[ai][bj][m][n] = __builtin_amdgcn_mfma_f32_16x16x32_bf16(Bt[n][k], At[m][k], acc[ai][bj][m][n], 0, 0, 0); __builtin_amdgcn_s_setprio(0); } while (0)
; #define PG8_WAIT_V(n) asm volatile("s_waitcnt vmcnt(" #n ")" ::: "memory")
; #define PG8_WAIT_L(n) asm volatile("s_waitcnt lgkmcnt(" #n ")" ::: "memory")
; #define PG8_BAR __builtin_amdgcn_s_barrier()
; template <class Epi, class Sched, bool ALIGN_EPI = false, bool SP2 = false>
; __device__ __forceinline__ void gemm_phase(PG8_LAS unsigned char* lds, const Gemm g, const Sched& S, const Epi& E) {
;     ...
;         for (int t = 0; t < nt; t += 2) {
;             const bool last = (t == nt - 2);
;             const char* a1 = cA + (size_t)(t + 1) * kstep;
;             const char* a2 = last ? nA : cA + (size_t)(t + 2) * kstep; const char* b2 = last ? nB : cB + (size_t)(t + 2) * kstep;
;             const char* a3 = a2 + kstep; const char* b3 = b2 + kstep;
;     ...
;             PG8_LDB(B0, 1, 0); PG8_LDB(B1, 1, 1); PG8_SCHED; PG8_LDA(At, 1, 0); PG8_STAGE(PG8_SA(0, 1), a2 + hstepA, voffA);
;             PG8_WAIT_V(8); PG8_WAIT_L(0); PG8_BAR; PG8_MMA(0, 0, At, B0); PG8_MMA(0, 1, At, B1); PG8_BAR; PG8_SCHED;
;             PG8_LDA(At, 1, 1); PG8_STAGE(PG8_SB(1, 0), b3, voffB); PG8_STAGE(PG8_SB(1, 1), b3 + hstep, voffB); PG8_STAGE(PG8_SA(1, 0), a3, voffA);
;             PG8_WAIT_V(8); PG8_WAIT_L(0); PG8_BAR; PG8_MMA(1, 0, At, B0); PG8_MMA(1, 1, At, B1); PG8_BAR; PG8_SCHED;
	s_add_i32 s62, 0, 0x18000
	v_add_u32_e32 v147, s62, v142
	s_add_i32 s63, 0, 0x1c000
	ds_read_b128 v[148:151], v147
	ds_read_b128 v[152:155], v147 offset:1024
	ds_read_b128 v[156:159], v147 offset:2048
	ds_read_b128 v[160:163], v147 offset:3072
	v_add_u32_e32 v147, s63, v142
	ds_read_b128 v[164:167], v147
	ds_read_b128 v[168:171], v147 offset:1024
	ds_read_b128 v[172:175], v147 offset:2048
	ds_read_b128 v[176:179], v147 offset:3072
	s_mov_b64 vcc, s[34:35]
	s_add_u32 s34, s34, 0x40000
	s_addc_u32 s35, s35, 0
	s_mov_b32 m0, s45
	ds_read_b128 v[180:183], v146 offset:32768
	ds_read_b128 v[184:187], v146 offset:33792
	ds_read_b128 v[190:193], v146 offset:34816
	ds_read_b128 v[194:197], v146 offset:35840
	ds_read_b128 v[198:201], v146 offset:36864
	ds_read_b128 v[202:205], v146 offset:37888
	ds_read_b128 v[206:209], v146 offset:38912
	global_load_lds_dwordx4 v128, s[34:35]
	s_mov_b32 m0, s47
	ds_read_b128 v[210:213], v146 offset:39936
	global_load_lds_dwordx4 v130, s[34:35]
	s_waitcnt vmcnt(8) lgkmcnt(0)
	s_barrier
	s_setprio 1
	v_mfma_f32_16x16x32_bf16 v[124:127], v[148:151], v[180:183], v[124:127]
	v_mfma_f32_16x16x32_bf16 v[120:123], v[156:159], v[180:183], v[120:123]
	v_mfma_f32_16x16x32_bf16 v[108:111], v[148:151], v[190:193], v[108:111]
	v_mfma_f32_16x16x32_bf16 v[104:107], v[156:159], v[190:193], v[104:107]
	v_mfma_f32_16x16x32_bf16 v[92:95], v[148:151], v[198:201], v[92:95]
	v_mfma_f32_16x16x32_bf16 v[88:91], v[156:159], v[198:201], v[88:91]
	v_mfma_f32_16x16x32_bf16 v[76:79], v[148:151], v[206:209], v[76:79]
	v_mfma_f32_16x16x32_bf16 v[72:75], v[156:159], v[206:209], v[72:75]
	v_mfma_f32_16x16x32_bf16 v[124:127], v[152:155], v[184:187], v[124:127]
	v_mfma_f32_16x16x32_bf16 v[120:123], v[160:163], v[184:187], v[120:123]
	v_mfma_f32_16x16x32_bf16 v[108:111], v[152:155], v[194:197], v[108:111]
	v_mfma_f32_16x16x32_bf16 v[104:107], v[160:163], v[194:197], v[104:107]
	v_mfma_f32_16x16x32_bf16 v[92:95], v[152:155], v[202:205], v[92:95]
	v_mfma_f32_16x16x32_bf16 v[88:91], v[160:163], v[202:205], v[88:91]
	v_mfma_f32_16x16x32_bf16 v[76:79], v[152:155], v[210:213], v[76:79]
	v_mfma_f32_16x16x32_bf16 v[72:75], v[160:163], v[210:213], v[72:75]
	v_mfma_f32_16x16x32_bf16 v[116:119], v[164:167], v[180:183], v[116:119]
	v_mfma_f32_16x16x32_bf16 v[112:115], v[172:175], v[180:183], v[112:115]
	v_mfma_f32_16x16x32_bf16 v[100:103], v[164:167], v[190:193], v[100:103]
	v_mfma_f32_16x16x32_bf16 v[96:99], v[172:175], v[190:193], v[96:99]
	v_mfma_f32_16x16x32_bf16 v[84:87], v[164:167], v[198:201], v[84:87]
	v_mfma_f32_16x16x32_bf16 v[80:83], v[172:175], v[198:201], v[80:83]
	v_mfma_f32_16x16x32_bf16 v[68:71], v[164:167], v[206:209], v[68:71]
	v_mfma_f32_16x16x32_bf16 v[64:67], v[172:175], v[206:209], v[64:67]
	v_mfma_f32_16x16x32_bf16 v[116:119], v[168:171], v[184:187], v[116:119]
	v_mfma_f32_16x16x32_bf16 v[112:115], v[176:179], v[184:187], v[112:115]
	v_mfma_f32_16x16x32_bf16 v[100:103], v[168:171], v[194:197], v[100:103]
	v_mfma_f32_16x16x32_bf16 v[96:99], v[176:179], v[194:197], v[96:99]
	v_mfma_f32_16x16x32_bf16 v[84:87], v[168:171], v[202:205], v[84:87]
	v_mfma_f32_16x16x32_bf16 v[80:83], v[176:179], v[202:205], v[80:83]
	v_mfma_f32_16x16x32_bf16 v[68:71], v[168:171], v[210:213], v[68:71]
	v_mfma_f32_16x16x32_bf16 v[64:67], v[176:179], v[210:213], v[64:67]
	s_setprio 0
	s_barrier
	s_add_i32 s34, s62, s44
	s_add_i32 m0, s34, 0xffffff80
	ds_read_b128 v[180:183], v146 offset:49152
	ds_read_b128 v[184:187], v146 offset:50176
	ds_read_b128 v[190:193], v146 offset:51200
	ds_read_b128 v[194:197], v146 offset:52224
	global_load_lds_dwordx4 v132, s[100:101] offset:128
	s_add_i32 m0, s34, 0x1f80
	s_add_i32 s34, s63, s44
	global_load_lds_dwordx4 v134, s[100:101] offset:128
	s_add_u32 s100, s100, s16
	s_addc_u32 s101, s101, s17
	s_add_i32 m0, s34, 0xffffff80
	ds_read_b128 v[210:213], v146 offset:56320
	global_load_lds_dwordx4 v132, s[100:101] offset:128
	s_add_i32 m0, s34, 0x1f80
	ds_read_b128 v[206:209], v146 offset:55296
	global_load_lds_dwordx4 v134, s[100:101] offset:128
	s_add_i32 m0, s48, 0xffffff80
	ds_read_b128 v[202:205], v146 offset:54272
	global_load_lds_dwordx4 v128, vcc offset:128
	s_add_i32 m0, s49, 0xffffff80
	ds_read_b128 v[198:201], v146 offset:53248
	global_load_lds_dwordx4 v130, vcc offset:128
	s_waitcnt vmcnt(8) lgkmcnt(0)
	s_barrier
	s_setprio 1
	v_mfma_f32_16x16x32_bf16 v[60:63], v[148:151], v[180:183], v[60:63]
	v_mfma_f32_16x16x32_bf16 v[56:59], v[156:159], v[180:183], v[56:59]
	v_mfma_f32_16x16x32_bf16 v[44:47], v[148:151], v[190:193], v[44:47]
	v_mfma_f32_16x16x32_bf16 v[40:43], v[156:159], v[190:193], v[40:43]
	v_mfma_f32_16x16x32_bf16 v[28:31], v[148:151], v[198:201], v[28:31]
	v_mfma_f32_16x16x32_bf16 v[24:27], v[156:159], v[198:201], v[24:27]
	v_mfma_f32_16x16x32_bf16 v[12:15], v[148:151], v[206:209], v[12:15]
	v_mfma_f32_16x16x32_bf16 v[8:11], v[156:159], v[206:209], v[8:11]
	v_mfma_f32_16x16x32_bf16 v[60:63], v[152:155], v[184:187], v[60:63]
	v_mfma_f32_16x16x32_bf16 v[56:59], v[160:163], v[184:187], v[56:59]
	v_mfma_f32_16x16x32_bf16 v[44:47], v[152:155], v[194:197], v[44:47]
	v_mfma_f32_16x16x32_bf16 v[40:43], v[160:163], v[194:197], v[40:43]
	v_mfma_f32_16x16x32_bf16 v[28:31], v[152:155], v[202:205], v[28:31]
	v_mfma_f32_16x16x32_bf16 v[24:27], v[160:163], v[202:205], v[24:27]
	v_mfma_f32_16x16x32_bf16 v[12:15], v[152:155], v[210:213], v[12:15]
	v_mfma_f32_16x16x32_bf16 v[8:11], v[160:163], v[210:213], v[8:11]
	v_mfma_f32_16x16x32_bf16 v[52:55], v[164:167], v[180:183], v[52:55]
	v_mfma_f32_16x16x32_bf16 v[48:51], v[172:175], v[180:183], v[48:51]
	v_mfma_f32_16x16x32_bf16 v[36:39], v[164:167], v[190:193], v[36:39]
	v_mfma_f32_16x16x32_bf16 v[32:35], v[172:175], v[190:193], v[32:35]
	v_mfma_f32_16x16x32_bf16 v[20:23], v[164:167], v[198:201], v[20:23]
	v_mfma_f32_16x16x32_bf16 v[16:19], v[172:175], v[198:201], v[16:19]
	v_mfma_f32_16x16x32_bf16 v[4:7], v[164:167], v[206:209], v[4:7]
	v_mfma_f32_16x16x32_bf16 v[0:3], v[172:175], v[206:209], v[0:3]
	v_mfma_f32_16x16x32_bf16 v[52:55], v[168:171], v[184:187], v[52:55]
	v_mfma_f32_16x16x32_bf16 v[48:51], v[176:179], v[184:187], v[48:51]
	v_mfma_f32_16x16x32_bf16 v[36:39], v[168:171], v[194:197], v[36:39]
	v_mfma_f32_16x16x32_bf16 v[32:35], v[176:179], v[194:197], v[32:35]
	v_mfma_f32_16x16x32_bf16 v[20:23], v[168:171], v[202:205], v[20:23]
	v_mfma_f32_16x16x32_bf16 v[16:19], v[176:179], v[202:205], v[16:19]
	v_mfma_f32_16x16x32_bf16 v[4:7], v[168:171], v[210:213], v[4:7]
	v_mfma_f32_16x16x32_bf16 v[0:3], v[176:179], v[210:213], v[0:3]
	s_setprio 0
	s_barrier
	s_add_u32 s30, s30, 0x100
	s_addc_u32 s31, s31, 0
	s_add_u32 s37, s37, 0x100
	s_addc_u32 s60, s60, 0
	s_cmp_ge_i32 s61, s50
	s_mov_b32 s34, s61
	s_cbranch_scc0 .LBB0_282

; #define PG8_STAGE(bufoff, gbase, voff) do { _Pragma("unroll") for (int _i = 0; _i < 2; ++_i) \
;         __builtin_amdgcn_global_load_lds((const unsigned*)((const char*)(gbase) + (voff)[_i]), (PG8_LAS unsigned*)(lds + (bufoff) + ldsw + _i * 8192), 16, 0, 0); } while (0)
; #define PG8_LDA(dst, b, h) do { _Pragma("unroll") for (int m = 0; m < 4; ++m) _Pragma("unroll") for (int k = 0; k < 2; ++k) dst[m][k] = *(const PG8_LAS bf16x8*)(lds + PG8_SA(b, h) + aoff + m * 2048 + k * 1024); } while (0)
; #define PG8_LDB(dst, b, h) do { _Pragma("unroll") for (int n = 0; n < 2; ++n) _Pragma("unroll") for (int k = 0; k < 2; ++k) dst[n][k] = *(const PG8_LAS bf16x8*)(lds + PG8_SB(b, h) + boff + n * 2048 + k * 1024); } while (0)
; #define PG8_MMA(ai, bj, At, Bt) do { __builtin_amdgcn_s_setprio(1); _Pragma("unroll") for (int m = 0; m < 4; ++m) _Pragma("unroll") for (int n = 0; n < 2; ++n) _Pragma("unroll") for (int k = 0; k < 2; ++k) \
;         acc[ai][bj][m][n] = __builtin_amdgcn_mfma_f32_16x16x32_bf16(Bt[n][k], At[m][k], acc[ai][bj][m][n], 0, 0, 0); __builtin_amdgcn_s_setprio(0); } while (0)
; #define PG8_WAIT_V(n) asm volatile("s_waitcnt vmcnt(" #n ")" ::: "memory")
; #define PG8_BAR __builtin_amdgcn_s_barrier()
; template <class Epi, class Sched, bool ALIGN_EPI = false, bool SP2 = false>
; __device__ __forceinline__ void gemm_phase(PG8_LAS unsigned char* lds, const Gemm g, const Sched& S, const Epi& E) {
;     ...
;         for (int t = 0; t < nt; t += 2) {
;             const bool last = (t == nt - 2);
;             const char* a1 = cA + (size_t)(t + 1) * kstep;
;             const char* a2 = last ? nA : cA + (size_t)(t + 2) * kstep; const char* b2 = last ? nB : cB + (size_t)(t + 2) * kstep;
;             const char* a3 = a2 + kstep; const char* b3 = b2 + kstep;
;             if (last && has_next) S.a_ready(nxt);
;             if constexpr (SP2) {
;             PG8_LDB(B0, 0, 0); PG8_LDB(B1, 0, 1); PG8_SCHED; PG8_LDA(At, 0, 0); PG8_STAGE(PG8_SA(1, 1), a1 + hstepA, voffA);
;             PG8_WAIT_V(8); PG8_WAIT_L(0); PG8_BAR; PG8_MMA(0, 0, At, B0); PG8_MMA(0, 1, At, B1); PG8_BAR; PG8_SCHED;
;             PG8_LDA(At, 0, 1); PG8_STAGE(PG8_SB(0, 0), b2, voffB); PG8_STAGE(PG8_SB(0, 1), b2 + hstep, voffB); PG8_STAGE(PG8_SA(0, 0), a2, voffA);
;             PG8_WAIT_V(8); PG8_WAIT_L(0); PG8_BAR; PG8_MMA(1, 0, At, B0); PG8_MMA(1, 1, At, B1); PG8_BAR; PG8_SCHED;
.LBB0_368:
	ds_read_b128 v[154:157], v150
	ds_read_b128 v[158:161], v150 offset:1024
	ds_read_b128 v[162:165], v150 offset:2048
	ds_read_b128 v[166:169], v150 offset:3072
	ds_read_b128 v[170:173], v151
	ds_read_b128 v[174:177], v151 offset:1024
	ds_read_b128 v[178:181], v151 offset:2048
	ds_read_b128 v[182:185], v151 offset:3072
	s_add_i32 s64, s28, 2
	s_add_u32 s65, s26, 0xfffe0080
	s_addc_u32 s29, s27, -1
	s_cmp_eq_u32 s50, s28
	s_cselect_b32 s28, s30, s65
	s_cselect_b32 s29, s13, s29
	s_cselect_b32 s67, s21, s63
	s_cselect_b32 s66, s20, s62
	s_mov_b32 m0, s54
	ds_read_b128 v[190:193], v152
	ds_read_b128 v[194:197], v152 offset:1024
	ds_read_b128 v[198:201], v152 offset:2048
	ds_read_b128 v[202:205], v152 offset:3072
	ds_read_b128 v[206:209], v152 offset:4096
	ds_read_b128 v[210:213], v152 offset:5120
	ds_read_b128 v[214:217], v152 offset:6144
	global_load_lds_dwordx4 v138, s[26:27]
	s_mov_b32 m0, s55
	ds_read_b128 v[218:221], v152 offset:7168
	global_load_lds_dwordx4 v140, s[26:27]
	s_waitcnt vmcnt(8) lgkmcnt(0)
	s_barrier
	s_setprio 1
	v_mfma_f32_16x16x32_bf16 v[124:127], v[154:157], v[190:193], v[124:127]
	v_mfma_f32_16x16x32_bf16 v[120:123], v[162:165], v[190:193], v[120:123]
	v_mfma_f32_16x16x32_bf16 v[108:111], v[154:157], v[198:201], v[108:111]
	v_mfma_f32_16x16x32_bf16 v[104:107], v[162:165], v[198:201], v[104:107]
	v_mfma_f32_16x16x32_bf16 v[92:95], v[154:157], v[206:209], v[92:95]
	v_mfma_f32_16x16x32_bf16 v[88:91], v[162:165], v[206:209], v[88:91]
	v_mfma_f32_16x16x32_bf16 v[76:79], v[154:157], v[214:217], v[76:79]
	v_mfma_f32_16x16x32_bf16 v[72:75], v[162:165], v[214:217], v[72:75]
	v_mfma_f32_16x16x32_bf16 v[124:127], v[158:161], v[194:197], v[124:127]
	v_mfma_f32_16x16x32_bf16 v[120:123], v[166:169], v[194:197], v[120:123]
	v_mfma_f32_16x16x32_bf16 v[108:111], v[158:161], v[202:205], v[108:111]
	v_mfma_f32_16x16x32_bf16 v[104:107], v[166:169], v[202:205], v[104:107]
	v_mfma_f32_16x16x32_bf16 v[92:95], v[158:161], v[210:213], v[92:95]
	v_mfma_f32_16x16x32_bf16 v[88:91], v[166:169], v[210:213], v[88:91]
	v_mfma_f32_16x16x32_bf16 v[76:79], v[158:161], v[218:221], v[76:79]
	v_mfma_f32_16x16x32_bf16 v[72:75], v[166:169], v[218:221], v[72:75]
	v_mfma_f32_16x16x32_bf16 v[116:119], v[170:173], v[190:193], v[116:119]
	v_mfma_f32_16x16x32_bf16 v[112:115], v[178:181], v[190:193], v[112:115]
	v_mfma_f32_16x16x32_bf16 v[100:103], v[170:173], v[198:201], v[100:103]
	v_mfma_f32_16x16x32_bf16 v[96:99], v[178:181], v[198:201], v[96:99]
	v_mfma_f32_16x16x32_bf16 v[84:87], v[170:173], v[206:209], v[84:87]
	v_mfma_f32_16x16x32_bf16 v[80:83], v[178:181], v[206:209], v[80:83]
	v_mfma_f32_16x16x32_bf16 v[68:71], v[170:173], v[214:217], v[68:71]
	v_mfma_f32_16x16x32_bf16 v[64:67], v[178:181], v[214:217], v[64:67]
	v_mfma_f32_16x16x32_bf16 v[116:119], v[174:177], v[194:197], v[116:119]
	v_mfma_f32_16x16x32_bf16 v[112:115], v[182:185], v[194:197], v[112:115]
	v_mfma_f32_16x16x32_bf16 v[100:103], v[174:177], v[202:205], v[100:103]
	v_mfma_f32_16x16x32_bf16 v[96:99], v[182:185], v[202:205], v[96:99]
	v_mfma_f32_16x16x32_bf16 v[84:87], v[174:177], v[210:213], v[84:87]
	v_mfma_f32_16x16x32_bf16 v[80:83], v[182:185], v[210:213], v[80:83]
	v_mfma_f32_16x16x32_bf16 v[68:71], v[174:177], v[218:221], v[68:71]
	v_mfma_f32_16x16x32_bf16 v[64:67], v[182:185], v[218:221], v[64:67]
	s_setprio 0
	s_barrier
	s_mov_b32 m0, s56
	s_mov_b64 s[100:101], s[66:67]
	ds_read_b128 v[190:193], v152 offset:16384
	ds_read_b128 v[194:197], v152 offset:17408
	ds_read_b128 v[198:201], v152 offset:18432
	global_load_lds_dwordx4 v134, s[66:67]
	s_mov_b32 m0, s57
	ds_read_b128 v[218:221], v152 offset:23552
	global_load_lds_dwordx4 v132, s[66:67]
	s_add_u32 s66, s66, s4
	s_addc_u32 s67, s67, s5
	s_mov_b32 m0, s58
	ds_read_b128 v[214:217], v152 offset:22528
	global_load_lds_dwordx4 v134, s[66:67]
	s_mov_b32 m0, s59
	ds_read_b128 v[210:213], v152 offset:21504
	global_load_lds_dwordx4 v132, s[66:67]
	s_mov_b32 m0, s38
	ds_read_b128 v[206:209], v152 offset:20480
	global_load_lds_dwordx4 v130, s[28:29]
	s_mov_b32 m0, s39
	ds_read_b128 v[202:205], v152 offset:19456
	global_load_lds_dwordx4 v128, s[28:29]
	s_waitcnt vmcnt(8) lgkmcnt(0)
	s_barrier
	s_setprio 1
	v_mfma_f32_16x16x32_bf16 v[60:63], v[154:157], v[190:193], v[60:63]
	v_mfma_f32_16x16x32_bf16 v[56:59], v[162:165], v[190:193], v[56:59]
	v_mfma_f32_16x16x32_bf16 v[44:47], v[154:157], v[198:201], v[44:47]
	v_mfma_f32_16x16x32_bf16 v[40:43], v[162:165], v[198:201], v[40:43]
	v_mfma_f32_16x16x32_bf16 v[28:31], v[154:157], v[206:209], v[28:31]
	v_mfma_f32_16x16x32_bf16 v[24:27], v[162:165], v[206:209], v[24:27]
	v_mfma_f32_16x16x32_bf16 v[12:15], v[154:157], v[214:217], v[12:15]
	v_mfma_f32_16x16x32_bf16 v[8:11], v[162:165], v[214:217], v[8:11]
	v_mfma_f32_16x16x32_bf16 v[60:63], v[158:161], v[194:197], v[60:63]
	v_mfma_f32_16x16x32_bf16 v[56:59], v[166:169], v[194:197], v[56:59]
	v_mfma_f32_16x16x32_bf16 v[44:47], v[158:161], v[202:205], v[44:47]
	v_mfma_f32_16x16x32_bf16 v[40:43], v[166:169], v[202:205], v[40:43]
	v_mfma_f32_16x16x32_bf16 v[28:31], v[158:161], v[210:213], v[28:31]
	v_mfma_f32_16x16x32_bf16 v[24:27], v[166:169], v[210:213], v[24:27]
	v_mfma_f32_16x16x32_bf16 v[12:15], v[158:161], v[218:221], v[12:15]
	v_mfma_f32_16x16x32_bf16 v[8:11], v[166:169], v[218:221], v[8:11]
	v_mfma_f32_16x16x32_bf16 v[52:55], v[170:173], v[190:193], v[52:55]
	v_mfma_f32_16x16x32_bf16 v[48:51], v[178:181], v[190:193], v[48:51]
	v_mfma_f32_16x16x32_bf16 v[36:39], v[170:173], v[198:201], v[36:39]
	v_mfma_f32_16x16x32_bf16 v[32:35], v[178:181], v[198:201], v[32:35]
	v_mfma_f32_16x16x32_bf16 v[20:23], v[170:173], v[206:209], v[20:23]
	v_mfma_f32_16x16x32_bf16 v[16:19], v[178:181], v[206:209], v[16:19]
	v_mfma_f32_16x16x32_bf16 v[4:7], v[170:173], v[214:217], v[4:7]
	v_mfma_f32_16x16x32_bf16 v[0:3], v[178:181], v[214:217], v[0:3]
	v_mfma_f32_16x16x32_bf16 v[52:55], v[174:177], v[194:197], v[52:55]
	v_mfma_f32_16x16x32_bf16 v[48:51], v[182:185], v[194:197], v[48:51]
	v_mfma_f32_16x16x32_bf16 v[36:39], v[174:177], v[202:205], v[36:39]
	v_mfma_f32_16x16x32_bf16 v[32:35], v[182:185], v[202:205], v[32:35]
	v_mfma_f32_16x16x32_bf16 v[20:23], v[174:177], v[210:213], v[20:23]
	v_mfma_f32_16x16x32_bf16 v[16:19], v[182:185], v[210:213], v[16:19]
	v_mfma_f32_16x16x32_bf16 v[4:7], v[174:177], v[218:221], v[4:7]
	v_mfma_f32_16x16x32_bf16 v[0:3], v[182:185], v[218:221], v[0:3]
	s_setprio 0
	s_barrier
; #define PG8_STAGE(bufoff, gbase, voff) do { _Pragma("unroll") for (int _i = 0; _i < 2; ++_i) \
;         __builtin_amdgcn_global_load_lds((const unsigned*)((const char*)(gbase) + (voff)[_i]), (PG8_LAS unsigned*)(lds + (bufoff) + ldsw + _i * 8192), 16, 0, 0); } while (0)
; #define PG8_LDA(dst, b, h) do { _Pragma("unroll") for (int m = 0; m < 4; ++m) _Pragma("unroll") for (int k = 0; k < 2; ++k) dst[m][k] = *(const PG8_LAS bf16x8*)(lds + PG8_SA(b, h) + aoff + m * 2048 + k * 1024); } while (0)
; #define PG8_LDB(dst, b, h) do { _Pragma("unroll") for (int n = 0; n < 2; ++n) _Pragma("unroll") for (int k = 0; k < 2; ++k) dst[n][k] = *(const PG8_LAS bf16x8*)(lds + PG8_SB(b, h) + boff + n * 2048 + k * 1024); } while (0)
; #define PG8_MMA(ai, bj, At, Bt) do { __builtin_amdgcn_s_setprio(1); _Pragma("unroll") for (int m = 0; m < 4; ++m) _Pragma("unroll") for (int n = 0; n < 2; ++n) _Pragma("unroll") for (int k = 0; k < 2; ++k) \
;         acc[ai][bj][m][n] = __builtin_amdgcn_mfma_f32_16x16x32_bf16(Bt[n][k], At[m][k], acc[ai][bj][m][n], 0, 0, 0); __builtin_amdgcn_s_setprio(0); } while (0)
; #define PG8_WAIT_V(n) asm volatile("s_waitcnt vmcnt(" #n ")" ::: "memory")
; #define PG8_WAIT_L(n) asm volatile("s_waitcnt lgkmcnt(" #n ")" ::: "memory")
; #define PG8_BAR __builtin_amdgcn_s_barrier()
; template <class Epi, class Sched, bool ALIGN_EPI = false, bool SP2 = false>
; __device__ __forceinline__ void gemm_phase(PG8_LAS unsigned char* lds, const Gemm g, const Sched& S, const Epi& E) {
;     ...
;         for (int t = 0; t < nt; t += 2) {
;             const bool last = (t == nt - 2);
;             const char* a1 = cA + (size_t)(t + 1) * kstep;
;             const char* a2 = last ? nA : cA + (size_t)(t + 2) * kstep; const char* b2 = last ? nB : cB + (size_t)(t + 2) * kstep;
;             const char* a3 = a2 + kstep; const char* b3 = b2 + kstep;
;     ...
;             PG8_LDB(B0, 1, 0); PG8_LDB(B1, 1, 1); PG8_SCHED; PG8_LDA(At, 1, 0); PG8_STAGE(PG8_SA(0, 1), a2 + hstepA, voffA);
;             PG8_WAIT_V(8); PG8_WAIT_L(0); PG8_BAR; PG8_MMA(0, 0, At, B0); PG8_MMA(0, 1, At, B1); PG8_BAR; PG8_SCHED;
;             PG8_LDA(At, 1, 1); PG8_STAGE(PG8_SB(1, 0), b3, voffB); PG8_STAGE(PG8_SB(1, 1), b3 + hstep, voffB); PG8_STAGE(PG8_SA(1, 0), a3, voffA);
;             PG8_WAIT_V(8); PG8_WAIT_L(0); PG8_BAR; PG8_MMA(1, 0, At, B0); PG8_MMA(1, 1, At, B1); PG8_BAR; PG8_SCHED;
	s_add_i32 s65, 0, 0x18000
	s_add_i32 s66, 0, 0x1c000
	v_add_u32_e32 v166, s65, v149
	v_add_u32_e32 v182, s66, v149
	ds_read_b128 v[154:157], v166
	ds_read_b128 v[158:161], v166 offset:1024
	ds_read_b128 v[162:165], v166 offset:2048
	ds_read_b128 v[166:169], v166 offset:3072
	ds_read_b128 v[170:173], v182
	ds_read_b128 v[174:177], v182 offset:1024
	ds_read_b128 v[178:181], v182 offset:2048
	ds_read_b128 v[182:185], v182 offset:3072
	s_mov_b64 vcc, s[28:29]
	s_add_u32 s28, s28, 0x20000
	s_addc_u32 s29, s29, 0
	s_mov_b32 m0, s40
	ds_read_b128 v[190:193], v152 offset:32768
	ds_read_b128 v[194:197], v152 offset:33792
	ds_read_b128 v[198:201], v152 offset:34816
	ds_read_b128 v[202:205], v152 offset:35840
	ds_read_b128 v[206:209], v152 offset:36864
	ds_read_b128 v[210:213], v152 offset:37888
	ds_read_b128 v[214:217], v152 offset:38912
	global_load_lds_dwordx4 v130, s[28:29]
	s_mov_b32 m0, s41
	ds_read_b128 v[218:221], v152 offset:39936
	global_load_lds_dwordx4 v128, s[28:29]
	s_waitcnt vmcnt(8) lgkmcnt(0)
	s_barrier
	s_setprio 1
	v_mfma_f32_16x16x32_bf16 v[124:127], v[154:157], v[190:193], v[124:127]
	v_mfma_f32_16x16x32_bf16 v[120:123], v[162:165], v[190:193], v[120:123]
	v_mfma_f32_16x16x32_bf16 v[108:111], v[154:157], v[198:201], v[108:111]
	v_mfma_f32_16x16x32_bf16 v[104:107], v[162:165], v[198:201], v[104:107]
	v_mfma_f32_16x16x32_bf16 v[92:95], v[154:157], v[206:209], v[92:95]
	v_mfma_f32_16x16x32_bf16 v[88:91], v[162:165], v[206:209], v[88:91]
	v_mfma_f32_16x16x32_bf16 v[76:79], v[154:157], v[214:217], v[76:79]
	v_mfma_f32_16x16x32_bf16 v[72:75], v[162:165], v[214:217], v[72:75]
	v_mfma_f32_16x16x32_bf16 v[124:127], v[158:161], v[194:197], v[124:127]
	v_mfma_f32_16x16x32_bf16 v[120:123], v[166:169], v[194:197], v[120:123]
	v_mfma_f32_16x16x32_bf16 v[108:111], v[158:161], v[202:205], v[108:111]
	v_mfma_f32_16x16x32_bf16 v[104:107], v[166:169], v[202:205], v[104:107]
	v_mfma_f32_16x16x32_bf16 v[92:95], v[158:161], v[210:213], v[92:95]
	v_mfma_f32_16x16x32_bf16 v[88:91], v[166:169], v[210:213], v[88:91]
	v_mfma_f32_16x16x32_bf16 v[76:79], v[158:161], v[218:221], v[76:79]
	v_mfma_f32_16x16x32_bf16 v[72:75], v[166:169], v[218:221], v[72:75]
	v_mfma_f32_16x16x32_bf16 v[116:119], v[170:173], v[190:193], v[116:119]
	v_mfma_f32_16x16x32_bf16 v[112:115], v[178:181], v[190:193], v[112:115]
	v_mfma_f32_16x16x32_bf16 v[100:103], v[170:173], v[198:201], v[100:103]
	v_mfma_f32_16x16x32_bf16 v[96:99], v[178:181], v[198:201], v[96:99]
	v_mfma_f32_16x16x32_bf16 v[84:87], v[170:173], v[206:209], v[84:87]
	v_mfma_f32_16x16x32_bf16 v[80:83], v[178:181], v[206:209], v[80:83]
	v_mfma_f32_16x16x32_bf16 v[68:71], v[170:173], v[214:217], v[68:71]
	v_mfma_f32_16x16x32_bf16 v[64:67], v[178:181], v[214:217], v[64:67]
	v_mfma_f32_16x16x32_bf16 v[116:119], v[174:177], v[194:197], v[116:119]
	v_mfma_f32_16x16x32_bf16 v[112:115], v[182:185], v[194:197], v[112:115]
	v_mfma_f32_16x16x32_bf16 v[100:103], v[174:177], v[202:205], v[100:103]
	v_mfma_f32_16x16x32_bf16 v[96:99], v[182:185], v[202:205], v[96:99]
	v_mfma_f32_16x16x32_bf16 v[84:87], v[174:177], v[210:213], v[84:87]
	v_mfma_f32_16x16x32_bf16 v[80:83], v[182:185], v[210:213], v[80:83]
	v_mfma_f32_16x16x32_bf16 v[68:71], v[174:177], v[218:221], v[68:71]
	v_mfma_f32_16x16x32_bf16 v[64:67], v[182:185], v[218:221], v[64:67]
	s_setprio 0
	s_barrier
	s_add_i32 s28, s65, s37
	s_add_i32 m0, s28, 0xffffff80
	ds_read_b128 v[190:193], v152 offset:49152
	ds_read_b128 v[194:197], v152 offset:50176
	ds_read_b128 v[198:201], v152 offset:51200
	ds_read_b128 v[202:205], v152 offset:52224
	global_load_lds_dwordx4 v134, s[100:101] offset:128
	s_add_i32 m0, s28, 0x1f80
	s_add_i32 s28, s66, s37
	global_load_lds_dwordx4 v132, s[100:101] offset:128
	s_add_u32 s100, s100, s4
	s_addc_u32 s101, s101, s5
	s_add_i32 m0, s28, 0xffffff80
	ds_read_b128 v[218:221], v152 offset:56320
	global_load_lds_dwordx4 v134, s[100:101] offset:128
	s_add_i32 m0, s28, 0x1f80
	ds_read_b128 v[214:217], v152 offset:55296
	global_load_lds_dwordx4 v132, s[100:101] offset:128
	s_add_i32 m0, s43, 0xffffff80
	ds_read_b128 v[210:213], v152 offset:54272
	global_load_lds_dwordx4 v130, vcc offset:128
	s_add_i32 m0, s44, 0xffffff80
	ds_read_b128 v[206:209], v152 offset:53248
	global_load_lds_dwordx4 v128, vcc offset:128
	s_waitcnt vmcnt(8) lgkmcnt(0)
	s_barrier
	s_setprio 1
	v_mfma_f32_16x16x32_bf16 v[60:63], v[154:157], v[190:193], v[60:63]
	v_mfma_f32_16x16x32_bf16 v[56:59], v[162:165], v[190:193], v[56:59]
	v_mfma_f32_16x16x32_bf16 v[44:47], v[154:157], v[198:201], v[44:47]
	v_mfma_f32_16x16x32_bf16 v[40:43], v[162:165], v[198:201], v[40:43]
	v_mfma_f32_16x16x32_bf16 v[28:31], v[154:157], v[206:209], v[28:31]
	v_mfma_f32_16x16x32_bf16 v[24:27], v[162:165], v[206:209], v[24:27]
	v_mfma_f32_16x16x32_bf16 v[12:15], v[154:157], v[214:217], v[12:15]
	v_mfma_f32_16x16x32_bf16 v[8:11], v[162:165], v[214:217], v[8:11]
	v_mfma_f32_16x16x32_bf16 v[60:63], v[158:161], v[194:197], v[60:63]
	v_mfma_f32_16x16x32_bf16 v[56:59], v[166:169], v[194:197], v[56:59]
	v_mfma_f32_16x16x32_bf16 v[44:47], v[158:161], v[202:205], v[44:47]
	v_mfma_f32_16x16x32_bf16 v[40:43], v[166:169], v[202:205], v[40:43]
	v_mfma_f32_16x16x32_bf16 v[28:31], v[158:161], v[210:213], v[28:31]
	v_mfma_f32_16x16x32_bf16 v[24:27], v[166:169], v[210:213], v[24:27]
	v_mfma_f32_16x16x32_bf16 v[12:15], v[158:161], v[218:221], v[12:15]
	v_mfma_f32_16x16x32_bf16 v[8:11], v[166:169], v[218:221], v[8:11]
	v_mfma_f32_16x16x32_bf16 v[52:55], v[170:173], v[190:193], v[52:55]
	v_mfma_f32_16x16x32_bf16 v[48:51], v[178:181], v[190:193], v[48:51]
	v_mfma_f32_16x16x32_bf16 v[36:39], v[170:173], v[198:201], v[36:39]
	v_mfma_f32_16x16x32_bf16 v[32:35], v[178:181], v[198:201], v[32:35]
	v_mfma_f32_16x16x32_bf16 v[20:23], v[170:173], v[206:209], v[20:23]
	v_mfma_f32_16x16x32_bf16 v[16:19], v[178:181], v[206:209], v[16:19]
	v_mfma_f32_16x16x32_bf16 v[4:7], v[170:173], v[214:217], v[4:7]
	v_mfma_f32_16x16x32_bf16 v[0:3], v[178:181], v[214:217], v[0:3]
	v_mfma_f32_16x16x32_bf16 v[52:55], v[174:177], v[194:197], v[52:55]
	v_mfma_f32_16x16x32_bf16 v[48:51], v[182:185], v[194:197], v[48:51]
	v_mfma_f32_16x16x32_bf16 v[36:39], v[174:177], v[202:205], v[36:39]
	v_mfma_f32_16x16x32_bf16 v[32:35], v[182:185], v[202:205], v[32:35]
	v_mfma_f32_16x16x32_bf16 v[20:23], v[174:177], v[210:213], v[20:23]
	v_mfma_f32_16x16x32_bf16 v[16:19], v[182:185], v[210:213], v[16:19]
	v_mfma_f32_16x16x32_bf16 v[4:7], v[174:177], v[218:221], v[4:7]
	v_mfma_f32_16x16x32_bf16 v[0:3], v[182:185], v[218:221], v[0:3]
	s_setprio 0
	s_barrier
	s_add_u32 s26, s26, 0x100
	s_addc_u32 s27, s27, 0
	s_add_u32 s62, s62, 0x100
	s_addc_u32 s63, s63, 0
	s_cmp_ge_i32 s64, s48
	s_mov_b32 s28, s64
	s_cbranch_scc0 .LBB0_368

; #define PG8_STAGE(bufoff, gbase, voff) do { _Pragma("unroll") for (int _i = 0; _i < 2; ++_i) \
;         __builtin_amdgcn_global_load_lds((const unsigned*)((const char*)(gbase) + (voff)[_i]), (PG8_LAS unsigned*)(lds + (bufoff) + ldsw + _i * 8192), 16, 0, 0); } while (0)
; #define PG8_LDA(dst, b, h) do { _Pragma("unroll") for (int m = 0; m < 4; ++m) _Pragma("unroll") for (int k = 0; k < 2; ++k) dst[m][k] = *(const PG8_LAS bf16x8*)(lds + PG8_SA(b, h) + aoff + m * 2048 + k * 1024); } while (0)
; #define PG8_LDB(dst, b, h) do { _Pragma("unroll") for (int n = 0; n < 2; ++n) _Pragma("unroll") for (int k = 0; k < 2; ++k) dst[n][k] = *(const PG8_LAS bf16x8*)(lds + PG8_SB(b, h) + boff + n * 2048 + k * 1024); } while (0)
; #define PG8_MMA(ai, bj, At, Bt) do { __builtin_amdgcn_s_setprio(1); _Pragma("unroll") for (int m = 0; m < 4; ++m) _Pragma("unroll") for (int n = 0; n < 2; ++n) _Pragma("unroll") for (int k = 0; k < 2; ++k) \
;         acc[ai][bj][m][n] = __builtin_amdgcn_mfma_f32_16x16x32_bf16(Bt[n][k], At[m][k], acc[ai][bj][m][n], 0, 0, 0); __builtin_amdgcn_s_setprio(0); } while (0)
; #define PG8_WAIT_V(n) asm volatile("s_waitcnt vmcnt(" #n ")" ::: "memory")
; #define PG8_BAR __builtin_amdgcn_s_barrier()
; template <class Epi, class Sched, bool ALIGN_EPI = false, bool SP2 = false>
; __device__ __forceinline__ void gemm_phase(PG8_LAS unsigned char* lds, const Gemm g, const Sched& S, const Epi& E) {
;     ...
;         for (int t = 0; t < nt; t += 2) {
;             const bool last = (t == nt - 2);
;             const char* a1 = cA + (size_t)(t + 1) * kstep;
;             const char* a2 = last ? nA : cA + (size_t)(t + 2) * kstep; const char* b2 = last ? nB : cB + (size_t)(t + 2) * kstep;
;             const char* a3 = a2 + kstep; const char* b3 = b2 + kstep;
;             if (last && has_next) S.a_ready(nxt);
;             if constexpr (SP2) {
;             PG8_LDB(B0, 0, 0); PG8_LDB(B1, 0, 1); PG8_SCHED; PG8_LDA(At, 0, 0); PG8_STAGE(PG8_SA(1, 1), a1 + hstepA, voffA);
;             PG8_WAIT_V(8); PG8_WAIT_L(0); PG8_BAR; PG8_MMA(0, 0, At, B0); PG8_MMA(0, 1, At, B1); PG8_BAR; PG8_SCHED;
;             PG8_LDA(At, 0, 1); PG8_STAGE(PG8_SB(0, 0), b2, voffB); PG8_STAGE(PG8_SB(0, 1), b2 + hstep, voffB); PG8_STAGE(PG8_SA(0, 0), a2, voffA);
;             PG8_WAIT_V(8); PG8_WAIT_L(0); PG8_BAR; PG8_MMA(1, 0, At, B0); PG8_MMA(1, 1, At, B1); PG8_BAR; PG8_SCHED;
.LBB0_523:
	ds_read_b128 v[154:157], v149
	ds_read_b128 v[158:161], v149 offset:1024
	ds_read_b128 v[162:165], v149 offset:2048
	ds_read_b128 v[166:169], v149 offset:3072
	ds_read_b128 v[170:173], v150
	ds_read_b128 v[174:177], v150 offset:1024
	ds_read_b128 v[178:181], v150 offset:2048
	ds_read_b128 v[182:185], v150 offset:3072
	s_add_i32 s61, s30, 2
	s_add_u32 s62, s4, 0xfffe0080
	s_addc_u32 s31, s5, -1
	s_cmp_eq_u32 s52, s30
	s_cselect_b32 s30, s34, s62
	s_cselect_b32 s31, s15, s31
	s_cselect_b32 s63, s25, s60
	s_cselect_b32 s62, s24, s59
	s_add_i32 m0, s41, 0xc000
	ds_read_b128 v[190:193], v151
	ds_read_b128 v[194:197], v151 offset:1024
	ds_read_b128 v[198:201], v151 offset:2048
	ds_read_b128 v[202:205], v151 offset:3072
	ds_read_b128 v[206:209], v151 offset:4096
	ds_read_b128 v[210:213], v151 offset:5120
	ds_read_b128 v[214:217], v151 offset:6144
	global_load_lds_dwordx4 v138, s[4:5]
	s_add_i32 m0, s41, 0xe000
	ds_read_b128 v[218:221], v151 offset:7168
	global_load_lds_dwordx4 v140, s[4:5]
	s_waitcnt vmcnt(8) lgkmcnt(0)
	s_barrier
	s_setprio 1
	v_mfma_f32_16x16x32_bf16 v[124:127], v[154:157], v[190:193], v[124:127]
	v_mfma_f32_16x16x32_bf16 v[120:123], v[162:165], v[190:193], v[120:123]
	v_mfma_f32_16x16x32_bf16 v[108:111], v[154:157], v[198:201], v[108:111]
	v_mfma_f32_16x16x32_bf16 v[104:107], v[162:165], v[198:201], v[104:107]
	v_mfma_f32_16x16x32_bf16 v[92:95], v[154:157], v[206:209], v[92:95]
	v_mfma_f32_16x16x32_bf16 v[88:91], v[162:165], v[206:209], v[88:91]
	v_mfma_f32_16x16x32_bf16 v[76:79], v[154:157], v[214:217], v[76:79]
	v_mfma_f32_16x16x32_bf16 v[72:75], v[162:165], v[214:217], v[72:75]
	v_mfma_f32_16x16x32_bf16 v[124:127], v[158:161], v[194:197], v[124:127]
	v_mfma_f32_16x16x32_bf16 v[120:123], v[166:169], v[194:197], v[120:123]
	v_mfma_f32_16x16x32_bf16 v[108:111], v[158:161], v[202:205], v[108:111]
	v_mfma_f32_16x16x32_bf16 v[104:107], v[166:169], v[202:205], v[104:107]
	v_mfma_f32_16x16x32_bf16 v[92:95], v[158:161], v[210:213], v[92:95]
	v_mfma_f32_16x16x32_bf16 v[88:91], v[166:169], v[210:213], v[88:91]
	v_mfma_f32_16x16x32_bf16 v[76:79], v[158:161], v[218:221], v[76:79]
	v_mfma_f32_16x16x32_bf16 v[72:75], v[166:169], v[218:221], v[72:75]
	v_mfma_f32_16x16x32_bf16 v[116:119], v[170:173], v[190:193], v[116:119]
	v_mfma_f32_16x16x32_bf16 v[112:115], v[178:181], v[190:193], v[112:115]
	v_mfma_f32_16x16x32_bf16 v[100:103], v[170:173], v[198:201], v[100:103]
	v_mfma_f32_16x16x32_bf16 v[96:99], v[178:181], v[198:201], v[96:99]
	v_mfma_f32_16x16x32_bf16 v[84:87], v[170:173], v[206:209], v[84:87]
	v_mfma_f32_16x16x32_bf16 v[80:83], v[178:181], v[206:209], v[80:83]
	v_mfma_f32_16x16x32_bf16 v[68:71], v[170:173], v[214:217], v[68:71]
	v_mfma_f32_16x16x32_bf16 v[64:67], v[178:181], v[214:217], v[64:67]
	v_mfma_f32_16x16x32_bf16 v[116:119], v[174:177], v[194:197], v[116:119]
	v_mfma_f32_16x16x32_bf16 v[112:115], v[182:185], v[194:197], v[112:115]
	v_mfma_f32_16x16x32_bf16 v[100:103], v[174:177], v[202:205], v[100:103]
	v_mfma_f32_16x16x32_bf16 v[96:99], v[182:185], v[202:205], v[96:99]
	v_mfma_f32_16x16x32_bf16 v[84:87], v[174:177], v[210:213], v[84:87]
	v_mfma_f32_16x16x32_bf16 v[80:83], v[182:185], v[210:213], v[80:83]
	v_mfma_f32_16x16x32_bf16 v[68:71], v[174:177], v[218:221], v[68:71]
	v_mfma_f32_16x16x32_bf16 v[64:67], v[182:185], v[218:221], v[64:67]
	s_setprio 0
	s_barrier
	s_add_i32 s64, s54, s40
	s_mov_b32 m0, s64
	ds_read_b128 v[190:193], v151 offset:16384
	ds_read_b128 v[194:197], v151 offset:17408
	ds_read_b128 v[198:201], v151 offset:18432
	ds_read_b128 v[202:205], v151 offset:19456
	global_load_lds_dwordx4 v134, s[62:63]
	s_add_i32 m0, s64, 0x2000
	s_mov_b64 s[100:101], s[62:63]
	s_add_i32 s64, s55, s40
	global_load_lds_dwordx4 v132, s[62:63]
	s_add_u32 s62, s62, s10
	s_addc_u32 s63, s63, s11
	s_mov_b32 m0, s64
	ds_read_b128 v[218:221], v151 offset:23552
	global_load_lds_dwordx4 v134, s[62:63]
	s_add_i32 m0, s64, 0x2000
	ds_read_b128 v[214:217], v151 offset:22528
	global_load_lds_dwordx4 v132, s[62:63]
	s_mov_b32 m0, s41
	ds_read_b128 v[210:213], v151 offset:21504
	global_load_lds_dwordx4 v130, s[30:31]
	s_mov_b32 m0, s42
	ds_read_b128 v[206:209], v151 offset:20480
	global_load_lds_dwordx4 v128, s[30:31]
	s_waitcnt vmcnt(8) lgkmcnt(0)
	s_barrier
	s_setprio 1
	v_mfma_f32_16x16x32_bf16 v[60:63], v[154:157], v[190:193], v[60:63]
	v_mfma_f32_16x16x32_bf16 v[56:59], v[162:165], v[190:193], v[56:59]
	v_mfma_f32_16x16x32_bf16 v[44:47], v[154:157], v[198:201], v[44:47]
	v_mfma_f32_16x16x32_bf16 v[40:43], v[162:165], v[198:201], v[40:43]
	v_mfma_f32_16x16x32_bf16 v[28:31], v[154:157], v[206:209], v[28:31]
	v_mfma_f32_16x16x32_bf16 v[24:27], v[162:165], v[206:209], v[24:27]
	v_mfma_f32_16x16x32_bf16 v[12:15], v[154:157], v[214:217], v[12:15]
	v_mfma_f32_16x16x32_bf16 v[8:11], v[162:165], v[214:217], v[8:11]
	v_mfma_f32_16x16x32_bf16 v[60:63], v[158:161], v[194:197], v[60:63]
	v_mfma_f32_16x16x32_bf16 v[56:59], v[166:169], v[194:197], v[56:59]
	v_mfma_f32_16x16x32_bf16 v[44:47], v[158:161], v[202:205], v[44:47]
	v_mfma_f32_16x16x32_bf16 v[40:43], v[166:169], v[202:205], v[40:43]
	v_mfma_f32_16x16x32_bf16 v[28:31], v[158:161], v[210:213], v[28:31]
	v_mfma_f32_16x16x32_bf16 v[24:27], v[166:169], v[210:213], v[24:27]
	v_mfma_f32_16x16x32_bf16 v[12:15], v[158:161], v[218:221], v[12:15]
	v_mfma_f32_16x16x32_bf16 v[8:11], v[166:169], v[218:221], v[8:11]
	v_mfma_f32_16x16x32_bf16 v[52:55], v[170:173], v[190:193], v[52:55]
	v_mfma_f32_16x16x32_bf16 v[48:51], v[178:181], v[190:193], v[48:51]
	v_mfma_f32_16x16x32_bf16 v[36:39], v[170:173], v[198:201], v[36:39]
	v_mfma_f32_16x16x32_bf16 v[32:35], v[178:181], v[198:201], v[32:35]
	v_mfma_f32_16x16x32_bf16 v[20:23], v[170:173], v[206:209], v[20:23]
	v_mfma_f32_16x16x32_bf16 v[16:19], v[178:181], v[206:209], v[16:19]
	v_mfma_f32_16x16x32_bf16 v[4:7], v[170:173], v[214:217], v[4:7]
	v_mfma_f32_16x16x32_bf16 v[0:3], v[178:181], v[214:217], v[0:3]
	v_mfma_f32_16x16x32_bf16 v[52:55], v[174:177], v[194:197], v[52:55]
	v_mfma_f32_16x16x32_bf16 v[48:51], v[182:185], v[194:197], v[48:51]
	v_mfma_f32_16x16x32_bf16 v[36:39], v[174:177], v[202:205], v[36:39]
	v_mfma_f32_16x16x32_bf16 v[32:35], v[182:185], v[202:205], v[32:35]
	v_mfma_f32_16x16x32_bf16 v[20:23], v[174:177], v[210:213], v[20:23]
	v_mfma_f32_16x16x32_bf16 v[16:19], v[182:185], v[210:213], v[16:19]
	v_mfma_f32_16x16x32_bf16 v[4:7], v[174:177], v[218:221], v[4:7]
	v_mfma_f32_16x16x32_bf16 v[0:3], v[182:185], v[218:221], v[0:3]
	s_setprio 0
	s_barrier
; #define PG8_STAGE(bufoff, gbase, voff) do { _Pragma("unroll") for (int _i = 0; _i < 2; ++_i) \
;         __builtin_amdgcn_global_load_lds((const unsigned*)((const char*)(gbase) + (voff)[_i]), (PG8_LAS unsigned*)(lds + (bufoff) + ldsw + _i * 8192), 16, 0, 0); } while (0)
; #define PG8_LDA(dst, b, h) do { _Pragma("unroll") for (int m = 0; m < 4; ++m) _Pragma("unroll") for (int k = 0; k < 2; ++k) dst[m][k] = *(const PG8_LAS bf16x8*)(lds + PG8_SA(b, h) + aoff + m * 2048 + k * 1024); } while (0)
; #define PG8_LDB(dst, b, h) do { _Pragma("unroll") for (int n = 0; n < 2; ++n) _Pragma("unroll") for (int k = 0; k < 2; ++k) dst[n][k] = *(const PG8_LAS bf16x8*)(lds + PG8_SB(b, h) + boff + n * 2048 + k * 1024); } while (0)
; #define PG8_MMA(ai, bj, At, Bt) do { __builtin_amdgcn_s_setprio(1); _Pragma("unroll") for (int m = 0; m < 4; ++m) _Pragma("unroll") for (int n = 0; n < 2; ++n) _Pragma("unroll") for (int k = 0; k < 2; ++k) \
;         acc[ai][bj][m][n] = __builtin_amdgcn_mfma_f32_16x16x32_bf16(Bt[n][k], At[m][k], acc[ai][bj][m][n], 0, 0, 0); __builtin_amdgcn_s_setprio(0); } while (0)
; #define PG8_WAIT_V(n) asm volatile("s_waitcnt vmcnt(" #n ")" ::: "memory")
; #define PG8_WAIT_L(n) asm volatile("s_waitcnt lgkmcnt(" #n ")" ::: "memory")
; #define PG8_BAR __builtin_amdgcn_s_barrier()
; template <class Epi, class Sched, bool ALIGN_EPI = false, bool SP2 = false>
; __device__ __forceinline__ void gemm_phase(PG8_LAS unsigned char* lds, const Gemm g, const Sched& S, const Epi& E) {
;     ...
;         for (int t = 0; t < nt; t += 2) {
;             const bool last = (t == nt - 2);
;             const char* a1 = cA + (size_t)(t + 1) * kstep;
;             const char* a2 = last ? nA : cA + (size_t)(t + 2) * kstep; const char* b2 = last ? nB : cB + (size_t)(t + 2) * kstep;
;             const char* a3 = a2 + kstep; const char* b3 = b2 + kstep;
;     ...
;             PG8_LDB(B0, 1, 0); PG8_LDB(B1, 1, 1); PG8_SCHED; PG8_LDA(At, 1, 0); PG8_STAGE(PG8_SA(0, 1), a2 + hstepA, voffA);
;             PG8_WAIT_V(8); PG8_WAIT_L(0); PG8_BAR; PG8_MMA(0, 0, At, B0); PG8_MMA(0, 1, At, B1); PG8_BAR; PG8_SCHED;
;             PG8_LDA(At, 1, 1); PG8_STAGE(PG8_SB(1, 0), b3, voffB); PG8_STAGE(PG8_SB(1, 1), b3 + hstep, voffB); PG8_STAGE(PG8_SA(1, 0), a3, voffA);
;             PG8_WAIT_V(8); PG8_WAIT_L(0); PG8_BAR; PG8_MMA(1, 0, At, B0); PG8_MMA(1, 1, At, B1); PG8_BAR; PG8_SCHED;
	s_add_i32 s62, 0, 0x18000
	s_add_i32 s63, 0, 0x1c000
	v_add_u32_e32 v166, s62, v147
	v_add_u32_e32 v182, s63, v147
	ds_read_b128 v[154:157], v166
	ds_read_b128 v[158:161], v166 offset:1024
	ds_read_b128 v[162:165], v166 offset:2048
	ds_read_b128 v[166:169], v166 offset:3072
	ds_read_b128 v[170:173], v182
	ds_read_b128 v[174:177], v182 offset:1024
	ds_read_b128 v[178:181], v182 offset:2048
	ds_read_b128 v[182:185], v182 offset:3072
	s_mov_b64 vcc, s[30:31]
	s_add_u32 s30, s30, 0x20000
	s_addc_u32 s31, s31, 0
	s_mov_b32 m0, s43
	ds_read_b128 v[190:193], v151 offset:32768
	ds_read_b128 v[194:197], v151 offset:33792
	ds_read_b128 v[198:201], v151 offset:34816
	ds_read_b128 v[202:205], v151 offset:35840
	ds_read_b128 v[206:209], v151 offset:36864
	ds_read_b128 v[210:213], v151 offset:37888
	ds_read_b128 v[214:217], v151 offset:38912
	global_load_lds_dwordx4 v130, s[30:31]
	s_mov_b32 m0, s44
	ds_read_b128 v[218:221], v151 offset:39936
	global_load_lds_dwordx4 v128, s[30:31]
	s_waitcnt vmcnt(8) lgkmcnt(0)
	s_barrier
	s_setprio 1
	v_mfma_f32_16x16x32_bf16 v[124:127], v[154:157], v[190:193], v[124:127]
	v_mfma_f32_16x16x32_bf16 v[120:123], v[162:165], v[190:193], v[120:123]
	v_mfma_f32_16x16x32_bf16 v[108:111], v[154:157], v[198:201], v[108:111]
	v_mfma_f32_16x16x32_bf16 v[104:107], v[162:165], v[198:201], v[104:107]
	v_mfma_f32_16x16x32_bf16 v[92:95], v[154:157], v[206:209], v[92:95]
	v_mfma_f32_16x16x32_bf16 v[88:91], v[162:165], v[206:209], v[88:91]
	v_mfma_f32_16x16x32_bf16 v[76:79], v[154:157], v[214:217], v[76:79]
	v_mfma_f32_16x16x32_bf16 v[72:75], v[162:165], v[214:217], v[72:75]
	v_mfma_f32_16x16x32_bf16 v[124:127], v[158:161], v[194:197], v[124:127]
	v_mfma_f32_16x16x32_bf16 v[120:123], v[166:169], v[194:197], v[120:123]
	v_mfma_f32_16x16x32_bf16 v[108:111], v[158:161], v[202:205], v[108:111]
	v_mfma_f32_16x16x32_bf16 v[104:107], v[166:169], v[202:205], v[104:107]
	v_mfma_f32_16x16x32_bf16 v[92:95], v[158:161], v[210:213], v[92:95]
	v_mfma_f32_16x16x32_bf16 v[88:91], v[166:169], v[210:213], v[88:91]
	v_mfma_f32_16x16x32_bf16 v[76:79], v[158:161], v[218:221], v[76:79]
	v_mfma_f32_16x16x32_bf16 v[72:75], v[166:169], v[218:221], v[72:75]
	v_mfma_f32_16x16x32_bf16 v[116:119], v[170:173], v[190:193], v[116:119]
	v_mfma_f32_16x16x32_bf16 v[112:115], v[178:181], v[190:193], v[112:115]
	v_mfma_f32_16x16x32_bf16 v[100:103], v[170:173], v[198:201], v[100:103]
	v_mfma_f32_16x16x32_bf16 v[96:99], v[178:181], v[198:201], v[96:99]
	v_mfma_f32_16x16x32_bf16 v[84:87], v[170:173], v[206:209], v[84:87]
	v_mfma_f32_16x16x32_bf16 v[80:83], v[178:181], v[206:209], v[80:83]
	v_mfma_f32_16x16x32_bf16 v[68:71], v[170:173], v[214:217], v[68:71]
	v_mfma_f32_16x16x32_bf16 v[64:67], v[178:181], v[214:217], v[64:67]
	v_mfma_f32_16x16x32_bf16 v[116:119], v[174:177], v[194:197], v[116:119]
	v_mfma_f32_16x16x32_bf16 v[112:115], v[182:185], v[194:197], v[112:115]
	v_mfma_f32_16x16x32_bf16 v[100:103], v[174:177], v[202:205], v[100:103]
	v_mfma_f32_16x16x32_bf16 v[96:99], v[182:185], v[202:205], v[96:99]
	v_mfma_f32_16x16x32_bf16 v[84:87], v[174:177], v[210:213], v[84:87]
	v_mfma_f32_16x16x32_bf16 v[80:83], v[182:185], v[210:213], v[80:83]
	v_mfma_f32_16x16x32_bf16 v[68:71], v[174:177], v[218:221], v[68:71]
	v_mfma_f32_16x16x32_bf16 v[64:67], v[182:185], v[218:221], v[64:67]
	s_setprio 0
	s_barrier
	s_add_i32 s30, s62, s40
	s_add_i32 m0, s30, 0xffffff80
	ds_read_b128 v[190:193], v151 offset:49152
	ds_read_b128 v[194:197], v151 offset:50176
	ds_read_b128 v[198:201], v151 offset:51200
	ds_read_b128 v[202:205], v151 offset:52224
	global_load_lds_dwordx4 v134, s[100:101] offset:128
	s_add_i32 m0, s30, 0x1f80
	s_add_i32 s30, s63, s40
	global_load_lds_dwordx4 v132, s[100:101] offset:128
	s_add_u32 s100, s100, s10
	s_addc_u32 s101, s101, s11
	s_add_i32 m0, s30, 0xffffff80
	ds_read_b128 v[218:221], v151 offset:56320
	global_load_lds_dwordx4 v134, s[100:101] offset:128
	s_add_i32 m0, s30, 0x1f80
	ds_read_b128 v[214:217], v151 offset:55296
	global_load_lds_dwordx4 v132, s[100:101] offset:128
	s_add_i32 m0, s48, 0xffffff80
	ds_read_b128 v[210:213], v151 offset:54272
	global_load_lds_dwordx4 v130, vcc offset:128
	s_add_i32 m0, s49, 0xffffff80
	ds_read_b128 v[206:209], v151 offset:53248
	global_load_lds_dwordx4 v128, vcc offset:128
	s_waitcnt vmcnt(8) lgkmcnt(0)
	s_barrier
	s_setprio 1
	v_mfma_f32_16x16x32_bf16 v[60:63], v[154:157], v[190:193], v[60:63]
	v_mfma_f32_16x16x32_bf16 v[56:59], v[162:165], v[190:193], v[56:59]
	v_mfma_f32_16x16x32_bf16 v[44:47], v[154:157], v[198:201], v[44:47]
	v_mfma_f32_16x16x32_bf16 v[40:43], v[162:165], v[198:201], v[40:43]
	v_mfma_f32_16x16x32_bf16 v[28:31], v[154:157], v[206:209], v[28:31]
	v_mfma_f32_16x16x32_bf16 v[24:27], v[162:165], v[206:209], v[24:27]
	v_mfma_f32_16x16x32_bf16 v[12:15], v[154:157], v[214:217], v[12:15]
	v_mfma_f32_16x16x32_bf16 v[8:11], v[162:165], v[214:217], v[8:11]
	v_mfma_f32_16x16x32_bf16 v[60:63], v[158:161], v[194:197], v[60:63]
	v_mfma_f32_16x16x32_bf16 v[56:59], v[166:169], v[194:197], v[56:59]
	v_mfma_f32_16x16x32_bf16 v[44:47], v[158:161], v[202:205], v[44:47]
	v_mfma_f32_16x16x32_bf16 v[40:43], v[166:169], v[202:205], v[40:43]
	v_mfma_f32_16x16x32_bf16 v[28:31], v[158:161], v[210:213], v[28:31]
	v_mfma_f32_16x16x32_bf16 v[24:27], v[166:169], v[210:213], v[24:27]
	v_mfma_f32_16x16x32_bf16 v[12:15], v[158:161], v[218:221], v[12:15]
	v_mfma_f32_16x16x32_bf16 v[8:11], v[166:169], v[218:221], v[8:11]
	v_mfma_f32_16x16x32_bf16 v[52:55], v[170:173], v[190:193], v[52:55]
	v_mfma_f32_16x16x32_bf16 v[48:51], v[178:181], v[190:193], v[48:51]
	v_mfma_f32_16x16x32_bf16 v[36:39], v[170:173], v[198:201], v[36:39]
	v_mfma_f32_16x16x32_bf16 v[32:35], v[178:181], v[198:201], v[32:35]
	v_mfma_f32_16x16x32_bf16 v[20:23], v[170:173], v[206:209], v[20:23]
	v_mfma_f32_16x16x32_bf16 v[16:19], v[178:181], v[206:209], v[16:19]
	v_mfma_f32_16x16x32_bf16 v[4:7], v[170:173], v[214:217], v[4:7]
	v_mfma_f32_16x16x32_bf16 v[0:3], v[178:181], v[214:217], v[0:3]
	v_mfma_f32_16x16x32_bf16 v[52:55], v[174:177], v[194:197], v[52:55]
	v_mfma_f32_16x16x32_bf16 v[48:51], v[182:185], v[194:197], v[48:51]
	v_mfma_f32_16x16x32_bf16 v[36:39], v[174:177], v[202:205], v[36:39]
	v_mfma_f32_16x16x32_bf16 v[32:35], v[182:185], v[202:205], v[32:35]
	v_mfma_f32_16x16x32_bf16 v[20:23], v[174:177], v[210:213], v[20:23]
	v_mfma_f32_16x16x32_bf16 v[16:19], v[182:185], v[210:213], v[16:19]
	v_mfma_f32_16x16x32_bf16 v[4:7], v[174:177], v[218:221], v[4:7]
	v_mfma_f32_16x16x32_bf16 v[0:3], v[182:185], v[218:221], v[0:3]
	s_setprio 0
	s_barrier
	s_add_u32 s4, s4, 0x100
	s_addc_u32 s5, s5, 0
	s_add_u32 s59, s59, 0x100
	s_addc_u32 s60, s60, 0
	s_cmp_ge_i32 s61, s51
	s_mov_b32 s30, s61
	s_cbranch_scc0 .LBB0_523

; #define PG8_STAGE(bufoff, gbase, voff) do { _Pragma("unroll") for (int _i = 0; _i < 2; ++_i) \
;         __builtin_amdgcn_global_load_lds((const unsigned*)((const char*)(gbase) + (voff)[_i]), (PG8_LAS unsigned*)(lds + (bufoff) + ldsw + _i * 8192), 16, 0, 0); } while (0)
; #define PG8_LDA(dst, b, h) do { _Pragma("unroll") for (int m = 0; m < 4; ++m) _Pragma("unroll") for (int k = 0; k < 2; ++k) dst[m][k] = *(const PG8_LAS bf16x8*)(lds + PG8_SA(b, h) + aoff + m * 2048 + k * 1024); } while (0)
; #define PG8_LDB(dst, b, h) do { _Pragma("unroll") for (int n = 0; n < 2; ++n) _Pragma("unroll") for (int k = 0; k < 2; ++k) dst[n][k] = *(const PG8_LAS bf16x8*)(lds + PG8_SB(b, h) + boff + n * 2048 + k * 1024); } while (0)
; #define PG8_MMA(ai, bj, At, Bt) do { __builtin_amdgcn_s_setprio(1); _Pragma("unroll") for (int m = 0; m < 4; ++m) _Pragma("unroll") for (int n = 0; n < 2; ++n) _Pragma("unroll") for (int k = 0; k < 2; ++k) \
;         acc[ai][bj][m][n] = __builtin_amdgcn_mfma_f32_16x16x32_bf16(Bt[n][k], At[m][k], acc[ai][bj][m][n], 0, 0, 0); __builtin_amdgcn_s_setprio(0); } while (0)
; #define PG8_WAIT_V(n) asm volatile("s_waitcnt vmcnt(" #n ")" ::: "memory")
; #define PG8_BAR __builtin_amdgcn_s_barrier()
; template <class Epi, class Sched, bool ALIGN_EPI = false, bool SP2 = false>
; __device__ __forceinline__ void gemm_phase(PG8_LAS unsigned char* lds, const Gemm g, const Sched& S, const Epi& E) {
;     ...
;         for (int t = 0; t < nt; t += 2) {
;             const bool last = (t == nt - 2);
;             const char* a1 = cA + (size_t)(t + 1) * kstep;
;             const char* a2 = last ? nA : cA + (size_t)(t + 2) * kstep; const char* b2 = last ? nB : cB + (size_t)(t + 2) * kstep;
;             const char* a3 = a2 + kstep; const char* b3 = b2 + kstep;
;             if (last && has_next) S.a_ready(nxt);
;             if constexpr (SP2) {
;             PG8_LDB(B0, 0, 0); PG8_LDB(B1, 0, 1); PG8_SCHED; PG8_LDA(At, 0, 0); PG8_STAGE(PG8_SA(1, 1), a1 + hstepA, voffA);
;             PG8_WAIT_V(8); PG8_WAIT_L(0); PG8_BAR; PG8_MMA(0, 0, At, B0); PG8_MMA(0, 1, At, B1); PG8_BAR; PG8_SCHED;
;             PG8_LDA(At, 0, 1); PG8_STAGE(PG8_SB(0, 0), b2, voffB); PG8_STAGE(PG8_SB(0, 1), b2 + hstep, voffB); PG8_STAGE(PG8_SA(0, 0), a2, voffA);
;             PG8_WAIT_V(8); PG8_WAIT_L(0); PG8_BAR; PG8_MMA(1, 0, At, B0); PG8_MMA(1, 1, At, B1); PG8_BAR; PG8_SCHED;
.LBB0_601:
	ds_read_b128 v[150:153], v147
	ds_read_b128 v[154:157], v147 offset:1024
	ds_read_b128 v[158:161], v147 offset:2048
	ds_read_b128 v[162:165], v147 offset:3072
	ds_read_b128 v[166:169], v148
	ds_read_b128 v[170:173], v148 offset:1024
	ds_read_b128 v[174:177], v148 offset:2048
	ds_read_b128 v[178:181], v148 offset:3072
	s_add_i32 s60, s30, 2
	s_add_u32 s61, s10, 0xfffc0080
	s_addc_u32 s31, s11, -1
	s_cmp_eq_u32 s51, s30
	s_cselect_b32 s30, s59, s61
	s_cselect_b32 s31, s23, s31
	s_cselect_b32 s63, s25, s35
	s_cselect_b32 s62, s24, s34
	s_add_i32 m0, s29, 0xc000
	ds_read_b128 v[182:185], v149
	ds_read_b128 v[190:193], v149 offset:1024
	ds_read_b128 v[194:197], v149 offset:2048
	ds_read_b128 v[198:201], v149 offset:3072
	ds_read_b128 v[202:205], v149 offset:4096
	ds_read_b128 v[206:209], v149 offset:5120
	ds_read_b128 v[210:213], v149 offset:6144
	global_load_lds_dwordx4 v136, s[10:11]
	s_add_i32 m0, s29, 0xe000
	ds_read_b128 v[214:217], v149 offset:7168
	global_load_lds_dwordx4 v138, s[10:11]
	s_waitcnt vmcnt(8) lgkmcnt(0)
	s_barrier
	s_setprio 1
	v_mfma_f32_16x16x32_bf16 v[120:123], v[150:153], v[182:185], v[120:123]
	v_mfma_f32_16x16x32_bf16 v[112:115], v[158:161], v[182:185], v[112:115]
	v_mfma_f32_16x16x32_bf16 v[104:107], v[150:153], v[194:197], v[104:107]
	v_mfma_f32_16x16x32_bf16 v[96:99], v[158:161], v[194:197], v[96:99]
	v_mfma_f32_16x16x32_bf16 v[88:91], v[150:153], v[202:205], v[88:91]
	v_mfma_f32_16x16x32_bf16 v[80:83], v[158:161], v[202:205], v[80:83]
	v_mfma_f32_16x16x32_bf16 v[72:75], v[150:153], v[210:213], v[72:75]
	v_mfma_f32_16x16x32_bf16 v[64:67], v[158:161], v[210:213], v[64:67]
	v_mfma_f32_16x16x32_bf16 v[120:123], v[154:157], v[190:193], v[120:123]
	v_mfma_f32_16x16x32_bf16 v[112:115], v[162:165], v[190:193], v[112:115]
	v_mfma_f32_16x16x32_bf16 v[104:107], v[154:157], v[198:201], v[104:107]
	v_mfma_f32_16x16x32_bf16 v[96:99], v[162:165], v[198:201], v[96:99]
	v_mfma_f32_16x16x32_bf16 v[88:91], v[154:157], v[206:209], v[88:91]
	v_mfma_f32_16x16x32_bf16 v[80:83], v[162:165], v[206:209], v[80:83]
	v_mfma_f32_16x16x32_bf16 v[72:75], v[154:157], v[214:217], v[72:75]
	v_mfma_f32_16x16x32_bf16 v[64:67], v[162:165], v[214:217], v[64:67]
	v_mfma_f32_16x16x32_bf16 v[124:127], v[166:169], v[182:185], v[124:127]
	v_mfma_f32_16x16x32_bf16 v[116:119], v[174:177], v[182:185], v[116:119]
	v_mfma_f32_16x16x32_bf16 v[108:111], v[166:169], v[194:197], v[108:111]
	v_mfma_f32_16x16x32_bf16 v[100:103], v[174:177], v[194:197], v[100:103]
	v_mfma_f32_16x16x32_bf16 v[92:95], v[166:169], v[202:205], v[92:95]
	v_mfma_f32_16x16x32_bf16 v[84:87], v[174:177], v[202:205], v[84:87]
	v_mfma_f32_16x16x32_bf16 v[76:79], v[166:169], v[210:213], v[76:79]
	v_mfma_f32_16x16x32_bf16 v[68:71], v[174:177], v[210:213], v[68:71]
	v_mfma_f32_16x16x32_bf16 v[124:127], v[170:173], v[190:193], v[124:127]
	v_mfma_f32_16x16x32_bf16 v[116:119], v[178:181], v[190:193], v[116:119]
	v_mfma_f32_16x16x32_bf16 v[108:111], v[170:173], v[198:201], v[108:111]
	v_mfma_f32_16x16x32_bf16 v[100:103], v[178:181], v[198:201], v[100:103]
	v_mfma_f32_16x16x32_bf16 v[92:95], v[170:173], v[206:209], v[92:95]
	v_mfma_f32_16x16x32_bf16 v[84:87], v[178:181], v[206:209], v[84:87]
	v_mfma_f32_16x16x32_bf16 v[76:79], v[170:173], v[214:217], v[76:79]
	v_mfma_f32_16x16x32_bf16 v[68:71], v[178:181], v[214:217], v[68:71]
	s_setprio 0
	s_barrier
	s_add_i32 s61, s52, s38
	s_mov_b32 m0, s61
	ds_read_b128 v[182:185], v149 offset:16384
	ds_read_b128 v[190:193], v149 offset:17408
	ds_read_b128 v[194:197], v149 offset:18432
	ds_read_b128 v[198:201], v149 offset:19456
	global_load_lds_dwordx4 v134, s[62:63]
	s_add_i32 m0, s61, 0x2000
	s_mov_b64 s[100:101], s[62:63]
	s_add_i32 s61, s53, s38
	global_load_lds_dwordx4 v132, s[62:63]
	s_add_u32 s62, s62, s4
	s_addc_u32 s63, s63, s5
	s_mov_b32 m0, s61
	ds_read_b128 v[214:217], v149 offset:23552
	global_load_lds_dwordx4 v134, s[62:63]
	s_add_i32 m0, s61, 0x2000
	ds_read_b128 v[210:213], v149 offset:22528
	global_load_lds_dwordx4 v132, s[62:63]
	s_mov_b32 m0, s29
	ds_read_b128 v[206:209], v149 offset:21504
	global_load_lds_dwordx4 v128, s[30:31]
	s_mov_b32 m0, s41
	ds_read_b128 v[202:205], v149 offset:20480
	global_load_lds_dwordx4 v130, s[30:31]
	s_waitcnt vmcnt(8) lgkmcnt(0)
	s_barrier
	s_setprio 1
	v_mfma_f32_16x16x32_bf16 v[56:59], v[150:153], v[182:185], v[56:59]
	v_mfma_f32_16x16x32_bf16 v[48:51], v[158:161], v[182:185], v[48:51]
	v_mfma_f32_16x16x32_bf16 v[40:43], v[150:153], v[194:197], v[40:43]
	v_mfma_f32_16x16x32_bf16 v[32:35], v[158:161], v[194:197], v[32:35]
	v_mfma_f32_16x16x32_bf16 v[24:27], v[150:153], v[202:205], v[24:27]
	v_mfma_f32_16x16x32_bf16 v[16:19], v[158:161], v[202:205], v[16:19]
	v_mfma_f32_16x16x32_bf16 v[8:11], v[150:153], v[210:213], v[8:11]
	v_mfma_f32_16x16x32_bf16 v[0:3], v[158:161], v[210:213], v[0:3]
	v_mfma_f32_16x16x32_bf16 v[56:59], v[154:157], v[190:193], v[56:59]
	v_mfma_f32_16x16x32_bf16 v[48:51], v[162:165], v[190:193], v[48:51]
	v_mfma_f32_16x16x32_bf16 v[40:43], v[154:157], v[198:201], v[40:43]
	v_mfma_f32_16x16x32_bf16 v[32:35], v[162:165], v[198:201], v[32:35]
	v_mfma_f32_16x16x32_bf16 v[24:27], v[154:157], v[206:209], v[24:27]
	v_mfma_f32_16x16x32_bf16 v[16:19], v[162:165], v[206:209], v[16:19]
	v_mfma_f32_16x16x32_bf16 v[8:11], v[154:157], v[214:217], v[8:11]
	v_mfma_f32_16x16x32_bf16 v[0:3], v[162:165], v[214:217], v[0:3]
	v_mfma_f32_16x16x32_bf16 v[60:63], v[166:169], v[182:185], v[60:63]
	v_mfma_f32_16x16x32_bf16 v[52:55], v[174:177], v[182:185], v[52:55]
	v_mfma_f32_16x16x32_bf16 v[44:47], v[166:169], v[194:197], v[44:47]
	v_mfma_f32_16x16x32_bf16 v[36:39], v[174:177], v[194:197], v[36:39]
	v_mfma_f32_16x16x32_bf16 v[28:31], v[166:169], v[202:205], v[28:31]
	v_mfma_f32_16x16x32_bf16 v[20:23], v[174:177], v[202:205], v[20:23]
	v_mfma_f32_16x16x32_bf16 v[12:15], v[166:169], v[210:213], v[12:15]
	v_mfma_f32_16x16x32_bf16 v[4:7], v[174:177], v[210:213], v[4:7]
	v_mfma_f32_16x16x32_bf16 v[60:63], v[170:173], v[190:193], v[60:63]
	v_mfma_f32_16x16x32_bf16 v[52:55], v[178:181], v[190:193], v[52:55]
	v_mfma_f32_16x16x32_bf16 v[44:47], v[170:173], v[198:201], v[44:47]
	v_mfma_f32_16x16x32_bf16 v[36:39], v[178:181], v[198:201], v[36:39]
	v_mfma_f32_16x16x32_bf16 v[28:31], v[170:173], v[206:209], v[28:31]
	v_mfma_f32_16x16x32_bf16 v[20:23], v[178:181], v[206:209], v[20:23]
	v_mfma_f32_16x16x32_bf16 v[12:15], v[170:173], v[214:217], v[12:15]
	v_mfma_f32_16x16x32_bf16 v[4:7], v[178:181], v[214:217], v[4:7]
	s_setprio 0
	s_barrier
; #define PG8_STAGE(bufoff, gbase, voff) do { _Pragma("unroll") for (int _i = 0; _i < 2; ++_i) \
;         __builtin_amdgcn_global_load_lds((const unsigned*)((const char*)(gbase) + (voff)[_i]), (PG8_LAS unsigned*)(lds + (bufoff) + ldsw + _i * 8192), 16, 0, 0); } while (0)
; #define PG8_LDA(dst, b, h) do { _Pragma("unroll") for (int m = 0; m < 4; ++m) _Pragma("unroll") for (int k = 0; k < 2; ++k) dst[m][k] = *(const PG8_LAS bf16x8*)(lds + PG8_SA(b, h) + aoff + m * 2048 + k * 1024); } while (0)
; #define PG8_LDB(dst, b, h) do { _Pragma("unroll") for (int n = 0; n < 2; ++n) _Pragma("unroll") for (int k = 0; k < 2; ++k) dst[n][k] = *(const PG8_LAS bf16x8*)(lds + PG8_SB(b, h) + boff + n * 2048 + k * 1024); } while (0)
; #define PG8_MMA(ai, bj, At, Bt) do { __builtin_amdgcn_s_setprio(1); _Pragma("unroll") for (int m = 0; m < 4; ++m) _Pragma("unroll") for (int n = 0; n < 2; ++n) _Pragma("unroll") for (int k = 0; k < 2; ++k) \
;         acc[ai][bj][m][n] = __builtin_amdgcn_mfma_f32_16x16x32_bf16(Bt[n][k], At[m][k], acc[ai][bj][m][n], 0, 0, 0); __builtin_amdgcn_s_setprio(0); } while (0)
; #define PG8_WAIT_V(n) asm volatile("s_waitcnt vmcnt(" #n ")" ::: "memory")
; #define PG8_WAIT_L(n) asm volatile("s_waitcnt lgkmcnt(" #n ")" ::: "memory")
; #define PG8_BAR __builtin_amdgcn_s_barrier()
; template <class Epi, class Sched, bool ALIGN_EPI = false, bool SP2 = false>
; __device__ __forceinline__ void gemm_phase(PG8_LAS unsigned char* lds, const Gemm g, const Sched& S, const Epi& E) {
;     ...
;         for (int t = 0; t < nt; t += 2) {
;             const bool last = (t == nt - 2);
;             const char* a1 = cA + (size_t)(t + 1) * kstep;
;             const char* a2 = last ? nA : cA + (size_t)(t + 2) * kstep; const char* b2 = last ? nB : cB + (size_t)(t + 2) * kstep;
;             const char* a3 = a2 + kstep; const char* b3 = b2 + kstep;
;     ...
;             PG8_LDB(B0, 1, 0); PG8_LDB(B1, 1, 1); PG8_SCHED; PG8_LDA(At, 1, 0); PG8_STAGE(PG8_SA(0, 1), a2 + hstepA, voffA);
;             PG8_WAIT_V(8); PG8_WAIT_L(0); PG8_BAR; PG8_MMA(0, 0, At, B0); PG8_MMA(0, 1, At, B1); PG8_BAR; PG8_SCHED;
;             PG8_LDA(At, 1, 1); PG8_STAGE(PG8_SB(1, 0), b3, voffB); PG8_STAGE(PG8_SB(1, 1), b3 + hstep, voffB); PG8_STAGE(PG8_SA(1, 0), a3, voffA);
;             PG8_WAIT_V(8); PG8_WAIT_L(0); PG8_BAR; PG8_MMA(1, 0, At, B0); PG8_MMA(1, 1, At, B1); PG8_BAR; PG8_SCHED;
	s_add_i32 s61, 0, 0x18000
	s_add_i32 s62, 0, 0x1c000
	v_add_u32_e32 v162, s61, v145
	v_add_u32_e32 v178, s62, v145
	ds_read_b128 v[150:153], v162
	ds_read_b128 v[154:157], v162 offset:1024
	ds_read_b128 v[158:161], v162 offset:2048
	ds_read_b128 v[162:165], v162 offset:3072
	ds_read_b128 v[166:169], v178
	ds_read_b128 v[170:173], v178 offset:1024
	ds_read_b128 v[174:177], v178 offset:2048
	ds_read_b128 v[178:181], v178 offset:3072
	s_mov_b64 vcc, s[30:31]
	s_add_u32 s30, s30, 0x40000
	s_addc_u32 s31, s31, 0
	s_mov_b32 m0, s42
	ds_read_b128 v[182:185], v149 offset:32768
	ds_read_b128 v[190:193], v149 offset:33792
	ds_read_b128 v[194:197], v149 offset:34816
	ds_read_b128 v[198:201], v149 offset:35840
	ds_read_b128 v[202:205], v149 offset:36864
	ds_read_b128 v[206:209], v149 offset:37888
	ds_read_b128 v[210:213], v149 offset:38912
	global_load_lds_dwordx4 v128, s[30:31]
	s_mov_b32 m0, s43
	ds_read_b128 v[214:217], v149 offset:39936
	global_load_lds_dwordx4 v130, s[30:31]
	s_waitcnt vmcnt(8) lgkmcnt(0)
	s_barrier
	s_setprio 1
	v_mfma_f32_16x16x32_bf16 v[120:123], v[150:153], v[182:185], v[120:123]
	v_mfma_f32_16x16x32_bf16 v[112:115], v[158:161], v[182:185], v[112:115]
	v_mfma_f32_16x16x32_bf16 v[104:107], v[150:153], v[194:197], v[104:107]
	v_mfma_f32_16x16x32_bf16 v[96:99], v[158:161], v[194:197], v[96:99]
	v_mfma_f32_16x16x32_bf16 v[88:91], v[150:153], v[202:205], v[88:91]
	v_mfma_f32_16x16x32_bf16 v[80:83], v[158:161], v[202:205], v[80:83]
	v_mfma_f32_16x16x32_bf16 v[72:75], v[150:153], v[210:213], v[72:75]
	v_mfma_f32_16x16x32_bf16 v[64:67], v[158:161], v[210:213], v[64:67]
	v_mfma_f32_16x16x32_bf16 v[120:123], v[154:157], v[190:193], v[120:123]
	v_mfma_f32_16x16x32_bf16 v[112:115], v[162:165], v[190:193], v[112:115]
	v_mfma_f32_16x16x32_bf16 v[104:107], v[154:157], v[198:201], v[104:107]
	v_mfma_f32_16x16x32_bf16 v[96:99], v[162:165], v[198:201], v[96:99]
	v_mfma_f32_16x16x32_bf16 v[88:91], v[154:157], v[206:209], v[88:91]
	v_mfma_f32_16x16x32_bf16 v[80:83], v[162:165], v[206:209], v[80:83]
	v_mfma_f32_16x16x32_bf16 v[72:75], v[154:157], v[214:217], v[72:75]
	v_mfma_f32_16x16x32_bf16 v[64:67], v[162:165], v[214:217], v[64:67]
	v_mfma_f32_16x16x32_bf16 v[124:127], v[166:169], v[182:185], v[124:127]
	v_mfma_f32_16x16x32_bf16 v[116:119], v[174:177], v[182:185], v[116:119]
	v_mfma_f32_16x16x32_bf16 v[108:111], v[166:169], v[194:197], v[108:111]
	v_mfma_f32_16x16x32_bf16 v[100:103], v[174:177], v[194:197], v[100:103]
	v_mfma_f32_16x16x32_bf16 v[92:95], v[166:169], v[202:205], v[92:95]
	v_mfma_f32_16x16x32_bf16 v[84:87], v[174:177], v[202:205], v[84:87]
	v_mfma_f32_16x16x32_bf16 v[76:79], v[166:169], v[210:213], v[76:79]
	v_mfma_f32_16x16x32_bf16 v[68:71], v[174:177], v[210:213], v[68:71]
	v_mfma_f32_16x16x32_bf16 v[124:127], v[170:173], v[190:193], v[124:127]
	v_mfma_f32_16x16x32_bf16 v[116:119], v[178:181], v[190:193], v[116:119]
	v_mfma_f32_16x16x32_bf16 v[108:111], v[170:173], v[198:201], v[108:111]
	v_mfma_f32_16x16x32_bf16 v[100:103], v[178:181], v[198:201], v[100:103]
	v_mfma_f32_16x16x32_bf16 v[92:95], v[170:173], v[206:209], v[92:95]
	v_mfma_f32_16x16x32_bf16 v[84:87], v[178:181], v[206:209], v[84:87]
	v_mfma_f32_16x16x32_bf16 v[76:79], v[170:173], v[214:217], v[76:79]
	v_mfma_f32_16x16x32_bf16 v[68:71], v[178:181], v[214:217], v[68:71]
	s_setprio 0
	s_barrier
	s_add_i32 s30, s61, s38
	s_add_i32 m0, s30, 0xffffff80
	ds_read_b128 v[182:185], v149 offset:49152
	ds_read_b128 v[190:193], v149 offset:50176
	ds_read_b128 v[194:197], v149 offset:51200
	ds_read_b128 v[198:201], v149 offset:52224
	global_load_lds_dwordx4 v134, s[100:101] offset:128
	s_add_i32 m0, s30, 0x1f80
	s_add_i32 s30, s62, s38
	global_load_lds_dwordx4 v132, s[100:101] offset:128
	s_add_u32 s100, s100, s4
	s_addc_u32 s101, s101, s5
	s_add_i32 m0, s30, 0xffffff80
	ds_read_b128 v[214:217], v149 offset:56320
	global_load_lds_dwordx4 v134, s[100:101] offset:128
	s_add_i32 m0, s30, 0x1f80
	ds_read_b128 v[210:213], v149 offset:55296
	global_load_lds_dwordx4 v132, s[100:101] offset:128
	s_add_i32 m0, s47, 0xffffff80
	ds_read_b128 v[206:209], v149 offset:54272
	global_load_lds_dwordx4 v128, vcc offset:128
	s_add_i32 m0, s48, 0xffffff80
	ds_read_b128 v[202:205], v149 offset:53248
	global_load_lds_dwordx4 v130, vcc offset:128
	s_waitcnt vmcnt(8) lgkmcnt(0)
	s_barrier
	s_setprio 1
	v_mfma_f32_16x16x32_bf16 v[56:59], v[150:153], v[182:185], v[56:59]
	v_mfma_f32_16x16x32_bf16 v[48:51], v[158:161], v[182:185], v[48:51]
	v_mfma_f32_16x16x32_bf16 v[40:43], v[150:153], v[194:197], v[40:43]
	v_mfma_f32_16x16x32_bf16 v[32:35], v[158:161], v[194:197], v[32:35]
	v_mfma_f32_16x16x32_bf16 v[24:27], v[150:153], v[202:205], v[24:27]
	v_mfma_f32_16x16x32_bf16 v[16:19], v[158:161], v[202:205], v[16:19]
	v_mfma_f32_16x16x32_bf16 v[8:11], v[150:153], v[210:213], v[8:11]
	v_mfma_f32_16x16x32_bf16 v[0:3], v[158:161], v[210:213], v[0:3]
	v_mfma_f32_16x16x32_bf16 v[56:59], v[154:157], v[190:193], v[56:59]
	v_mfma_f32_16x16x32_bf16 v[48:51], v[162:165], v[190:193], v[48:51]
	v_mfma_f32_16x16x32_bf16 v[40:43], v[154:157], v[198:201], v[40:43]
	v_mfma_f32_16x16x32_bf16 v[32:35], v[162:165], v[198:201], v[32:35]
	v_mfma_f32_16x16x32_bf16 v[24:27], v[154:157], v[206:209], v[24:27]
	v_mfma_f32_16x16x32_bf16 v[16:19], v[162:165], v[206:209], v[16:19]
	v_mfma_f32_16x16x32_bf16 v[8:11], v[154:157], v[214:217], v[8:11]
	v_mfma_f32_16x16x32_bf16 v[0:3], v[162:165], v[214:217], v[0:3]
	v_mfma_f32_16x16x32_bf16 v[60:63], v[166:169], v[182:185], v[60:63]
	v_mfma_f32_16x16x32_bf16 v[52:55], v[174:177], v[182:185], v[52:55]
	v_mfma_f32_16x16x32_bf16 v[44:47], v[166:169], v[194:197], v[44:47]
	v_mfma_f32_16x16x32_bf16 v[36:39], v[174:177], v[194:197], v[36:39]
	v_mfma_f32_16x16x32_bf16 v[28:31], v[166:169], v[202:205], v[28:31]
	v_mfma_f32_16x16x32_bf16 v[20:23], v[174:177], v[202:205], v[20:23]
	v_mfma_f32_16x16x32_bf16 v[12:15], v[166:169], v[210:213], v[12:15]
	v_mfma_f32_16x16x32_bf16 v[4:7], v[174:177], v[210:213], v[4:7]
	v_mfma_f32_16x16x32_bf16 v[60:63], v[170:173], v[190:193], v[60:63]
	v_mfma_f32_16x16x32_bf16 v[52:55], v[178:181], v[190:193], v[52:55]
	v_mfma_f32_16x16x32_bf16 v[44:47], v[170:173], v[198:201], v[44:47]
	v_mfma_f32_16x16x32_bf16 v[36:39], v[178:181], v[198:201], v[36:39]
	v_mfma_f32_16x16x32_bf16 v[28:31], v[170:173], v[206:209], v[28:31]
	v_mfma_f32_16x16x32_bf16 v[20:23], v[178:181], v[206:209], v[20:23]
	v_mfma_f32_16x16x32_bf16 v[12:15], v[170:173], v[214:217], v[12:15]
	v_mfma_f32_16x16x32_bf16 v[4:7], v[178:181], v[214:217], v[4:7]
	s_setprio 0
	s_barrier
	s_add_u32 s10, s10, 0x100
	s_addc_u32 s11, s11, 0
	s_add_u32 s34, s34, 0x100
	s_addc_u32 s35, s35, 0
	s_cmp_ge_i32 s60, s50
	s_mov_b32 s30, s60
	s_cbranch_scc0 .LBB0_601

; #define PG8_STAGE(bufoff, gbase, voff) do { _Pragma("unroll") for (int _i = 0; _i < 2; ++_i) \
;         __builtin_amdgcn_global_load_lds((const unsigned*)((const char*)(gbase) + (voff)[_i]), (PG8_LAS unsigned*)(lds + (bufoff) + ldsw + _i * 8192), 16, 0, 0); } while (0)
; #define PG8_LDA(dst, b, h) do { _Pragma("unroll") for (int m = 0; m < 4; ++m) _Pragma("unroll") for (int k = 0; k < 2; ++k) dst[m][k] = *(const PG8_LAS bf16x8*)(lds + PG8_SA(b, h) + aoff + m * 2048 + k * 1024); } while (0)
; #define PG8_LDB(dst, b, h) do { _Pragma("unroll") for (int n = 0; n < 2; ++n) _Pragma("unroll") for (int k = 0; k < 2; ++k) dst[n][k] = *(const PG8_LAS bf16x8*)(lds + PG8_SB(b, h) + boff + n * 2048 + k * 1024); } while (0)
; #define PG8_MMA(ai, bj, At, Bt) do { __builtin_amdgcn_s_setprio(1); _Pragma("unroll") for (int m = 0; m < 4; ++m) _Pragma("unroll") for (int n = 0; n < 2; ++n) _Pragma("unroll") for (int k = 0; k < 2; ++k) \
;         acc[ai][bj][m][n] = __builtin_amdgcn_mfma_f32_16x16x32_bf16(Bt[n][k], At[m][k], acc[ai][bj][m][n], 0, 0, 0); __builtin_amdgcn_s_setprio(0); } while (0)
; #define PG8_WAIT_V(n) asm volatile("s_waitcnt vmcnt(" #n ")" ::: "memory")
; #define PG8_BAR __builtin_amdgcn_s_barrier()
; template <class Epi, class Sched, bool ALIGN_EPI = false, bool SP2 = false>
; __device__ __forceinline__ void gemm_phase(PG8_LAS unsigned char* lds, const Gemm g, const Sched& S, const Epi& E) {
;     ...
;         for (int t = 0; t < nt; t += 2) {
;             const bool last = (t == nt - 2);
;             const char* a1 = cA + (size_t)(t + 1) * kstep;
;             const char* a2 = last ? nA : cA + (size_t)(t + 2) * kstep; const char* b2 = last ? nB : cB + (size_t)(t + 2) * kstep;
;             const char* a3 = a2 + kstep; const char* b3 = b2 + kstep;
;             if (last && has_next) S.a_ready(nxt);
;             if constexpr (SP2) {
;             PG8_LDB(B0, 0, 0); PG8_LDB(B1, 0, 1); PG8_SCHED; PG8_LDA(At, 0, 0); PG8_STAGE(PG8_SA(1, 1), a1 + hstepA, voffA);
;             PG8_WAIT_V(8); PG8_WAIT_L(0); PG8_BAR; PG8_MMA(0, 0, At, B0); PG8_MMA(0, 1, At, B1); PG8_BAR; PG8_SCHED;
;             PG8_LDA(At, 0, 1); PG8_STAGE(PG8_SB(0, 0), b2, voffB); PG8_STAGE(PG8_SB(0, 1), b2 + hstep, voffB); PG8_STAGE(PG8_SA(0, 0), a2, voffA);
;             PG8_WAIT_V(8); PG8_WAIT_L(0); PG8_BAR; PG8_MMA(1, 0, At, B0); PG8_MMA(1, 1, At, B1); PG8_BAR; PG8_SCHED;
.LBB0_681:
	ds_read_b128 v[128:131], v175
	ds_read_b128 v[132:135], v175 offset:1024
	ds_read_b128 v[136:139], v175 offset:2048
	ds_read_b128 v[140:143], v175 offset:3072
	ds_read_b128 v[162:165], v176
	ds_read_b128 v[166:169], v176 offset:1024
	ds_read_b128 v[180:183], v176 offset:2048
	ds_read_b128 v[184:187], v176 offset:3072
	s_add_i32 s71, s48, 2
	s_add_u32 s72, s8, 0xfffc0080
	s_addc_u32 s49, s9, -1
	s_cmp_eq_u32 s64, s48
	s_cselect_b32 s48, s70, s72
	s_cselect_b32 s49, s39, s49
	s_cselect_b32 s73, s41, s51
	s_cselect_b32 s72, s40, s50
	s_add_i32 m0, s45, 0xc000
	ds_read_b128 v[190:193], v177
	ds_read_b128 v[194:197], v177 offset:1024
	ds_read_b128 v[198:201], v177 offset:2048
	ds_read_b128 v[202:205], v177 offset:3072
	ds_read_b128 v[206:209], v177 offset:4096
	ds_read_b128 v[210:213], v177 offset:5120
	ds_read_b128 v[214:217], v177 offset:6144
	global_load_lds_dwordx4 v154, s[8:9]
	s_add_i32 m0, s45, 0xe000
	ds_read_b128 v[218:221], v177 offset:7168
	global_load_lds_dwordx4 v156, s[8:9]
	s_waitcnt vmcnt(8) lgkmcnt(0)
	s_barrier
	s_setprio 1
	v_mfma_f32_16x16x32_bf16 v[124:127], v[128:131], v[190:193], v[124:127]
	v_mfma_f32_16x16x32_bf16 v[120:123], v[136:139], v[190:193], v[120:123]
	v_mfma_f32_16x16x32_bf16 v[108:111], v[128:131], v[198:201], v[108:111]
	v_mfma_f32_16x16x32_bf16 v[104:107], v[136:139], v[198:201], v[104:107]
	v_mfma_f32_16x16x32_bf16 v[92:95], v[128:131], v[206:209], v[92:95]
	v_mfma_f32_16x16x32_bf16 v[88:91], v[136:139], v[206:209], v[88:91]
	v_mfma_f32_16x16x32_bf16 v[76:79], v[128:131], v[214:217], v[76:79]
	v_mfma_f32_16x16x32_bf16 v[72:75], v[136:139], v[214:217], v[72:75]
	v_mfma_f32_16x16x32_bf16 v[124:127], v[132:135], v[194:197], v[124:127]
	v_mfma_f32_16x16x32_bf16 v[120:123], v[140:143], v[194:197], v[120:123]
	v_mfma_f32_16x16x32_bf16 v[108:111], v[132:135], v[202:205], v[108:111]
	v_mfma_f32_16x16x32_bf16 v[104:107], v[140:143], v[202:205], v[104:107]
	v_mfma_f32_16x16x32_bf16 v[92:95], v[132:135], v[210:213], v[92:95]
	v_mfma_f32_16x16x32_bf16 v[88:91], v[140:143], v[210:213], v[88:91]
	v_mfma_f32_16x16x32_bf16 v[76:79], v[132:135], v[218:221], v[76:79]
	v_mfma_f32_16x16x32_bf16 v[72:75], v[140:143], v[218:221], v[72:75]
	v_mfma_f32_16x16x32_bf16 v[116:119], v[162:165], v[190:193], v[116:119]
	v_mfma_f32_16x16x32_bf16 v[112:115], v[180:183], v[190:193], v[112:115]
	v_mfma_f32_16x16x32_bf16 v[100:103], v[162:165], v[198:201], v[100:103]
	v_mfma_f32_16x16x32_bf16 v[96:99], v[180:183], v[198:201], v[96:99]
	v_mfma_f32_16x16x32_bf16 v[84:87], v[162:165], v[206:209], v[84:87]
	v_mfma_f32_16x16x32_bf16 v[80:83], v[180:183], v[206:209], v[80:83]
	v_mfma_f32_16x16x32_bf16 v[68:71], v[162:165], v[214:217], v[68:71]
	v_mfma_f32_16x16x32_bf16 v[64:67], v[180:183], v[214:217], v[64:67]
	v_mfma_f32_16x16x32_bf16 v[116:119], v[166:169], v[194:197], v[116:119]
	v_mfma_f32_16x16x32_bf16 v[112:115], v[184:187], v[194:197], v[112:115]
	v_mfma_f32_16x16x32_bf16 v[100:103], v[166:169], v[202:205], v[100:103]
	v_mfma_f32_16x16x32_bf16 v[96:99], v[184:187], v[202:205], v[96:99]
	v_mfma_f32_16x16x32_bf16 v[84:87], v[166:169], v[210:213], v[84:87]
	v_mfma_f32_16x16x32_bf16 v[80:83], v[184:187], v[210:213], v[80:83]
	v_mfma_f32_16x16x32_bf16 v[68:71], v[166:169], v[218:221], v[68:71]
	v_mfma_f32_16x16x32_bf16 v[64:67], v[184:187], v[218:221], v[64:67]
	s_setprio 0
	s_barrier
	s_add_i32 s74, s65, s53
	s_mov_b32 m0, s74
	ds_read_b128 v[190:193], v177 offset:16384
	ds_read_b128 v[194:197], v177 offset:17408
	ds_read_b128 v[198:201], v177 offset:18432
	ds_read_b128 v[202:205], v177 offset:19456
	global_load_lds_dwordx4 v150, s[72:73]
	s_add_i32 m0, s74, 0x2000
	s_mov_b64 s[100:101], s[72:73]
	s_add_i32 s74, s66, s53
	global_load_lds_dwordx4 v148, s[72:73]
	s_add_u32 s72, s72, s10
	s_addc_u32 s73, s73, s11
	s_mov_b32 m0, s74
	ds_read_b128 v[218:221], v177 offset:23552
	global_load_lds_dwordx4 v150, s[72:73]
	s_add_i32 m0, s74, 0x2000
	ds_read_b128 v[214:217], v177 offset:22528
	global_load_lds_dwordx4 v148, s[72:73]
	s_mov_b32 m0, s45
	ds_read_b128 v[210:213], v177 offset:21504
	global_load_lds_dwordx4 v144, s[48:49]
	s_mov_b32 m0, s55
	ds_read_b128 v[206:209], v177 offset:20480
	global_load_lds_dwordx4 v146, s[48:49]
	s_waitcnt vmcnt(8) lgkmcnt(0)
	s_barrier
	s_setprio 1
	v_mfma_f32_16x16x32_bf16 v[60:63], v[128:131], v[190:193], v[60:63]
	v_mfma_f32_16x16x32_bf16 v[56:59], v[136:139], v[190:193], v[56:59]
	v_mfma_f32_16x16x32_bf16 v[44:47], v[128:131], v[198:201], v[44:47]
	v_mfma_f32_16x16x32_bf16 v[40:43], v[136:139], v[198:201], v[40:43]
	v_mfma_f32_16x16x32_bf16 v[28:31], v[128:131], v[206:209], v[28:31]
	v_mfma_f32_16x16x32_bf16 v[24:27], v[136:139], v[206:209], v[24:27]
	v_mfma_f32_16x16x32_bf16 v[12:15], v[128:131], v[214:217], v[12:15]
	v_mfma_f32_16x16x32_bf16 v[8:11], v[136:139], v[214:217], v[8:11]
	v_mfma_f32_16x16x32_bf16 v[60:63], v[132:135], v[194:197], v[60:63]
	v_mfma_f32_16x16x32_bf16 v[56:59], v[140:143], v[194:197], v[56:59]
	v_mfma_f32_16x16x32_bf16 v[44:47], v[132:135], v[202:205], v[44:47]
	v_mfma_f32_16x16x32_bf16 v[40:43], v[140:143], v[202:205], v[40:43]
	v_mfma_f32_16x16x32_bf16 v[28:31], v[132:135], v[210:213], v[28:31]
	v_mfma_f32_16x16x32_bf16 v[24:27], v[140:143], v[210:213], v[24:27]
	v_mfma_f32_16x16x32_bf16 v[12:15], v[132:135], v[218:221], v[12:15]
	v_mfma_f32_16x16x32_bf16 v[8:11], v[140:143], v[218:221], v[8:11]
	v_mfma_f32_16x16x32_bf16 v[52:55], v[162:165], v[190:193], v[52:55]
	v_mfma_f32_16x16x32_bf16 v[48:51], v[180:183], v[190:193], v[48:51]
	v_mfma_f32_16x16x32_bf16 v[36:39], v[162:165], v[198:201], v[36:39]
	v_mfma_f32_16x16x32_bf16 v[32:35], v[180:183], v[198:201], v[32:35]
	v_mfma_f32_16x16x32_bf16 v[20:23], v[162:165], v[206:209], v[20:23]
	v_mfma_f32_16x16x32_bf16 v[16:19], v[180:183], v[206:209], v[16:19]
	v_mfma_f32_16x16x32_bf16 v[4:7], v[162:165], v[214:217], v[4:7]
	v_mfma_f32_16x16x32_bf16 v[0:3], v[180:183], v[214:217], v[0:3]
	v_mfma_f32_16x16x32_bf16 v[52:55], v[166:169], v[194:197], v[52:55]
	v_mfma_f32_16x16x32_bf16 v[48:51], v[184:187], v[194:197], v[48:51]
	v_mfma_f32_16x16x32_bf16 v[36:39], v[166:169], v[202:205], v[36:39]
	v_mfma_f32_16x16x32_bf16 v[32:35], v[184:187], v[202:205], v[32:35]
	v_mfma_f32_16x16x32_bf16 v[20:23], v[166:169], v[210:213], v[20:23]
	v_mfma_f32_16x16x32_bf16 v[16:19], v[184:187], v[210:213], v[16:19]
	v_mfma_f32_16x16x32_bf16 v[4:7], v[166:169], v[218:221], v[4:7]
	v_mfma_f32_16x16x32_bf16 v[0:3], v[184:187], v[218:221], v[0:3]
	s_setprio 0
	s_barrier
; #define PG8_STAGE(bufoff, gbase, voff) do { _Pragma("unroll") for (int _i = 0; _i < 2; ++_i) \
;         __builtin_amdgcn_global_load_lds((const unsigned*)((const char*)(gbase) + (voff)[_i]), (PG8_LAS unsigned*)(lds + (bufoff) + ldsw + _i * 8192), 16, 0, 0); } while (0)
; #define PG8_LDA(dst, b, h) do { _Pragma("unroll") for (int m = 0; m < 4; ++m) _Pragma("unroll") for (int k = 0; k < 2; ++k) dst[m][k] = *(const PG8_LAS bf16x8*)(lds + PG8_SA(b, h) + aoff + m * 2048 + k * 1024); } while (0)
; #define PG8_LDB(dst, b, h) do { _Pragma("unroll") for (int n = 0; n < 2; ++n) _Pragma("unroll") for (int k = 0; k < 2; ++k) dst[n][k] = *(const PG8_LAS bf16x8*)(lds + PG8_SB(b, h) + boff + n * 2048 + k * 1024); } while (0)
; #define PG8_MMA(ai, bj, At, Bt) do { __builtin_amdgcn_s_setprio(1); _Pragma("unroll") for (int m = 0; m < 4; ++m) _Pragma("unroll") for (int n = 0; n < 2; ++n) _Pragma("unroll") for (int k = 0; k < 2; ++k) \
;         acc[ai][bj][m][n] = __builtin_amdgcn_mfma_f32_16x16x32_bf16(Bt[n][k], At[m][k], acc[ai][bj][m][n], 0, 0, 0); __builtin_amdgcn_s_setprio(0); } while (0)
; #define PG8_WAIT_V(n) asm volatile("s_waitcnt vmcnt(" #n ")" ::: "memory")
; #define PG8_WAIT_L(n) asm volatile("s_waitcnt lgkmcnt(" #n ")" ::: "memory")
; #define PG8_BAR __builtin_amdgcn_s_barrier()
; template <class Epi, class Sched, bool ALIGN_EPI = false, bool SP2 = false>
; __device__ __forceinline__ void gemm_phase(PG8_LAS unsigned char* lds, const Gemm g, const Sched& S, const Epi& E) {
;     ...
;         for (int t = 0; t < nt; t += 2) {
;             const bool last = (t == nt - 2);
;             const char* a1 = cA + (size_t)(t + 1) * kstep;
;             const char* a2 = last ? nA : cA + (size_t)(t + 2) * kstep; const char* b2 = last ? nB : cB + (size_t)(t + 2) * kstep;
;             const char* a3 = a2 + kstep; const char* b3 = b2 + kstep;
;     ...
;             PG8_LDB(B0, 1, 0); PG8_LDB(B1, 1, 1); PG8_SCHED; PG8_LDA(At, 1, 0); PG8_STAGE(PG8_SA(0, 1), a2 + hstepA, voffA);
;             PG8_WAIT_V(8); PG8_WAIT_L(0); PG8_BAR; PG8_MMA(0, 0, At, B0); PG8_MMA(0, 1, At, B1); PG8_BAR; PG8_SCHED;
;             PG8_LDA(At, 1, 1); PG8_STAGE(PG8_SB(1, 0), b3, voffB); PG8_STAGE(PG8_SB(1, 1), b3 + hstep, voffB); PG8_STAGE(PG8_SA(1, 0), a3, voffA);
;             PG8_WAIT_V(8); PG8_WAIT_L(0); PG8_BAR; PG8_MMA(1, 0, At, B0); PG8_MMA(1, 1, At, B1); PG8_BAR; PG8_SCHED;
	s_add_i32 s72, 0, 0x18000
	s_add_i32 s73, 0, 0x1c000
	v_add_u32_e32 v140, s72, v173
	v_add_u32_e32 v152, s73, v173
	ds_read_b128 v[128:131], v140
	ds_read_b128 v[132:135], v140 offset:1024
	ds_read_b128 v[136:139], v140 offset:2048
	ds_read_b128 v[140:143], v140 offset:3072
	ds_read_b128 v[162:165], v152
	ds_read_b128 v[166:169], v152 offset:1024
	ds_read_b128 v[180:183], v152 offset:2048
	ds_read_b128 v[184:187], v152 offset:3072
	s_mov_b64 vcc, s[48:49]
	s_add_u32 s48, s48, 0x40000
	s_addc_u32 s49, s49, 0
	s_mov_b32 m0, s56
	ds_read_b128 v[190:193], v177 offset:32768
	ds_read_b128 v[194:197], v177 offset:33792
	ds_read_b128 v[198:201], v177 offset:34816
	ds_read_b128 v[202:205], v177 offset:35840
	ds_read_b128 v[206:209], v177 offset:36864
	ds_read_b128 v[210:213], v177 offset:37888
	ds_read_b128 v[214:217], v177 offset:38912
	global_load_lds_dwordx4 v144, s[48:49]
	s_mov_b32 m0, s57
	ds_read_b128 v[218:221], v177 offset:39936
	global_load_lds_dwordx4 v146, s[48:49]
	s_waitcnt vmcnt(8) lgkmcnt(0)
	s_barrier
	s_setprio 1
	v_mfma_f32_16x16x32_bf16 v[124:127], v[128:131], v[190:193], v[124:127]
	v_mfma_f32_16x16x32_bf16 v[120:123], v[136:139], v[190:193], v[120:123]
	v_mfma_f32_16x16x32_bf16 v[108:111], v[128:131], v[198:201], v[108:111]
	v_mfma_f32_16x16x32_bf16 v[104:107], v[136:139], v[198:201], v[104:107]
	v_mfma_f32_16x16x32_bf16 v[92:95], v[128:131], v[206:209], v[92:95]
	v_mfma_f32_16x16x32_bf16 v[88:91], v[136:139], v[206:209], v[88:91]
	v_mfma_f32_16x16x32_bf16 v[76:79], v[128:131], v[214:217], v[76:79]
	v_mfma_f32_16x16x32_bf16 v[72:75], v[136:139], v[214:217], v[72:75]
	v_mfma_f32_16x16x32_bf16 v[124:127], v[132:135], v[194:197], v[124:127]
	v_mfma_f32_16x16x32_bf16 v[120:123], v[140:143], v[194:197], v[120:123]
	v_mfma_f32_16x16x32_bf16 v[108:111], v[132:135], v[202:205], v[108:111]
	v_mfma_f32_16x16x32_bf16 v[104:107], v[140:143], v[202:205], v[104:107]
	v_mfma_f32_16x16x32_bf16 v[92:95], v[132:135], v[210:213], v[92:95]
	v_mfma_f32_16x16x32_bf16 v[88:91], v[140:143], v[210:213], v[88:91]
	v_mfma_f32_16x16x32_bf16 v[76:79], v[132:135], v[218:221], v[76:79]
	v_mfma_f32_16x16x32_bf16 v[72:75], v[140:143], v[218:221], v[72:75]
	v_mfma_f32_16x16x32_bf16 v[116:119], v[162:165], v[190:193], v[116:119]
	v_mfma_f32_16x16x32_bf16 v[112:115], v[180:183], v[190:193], v[112:115]
	v_mfma_f32_16x16x32_bf16 v[100:103], v[162:165], v[198:201], v[100:103]
	v_mfma_f32_16x16x32_bf16 v[96:99], v[180:183], v[198:201], v[96:99]
	v_mfma_f32_16x16x32_bf16 v[84:87], v[162:165], v[206:209], v[84:87]
	v_mfma_f32_16x16x32_bf16 v[80:83], v[180:183], v[206:209], v[80:83]
	v_mfma_f32_16x16x32_bf16 v[68:71], v[162:165], v[214:217], v[68:71]
	v_mfma_f32_16x16x32_bf16 v[64:67], v[180:183], v[214:217], v[64:67]
	v_mfma_f32_16x16x32_bf16 v[116:119], v[166:169], v[194:197], v[116:119]
	v_mfma_f32_16x16x32_bf16 v[112:115], v[184:187], v[194:197], v[112:115]
	v_mfma_f32_16x16x32_bf16 v[100:103], v[166:169], v[202:205], v[100:103]
	v_mfma_f32_16x16x32_bf16 v[96:99], v[184:187], v[202:205], v[96:99]
	v_mfma_f32_16x16x32_bf16 v[84:87], v[166:169], v[210:213], v[84:87]
	v_mfma_f32_16x16x32_bf16 v[80:83], v[184:187], v[210:213], v[80:83]
	v_mfma_f32_16x16x32_bf16 v[68:71], v[166:169], v[218:221], v[68:71]
	v_mfma_f32_16x16x32_bf16 v[64:67], v[184:187], v[218:221], v[64:67]
	s_setprio 0
	s_barrier
	s_add_i32 s48, s72, s53
	s_add_i32 m0, s48, 0xffffff80
	ds_read_b128 v[190:193], v177 offset:49152
	ds_read_b128 v[194:197], v177 offset:50176
	ds_read_b128 v[198:201], v177 offset:51200
	ds_read_b128 v[202:205], v177 offset:52224
	global_load_lds_dwordx4 v150, s[100:101] offset:128
	s_add_i32 m0, s48, 0x1f80
	s_add_i32 s48, s73, s53
	global_load_lds_dwordx4 v148, s[100:101] offset:128
	s_add_u32 s100, s100, s10
	s_addc_u32 s101, s101, s11
	s_add_i32 m0, s48, 0xffffff80
	ds_read_b128 v[218:221], v177 offset:56320
	global_load_lds_dwordx4 v150, s[100:101] offset:128
	s_add_i32 m0, s48, 0x1f80
	ds_read_b128 v[214:217], v177 offset:55296
	global_load_lds_dwordx4 v148, s[100:101] offset:128
	s_add_i32 m0, s60, 0xffffff80
	ds_read_b128 v[210:213], v177 offset:54272
	global_load_lds_dwordx4 v144, vcc offset:128
	s_add_i32 m0, s61, 0xffffff80
	ds_read_b128 v[206:209], v177 offset:53248
	global_load_lds_dwordx4 v146, vcc offset:128
	s_waitcnt vmcnt(8) lgkmcnt(0)
	s_barrier
	s_setprio 1
	v_mfma_f32_16x16x32_bf16 v[60:63], v[128:131], v[190:193], v[60:63]
	v_mfma_f32_16x16x32_bf16 v[56:59], v[136:139], v[190:193], v[56:59]
	v_mfma_f32_16x16x32_bf16 v[44:47], v[128:131], v[198:201], v[44:47]
	v_mfma_f32_16x16x32_bf16 v[40:43], v[136:139], v[198:201], v[40:43]
	v_mfma_f32_16x16x32_bf16 v[28:31], v[128:131], v[206:209], v[28:31]
	v_mfma_f32_16x16x32_bf16 v[24:27], v[136:139], v[206:209], v[24:27]
	v_mfma_f32_16x16x32_bf16 v[12:15], v[128:131], v[214:217], v[12:15]
	v_mfma_f32_16x16x32_bf16 v[8:11], v[136:139], v[214:217], v[8:11]
	v_mfma_f32_16x16x32_bf16 v[60:63], v[132:135], v[194:197], v[60:63]
	v_mfma_f32_16x16x32_bf16 v[56:59], v[140:143], v[194:197], v[56:59]
	v_mfma_f32_16x16x32_bf16 v[44:47], v[132:135], v[202:205], v[44:47]
	v_mfma_f32_16x16x32_bf16 v[40:43], v[140:143], v[202:205], v[40:43]
	v_mfma_f32_16x16x32_bf16 v[28:31], v[132:135], v[210:213], v[28:31]
	v_mfma_f32_16x16x32_bf16 v[24:27], v[140:143], v[210:213], v[24:27]
	v_mfma_f32_16x16x32_bf16 v[12:15], v[132:135], v[218:221], v[12:15]
	v_mfma_f32_16x16x32_bf16 v[8:11], v[140:143], v[218:221], v[8:11]
	v_mfma_f32_16x16x32_bf16 v[52:55], v[162:165], v[190:193], v[52:55]
	v_mfma_f32_16x16x32_bf16 v[48:51], v[180:183], v[190:193], v[48:51]
	v_mfma_f32_16x16x32_bf16 v[36:39], v[162:165], v[198:201], v[36:39]
	v_mfma_f32_16x16x32_bf16 v[32:35], v[180:183], v[198:201], v[32:35]
	v_mfma_f32_16x16x32_bf16 v[20:23], v[162:165], v[206:209], v[20:23]
	v_mfma_f32_16x16x32_bf16 v[16:19], v[180:183], v[206:209], v[16:19]
	v_mfma_f32_16x16x32_bf16 v[4:7], v[162:165], v[214:217], v[4:7]
	v_mfma_f32_16x16x32_bf16 v[0:3], v[180:183], v[214:217], v[0:3]
	v_mfma_f32_16x16x32_bf16 v[52:55], v[166:169], v[194:197], v[52:55]
	v_mfma_f32_16x16x32_bf16 v[48:51], v[184:187], v[194:197], v[48:51]
	v_mfma_f32_16x16x32_bf16 v[36:39], v[166:169], v[202:205], v[36:39]
	v_mfma_f32_16x16x32_bf16 v[32:35], v[184:187], v[202:205], v[32:35]
	v_mfma_f32_16x16x32_bf16 v[20:23], v[166:169], v[210:213], v[20:23]
	v_mfma_f32_16x16x32_bf16 v[16:19], v[184:187], v[210:213], v[16:19]
	v_mfma_f32_16x16x32_bf16 v[4:7], v[166:169], v[218:221], v[4:7]
	v_mfma_f32_16x16x32_bf16 v[0:3], v[184:187], v[218:221], v[0:3]
	s_setprio 0
	s_barrier
	s_add_u32 s8, s8, 0x100
	s_addc_u32 s9, s9, 0
	s_add_u32 s50, s50, 0x100
	s_addc_u32 s51, s51, 0
	s_cmp_ge_i32 s71, s63
	s_mov_b32 s48, s71
	s_cbranch_scc0 .LBB0_681

; #define PG8_STAGE(bufoff, gbase, voff) do { _Pragma("unroll") for (int _i = 0; _i < 2; ++_i) \
;         __builtin_amdgcn_global_load_lds((const unsigned*)((const char*)(gbase) + (voff)[_i]), (PG8_LAS unsigned*)(lds + (bufoff) + ldsw + _i * 8192), 16, 0, 0); } while (0)
; #define PG8_LDA(dst, b, h) do { _Pragma("unroll") for (int m = 0; m < 4; ++m) _Pragma("unroll") for (int k = 0; k < 2; ++k) dst[m][k] = *(const PG8_LAS bf16x8*)(lds + PG8_SA(b, h) + aoff + m * 2048 + k * 1024); } while (0)
; #define PG8_LDB(dst, b, h) do { _Pragma("unroll") for (int n = 0; n < 2; ++n) _Pragma("unroll") for (int k = 0; k < 2; ++k) dst[n][k] = *(const PG8_LAS bf16x8*)(lds + PG8_SB(b, h) + boff + n * 2048 + k * 1024); } while (0)
; #define PG8_MMA(ai, bj, At, Bt) do { __builtin_amdgcn_s_setprio(1); _Pragma("unroll") for (int m = 0; m < 4; ++m) _Pragma("unroll") for (int n = 0; n < 2; ++n) _Pragma("unroll") for (int k = 0; k < 2; ++k) \
;         acc[ai][bj][m][n] = __builtin_amdgcn_mfma_f32_16x16x32_bf16(Bt[n][k], At[m][k], acc[ai][bj][m][n], 0, 0, 0); __builtin_amdgcn_s_setprio(0); } while (0)
; #define PG8_WAIT_V(n) asm volatile("s_waitcnt vmcnt(" #n ")" ::: "memory")
; #define PG8_BAR __builtin_amdgcn_s_barrier()
; template <class Epi, class Sched, bool ALIGN_EPI = false, bool SP2 = false>
; __device__ __forceinline__ void gemm_phase(PG8_LAS unsigned char* lds, const Gemm g, const Sched& S, const Epi& E) {
;     ...
;         for (int t = 0; t < nt; t += 2) {
;             const bool last = (t == nt - 2);
;             const char* a1 = cA + (size_t)(t + 1) * kstep;
;             const char* a2 = last ? nA : cA + (size_t)(t + 2) * kstep; const char* b2 = last ? nB : cB + (size_t)(t + 2) * kstep;
;             const char* a3 = a2 + kstep; const char* b3 = b2 + kstep;
;             if (last && has_next) S.a_ready(nxt);
;             if constexpr (SP2) {
;             PG8_LDB(B0, 0, 0); PG8_LDB(B1, 0, 1); PG8_SCHED; PG8_LDA(At, 0, 0); PG8_STAGE(PG8_SA(1, 1), a1 + hstepA, voffA);
;             PG8_WAIT_V(8); PG8_WAIT_L(0); PG8_BAR; PG8_MMA(0, 0, At, B0); PG8_MMA(0, 1, At, B1); PG8_BAR; PG8_SCHED;
;             PG8_LDA(At, 0, 1); PG8_STAGE(PG8_SB(0, 0), b2, voffB); PG8_STAGE(PG8_SB(0, 1), b2 + hstep, voffB); PG8_STAGE(PG8_SA(0, 0), a2, voffA);
;             PG8_WAIT_V(8); PG8_WAIT_L(0); PG8_BAR; PG8_MMA(1, 0, At, B0); PG8_MMA(1, 1, At, B1); PG8_BAR; PG8_SCHED;
.LBB0_762:
	ds_read_b128 v[128:131], v169
	ds_read_b128 v[132:135], v169 offset:1024
	ds_read_b128 v[136:139], v169 offset:2048
	ds_read_b128 v[140:143], v169 offset:3072
	ds_read_b128 v[156:159], v170
	ds_read_b128 v[160:163], v170 offset:1024
	ds_read_b128 v[172:175], v170 offset:2048
	ds_read_b128 v[176:179], v170 offset:3072
	s_add_i32 s76, s48, 2
	s_add_u32 s77, s44, 0xfffc0080
	s_addc_u32 s49, s45, -1
	s_cmp_eq_u32 s70, s48
	s_cselect_b32 s48, s50, s77
	s_cselect_b32 s49, s37, s49
	s_cselect_b32 s79, s39, s75
	s_cselect_b32 s78, s38, s51
	s_add_i32 m0, s43, 0xc000
	ds_read_b128 v[180:183], v171
	ds_read_b128 v[184:187], v171 offset:1024
	ds_read_b128 v[190:193], v171 offset:2048
	ds_read_b128 v[194:197], v171 offset:3072
	ds_read_b128 v[198:201], v171 offset:4096
	ds_read_b128 v[202:205], v171 offset:5120
	ds_read_b128 v[206:209], v171 offset:6144
	global_load_lds_dwordx4 v152, s[44:45]
	s_add_i32 m0, s43, 0xe000
	ds_read_b128 v[210:213], v171 offset:7168
	global_load_lds_dwordx4 v154, s[44:45]
	s_waitcnt vmcnt(8) lgkmcnt(0)
	s_barrier
	s_setprio 1
	v_mfma_f32_16x16x32_bf16 v[124:127], v[128:131], v[180:183], v[124:127]
	v_mfma_f32_16x16x32_bf16 v[120:123], v[136:139], v[180:183], v[120:123]
	v_mfma_f32_16x16x32_bf16 v[108:111], v[128:131], v[190:193], v[108:111]
	v_mfma_f32_16x16x32_bf16 v[104:107], v[136:139], v[190:193], v[104:107]
	v_mfma_f32_16x16x32_bf16 v[92:95], v[128:131], v[198:201], v[92:95]
	v_mfma_f32_16x16x32_bf16 v[88:91], v[136:139], v[198:201], v[88:91]
	v_mfma_f32_16x16x32_bf16 v[76:79], v[128:131], v[206:209], v[76:79]
	v_mfma_f32_16x16x32_bf16 v[72:75], v[136:139], v[206:209], v[72:75]
	v_mfma_f32_16x16x32_bf16 v[124:127], v[132:135], v[184:187], v[124:127]
	v_mfma_f32_16x16x32_bf16 v[120:123], v[140:143], v[184:187], v[120:123]
	v_mfma_f32_16x16x32_bf16 v[108:111], v[132:135], v[194:197], v[108:111]
	v_mfma_f32_16x16x32_bf16 v[104:107], v[140:143], v[194:197], v[104:107]
	v_mfma_f32_16x16x32_bf16 v[92:95], v[132:135], v[202:205], v[92:95]
	v_mfma_f32_16x16x32_bf16 v[88:91], v[140:143], v[202:205], v[88:91]
	v_mfma_f32_16x16x32_bf16 v[76:79], v[132:135], v[210:213], v[76:79]
	v_mfma_f32_16x16x32_bf16 v[72:75], v[140:143], v[210:213], v[72:75]
	v_mfma_f32_16x16x32_bf16 v[116:119], v[156:159], v[180:183], v[116:119]
	v_mfma_f32_16x16x32_bf16 v[112:115], v[172:175], v[180:183], v[112:115]
	v_mfma_f32_16x16x32_bf16 v[100:103], v[156:159], v[190:193], v[100:103]
	v_mfma_f32_16x16x32_bf16 v[96:99], v[172:175], v[190:193], v[96:99]
	v_mfma_f32_16x16x32_bf16 v[84:87], v[156:159], v[198:201], v[84:87]
	v_mfma_f32_16x16x32_bf16 v[80:83], v[172:175], v[198:201], v[80:83]
	v_mfma_f32_16x16x32_bf16 v[68:71], v[156:159], v[206:209], v[68:71]
	v_mfma_f32_16x16x32_bf16 v[64:67], v[172:175], v[206:209], v[64:67]
	v_mfma_f32_16x16x32_bf16 v[116:119], v[160:163], v[184:187], v[116:119]
	v_mfma_f32_16x16x32_bf16 v[112:115], v[176:179], v[184:187], v[112:115]
	v_mfma_f32_16x16x32_bf16 v[100:103], v[160:163], v[194:197], v[100:103]
	v_mfma_f32_16x16x32_bf16 v[96:99], v[176:179], v[194:197], v[96:99]
	v_mfma_f32_16x16x32_bf16 v[84:87], v[160:163], v[202:205], v[84:87]
	v_mfma_f32_16x16x32_bf16 v[80:83], v[176:179], v[202:205], v[80:83]
	v_mfma_f32_16x16x32_bf16 v[68:71], v[160:163], v[210:213], v[68:71]
	v_mfma_f32_16x16x32_bf16 v[64:67], v[176:179], v[210:213], v[64:67]
	s_setprio 0
	s_barrier
	s_add_i32 s77, s71, s57
	s_mov_b32 m0, s77
	ds_read_b128 v[180:183], v171 offset:16384
	ds_read_b128 v[184:187], v171 offset:17408
	ds_read_b128 v[190:193], v171 offset:18432
	ds_read_b128 v[194:197], v171 offset:19456
	global_load_lds_dwordx4 v150, s[78:79]
	s_add_i32 m0, s77, 0x2000
	s_mov_b64 s[100:101], s[78:79]
	s_add_i32 s77, s72, s57
	global_load_lds_dwordx4 v148, s[78:79]
	s_add_u32 s78, s78, s8
	s_addc_u32 s79, s79, s9
	s_mov_b32 m0, s77
	ds_read_b128 v[210:213], v171 offset:23552
	global_load_lds_dwordx4 v150, s[78:79]
	s_add_i32 m0, s77, 0x2000
	ds_read_b128 v[206:209], v171 offset:22528
	global_load_lds_dwordx4 v148, s[78:79]
	s_mov_b32 m0, s43
	ds_read_b128 v[202:205], v171 offset:21504
	global_load_lds_dwordx4 v144, s[48:49]
	s_mov_b32 m0, s59
	ds_read_b128 v[198:201], v171 offset:20480
	global_load_lds_dwordx4 v146, s[48:49]
	s_waitcnt vmcnt(8) lgkmcnt(0)
	s_barrier
	s_setprio 1
	v_mfma_f32_16x16x32_bf16 v[60:63], v[128:131], v[180:183], v[60:63]
	v_mfma_f32_16x16x32_bf16 v[56:59], v[136:139], v[180:183], v[56:59]
	v_mfma_f32_16x16x32_bf16 v[44:47], v[128:131], v[190:193], v[44:47]
	v_mfma_f32_16x16x32_bf16 v[40:43], v[136:139], v[190:193], v[40:43]
	v_mfma_f32_16x16x32_bf16 v[28:31], v[128:131], v[198:201], v[28:31]
	v_mfma_f32_16x16x32_bf16 v[24:27], v[136:139], v[198:201], v[24:27]
	v_mfma_f32_16x16x32_bf16 v[12:15], v[128:131], v[206:209], v[12:15]
	v_mfma_f32_16x16x32_bf16 v[8:11], v[136:139], v[206:209], v[8:11]
	v_mfma_f32_16x16x32_bf16 v[60:63], v[132:135], v[184:187], v[60:63]
	v_mfma_f32_16x16x32_bf16 v[56:59], v[140:143], v[184:187], v[56:59]
	v_mfma_f32_16x16x32_bf16 v[44:47], v[132:135], v[194:197], v[44:47]
	v_mfma_f32_16x16x32_bf16 v[40:43], v[140:143], v[194:197], v[40:43]
	v_mfma_f32_16x16x32_bf16 v[28:31], v[132:135], v[202:205], v[28:31]
	v_mfma_f32_16x16x32_bf16 v[24:27], v[140:143], v[202:205], v[24:27]
	v_mfma_f32_16x16x32_bf16 v[12:15], v[132:135], v[210:213], v[12:15]
	v_mfma_f32_16x16x32_bf16 v[8:11], v[140:143], v[210:213], v[8:11]
	v_mfma_f32_16x16x32_bf16 v[52:55], v[156:159], v[180:183], v[52:55]
	v_mfma_f32_16x16x32_bf16 v[48:51], v[172:175], v[180:183], v[48:51]
	v_mfma_f32_16x16x32_bf16 v[36:39], v[156:159], v[190:193], v[36:39]
	v_mfma_f32_16x16x32_bf16 v[32:35], v[172:175], v[190:193], v[32:35]
	v_mfma_f32_16x16x32_bf16 v[20:23], v[156:159], v[198:201], v[20:23]
	v_mfma_f32_16x16x32_bf16 v[16:19], v[172:175], v[198:201], v[16:19]
	v_mfma_f32_16x16x32_bf16 v[4:7], v[156:159], v[206:209], v[4:7]
	v_mfma_f32_16x16x32_bf16 v[0:3], v[172:175], v[206:209], v[0:3]
	v_mfma_f32_16x16x32_bf16 v[52:55], v[160:163], v[184:187], v[52:55]
	v_mfma_f32_16x16x32_bf16 v[48:51], v[176:179], v[184:187], v[48:51]
	v_mfma_f32_16x16x32_bf16 v[36:39], v[160:163], v[194:197], v[36:39]
	v_mfma_f32_16x16x32_bf16 v[32:35], v[176:179], v[194:197], v[32:35]
	v_mfma_f32_16x16x32_bf16 v[20:23], v[160:163], v[202:205], v[20:23]
	v_mfma_f32_16x16x32_bf16 v[16:19], v[176:179], v[202:205], v[16:19]
	v_mfma_f32_16x16x32_bf16 v[4:7], v[160:163], v[210:213], v[4:7]
	v_mfma_f32_16x16x32_bf16 v[0:3], v[176:179], v[210:213], v[0:3]
	s_setprio 0
	s_barrier
; #define PG8_STAGE(bufoff, gbase, voff) do { _Pragma("unroll") for (int _i = 0; _i < 2; ++_i) \
;         __builtin_amdgcn_global_load_lds((const unsigned*)((const char*)(gbase) + (voff)[_i]), (PG8_LAS unsigned*)(lds + (bufoff) + ldsw + _i * 8192), 16, 0, 0); } while (0)
; #define PG8_LDA(dst, b, h) do { _Pragma("unroll") for (int m = 0; m < 4; ++m) _Pragma("unroll") for (int k = 0; k < 2; ++k) dst[m][k] = *(const PG8_LAS bf16x8*)(lds + PG8_SA(b, h) + aoff + m * 2048 + k * 1024); } while (0)
; #define PG8_LDB(dst, b, h) do { _Pragma("unroll") for (int n = 0; n < 2; ++n) _Pragma("unroll") for (int k = 0; k < 2; ++k) dst[n][k] = *(const PG8_LAS bf16x8*)(lds + PG8_SB(b, h) + boff + n * 2048 + k * 1024); } while (0)
; #define PG8_MMA(ai, bj, At, Bt) do { __builtin_amdgcn_s_setprio(1); _Pragma("unroll") for (int m = 0; m < 4; ++m) _Pragma("unroll") for (int n = 0; n < 2; ++n) _Pragma("unroll") for (int k = 0; k < 2; ++k) \
;         acc[ai][bj][m][n] = __builtin_amdgcn_mfma_f32_16x16x32_bf16(Bt[n][k], At[m][k], acc[ai][bj][m][n], 0, 0, 0); __builtin_amdgcn_s_setprio(0); } while (0)
; #define PG8_WAIT_V(n) asm volatile("s_waitcnt vmcnt(" #n ")" ::: "memory")
; #define PG8_WAIT_L(n) asm volatile("s_waitcnt lgkmcnt(" #n ")" ::: "memory")
; #define PG8_BAR __builtin_amdgcn_s_barrier()
; template <class Epi, class Sched, bool ALIGN_EPI = false, bool SP2 = false>
; __device__ __forceinline__ void gemm_phase(PG8_LAS unsigned char* lds, const Gemm g, const Sched& S, const Epi& E) {
;     ...
;         for (int t = 0; t < nt; t += 2) {
;             const bool last = (t == nt - 2);
;             const char* a1 = cA + (size_t)(t + 1) * kstep;
;             const char* a2 = last ? nA : cA + (size_t)(t + 2) * kstep; const char* b2 = last ? nB : cB + (size_t)(t + 2) * kstep;
;             const char* a3 = a2 + kstep; const char* b3 = b2 + kstep;
;     ...
;             PG8_LDB(B0, 1, 0); PG8_LDB(B1, 1, 1); PG8_SCHED; PG8_LDA(At, 1, 0); PG8_STAGE(PG8_SA(0, 1), a2 + hstepA, voffA);
;             PG8_WAIT_V(8); PG8_WAIT_L(0); PG8_BAR; PG8_MMA(0, 0, At, B0); PG8_MMA(0, 1, At, B1); PG8_BAR; PG8_SCHED;
;             PG8_LDA(At, 1, 1); PG8_STAGE(PG8_SB(1, 0), b3, voffB); PG8_STAGE(PG8_SB(1, 1), b3 + hstep, voffB); PG8_STAGE(PG8_SA(1, 0), a3, voffA);
;             PG8_WAIT_V(8); PG8_WAIT_L(0); PG8_BAR; PG8_MMA(1, 0, At, B0); PG8_MMA(1, 1, At, B1); PG8_BAR; PG8_SCHED;
	s_add_i32 s77, 0, 0x18000
	s_add_i32 s78, 0, 0x1c000
	v_add_u32_e32 v140, s77, v167
	v_add_u32_e32 v176, s78, v167
	ds_read_b128 v[128:131], v140
	ds_read_b128 v[132:135], v140 offset:1024
	ds_read_b128 v[136:139], v140 offset:2048
	ds_read_b128 v[140:143], v140 offset:3072
	ds_read_b128 v[156:159], v176
	ds_read_b128 v[160:163], v176 offset:1024
	ds_read_b128 v[172:175], v176 offset:2048
	ds_read_b128 v[176:179], v176 offset:3072
	s_mov_b64 vcc, s[48:49]
	s_add_u32 s48, s48, 0x40000
	s_addc_u32 s49, s49, 0
	s_mov_b32 m0, s60
	ds_read_b128 v[180:183], v171 offset:32768
	ds_read_b128 v[184:187], v171 offset:33792
	ds_read_b128 v[190:193], v171 offset:34816
	ds_read_b128 v[194:197], v171 offset:35840
	ds_read_b128 v[198:201], v171 offset:36864
	ds_read_b128 v[202:205], v171 offset:37888
	ds_read_b128 v[206:209], v171 offset:38912
	global_load_lds_dwordx4 v144, s[48:49]
	s_mov_b32 m0, s61
	ds_read_b128 v[210:213], v171 offset:39936
	global_load_lds_dwordx4 v146, s[48:49]
	s_waitcnt vmcnt(8) lgkmcnt(0)
	s_barrier
	s_setprio 1
	v_mfma_f32_16x16x32_bf16 v[124:127], v[128:131], v[180:183], v[124:127]
	v_mfma_f32_16x16x32_bf16 v[120:123], v[136:139], v[180:183], v[120:123]
	v_mfma_f32_16x16x32_bf16 v[108:111], v[128:131], v[190:193], v[108:111]
	v_mfma_f32_16x16x32_bf16 v[104:107], v[136:139], v[190:193], v[104:107]
	v_mfma_f32_16x16x32_bf16 v[92:95], v[128:131], v[198:201], v[92:95]
	v_mfma_f32_16x16x32_bf16 v[88:91], v[136:139], v[198:201], v[88:91]
	v_mfma_f32_16x16x32_bf16 v[76:79], v[128:131], v[206:209], v[76:79]
	v_mfma_f32_16x16x32_bf16 v[72:75], v[136:139], v[206:209], v[72:75]
	v_mfma_f32_16x16x32_bf16 v[124:127], v[132:135], v[184:187], v[124:127]
	v_mfma_f32_16x16x32_bf16 v[120:123], v[140:143], v[184:187], v[120:123]
	v_mfma_f32_16x16x32_bf16 v[108:111], v[132:135], v[194:197], v[108:111]
	v_mfma_f32_16x16x32_bf16 v[104:107], v[140:143], v[194:197], v[104:107]
	v_mfma_f32_16x16x32_bf16 v[92:95], v[132:135], v[202:205], v[92:95]
	v_mfma_f32_16x16x32_bf16 v[88:91], v[140:143], v[202:205], v[88:91]
	v_mfma_f32_16x16x32_bf16 v[76:79], v[132:135], v[210:213], v[76:79]
	v_mfma_f32_16x16x32_bf16 v[72:75], v[140:143], v[210:213], v[72:75]
	v_mfma_f32_16x16x32_bf16 v[116:119], v[156:159], v[180:183], v[116:119]
	v_mfma_f32_16x16x32_bf16 v[112:115], v[172:175], v[180:183], v[112:115]
	v_mfma_f32_16x16x32_bf16 v[100:103], v[156:159], v[190:193], v[100:103]
	v_mfma_f32_16x16x32_bf16 v[96:99], v[172:175], v[190:193], v[96:99]
	v_mfma_f32_16x16x32_bf16 v[84:87], v[156:159], v[198:201], v[84:87]
	v_mfma_f32_16x16x32_bf16 v[80:83], v[172:175], v[198:201], v[80:83]
	v_mfma_f32_16x16x32_bf16 v[68:71], v[156:159], v[206:209], v[68:71]
	v_mfma_f32_16x16x32_bf16 v[64:67], v[172:175], v[206:209], v[64:67]
	v_mfma_f32_16x16x32_bf16 v[116:119], v[160:163], v[184:187], v[116:119]
	v_mfma_f32_16x16x32_bf16 v[112:115], v[176:179], v[184:187], v[112:115]
	v_mfma_f32_16x16x32_bf16 v[100:103], v[160:163], v[194:197], v[100:103]
	v_mfma_f32_16x16x32_bf16 v[96:99], v[176:179], v[194:197], v[96:99]
	v_mfma_f32_16x16x32_bf16 v[84:87], v[160:163], v[202:205], v[84:87]
	v_mfma_f32_16x16x32_bf16 v[80:83], v[176:179], v[202:205], v[80:83]
	v_mfma_f32_16x16x32_bf16 v[68:71], v[160:163], v[210:213], v[68:71]
	v_mfma_f32_16x16x32_bf16 v[64:67], v[176:179], v[210:213], v[64:67]
	s_setprio 0
	s_barrier
	s_add_i32 s48, s77, s57
	s_add_i32 m0, s48, 0xffffff80
	ds_read_b128 v[180:183], v171 offset:49152
	ds_read_b128 v[184:187], v171 offset:50176
	ds_read_b128 v[190:193], v171 offset:51200
	ds_read_b128 v[194:197], v171 offset:52224
	global_load_lds_dwordx4 v150, s[100:101] offset:128
	s_add_i32 m0, s48, 0x1f80
	s_add_i32 s48, s78, s57
	global_load_lds_dwordx4 v148, s[100:101] offset:128
	s_add_u32 s100, s100, s8
	s_addc_u32 s101, s101, s9
	s_add_i32 m0, s48, 0xffffff80
	ds_read_b128 v[210:213], v171 offset:56320
	global_load_lds_dwordx4 v150, s[100:101] offset:128
	s_add_i32 m0, s48, 0x1f80
	ds_read_b128 v[206:209], v171 offset:55296
	global_load_lds_dwordx4 v148, s[100:101] offset:128
	s_add_i32 m0, s65, 0xffffff80
	ds_read_b128 v[202:205], v171 offset:54272
	global_load_lds_dwordx4 v144, vcc offset:128
	s_add_i32 m0, s66, 0xffffff80
	ds_read_b128 v[198:201], v171 offset:53248
	global_load_lds_dwordx4 v146, vcc offset:128
	s_waitcnt vmcnt(8) lgkmcnt(0)
	s_barrier
	s_setprio 1
	v_mfma_f32_16x16x32_bf16 v[60:63], v[128:131], v[180:183], v[60:63]
	v_mfma_f32_16x16x32_bf16 v[56:59], v[136:139], v[180:183], v[56:59]
	v_mfma_f32_16x16x32_bf16 v[44:47], v[128:131], v[190:193], v[44:47]
	v_mfma_f32_16x16x32_bf16 v[40:43], v[136:139], v[190:193], v[40:43]
	v_mfma_f32_16x16x32_bf16 v[28:31], v[128:131], v[198:201], v[28:31]
	v_mfma_f32_16x16x32_bf16 v[24:27], v[136:139], v[198:201], v[24:27]
	v_mfma_f32_16x16x32_bf16 v[12:15], v[128:131], v[206:209], v[12:15]
	v_mfma_f32_16x16x32_bf16 v[8:11], v[136:139], v[206:209], v[8:11]
	v_mfma_f32_16x16x32_bf16 v[60:63], v[132:135], v[184:187], v[60:63]
	v_mfma_f32_16x16x32_bf16 v[56:59], v[140:143], v[184:187], v[56:59]
	v_mfma_f32_16x16x32_bf16 v[44:47], v[132:135], v[194:197], v[44:47]
	v_mfma_f32_16x16x32_bf16 v[40:43], v[140:143], v[194:197], v[40:43]
	v_mfma_f32_16x16x32_bf16 v[28:31], v[132:135], v[202:205], v[28:31]
	v_mfma_f32_16x16x32_bf16 v[24:27], v[140:143], v[202:205], v[24:27]
	v_mfma_f32_16x16x32_bf16 v[12:15], v[132:135], v[210:213], v[12:15]
	v_mfma_f32_16x16x32_bf16 v[8:11], v[140:143], v[210:213], v[8:11]
	v_mfma_f32_16x16x32_bf16 v[52:55], v[156:159], v[180:183], v[52:55]
	v_mfma_f32_16x16x32_bf16 v[48:51], v[172:175], v[180:183], v[48:51]
	v_mfma_f32_16x16x32_bf16 v[36:39], v[156:159], v[190:193], v[36:39]
	v_mfma_f32_16x16x32_bf16 v[32:35], v[172:175], v[190:193], v[32:35]
	v_mfma_f32_16x16x32_bf16 v[20:23], v[156:159], v[198:201], v[20:23]
	v_mfma_f32_16x16x32_bf16 v[16:19], v[172:175], v[198:201], v[16:19]
	v_mfma_f32_16x16x32_bf16 v[4:7], v[156:159], v[206:209], v[4:7]
	v_mfma_f32_16x16x32_bf16 v[0:3], v[172:175], v[206:209], v[0:3]
	v_mfma_f32_16x16x32_bf16 v[52:55], v[160:163], v[184:187], v[52:55]
	v_mfma_f32_16x16x32_bf16 v[48:51], v[176:179], v[184:187], v[48:51]
	v_mfma_f32_16x16x32_bf16 v[36:39], v[160:163], v[194:197], v[36:39]
	v_mfma_f32_16x16x32_bf16 v[32:35], v[176:179], v[194:197], v[32:35]
	v_mfma_f32_16x16x32_bf16 v[20:23], v[160:163], v[202:205], v[20:23]
	v_mfma_f32_16x16x32_bf16 v[16:19], v[176:179], v[202:205], v[16:19]
	v_mfma_f32_16x16x32_bf16 v[4:7], v[160:163], v[210:213], v[4:7]
	v_mfma_f32_16x16x32_bf16 v[0:3], v[176:179], v[210:213], v[0:3]
	s_setprio 0
	s_barrier
	s_add_u32 s44, s44, 0x100
	s_addc_u32 s45, s45, 0
	s_add_u32 s51, s51, 0x100
	s_addc_u32 s75, s75, 0
	s_cmp_ge_i32 s76, s67
	s_mov_b32 s48, s76
	s_cbranch_scc0 .LBB0_762

; __device__ __forceinline__ unsigned xb_ld(unsigned* p)              { return __hip_atomic_load(p, __ATOMIC_RELAXED, __HIP_MEMORY_SCOPE_AGENT); }
; __device__ __forceinline__ unsigned xb_add(unsigned* p, unsigned v) { return __hip_atomic_fetch_add(p, v, __ATOMIC_RELAXED, __HIP_MEMORY_SCOPE_AGENT); }
; #define XB_SPIN(cond, bar) do { unsigned _sp = 0; while (cond) { __builtin_amdgcn_s_sleep(1); \
;     if ((++_sp & 255u) == 0u) { if (xb_ld(&(bar)[XB_TMO])) break; if (_sp > XB_SPIN_CAP) { atomicAdd(&(bar)[XB_TMO], 1u); break; } } } } while (0)
; __device__ __forceinline__ void xcd_barrier(const XcdBarrier& b) {
;     ...
;         const unsigned old = xb_add(&bar[XB_XSUB(b.x)], 1u);
;         const unsigned gen = old / nloc;
;         if (old + 1u == (gen + 1u) * nloc) {
;             __builtin_amdgcn_fence(__ATOMIC_RELEASE, "agent");
;             asm volatile("s_waitcnt vmcnt(0)" ::: "memory");
;             const unsigned og = xb_add(&bar[XB_TOP], 1u);
;             const unsigned tg = og / nx;
;             if (og + 1u == (tg + 1u) * nx) xb_add(&bar[XB_TOPGEN], 1u);
;             else XB_SPIN(xb_ld(&bar[XB_TOPGEN]) == tg, bar);
.LBB0_805:
	s_andn2_saveexec_b64 s[6:7], s[90:91]
	s_cbranch_execz .LBB0_825
	s_mov_b64 s[6:7], exec
	buffer_wbl2 sc1
	s_waitcnt vmcnt(0) lgkmcnt(0)
	v_mbcnt_lo_u32_b32 v1, s6, 0
	v_mbcnt_hi_u32_b32 v1, s7, v1
	v_cmp_eq_u32_e32 vcc, 0, v1
	s_and_saveexec_b64 s[8:9], vcc
	s_cbranch_execz .LBB0_808
	s_bcnt1_i32_b64 s6, s[6:7]
	v_mov_b32_e32 v2, 0
	v_mov_b32_e32 v3, s6
	global_atomic_add v2, v2, v3, s[44:45] sc0

; __device__ __forceinline__ unsigned xb_ld(unsigned* p)              { return __hip_atomic_load(p, __ATOMIC_RELAXED, __HIP_MEMORY_SCOPE_AGENT); }
; __device__ __forceinline__ unsigned xb_add(unsigned* p, unsigned v) { return __hip_atomic_fetch_add(p, v, __ATOMIC_RELAXED, __HIP_MEMORY_SCOPE_AGENT); }
; #define XB_SPIN(cond, bar) do { unsigned _sp = 0; while (cond) { __builtin_amdgcn_s_sleep(1); \
;     if ((++_sp & 255u) == 0u) { if (xb_ld(&(bar)[XB_TMO])) break; if (_sp > XB_SPIN_CAP) { atomicAdd(&(bar)[XB_TMO], 1u); break; } } } } while (0)
; __device__ __forceinline__ void xcd_barrier(const XcdBarrier& b) {
;     ...
;         const unsigned old = xb_add(&bar[XB_XSUB(b.x)], 1u);
;         const unsigned gen = old / nloc;
;         if (old + 1u == (gen + 1u) * nloc) {
;             __builtin_amdgcn_fence(__ATOMIC_RELEASE, "agent");
;             asm volatile("s_waitcnt vmcnt(0)" ::: "memory");
;             const unsigned og = xb_add(&bar[XB_TOP], 1u);
;             const unsigned tg = og / nx;
;             if (og + 1u == (tg + 1u) * nx) xb_add(&bar[XB_TOPGEN], 1u);
;             else XB_SPIN(xb_ld(&bar[XB_TOPGEN]) == tg, bar);
.LBB0_862:
	s_andn2_saveexec_b64 s[6:7], s[6:7]
	s_cbranch_execz .LBB0_882
	s_mov_b64 s[6:7], exec
	buffer_wbl2 sc1
	s_waitcnt vmcnt(0) lgkmcnt(0)
	v_mbcnt_lo_u32_b32 v1, s6, 0
	v_mbcnt_hi_u32_b32 v1, s7, v1
	v_cmp_eq_u32_e32 vcc, 0, v1
	s_and_saveexec_b64 s[8:9], vcc
	s_cbranch_execz .LBB0_865
	s_bcnt1_i32_b64 s3, s[6:7]
	v_mov_b32_e32 v2, 0
	v_mov_b32_e32 v3, s3
	global_atomic_add v2, v2, v3, s[44:45] sc0

; #define PG8_STAGE(bufoff, gbase, voff) do { _Pragma("unroll") for (int _i = 0; _i < 2; ++_i) \
;         __builtin_amdgcn_global_load_lds((const unsigned*)((const char*)(gbase) + (voff)[_i]), (PG8_LAS unsigned*)(lds + (bufoff) + ldsw + _i * 8192), 16, 0, 0); } while (0)
; #define PG8_LDA(dst, b, h) do { _Pragma("unroll") for (int m = 0; m < 4; ++m) _Pragma("unroll") for (int k = 0; k < 2; ++k) dst[m][k] = *(const PG8_LAS bf16x8*)(lds + PG8_SA(b, h) + aoff + m * 2048 + k * 1024); } while (0)
; #define PG8_LDB(dst, b, h) do { _Pragma("unroll") for (int n = 0; n < 2; ++n) _Pragma("unroll") for (int k = 0; k < 2; ++k) dst[n][k] = *(const PG8_LAS bf16x8*)(lds + PG8_SB(b, h) + boff + n * 2048 + k * 1024); } while (0)
; #define PG8_MMA(ai, bj, At, Bt) do { __builtin_amdgcn_s_setprio(1); _Pragma("unroll") for (int m = 0; m < 4; ++m) _Pragma("unroll") for (int n = 0; n < 2; ++n) _Pragma("unroll") for (int k = 0; k < 2; ++k) \
;         acc[ai][bj][m][n] = __builtin_amdgcn_mfma_f32_16x16x32_bf16(Bt[n][k], At[m][k], acc[ai][bj][m][n], 0, 0, 0); __builtin_amdgcn_s_setprio(0); } while (0)
; #define PG8_WAIT_V(n) asm volatile("s_waitcnt vmcnt(" #n ")" ::: "memory")
; #define PG8_BAR __builtin_amdgcn_s_barrier()
; template <class Epi, class Sched, bool ALIGN_EPI = false, bool SP2 = false>
; __device__ __forceinline__ void gemm_phase(PG8_LAS unsigned char* lds, const Gemm g, const Sched& S, const Epi& E) {
;     ...
;         for (int t = 0; t < nt; t += 2) {
;             const bool last = (t == nt - 2);
;             const char* a1 = cA + (size_t)(t + 1) * kstep;
;             const char* a2 = last ? nA : cA + (size_t)(t + 2) * kstep; const char* b2 = last ? nB : cB + (size_t)(t + 2) * kstep;
;             const char* a3 = a2 + kstep; const char* b3 = b2 + kstep;
;             if (last && has_next) S.a_ready(nxt);
;             if constexpr (SP2) {
;             PG8_LDB(B0, 0, 0); PG8_LDB(B1, 0, 1); PG8_SCHED; PG8_LDA(At, 0, 0); PG8_STAGE(PG8_SA(1, 1), a1 + hstepA, voffA);
;             PG8_WAIT_V(8); PG8_WAIT_L(0); PG8_BAR; PG8_MMA(0, 0, At, B0); PG8_MMA(0, 1, At, B1); PG8_BAR; PG8_SCHED;
;             PG8_LDA(At, 0, 1); PG8_STAGE(PG8_SB(0, 0), b2, voffB); PG8_STAGE(PG8_SB(0, 1), b2 + hstep, voffB); PG8_STAGE(PG8_SA(0, 0), a2, voffA);
;             PG8_WAIT_V(8); PG8_WAIT_L(0); PG8_BAR; PG8_MMA(1, 0, At, B0); PG8_MMA(1, 1, At, B1); PG8_BAR; PG8_SCHED;
.LBB0_898:
	ds_read_b128 v[150:153], v147
	ds_read_b128 v[154:157], v147 offset:1024
	ds_read_b128 v[158:161], v147 offset:2048
	ds_read_b128 v[162:165], v147 offset:3072
	ds_read_b128 v[166:169], v148
	ds_read_b128 v[170:173], v148 offset:1024
	ds_read_b128 v[174:177], v148 offset:2048
	ds_read_b128 v[178:181], v148 offset:3072
	s_add_i32 s58, s30, 2
	s_add_u32 s59, s10, 0xfffc0080
	s_addc_u32 s31, s11, -1
	s_cmp_eq_u32 s51, s30
	s_cselect_b32 s30, s57, s59
	s_cselect_b32 s31, s23, s31
	s_cselect_b32 s61, s25, s35
	s_cselect_b32 s60, s24, s34
	s_add_i32 m0, s29, 0xc000
	ds_read_b128 v[182:185], v149
	ds_read_b128 v[190:193], v149 offset:1024
	ds_read_b128 v[194:197], v149 offset:2048
	ds_read_b128 v[198:201], v149 offset:3072
	ds_read_b128 v[202:205], v149 offset:4096
	ds_read_b128 v[206:209], v149 offset:5120
	ds_read_b128 v[210:213], v149 offset:6144
	global_load_lds_dwordx4 v136, s[10:11]
	s_add_i32 m0, s29, 0xe000
	ds_read_b128 v[214:217], v149 offset:7168
	global_load_lds_dwordx4 v138, s[10:11]
	s_waitcnt vmcnt(8) lgkmcnt(0)
	s_barrier
	s_setprio 1
	v_mfma_f32_16x16x32_bf16 v[124:127], v[150:153], v[182:185], v[124:127]
	v_mfma_f32_16x16x32_bf16 v[116:119], v[158:161], v[182:185], v[116:119]
	v_mfma_f32_16x16x32_bf16 v[108:111], v[150:153], v[194:197], v[108:111]
	v_mfma_f32_16x16x32_bf16 v[100:103], v[158:161], v[194:197], v[100:103]
	v_mfma_f32_16x16x32_bf16 v[92:95], v[150:153], v[202:205], v[92:95]
	v_mfma_f32_16x16x32_bf16 v[84:87], v[158:161], v[202:205], v[84:87]
	v_mfma_f32_16x16x32_bf16 v[76:79], v[150:153], v[210:213], v[76:79]
	v_mfma_f32_16x16x32_bf16 v[68:71], v[158:161], v[210:213], v[68:71]
	v_mfma_f32_16x16x32_bf16 v[124:127], v[154:157], v[190:193], v[124:127]
	v_mfma_f32_16x16x32_bf16 v[116:119], v[162:165], v[190:193], v[116:119]
	v_mfma_f32_16x16x32_bf16 v[108:111], v[154:157], v[198:201], v[108:111]
	v_mfma_f32_16x16x32_bf16 v[100:103], v[162:165], v[198:201], v[100:103]
	v_mfma_f32_16x16x32_bf16 v[92:95], v[154:157], v[206:209], v[92:95]
	v_mfma_f32_16x16x32_bf16 v[84:87], v[162:165], v[206:209], v[84:87]
	v_mfma_f32_16x16x32_bf16 v[76:79], v[154:157], v[214:217], v[76:79]
	v_mfma_f32_16x16x32_bf16 v[68:71], v[162:165], v[214:217], v[68:71]
	v_mfma_f32_16x16x32_bf16 v[120:123], v[166:169], v[182:185], v[120:123]
	v_mfma_f32_16x16x32_bf16 v[112:115], v[174:177], v[182:185], v[112:115]
	v_mfma_f32_16x16x32_bf16 v[104:107], v[166:169], v[194:197], v[104:107]
	v_mfma_f32_16x16x32_bf16 v[96:99], v[174:177], v[194:197], v[96:99]
	v_mfma_f32_16x16x32_bf16 v[88:91], v[166:169], v[202:205], v[88:91]
	v_mfma_f32_16x16x32_bf16 v[80:83], v[174:177], v[202:205], v[80:83]
	v_mfma_f32_16x16x32_bf16 v[72:75], v[166:169], v[210:213], v[72:75]
	v_mfma_f32_16x16x32_bf16 v[64:67], v[174:177], v[210:213], v[64:67]
	v_mfma_f32_16x16x32_bf16 v[120:123], v[170:173], v[190:193], v[120:123]
	v_mfma_f32_16x16x32_bf16 v[112:115], v[178:181], v[190:193], v[112:115]
	v_mfma_f32_16x16x32_bf16 v[104:107], v[170:173], v[198:201], v[104:107]
	v_mfma_f32_16x16x32_bf16 v[96:99], v[178:181], v[198:201], v[96:99]
	v_mfma_f32_16x16x32_bf16 v[88:91], v[170:173], v[206:209], v[88:91]
	v_mfma_f32_16x16x32_bf16 v[80:83], v[178:181], v[206:209], v[80:83]
	v_mfma_f32_16x16x32_bf16 v[72:75], v[170:173], v[214:217], v[72:75]
	v_mfma_f32_16x16x32_bf16 v[64:67], v[178:181], v[214:217], v[64:67]
	s_setprio 0
	s_barrier
	s_add_i32 s59, s52, s38
	s_mov_b32 m0, s59
	ds_read_b128 v[182:185], v149 offset:16384
	ds_read_b128 v[190:193], v149 offset:17408
	ds_read_b128 v[194:197], v149 offset:18432
	ds_read_b128 v[198:201], v149 offset:19456
	global_load_lds_dwordx4 v134, s[60:61]
	s_add_i32 m0, s59, 0x2000
	s_mov_b64 s[100:101], s[60:61]
	s_add_i32 s59, s53, s38
	global_load_lds_dwordx4 v132, s[60:61]
	s_add_u32 s60, s60, s4
	s_addc_u32 s61, s61, s5
	s_mov_b32 m0, s59
	ds_read_b128 v[214:217], v149 offset:23552
	global_load_lds_dwordx4 v134, s[60:61]
	s_add_i32 m0, s59, 0x2000
	ds_read_b128 v[210:213], v149 offset:22528
	global_load_lds_dwordx4 v132, s[60:61]
	s_mov_b32 m0, s29
	ds_read_b128 v[206:209], v149 offset:21504
	global_load_lds_dwordx4 v128, s[30:31]
	s_mov_b32 m0, s41
	ds_read_b128 v[202:205], v149 offset:20480
	global_load_lds_dwordx4 v130, s[30:31]
	s_waitcnt vmcnt(8) lgkmcnt(0)
	s_barrier
	s_setprio 1
	v_mfma_f32_16x16x32_bf16 v[60:63], v[150:153], v[182:185], v[60:63]
	v_mfma_f32_16x16x32_bf16 v[52:55], v[158:161], v[182:185], v[52:55]
	v_mfma_f32_16x16x32_bf16 v[44:47], v[150:153], v[194:197], v[44:47]
	v_mfma_f32_16x16x32_bf16 v[36:39], v[158:161], v[194:197], v[36:39]
	v_mfma_f32_16x16x32_bf16 v[28:31], v[150:153], v[202:205], v[28:31]
	v_mfma_f32_16x16x32_bf16 v[20:23], v[158:161], v[202:205], v[20:23]
	v_mfma_f32_16x16x32_bf16 v[12:15], v[150:153], v[210:213], v[12:15]
	v_mfma_f32_16x16x32_bf16 v[4:7], v[158:161], v[210:213], v[4:7]
	v_mfma_f32_16x16x32_bf16 v[60:63], v[154:157], v[190:193], v[60:63]
	v_mfma_f32_16x16x32_bf16 v[52:55], v[162:165], v[190:193], v[52:55]
	v_mfma_f32_16x16x32_bf16 v[44:47], v[154:157], v[198:201], v[44:47]
	v_mfma_f32_16x16x32_bf16 v[36:39], v[162:165], v[198:201], v[36:39]
	v_mfma_f32_16x16x32_bf16 v[28:31], v[154:157], v[206:209], v[28:31]
	v_mfma_f32_16x16x32_bf16 v[20:23], v[162:165], v[206:209], v[20:23]
	v_mfma_f32_16x16x32_bf16 v[12:15], v[154:157], v[214:217], v[12:15]
	v_mfma_f32_16x16x32_bf16 v[4:7], v[162:165], v[214:217], v[4:7]
	v_mfma_f32_16x16x32_bf16 v[56:59], v[166:169], v[182:185], v[56:59]
	v_mfma_f32_16x16x32_bf16 v[48:51], v[174:177], v[182:185], v[48:51]
	v_mfma_f32_16x16x32_bf16 v[40:43], v[166:169], v[194:197], v[40:43]
	v_mfma_f32_16x16x32_bf16 v[32:35], v[174:177], v[194:197], v[32:35]
	v_mfma_f32_16x16x32_bf16 v[24:27], v[166:169], v[202:205], v[24:27]
	v_mfma_f32_16x16x32_bf16 v[16:19], v[174:177], v[202:205], v[16:19]
	v_mfma_f32_16x16x32_bf16 v[8:11], v[166:169], v[210:213], v[8:11]
	v_mfma_f32_16x16x32_bf16 v[0:3], v[174:177], v[210:213], v[0:3]
	v_mfma_f32_16x16x32_bf16 v[56:59], v[170:173], v[190:193], v[56:59]
	v_mfma_f32_16x16x32_bf16 v[48:51], v[178:181], v[190:193], v[48:51]
	v_mfma_f32_16x16x32_bf16 v[40:43], v[170:173], v[198:201], v[40:43]
	v_mfma_f32_16x16x32_bf16 v[32:35], v[178:181], v[198:201], v[32:35]
	v_mfma_f32_16x16x32_bf16 v[24:27], v[170:173], v[206:209], v[24:27]
	v_mfma_f32_16x16x32_bf16 v[16:19], v[178:181], v[206:209], v[16:19]
	v_mfma_f32_16x16x32_bf16 v[8:11], v[170:173], v[214:217], v[8:11]
	v_mfma_f32_16x16x32_bf16 v[0:3], v[178:181], v[214:217], v[0:3]
	s_setprio 0
	s_barrier
; #define PG8_STAGE(bufoff, gbase, voff) do { _Pragma("unroll") for (int _i = 0; _i < 2; ++_i) \
;         __builtin_amdgcn_global_load_lds((const unsigned*)((const char*)(gbase) + (voff)[_i]), (PG8_LAS unsigned*)(lds + (bufoff) + ldsw + _i * 8192), 16, 0, 0); } while (0)
; #define PG8_LDA(dst, b, h) do { _Pragma("unroll") for (int m = 0; m < 4; ++m) _Pragma("unroll") for (int k = 0; k < 2; ++k) dst[m][k] = *(const PG8_LAS bf16x8*)(lds + PG8_SA(b, h) + aoff + m * 2048 + k * 1024); } while (0)
; #define PG8_LDB(dst, b, h) do { _Pragma("unroll") for (int n = 0; n < 2; ++n) _Pragma("unroll") for (int k = 0; k < 2; ++k) dst[n][k] = *(const PG8_LAS bf16x8*)(lds + PG8_SB(b, h) + boff + n * 2048 + k * 1024); } while (0)
; #define PG8_MMA(ai, bj, At, Bt) do { __builtin_amdgcn_s_setprio(1); _Pragma("unroll") for (int m = 0; m < 4; ++m) _Pragma("unroll") for (int n = 0; n < 2; ++n) _Pragma("unroll") for (int k = 0; k < 2; ++k) \
;         acc[ai][bj][m][n] = __builtin_amdgcn_mfma_f32_16x16x32_bf16(Bt[n][k], At[m][k], acc[ai][bj][m][n], 0, 0, 0); __builtin_amdgcn_s_setprio(0); } while (0)
; #define PG8_WAIT_V(n) asm volatile("s_waitcnt vmcnt(" #n ")" ::: "memory")
; #define PG8_WAIT_L(n) asm volatile("s_waitcnt lgkmcnt(" #n ")" ::: "memory")
; #define PG8_BAR __builtin_amdgcn_s_barrier()
; template <class Epi, class Sched, bool ALIGN_EPI = false, bool SP2 = false>
; __device__ __forceinline__ void gemm_phase(PG8_LAS unsigned char* lds, const Gemm g, const Sched& S, const Epi& E) {
;     ...
;         for (int t = 0; t < nt; t += 2) {
;             const bool last = (t == nt - 2);
;             const char* a1 = cA + (size_t)(t + 1) * kstep;
;             const char* a2 = last ? nA : cA + (size_t)(t + 2) * kstep; const char* b2 = last ? nB : cB + (size_t)(t + 2) * kstep;
;             const char* a3 = a2 + kstep; const char* b3 = b2 + kstep;
;     ...
;             PG8_LDB(B0, 1, 0); PG8_LDB(B1, 1, 1); PG8_SCHED; PG8_LDA(At, 1, 0); PG8_STAGE(PG8_SA(0, 1), a2 + hstepA, voffA);
;             PG8_WAIT_V(8); PG8_WAIT_L(0); PG8_BAR; PG8_MMA(0, 0, At, B0); PG8_MMA(0, 1, At, B1); PG8_BAR; PG8_SCHED;
;             PG8_LDA(At, 1, 1); PG8_STAGE(PG8_SB(1, 0), b3, voffB); PG8_STAGE(PG8_SB(1, 1), b3 + hstep, voffB); PG8_STAGE(PG8_SA(1, 0), a3, voffA);
;             PG8_WAIT_V(8); PG8_WAIT_L(0); PG8_BAR; PG8_MMA(1, 0, At, B0); PG8_MMA(1, 1, At, B1); PG8_BAR; PG8_SCHED;
	s_add_i32 s59, 0, 0x18000
	s_add_i32 s60, 0, 0x1c000
	v_add_u32_e32 v162, s59, v145
	v_add_u32_e32 v178, s60, v145
	ds_read_b128 v[150:153], v162
	ds_read_b128 v[154:157], v162 offset:1024
	ds_read_b128 v[158:161], v162 offset:2048
	ds_read_b128 v[162:165], v162 offset:3072
	ds_read_b128 v[166:169], v178
	ds_read_b128 v[170:173], v178 offset:1024
	ds_read_b128 v[174:177], v178 offset:2048
	ds_read_b128 v[178:181], v178 offset:3072
	s_mov_b64 vcc, s[30:31]
	s_add_u32 s30, s30, 0x40000
	s_addc_u32 s31, s31, 0
	s_mov_b32 m0, s42
	ds_read_b128 v[182:185], v149 offset:32768
	ds_read_b128 v[190:193], v149 offset:33792
	ds_read_b128 v[194:197], v149 offset:34816
	ds_read_b128 v[198:201], v149 offset:35840
	ds_read_b128 v[202:205], v149 offset:36864
	ds_read_b128 v[206:209], v149 offset:37888
	ds_read_b128 v[210:213], v149 offset:38912
	global_load_lds_dwordx4 v128, s[30:31]
	s_mov_b32 m0, s43
	ds_read_b128 v[214:217], v149 offset:39936
	global_load_lds_dwordx4 v130, s[30:31]
	s_waitcnt vmcnt(8) lgkmcnt(0)
	s_barrier
	s_setprio 1
	v_mfma_f32_16x16x32_bf16 v[124:127], v[150:153], v[182:185], v[124:127]
	v_mfma_f32_16x16x32_bf16 v[116:119], v[158:161], v[182:185], v[116:119]
	v_mfma_f32_16x16x32_bf16 v[108:111], v[150:153], v[194:197], v[108:111]
	v_mfma_f32_16x16x32_bf16 v[100:103], v[158:161], v[194:197], v[100:103]
	v_mfma_f32_16x16x32_bf16 v[92:95], v[150:153], v[202:205], v[92:95]
	v_mfma_f32_16x16x32_bf16 v[84:87], v[158:161], v[202:205], v[84:87]
	v_mfma_f32_16x16x32_bf16 v[76:79], v[150:153], v[210:213], v[76:79]
	v_mfma_f32_16x16x32_bf16 v[68:71], v[158:161], v[210:213], v[68:71]
	v_mfma_f32_16x16x32_bf16 v[124:127], v[154:157], v[190:193], v[124:127]
	v_mfma_f32_16x16x32_bf16 v[116:119], v[162:165], v[190:193], v[116:119]
	v_mfma_f32_16x16x32_bf16 v[108:111], v[154:157], v[198:201], v[108:111]
	v_mfma_f32_16x16x32_bf16 v[100:103], v[162:165], v[198:201], v[100:103]
	v_mfma_f32_16x16x32_bf16 v[92:95], v[154:157], v[206:209], v[92:95]
	v_mfma_f32_16x16x32_bf16 v[84:87], v[162:165], v[206:209], v[84:87]
	v_mfma_f32_16x16x32_bf16 v[76:79], v[154:157], v[214:217], v[76:79]
	v_mfma_f32_16x16x32_bf16 v[68:71], v[162:165], v[214:217], v[68:71]
	v_mfma_f32_16x16x32_bf16 v[120:123], v[166:169], v[182:185], v[120:123]
	v_mfma_f32_16x16x32_bf16 v[112:115], v[174:177], v[182:185], v[112:115]
	v_mfma_f32_16x16x32_bf16 v[104:107], v[166:169], v[194:197], v[104:107]
	v_mfma_f32_16x16x32_bf16 v[96:99], v[174:177], v[194:197], v[96:99]
	v_mfma_f32_16x16x32_bf16 v[88:91], v[166:169], v[202:205], v[88:91]
	v_mfma_f32_16x16x32_bf16 v[80:83], v[174:177], v[202:205], v[80:83]
	v_mfma_f32_16x16x32_bf16 v[72:75], v[166:169], v[210:213], v[72:75]
	v_mfma_f32_16x16x32_bf16 v[64:67], v[174:177], v[210:213], v[64:67]
	v_mfma_f32_16x16x32_bf16 v[120:123], v[170:173], v[190:193], v[120:123]
	v_mfma_f32_16x16x32_bf16 v[112:115], v[178:181], v[190:193], v[112:115]
	v_mfma_f32_16x16x32_bf16 v[104:107], v[170:173], v[198:201], v[104:107]
	v_mfma_f32_16x16x32_bf16 v[96:99], v[178:181], v[198:201], v[96:99]
	v_mfma_f32_16x16x32_bf16 v[88:91], v[170:173], v[206:209], v[88:91]
	v_mfma_f32_16x16x32_bf16 v[80:83], v[178:181], v[206:209], v[80:83]
	v_mfma_f32_16x16x32_bf16 v[72:75], v[170:173], v[214:217], v[72:75]
	v_mfma_f32_16x16x32_bf16 v[64:67], v[178:181], v[214:217], v[64:67]
	s_setprio 0
	s_barrier
	s_add_i32 s30, s59, s38
	s_add_i32 m0, s30, 0xffffff80
	ds_read_b128 v[182:185], v149 offset:49152
	ds_read_b128 v[190:193], v149 offset:50176
	ds_read_b128 v[194:197], v149 offset:51200
	ds_read_b128 v[198:201], v149 offset:52224
	global_load_lds_dwordx4 v134, s[100:101] offset:128
	s_add_i32 m0, s30, 0x1f80
	s_add_i32 s30, s60, s38
	global_load_lds_dwordx4 v132, s[100:101] offset:128
	s_add_u32 s100, s100, s4
	s_addc_u32 s101, s101, s5
	s_add_i32 m0, s30, 0xffffff80
	ds_read_b128 v[214:217], v149 offset:56320
	global_load_lds_dwordx4 v134, s[100:101] offset:128
	s_add_i32 m0, s30, 0x1f80
	ds_read_b128 v[210:213], v149 offset:55296
	global_load_lds_dwordx4 v132, s[100:101] offset:128
	s_add_i32 m0, s47, 0xffffff80
	ds_read_b128 v[206:209], v149 offset:54272
	global_load_lds_dwordx4 v128, vcc offset:128
	s_add_i32 m0, s48, 0xffffff80
	ds_read_b128 v[202:205], v149 offset:53248
	global_load_lds_dwordx4 v130, vcc offset:128
	s_waitcnt vmcnt(8) lgkmcnt(0)
	s_barrier
	s_setprio 1
	v_mfma_f32_16x16x32_bf16 v[60:63], v[150:153], v[182:185], v[60:63]
	v_mfma_f32_16x16x32_bf16 v[52:55], v[158:161], v[182:185], v[52:55]
	v_mfma_f32_16x16x32_bf16 v[44:47], v[150:153], v[194:197], v[44:47]
	v_mfma_f32_16x16x32_bf16 v[36:39], v[158:161], v[194:197], v[36:39]
	v_mfma_f32_16x16x32_bf16 v[28:31], v[150:153], v[202:205], v[28:31]
	v_mfma_f32_16x16x32_bf16 v[20:23], v[158:161], v[202:205], v[20:23]
	v_mfma_f32_16x16x32_bf16 v[12:15], v[150:153], v[210:213], v[12:15]
	v_mfma_f32_16x16x32_bf16 v[4:7], v[158:161], v[210:213], v[4:7]
	v_mfma_f32_16x16x32_bf16 v[60:63], v[154:157], v[190:193], v[60:63]
	v_mfma_f32_16x16x32_bf16 v[52:55], v[162:165], v[190:193], v[52:55]
	v_mfma_f32_16x16x32_bf16 v[44:47], v[154:157], v[198:201], v[44:47]
	v_mfma_f32_16x16x32_bf16 v[36:39], v[162:165], v[198:201], v[36:39]
	v_mfma_f32_16x16x32_bf16 v[28:31], v[154:157], v[206:209], v[28:31]
	v_mfma_f32_16x16x32_bf16 v[20:23], v[162:165], v[206:209], v[20:23]
	v_mfma_f32_16x16x32_bf16 v[12:15], v[154:157], v[214:217], v[12:15]
	v_mfma_f32_16x16x32_bf16 v[4:7], v[162:165], v[214:217], v[4:7]
	v_mfma_f32_16x16x32_bf16 v[56:59], v[166:169], v[182:185], v[56:59]
	v_mfma_f32_16x16x32_bf16 v[48:51], v[174:177], v[182:185], v[48:51]
	v_mfma_f32_16x16x32_bf16 v[40:43], v[166:169], v[194:197], v[40:43]
	v_mfma_f32_16x16x32_bf16 v[32:35], v[174:177], v[194:197], v[32:35]
	v_mfma_f32_16x16x32_bf16 v[24:27], v[166:169], v[202:205], v[24:27]
	v_mfma_f32_16x16x32_bf16 v[16:19], v[174:177], v[202:205], v[16:19]
	v_mfma_f32_16x16x32_bf16 v[8:11], v[166:169], v[210:213], v[8:11]
	v_mfma_f32_16x16x32_bf16 v[0:3], v[174:177], v[210:213], v[0:3]
	v_mfma_f32_16x16x32_bf16 v[56:59], v[170:173], v[190:193], v[56:59]
	v_mfma_f32_16x16x32_bf16 v[48:51], v[178:181], v[190:193], v[48:51]
	v_mfma_f32_16x16x32_bf16 v[40:43], v[170:173], v[198:201], v[40:43]
	v_mfma_f32_16x16x32_bf16 v[32:35], v[178:181], v[198:201], v[32:35]
	v_mfma_f32_16x16x32_bf16 v[24:27], v[170:173], v[206:209], v[24:27]
	v_mfma_f32_16x16x32_bf16 v[16:19], v[178:181], v[206:209], v[16:19]
	v_mfma_f32_16x16x32_bf16 v[8:11], v[170:173], v[214:217], v[8:11]
	v_mfma_f32_16x16x32_bf16 v[0:3], v[178:181], v[214:217], v[0:3]
	s_setprio 0
	s_barrier
	s_add_u32 s10, s10, 0x100
	s_addc_u32 s11, s11, 0
	s_add_u32 s34, s34, 0x100
	s_addc_u32 s35, s35, 0
	s_cmp_ge_i32 s58, s50
	s_mov_b32 s30, s58
	s_cbranch_scc0 .LBB0_898

; #define PG8_STAGE(bufoff, gbase, voff) do { _Pragma("unroll") for (int _i = 0; _i < 2; ++_i) \
;         __builtin_amdgcn_global_load_lds((const unsigned*)((const char*)(gbase) + (voff)[_i]), (PG8_LAS unsigned*)(lds + (bufoff) + ldsw + _i * 8192), 16, 0, 0); } while (0)
; #define PG8_LDA(dst, b, h) do { _Pragma("unroll") for (int m = 0; m < 4; ++m) _Pragma("unroll") for (int k = 0; k < 2; ++k) dst[m][k] = *(const PG8_LAS bf16x8*)(lds + PG8_SA(b, h) + aoff + m * 2048 + k * 1024); } while (0)
; #define PG8_LDB(dst, b, h) do { _Pragma("unroll") for (int n = 0; n < 2; ++n) _Pragma("unroll") for (int k = 0; k < 2; ++k) dst[n][k] = *(const PG8_LAS bf16x8*)(lds + PG8_SB(b, h) + boff + n * 2048 + k * 1024); } while (0)
; #define PG8_MMA(ai, bj, At, Bt) do { __builtin_amdgcn_s_setprio(1); _Pragma("unroll") for (int m = 0; m < 4; ++m) _Pragma("unroll") for (int n = 0; n < 2; ++n) _Pragma("unroll") for (int k = 0; k < 2; ++k) \
;         acc[ai][bj][m][n] = __builtin_amdgcn_mfma_f32_16x16x32_bf16(Bt[n][k], At[m][k], acc[ai][bj][m][n], 0, 0, 0); __builtin_amdgcn_s_setprio(0); } while (0)
; #define PG8_WAIT_V(n) asm volatile("s_waitcnt vmcnt(" #n ")" ::: "memory")
; #define PG8_BAR __builtin_amdgcn_s_barrier()
; template <class Epi, class Sched, bool ALIGN_EPI = false, bool SP2 = false>
; __device__ __forceinline__ void gemm_phase(PG8_LAS unsigned char* lds, const Gemm g, const Sched& S, const Epi& E) {
;     ...
;         for (int t = 0; t < nt; t += 2) {
;             const bool last = (t == nt - 2);
;             const char* a1 = cA + (size_t)(t + 1) * kstep;
;             const char* a2 = last ? nA : cA + (size_t)(t + 2) * kstep; const char* b2 = last ? nB : cB + (size_t)(t + 2) * kstep;
;             const char* a3 = a2 + kstep; const char* b3 = b2 + kstep;
;             if (last && has_next) S.a_ready(nxt);
;             if constexpr (SP2) {
;             PG8_LDB(B0, 0, 0); PG8_LDB(B1, 0, 1); PG8_SCHED; PG8_LDA(At, 0, 0); PG8_STAGE(PG8_SA(1, 1), a1 + hstepA, voffA);
;             PG8_WAIT_V(8); PG8_WAIT_L(0); PG8_BAR; PG8_MMA(0, 0, At, B0); PG8_MMA(0, 1, At, B1); PG8_BAR; PG8_SCHED;
;             PG8_LDA(At, 0, 1); PG8_STAGE(PG8_SB(0, 0), b2, voffB); PG8_STAGE(PG8_SB(0, 1), b2 + hstep, voffB); PG8_STAGE(PG8_SA(0, 0), a2, voffA);
;             PG8_WAIT_V(8); PG8_WAIT_L(0); PG8_BAR; PG8_MMA(1, 0, At, B0); PG8_MMA(1, 1, At, B1); PG8_BAR; PG8_SCHED;
.LBB0_980:
	ds_read_b128 v[128:131], v169
	ds_read_b128 v[132:135], v169 offset:1024
	ds_read_b128 v[136:139], v169 offset:2048
	ds_read_b128 v[140:143], v169 offset:3072
	ds_read_b128 v[160:163], v170
	ds_read_b128 v[172:175], v170 offset:1024
	ds_read_b128 v[176:179], v170 offset:2048
	ds_read_b128 v[180:183], v170 offset:3072
	s_add_i32 s69, s38, 2
	s_add_u32 s70, s36, 0xfff50080
	s_addc_u32 s39, s37, -1
	s_cmp_eq_u32 s55, s38
	s_cselect_b32 s38, s8, s70
	s_cselect_b32 s39, s9, s39
	s_cselect_b32 s71, s35, s68
	s_cselect_b32 s70, s34, s67
	s_add_i32 m0, s44, 0xc000
	ds_read_b128 v[184:187], v171
	ds_read_b128 v[190:193], v171 offset:1024
	ds_read_b128 v[194:197], v171 offset:2048
	ds_read_b128 v[198:201], v171 offset:3072
	ds_read_b128 v[202:205], v171 offset:4096
	ds_read_b128 v[206:209], v171 offset:5120
	ds_read_b128 v[210:213], v171 offset:6144
	global_load_lds_dwordx4 v152, s[36:37]
	s_add_i32 m0, s44, 0xe000
	ds_read_b128 v[214:217], v171 offset:7168
	global_load_lds_dwordx4 v154, s[36:37]
	s_waitcnt vmcnt(8) lgkmcnt(0)
	s_barrier
	s_setprio 1
	v_mfma_f32_16x16x32_bf16 v[124:127], v[128:131], v[184:187], v[124:127]
	v_mfma_f32_16x16x32_bf16 v[120:123], v[136:139], v[184:187], v[120:123]
	v_mfma_f32_16x16x32_bf16 v[108:111], v[128:131], v[194:197], v[108:111]
	v_mfma_f32_16x16x32_bf16 v[104:107], v[136:139], v[194:197], v[104:107]
	v_mfma_f32_16x16x32_bf16 v[92:95], v[128:131], v[202:205], v[92:95]
	v_mfma_f32_16x16x32_bf16 v[88:91], v[136:139], v[202:205], v[88:91]
	v_mfma_f32_16x16x32_bf16 v[76:79], v[128:131], v[210:213], v[76:79]
	v_mfma_f32_16x16x32_bf16 v[72:75], v[136:139], v[210:213], v[72:75]
	v_mfma_f32_16x16x32_bf16 v[124:127], v[132:135], v[190:193], v[124:127]
	v_mfma_f32_16x16x32_bf16 v[120:123], v[140:143], v[190:193], v[120:123]
	v_mfma_f32_16x16x32_bf16 v[108:111], v[132:135], v[198:201], v[108:111]
	v_mfma_f32_16x16x32_bf16 v[104:107], v[140:143], v[198:201], v[104:107]
	v_mfma_f32_16x16x32_bf16 v[92:95], v[132:135], v[206:209], v[92:95]
	v_mfma_f32_16x16x32_bf16 v[88:91], v[140:143], v[206:209], v[88:91]
	v_mfma_f32_16x16x32_bf16 v[76:79], v[132:135], v[214:217], v[76:79]
	v_mfma_f32_16x16x32_bf16 v[72:75], v[140:143], v[214:217], v[72:75]
	v_mfma_f32_16x16x32_bf16 v[116:119], v[160:163], v[184:187], v[116:119]
	v_mfma_f32_16x16x32_bf16 v[112:115], v[176:179], v[184:187], v[112:115]
	v_mfma_f32_16x16x32_bf16 v[100:103], v[160:163], v[194:197], v[100:103]
	v_mfma_f32_16x16x32_bf16 v[96:99], v[176:179], v[194:197], v[96:99]
	v_mfma_f32_16x16x32_bf16 v[84:87], v[160:163], v[202:205], v[84:87]
	v_mfma_f32_16x16x32_bf16 v[80:83], v[176:179], v[202:205], v[80:83]
	v_mfma_f32_16x16x32_bf16 v[68:71], v[160:163], v[210:213], v[68:71]
	v_mfma_f32_16x16x32_bf16 v[64:67], v[176:179], v[210:213], v[64:67]
	v_mfma_f32_16x16x32_bf16 v[116:119], v[172:175], v[190:193], v[116:119]
	v_mfma_f32_16x16x32_bf16 v[112:115], v[180:183], v[190:193], v[112:115]
	v_mfma_f32_16x16x32_bf16 v[100:103], v[172:175], v[198:201], v[100:103]
	v_mfma_f32_16x16x32_bf16 v[96:99], v[180:183], v[198:201], v[96:99]
	v_mfma_f32_16x16x32_bf16 v[84:87], v[172:175], v[206:209], v[84:87]
	v_mfma_f32_16x16x32_bf16 v[80:83], v[180:183], v[206:209], v[80:83]
	v_mfma_f32_16x16x32_bf16 v[68:71], v[172:175], v[214:217], v[68:71]
	v_mfma_f32_16x16x32_bf16 v[64:67], v[180:183], v[214:217], v[64:67]
	s_setprio 0
	s_barrier
	s_add_i32 s72, s56, s42
	s_mov_b32 m0, s72
	ds_read_b128 v[184:187], v171 offset:16384
	ds_read_b128 v[190:193], v171 offset:17408
	ds_read_b128 v[194:197], v171 offset:18432
	ds_read_b128 v[198:201], v171 offset:19456
	global_load_lds_dwordx4 v150, s[70:71]
	s_add_i32 m0, s72, 0x2000
	s_mov_b64 s[100:101], s[70:71]
	s_add_i32 s72, s57, s42
	global_load_lds_dwordx4 v148, s[70:71]
	s_add_u32 s70, s70, s4
	s_addc_u32 s71, s71, s5
	s_mov_b32 m0, s72
	ds_read_b128 v[214:217], v171 offset:23552
	global_load_lds_dwordx4 v150, s[70:71]
	s_add_i32 m0, s72, 0x2000
	ds_read_b128 v[210:213], v171 offset:22528
	global_load_lds_dwordx4 v148, s[70:71]
	s_mov_b32 m0, s44
	ds_read_b128 v[206:209], v171 offset:21504
	global_load_lds_dwordx4 v144, s[38:39]
	s_mov_b32 m0, s45
	ds_read_b128 v[202:205], v171 offset:20480
	global_load_lds_dwordx4 v146, s[38:39]
	s_waitcnt vmcnt(8) lgkmcnt(0)
	s_barrier
	s_setprio 1
	v_mfma_f32_16x16x32_bf16 v[60:63], v[128:131], v[184:187], v[60:63]
	v_mfma_f32_16x16x32_bf16 v[56:59], v[136:139], v[184:187], v[56:59]
	v_mfma_f32_16x16x32_bf16 v[44:47], v[128:131], v[194:197], v[44:47]
	v_mfma_f32_16x16x32_bf16 v[40:43], v[136:139], v[194:197], v[40:43]
	v_mfma_f32_16x16x32_bf16 v[28:31], v[128:131], v[202:205], v[28:31]
	v_mfma_f32_16x16x32_bf16 v[24:27], v[136:139], v[202:205], v[24:27]
	v_mfma_f32_16x16x32_bf16 v[12:15], v[128:131], v[210:213], v[12:15]
	v_mfma_f32_16x16x32_bf16 v[8:11], v[136:139], v[210:213], v[8:11]
	v_mfma_f32_16x16x32_bf16 v[60:63], v[132:135], v[190:193], v[60:63]
	v_mfma_f32_16x16x32_bf16 v[56:59], v[140:143], v[190:193], v[56:59]
	v_mfma_f32_16x16x32_bf16 v[44:47], v[132:135], v[198:201], v[44:47]
	v_mfma_f32_16x16x32_bf16 v[40:43], v[140:143], v[198:201], v[40:43]
	v_mfma_f32_16x16x32_bf16 v[28:31], v[132:135], v[206:209], v[28:31]
	v_mfma_f32_16x16x32_bf16 v[24:27], v[140:143], v[206:209], v[24:27]
	v_mfma_f32_16x16x32_bf16 v[12:15], v[132:135], v[214:217], v[12:15]
	v_mfma_f32_16x16x32_bf16 v[8:11], v[140:143], v[214:217], v[8:11]
	v_mfma_f32_16x16x32_bf16 v[52:55], v[160:163], v[184:187], v[52:55]
	v_mfma_f32_16x16x32_bf16 v[48:51], v[176:179], v[184:187], v[48:51]
	v_mfma_f32_16x16x32_bf16 v[36:39], v[160:163], v[194:197], v[36:39]
	v_mfma_f32_16x16x32_bf16 v[32:35], v[176:179], v[194:197], v[32:35]
	v_mfma_f32_16x16x32_bf16 v[20:23], v[160:163], v[202:205], v[20:23]
	v_mfma_f32_16x16x32_bf16 v[16:19], v[176:179], v[202:205], v[16:19]
	v_mfma_f32_16x16x32_bf16 v[4:7], v[160:163], v[210:213], v[4:7]
	v_mfma_f32_16x16x32_bf16 v[0:3], v[176:179], v[210:213], v[0:3]
	v_mfma_f32_16x16x32_bf16 v[52:55], v[172:175], v[190:193], v[52:55]
	v_mfma_f32_16x16x32_bf16 v[48:51], v[180:183], v[190:193], v[48:51]
	v_mfma_f32_16x16x32_bf16 v[36:39], v[172:175], v[198:201], v[36:39]
	v_mfma_f32_16x16x32_bf16 v[32:35], v[180:183], v[198:201], v[32:35]
	v_mfma_f32_16x16x32_bf16 v[20:23], v[172:175], v[206:209], v[20:23]
	v_mfma_f32_16x16x32_bf16 v[16:19], v[180:183], v[206:209], v[16:19]
	v_mfma_f32_16x16x32_bf16 v[4:7], v[172:175], v[214:217], v[4:7]
	v_mfma_f32_16x16x32_bf16 v[0:3], v[180:183], v[214:217], v[0:3]
	s_setprio 0
	s_barrier
; #define PG8_STAGE(bufoff, gbase, voff) do { _Pragma("unroll") for (int _i = 0; _i < 2; ++_i) \
;         __builtin_amdgcn_global_load_lds((const unsigned*)((const char*)(gbase) + (voff)[_i]), (PG8_LAS unsigned*)(lds + (bufoff) + ldsw + _i * 8192), 16, 0, 0); } while (0)
; #define PG8_LDA(dst, b, h) do { _Pragma("unroll") for (int m = 0; m < 4; ++m) _Pragma("unroll") for (int k = 0; k < 2; ++k) dst[m][k] = *(const PG8_LAS bf16x8*)(lds + PG8_SA(b, h) + aoff + m * 2048 + k * 1024); } while (0)
; #define PG8_LDB(dst, b, h) do { _Pragma("unroll") for (int n = 0; n < 2; ++n) _Pragma("unroll") for (int k = 0; k < 2; ++k) dst[n][k] = *(const PG8_LAS bf16x8*)(lds + PG8_SB(b, h) + boff + n * 2048 + k * 1024); } while (0)
; #define PG8_MMA(ai, bj, At, Bt) do { __builtin_amdgcn_s_setprio(1); _Pragma("unroll") for (int m = 0; m < 4; ++m) _Pragma("unroll") for (int n = 0; n < 2; ++n) _Pragma("unroll") for (int k = 0; k < 2; ++k) \
;         acc[ai][bj][m][n] = __builtin_amdgcn_mfma_f32_16x16x32_bf16(Bt[n][k], At[m][k], acc[ai][bj][m][n], 0, 0, 0); __builtin_amdgcn_s_setprio(0); } while (0)
; #define PG8_WAIT_V(n) asm volatile("s_waitcnt vmcnt(" #n ")" ::: "memory")
; #define PG8_WAIT_L(n) asm volatile("s_waitcnt lgkmcnt(" #n ")" ::: "memory")
; #define PG8_BAR __builtin_amdgcn_s_barrier()
; template <class Epi, class Sched, bool ALIGN_EPI = false, bool SP2 = false>
; __device__ __forceinline__ void gemm_phase(PG8_LAS unsigned char* lds, const Gemm g, const Sched& S, const Epi& E) {
;     ...
;         for (int t = 0; t < nt; t += 2) {
;             const bool last = (t == nt - 2);
;             const char* a1 = cA + (size_t)(t + 1) * kstep;
;             const char* a2 = last ? nA : cA + (size_t)(t + 2) * kstep; const char* b2 = last ? nB : cB + (size_t)(t + 2) * kstep;
;             const char* a3 = a2 + kstep; const char* b3 = b2 + kstep;
;     ...
;             PG8_LDB(B0, 1, 0); PG8_LDB(B1, 1, 1); PG8_SCHED; PG8_LDA(At, 1, 0); PG8_STAGE(PG8_SA(0, 1), a2 + hstepA, voffA);
;             PG8_WAIT_V(8); PG8_WAIT_L(0); PG8_BAR; PG8_MMA(0, 0, At, B0); PG8_MMA(0, 1, At, B1); PG8_BAR; PG8_SCHED;
;             PG8_LDA(At, 1, 1); PG8_STAGE(PG8_SB(1, 0), b3, voffB); PG8_STAGE(PG8_SB(1, 1), b3 + hstep, voffB); PG8_STAGE(PG8_SA(1, 0), a3, voffA);
;             PG8_WAIT_V(8); PG8_WAIT_L(0); PG8_BAR; PG8_MMA(1, 0, At, B0); PG8_MMA(1, 1, At, B1); PG8_BAR; PG8_SCHED;
	s_add_i32 s70, 0, 0x18000
	s_add_i32 s71, 0, 0x1c000
	v_add_u32_e32 v140, s70, v167
	v_add_u32_e32 v180, s71, v167
	ds_read_b128 v[128:131], v140
	ds_read_b128 v[132:135], v140 offset:1024
	ds_read_b128 v[136:139], v140 offset:2048
	ds_read_b128 v[140:143], v140 offset:3072
	ds_read_b128 v[160:163], v180
	ds_read_b128 v[172:175], v180 offset:1024
	ds_read_b128 v[176:179], v180 offset:2048
	ds_read_b128 v[180:183], v180 offset:3072
	s_mov_b64 vcc, s[38:39]
	s_add_u32 s38, s38, 0xb0000
	s_addc_u32 s39, s39, 0
	s_mov_b32 m0, s47
	ds_read_b128 v[184:187], v171 offset:32768
	ds_read_b128 v[190:193], v171 offset:33792
	ds_read_b128 v[194:197], v171 offset:34816
	ds_read_b128 v[198:201], v171 offset:35840
	ds_read_b128 v[202:205], v171 offset:36864
	ds_read_b128 v[206:209], v171 offset:37888
	ds_read_b128 v[210:213], v171 offset:38912
	global_load_lds_dwordx4 v144, s[38:39]
	s_mov_b32 m0, s48
	ds_read_b128 v[214:217], v171 offset:39936
	global_load_lds_dwordx4 v146, s[38:39]
	s_waitcnt vmcnt(8) lgkmcnt(0)
	s_barrier
	s_setprio 1
	v_mfma_f32_16x16x32_bf16 v[124:127], v[128:131], v[184:187], v[124:127]
	v_mfma_f32_16x16x32_bf16 v[120:123], v[136:139], v[184:187], v[120:123]
	v_mfma_f32_16x16x32_bf16 v[108:111], v[128:131], v[194:197], v[108:111]
	v_mfma_f32_16x16x32_bf16 v[104:107], v[136:139], v[194:197], v[104:107]
	v_mfma_f32_16x16x32_bf16 v[92:95], v[128:131], v[202:205], v[92:95]
	v_mfma_f32_16x16x32_bf16 v[88:91], v[136:139], v[202:205], v[88:91]
	v_mfma_f32_16x16x32_bf16 v[76:79], v[128:131], v[210:213], v[76:79]
	v_mfma_f32_16x16x32_bf16 v[72:75], v[136:139], v[210:213], v[72:75]
	v_mfma_f32_16x16x32_bf16 v[124:127], v[132:135], v[190:193], v[124:127]
	v_mfma_f32_16x16x32_bf16 v[120:123], v[140:143], v[190:193], v[120:123]
	v_mfma_f32_16x16x32_bf16 v[108:111], v[132:135], v[198:201], v[108:111]
	v_mfma_f32_16x16x32_bf16 v[104:107], v[140:143], v[198:201], v[104:107]
	v_mfma_f32_16x16x32_bf16 v[92:95], v[132:135], v[206:209], v[92:95]
	v_mfma_f32_16x16x32_bf16 v[88:91], v[140:143], v[206:209], v[88:91]
	v_mfma_f32_16x16x32_bf16 v[76:79], v[132:135], v[214:217], v[76:79]
	v_mfma_f32_16x16x32_bf16 v[72:75], v[140:143], v[214:217], v[72:75]
	v_mfma_f32_16x16x32_bf16 v[116:119], v[160:163], v[184:187], v[116:119]
	v_mfma_f32_16x16x32_bf16 v[112:115], v[176:179], v[184:187], v[112:115]
	v_mfma_f32_16x16x32_bf16 v[100:103], v[160:163], v[194:197], v[100:103]
	v_mfma_f32_16x16x32_bf16 v[96:99], v[176:179], v[194:197], v[96:99]
	v_mfma_f32_16x16x32_bf16 v[84:87], v[160:163], v[202:205], v[84:87]
	v_mfma_f32_16x16x32_bf16 v[80:83], v[176:179], v[202:205], v[80:83]
	v_mfma_f32_16x16x32_bf16 v[68:71], v[160:163], v[210:213], v[68:71]
	v_mfma_f32_16x16x32_bf16 v[64:67], v[176:179], v[210:213], v[64:67]
	v_mfma_f32_16x16x32_bf16 v[116:119], v[172:175], v[190:193], v[116:119]
	v_mfma_f32_16x16x32_bf16 v[112:115], v[180:183], v[190:193], v[112:115]
	v_mfma_f32_16x16x32_bf16 v[100:103], v[172:175], v[198:201], v[100:103]
	v_mfma_f32_16x16x32_bf16 v[96:99], v[180:183], v[198:201], v[96:99]
	v_mfma_f32_16x16x32_bf16 v[84:87], v[172:175], v[206:209], v[84:87]
	v_mfma_f32_16x16x32_bf16 v[80:83], v[180:183], v[206:209], v[80:83]
	v_mfma_f32_16x16x32_bf16 v[68:71], v[172:175], v[214:217], v[68:71]
	v_mfma_f32_16x16x32_bf16 v[64:67], v[180:183], v[214:217], v[64:67]
	s_setprio 0
	s_barrier
	s_add_i32 s38, s70, s42
	s_add_i32 m0, s38, 0xffffff80
	ds_read_b128 v[184:187], v171 offset:49152
	ds_read_b128 v[190:193], v171 offset:50176
	ds_read_b128 v[194:197], v171 offset:51200
	ds_read_b128 v[198:201], v171 offset:52224
	global_load_lds_dwordx4 v150, s[100:101] offset:128
	s_add_i32 m0, s38, 0x1f80
	s_add_i32 s38, s71, s42
	global_load_lds_dwordx4 v148, s[100:101] offset:128
	s_add_u32 s100, s100, s4
	s_addc_u32 s101, s101, s5
	s_add_i32 m0, s38, 0xffffff80
	ds_read_b128 v[214:217], v171 offset:56320
	global_load_lds_dwordx4 v150, s[100:101] offset:128
	s_add_i32 m0, s38, 0x1f80
	ds_read_b128 v[210:213], v171 offset:55296
	global_load_lds_dwordx4 v148, s[100:101] offset:128
	s_add_i32 m0, s51, 0xffffff80
	ds_read_b128 v[206:209], v171 offset:54272
	global_load_lds_dwordx4 v144, vcc offset:128
	s_add_i32 m0, s52, 0xffffff80
	ds_read_b128 v[202:205], v171 offset:53248
	global_load_lds_dwordx4 v146, vcc offset:128
	s_waitcnt vmcnt(8) lgkmcnt(0)
	s_barrier
	s_setprio 1
	v_mfma_f32_16x16x32_bf16 v[60:63], v[128:131], v[184:187], v[60:63]
	v_mfma_f32_16x16x32_bf16 v[56:59], v[136:139], v[184:187], v[56:59]
	v_mfma_f32_16x16x32_bf16 v[44:47], v[128:131], v[194:197], v[44:47]
	v_mfma_f32_16x16x32_bf16 v[40:43], v[136:139], v[194:197], v[40:43]
	v_mfma_f32_16x16x32_bf16 v[28:31], v[128:131], v[202:205], v[28:31]
	v_mfma_f32_16x16x32_bf16 v[24:27], v[136:139], v[202:205], v[24:27]
	v_mfma_f32_16x16x32_bf16 v[12:15], v[128:131], v[210:213], v[12:15]
	v_mfma_f32_16x16x32_bf16 v[8:11], v[136:139], v[210:213], v[8:11]
	v_mfma_f32_16x16x32_bf16 v[60:63], v[132:135], v[190:193], v[60:63]
	v_mfma_f32_16x16x32_bf16 v[56:59], v[140:143], v[190:193], v[56:59]
	v_mfma_f32_16x16x32_bf16 v[44:47], v[132:135], v[198:201], v[44:47]
	v_mfma_f32_16x16x32_bf16 v[40:43], v[140:143], v[198:201], v[40:43]
	v_mfma_f32_16x16x32_bf16 v[28:31], v[132:135], v[206:209], v[28:31]
	v_mfma_f32_16x16x32_bf16 v[24:27], v[140:143], v[206:209], v[24:27]
	v_mfma_f32_16x16x32_bf16 v[12:15], v[132:135], v[214:217], v[12:15]
	v_mfma_f32_16x16x32_bf16 v[8:11], v[140:143], v[214:217], v[8:11]
	v_mfma_f32_16x16x32_bf16 v[52:55], v[160:163], v[184:187], v[52:55]
	v_mfma_f32_16x16x32_bf16 v[48:51], v[176:179], v[184:187], v[48:51]
	v_mfma_f32_16x16x32_bf16 v[36:39], v[160:163], v[194:197], v[36:39]
	v_mfma_f32_16x16x32_bf16 v[32:35], v[176:179], v[194:197], v[32:35]
	v_mfma_f32_16x16x32_bf16 v[20:23], v[160:163], v[202:205], v[20:23]
	v_mfma_f32_16x16x32_bf16 v[16:19], v[176:179], v[202:205], v[16:19]
	v_mfma_f32_16x16x32_bf16 v[4:7], v[160:163], v[210:213], v[4:7]
	v_mfma_f32_16x16x32_bf16 v[0:3], v[176:179], v[210:213], v[0:3]
	v_mfma_f32_16x16x32_bf16 v[52:55], v[172:175], v[190:193], v[52:55]
	v_mfma_f32_16x16x32_bf16 v[48:51], v[180:183], v[190:193], v[48:51]
	v_mfma_f32_16x16x32_bf16 v[36:39], v[172:175], v[198:201], v[36:39]
	v_mfma_f32_16x16x32_bf16 v[32:35], v[180:183], v[198:201], v[32:35]
	v_mfma_f32_16x16x32_bf16 v[20:23], v[172:175], v[206:209], v[20:23]
	v_mfma_f32_16x16x32_bf16 v[16:19], v[180:183], v[206:209], v[16:19]
	v_mfma_f32_16x16x32_bf16 v[4:7], v[172:175], v[214:217], v[4:7]
	v_mfma_f32_16x16x32_bf16 v[0:3], v[180:183], v[214:217], v[0:3]
	s_setprio 0
	s_barrier
	s_add_u32 s36, s36, 0x100
	s_addc_u32 s37, s37, 0
	s_add_u32 s67, s67, 0x100
	s_addc_u32 s68, s68, 0
	s_cmp_ge_i32 s69, s54
	s_mov_b32 s38, s69
	s_cbranch_scc0 .LBB0_980

; #define PG8_STAGE(bufoff, gbase, voff) do { _Pragma("unroll") for (int _i = 0; _i < 2; ++_i) \
;         __builtin_amdgcn_global_load_lds((const unsigned*)((const char*)(gbase) + (voff)[_i]), (PG8_LAS unsigned*)(lds + (bufoff) + ldsw + _i * 8192), 16, 0, 0); } while (0)
; #define PG8_LDA(dst, b, h) do { _Pragma("unroll") for (int m = 0; m < 4; ++m) _Pragma("unroll") for (int k = 0; k < 2; ++k) dst[m][k] = *(const PG8_LAS bf16x8*)(lds + PG8_SA(b, h) + aoff + m * 2048 + k * 1024); } while (0)
; #define PG8_LDB(dst, b, h) do { _Pragma("unroll") for (int n = 0; n < 2; ++n) _Pragma("unroll") for (int k = 0; k < 2; ++k) dst[n][k] = *(const PG8_LAS bf16x8*)(lds + PG8_SB(b, h) + boff + n * 2048 + k * 1024); } while (0)
; #define PG8_MMA(ai, bj, At, Bt) do { __builtin_amdgcn_s_setprio(1); _Pragma("unroll") for (int m = 0; m < 4; ++m) _Pragma("unroll") for (int n = 0; n < 2; ++n) _Pragma("unroll") for (int k = 0; k < 2; ++k) \
;         acc[ai][bj][m][n] = __builtin_amdgcn_mfma_f32_16x16x32_bf16(Bt[n][k], At[m][k], acc[ai][bj][m][n], 0, 0, 0); __builtin_amdgcn_s_setprio(0); } while (0)
; #define PG8_WAIT_V(n) asm volatile("s_waitcnt vmcnt(" #n ")" ::: "memory")
; #define PG8_BAR __builtin_amdgcn_s_barrier()
; template <class Epi, class Sched, bool ALIGN_EPI = false, bool SP2 = false>
; __device__ __forceinline__ void gemm_phase(PG8_LAS unsigned char* lds, const Gemm g, const Sched& S, const Epi& E) {
;     ...
;         for (int t = 0; t < nt; t += 2) {
;             const bool last = (t == nt - 2);
;             const char* a1 = cA + (size_t)(t + 1) * kstep;
;             const char* a2 = last ? nA : cA + (size_t)(t + 2) * kstep; const char* b2 = last ? nB : cB + (size_t)(t + 2) * kstep;
;             const char* a3 = a2 + kstep; const char* b3 = b2 + kstep;
;             if (last && has_next) S.a_ready(nxt);
;             if constexpr (SP2) {
;             PG8_LDB(B0, 0, 0); PG8_LDB(B1, 0, 1); PG8_SCHED; PG8_LDA(At, 0, 0); PG8_STAGE(PG8_SA(1, 1), a1 + hstepA, voffA);
;             PG8_WAIT_V(8); PG8_WAIT_L(0); PG8_BAR; PG8_MMA(0, 0, At, B0); PG8_MMA(0, 1, At, B1); PG8_BAR; PG8_SCHED;
;             PG8_LDA(At, 0, 1); PG8_STAGE(PG8_SB(0, 0), b2, voffB); PG8_STAGE(PG8_SB(0, 1), b2 + hstep, voffB); PG8_STAGE(PG8_SA(0, 0), a2, voffA);
;             PG8_WAIT_V(8); PG8_WAIT_L(0); PG8_BAR; PG8_MMA(1, 0, At, B0); PG8_MMA(1, 1, At, B1); PG8_BAR; PG8_SCHED;
.LBB0_1068:
	ds_read_b128 v[152:155], v148
	ds_read_b128 v[156:159], v148 offset:1024
	ds_read_b128 v[160:163], v148 offset:2048
	ds_read_b128 v[164:167], v148 offset:3072
	ds_read_b128 v[168:171], v149
	ds_read_b128 v[172:175], v149 offset:1024
	ds_read_b128 v[176:179], v149 offset:2048
	ds_read_b128 v[180:183], v149 offset:3072
	s_add_i32 s69, s26, 2
	s_add_u32 s27, s24, 0xfff50080
	s_addc_u32 s28, s25, -1
	s_cmp_eq_u32 s51, s26
	s_cselect_b32 s26, s22, s67
	s_cselect_b32 s29, s21, s28
	s_cselect_b32 s28, s20, s27
	s_cselect_b32 s27, s23, s68
	s_add_i32 m0, s42, 0xc000
	ds_read_b128 v[184:187], v150
	ds_read_b128 v[190:193], v150 offset:1024
	ds_read_b128 v[194:197], v150 offset:2048
	ds_read_b128 v[198:201], v150 offset:3072
	ds_read_b128 v[202:205], v150 offset:4096
	ds_read_b128 v[206:209], v150 offset:5120
	ds_read_b128 v[210:213], v150 offset:6144
	global_load_lds_dwordx4 v132, s[24:25]
	s_add_i32 m0, s42, 0xe000
	ds_read_b128 v[214:217], v150 offset:7168
	global_load_lds_dwordx4 v136, s[24:25]
	s_waitcnt vmcnt(8) lgkmcnt(0)
	s_barrier
	s_setprio 1
	v_mfma_f32_16x16x32_bf16 v[124:127], v[152:155], v[184:187], v[124:127]
	v_mfma_f32_16x16x32_bf16 v[120:123], v[160:163], v[184:187], v[120:123]
	v_mfma_f32_16x16x32_bf16 v[108:111], v[152:155], v[194:197], v[108:111]
	v_mfma_f32_16x16x32_bf16 v[104:107], v[160:163], v[194:197], v[104:107]
	v_mfma_f32_16x16x32_bf16 v[92:95], v[152:155], v[202:205], v[92:95]
	v_mfma_f32_16x16x32_bf16 v[88:91], v[160:163], v[202:205], v[88:91]
	v_mfma_f32_16x16x32_bf16 v[76:79], v[152:155], v[210:213], v[76:79]
	v_mfma_f32_16x16x32_bf16 v[72:75], v[160:163], v[210:213], v[72:75]
	v_mfma_f32_16x16x32_bf16 v[124:127], v[156:159], v[190:193], v[124:127]
	v_mfma_f32_16x16x32_bf16 v[120:123], v[164:167], v[190:193], v[120:123]
	v_mfma_f32_16x16x32_bf16 v[108:111], v[156:159], v[198:201], v[108:111]
	v_mfma_f32_16x16x32_bf16 v[104:107], v[164:167], v[198:201], v[104:107]
	v_mfma_f32_16x16x32_bf16 v[92:95], v[156:159], v[206:209], v[92:95]
	v_mfma_f32_16x16x32_bf16 v[88:91], v[164:167], v[206:209], v[88:91]
	v_mfma_f32_16x16x32_bf16 v[76:79], v[156:159], v[214:217], v[76:79]
	v_mfma_f32_16x16x32_bf16 v[72:75], v[164:167], v[214:217], v[72:75]
	v_mfma_f32_16x16x32_bf16 v[116:119], v[168:171], v[184:187], v[116:119]
	v_mfma_f32_16x16x32_bf16 v[112:115], v[176:179], v[184:187], v[112:115]
	v_mfma_f32_16x16x32_bf16 v[100:103], v[168:171], v[194:197], v[100:103]
	v_mfma_f32_16x16x32_bf16 v[96:99], v[176:179], v[194:197], v[96:99]
	v_mfma_f32_16x16x32_bf16 v[84:87], v[168:171], v[202:205], v[84:87]
	v_mfma_f32_16x16x32_bf16 v[80:83], v[176:179], v[202:205], v[80:83]
	v_mfma_f32_16x16x32_bf16 v[68:71], v[168:171], v[210:213], v[68:71]
	v_mfma_f32_16x16x32_bf16 v[64:67], v[176:179], v[210:213], v[64:67]
	v_mfma_f32_16x16x32_bf16 v[116:119], v[172:175], v[190:193], v[116:119]
	v_mfma_f32_16x16x32_bf16 v[112:115], v[180:183], v[190:193], v[112:115]
	v_mfma_f32_16x16x32_bf16 v[100:103], v[172:175], v[198:201], v[100:103]
	v_mfma_f32_16x16x32_bf16 v[96:99], v[180:183], v[198:201], v[96:99]
	v_mfma_f32_16x16x32_bf16 v[84:87], v[172:175], v[206:209], v[84:87]
	v_mfma_f32_16x16x32_bf16 v[80:83], v[180:183], v[206:209], v[80:83]
	v_mfma_f32_16x16x32_bf16 v[68:71], v[172:175], v[214:217], v[68:71]
	v_mfma_f32_16x16x32_bf16 v[64:67], v[180:183], v[214:217], v[64:67]
	s_setprio 0
	s_barrier
	s_add_i32 s70, s54, s41
	s_mov_b32 m0, s70
	ds_read_b128 v[184:187], v150 offset:16384
	ds_read_b128 v[190:193], v150 offset:17408
	ds_read_b128 v[194:197], v150 offset:18432
	ds_read_b128 v[198:201], v150 offset:19456
	global_load_lds_dwordx4 v128, s[26:27]
	s_add_i32 m0, s70, 0x2000
	s_add_u32 s70, s26, 0xb0000
	s_addc_u32 s71, s27, 0
	s_add_i32 s72, s55, s41
	global_load_lds_dwordx4 v130, s[26:27]
	s_mov_b32 m0, s72
	ds_read_b128 v[214:217], v150 offset:23552
	global_load_lds_dwordx4 v128, s[70:71]
	s_add_i32 m0, s72, 0x2000
	ds_read_b128 v[210:213], v150 offset:22528
	global_load_lds_dwordx4 v130, s[70:71]
	s_mov_b32 m0, s42
	ds_read_b128 v[206:209], v150 offset:21504
	global_load_lds_dwordx4 v128, s[28:29]
	s_mov_b32 m0, s43
	ds_read_b128 v[202:205], v150 offset:20480
	global_load_lds_dwordx4 v130, s[28:29]
	s_waitcnt vmcnt(8) lgkmcnt(0)
	s_barrier
	s_setprio 1
	v_mfma_f32_16x16x32_bf16 v[60:63], v[152:155], v[184:187], v[60:63]
	v_mfma_f32_16x16x32_bf16 v[56:59], v[160:163], v[184:187], v[56:59]
	v_mfma_f32_16x16x32_bf16 v[44:47], v[152:155], v[194:197], v[44:47]
	v_mfma_f32_16x16x32_bf16 v[40:43], v[160:163], v[194:197], v[40:43]
	v_mfma_f32_16x16x32_bf16 v[28:31], v[152:155], v[202:205], v[28:31]
	v_mfma_f32_16x16x32_bf16 v[24:27], v[160:163], v[202:205], v[24:27]
	v_mfma_f32_16x16x32_bf16 v[12:15], v[152:155], v[210:213], v[12:15]
	v_mfma_f32_16x16x32_bf16 v[8:11], v[160:163], v[210:213], v[8:11]
	v_mfma_f32_16x16x32_bf16 v[60:63], v[156:159], v[190:193], v[60:63]
	v_mfma_f32_16x16x32_bf16 v[56:59], v[164:167], v[190:193], v[56:59]
	v_mfma_f32_16x16x32_bf16 v[44:47], v[156:159], v[198:201], v[44:47]
	v_mfma_f32_16x16x32_bf16 v[40:43], v[164:167], v[198:201], v[40:43]
	v_mfma_f32_16x16x32_bf16 v[28:31], v[156:159], v[206:209], v[28:31]
	v_mfma_f32_16x16x32_bf16 v[24:27], v[164:167], v[206:209], v[24:27]
	v_mfma_f32_16x16x32_bf16 v[12:15], v[156:159], v[214:217], v[12:15]
	v_mfma_f32_16x16x32_bf16 v[8:11], v[164:167], v[214:217], v[8:11]
	v_mfma_f32_16x16x32_bf16 v[52:55], v[168:171], v[184:187], v[52:55]
	v_mfma_f32_16x16x32_bf16 v[48:51], v[176:179], v[184:187], v[48:51]
	v_mfma_f32_16x16x32_bf16 v[36:39], v[168:171], v[194:197], v[36:39]
	v_mfma_f32_16x16x32_bf16 v[32:35], v[176:179], v[194:197], v[32:35]
	v_mfma_f32_16x16x32_bf16 v[20:23], v[168:171], v[202:205], v[20:23]
	v_mfma_f32_16x16x32_bf16 v[16:19], v[176:179], v[202:205], v[16:19]
	v_mfma_f32_16x16x32_bf16 v[4:7], v[168:171], v[210:213], v[4:7]
	v_mfma_f32_16x16x32_bf16 v[0:3], v[176:179], v[210:213], v[0:3]
	v_mfma_f32_16x16x32_bf16 v[52:55], v[172:175], v[190:193], v[52:55]
	v_mfma_f32_16x16x32_bf16 v[48:51], v[180:183], v[190:193], v[48:51]
	v_mfma_f32_16x16x32_bf16 v[36:39], v[172:175], v[198:201], v[36:39]
	v_mfma_f32_16x16x32_bf16 v[32:35], v[180:183], v[198:201], v[32:35]
	v_mfma_f32_16x16x32_bf16 v[20:23], v[172:175], v[206:209], v[20:23]
	v_mfma_f32_16x16x32_bf16 v[16:19], v[180:183], v[206:209], v[16:19]
	v_mfma_f32_16x16x32_bf16 v[4:7], v[172:175], v[214:217], v[4:7]
	v_mfma_f32_16x16x32_bf16 v[0:3], v[180:183], v[214:217], v[0:3]
	s_setprio 0
	s_barrier
; #define PG8_STAGE(bufoff, gbase, voff) do { _Pragma("unroll") for (int _i = 0; _i < 2; ++_i) \
;         __builtin_amdgcn_global_load_lds((const unsigned*)((const char*)(gbase) + (voff)[_i]), (PG8_LAS unsigned*)(lds + (bufoff) + ldsw + _i * 8192), 16, 0, 0); } while (0)
; #define PG8_LDA(dst, b, h) do { _Pragma("unroll") for (int m = 0; m < 4; ++m) _Pragma("unroll") for (int k = 0; k < 2; ++k) dst[m][k] = *(const PG8_LAS bf16x8*)(lds + PG8_SA(b, h) + aoff + m * 2048 + k * 1024); } while (0)
; #define PG8_LDB(dst, b, h) do { _Pragma("unroll") for (int n = 0; n < 2; ++n) _Pragma("unroll") for (int k = 0; k < 2; ++k) dst[n][k] = *(const PG8_LAS bf16x8*)(lds + PG8_SB(b, h) + boff + n * 2048 + k * 1024); } while (0)
; #define PG8_MMA(ai, bj, At, Bt) do { __builtin_amdgcn_s_setprio(1); _Pragma("unroll") for (int m = 0; m < 4; ++m) _Pragma("unroll") for (int n = 0; n < 2; ++n) _Pragma("unroll") for (int k = 0; k < 2; ++k) \
;         acc[ai][bj][m][n] = __builtin_amdgcn_mfma_f32_16x16x32_bf16(Bt[n][k], At[m][k], acc[ai][bj][m][n], 0, 0, 0); __builtin_amdgcn_s_setprio(0); } while (0)
; #define PG8_WAIT_V(n) asm volatile("s_waitcnt vmcnt(" #n ")" ::: "memory")
; #define PG8_WAIT_L(n) asm volatile("s_waitcnt lgkmcnt(" #n ")" ::: "memory")
; #define PG8_BAR __builtin_amdgcn_s_barrier()
; template <class Epi, class Sched, bool ALIGN_EPI = false, bool SP2 = false>
; __device__ __forceinline__ void gemm_phase(PG8_LAS unsigned char* lds, const Gemm g, const Sched& S, const Epi& E) {
;     ...
;         for (int t = 0; t < nt; t += 2) {
;             const bool last = (t == nt - 2);
;             const char* a1 = cA + (size_t)(t + 1) * kstep;
;             const char* a2 = last ? nA : cA + (size_t)(t + 2) * kstep; const char* b2 = last ? nB : cB + (size_t)(t + 2) * kstep;
;             const char* a3 = a2 + kstep; const char* b3 = b2 + kstep;
;     ...
;             PG8_LDB(B0, 1, 0); PG8_LDB(B1, 1, 1); PG8_SCHED; PG8_LDA(At, 1, 0); PG8_STAGE(PG8_SA(0, 1), a2 + hstepA, voffA);
;             PG8_WAIT_V(8); PG8_WAIT_L(0); PG8_BAR; PG8_MMA(0, 0, At, B0); PG8_MMA(0, 1, At, B1); PG8_BAR; PG8_SCHED;
;             PG8_LDA(At, 1, 1); PG8_STAGE(PG8_SB(1, 0), b3, voffB); PG8_STAGE(PG8_SB(1, 1), b3 + hstep, voffB); PG8_STAGE(PG8_SA(1, 0), a3, voffA);
;             PG8_WAIT_V(8); PG8_WAIT_L(0); PG8_BAR; PG8_MMA(1, 0, At, B0); PG8_MMA(1, 1, At, B1); PG8_BAR; PG8_SCHED;
	s_add_i32 s70, 0, 0x18000
	v_add_u32_e32 v151, s70, v147
	s_add_i32 s71, 0, 0x1c000
	ds_read_b128 v[152:155], v151
	ds_read_b128 v[156:159], v151 offset:1024
	ds_read_b128 v[160:163], v151 offset:2048
	ds_read_b128 v[164:167], v151 offset:3072
	v_add_u32_e32 v151, s71, v147
	ds_read_b128 v[168:171], v151
	ds_read_b128 v[172:175], v151 offset:1024
	ds_read_b128 v[176:179], v151 offset:2048
	ds_read_b128 v[180:183], v151 offset:3072
	s_mov_b64 vcc, s[28:29]
	s_add_u32 s28, s28, 0xb0000
	s_addc_u32 s29, s29, 0
	s_mov_b32 m0, s44
	ds_read_b128 v[184:187], v150 offset:32768
	ds_read_b128 v[190:193], v150 offset:33792
	ds_read_b128 v[194:197], v150 offset:34816
	ds_read_b128 v[198:201], v150 offset:35840
	ds_read_b128 v[202:205], v150 offset:36864
	ds_read_b128 v[206:209], v150 offset:37888
	ds_read_b128 v[210:213], v150 offset:38912
	global_load_lds_dwordx4 v128, s[28:29]
	s_mov_b32 m0, s45
	ds_read_b128 v[214:217], v150 offset:39936
	global_load_lds_dwordx4 v130, s[28:29]
	s_waitcnt vmcnt(8) lgkmcnt(0)
	s_barrier
	s_setprio 1
	v_mfma_f32_16x16x32_bf16 v[124:127], v[152:155], v[184:187], v[124:127]
	v_mfma_f32_16x16x32_bf16 v[120:123], v[160:163], v[184:187], v[120:123]
	v_mfma_f32_16x16x32_bf16 v[108:111], v[152:155], v[194:197], v[108:111]
	v_mfma_f32_16x16x32_bf16 v[104:107], v[160:163], v[194:197], v[104:107]
	v_mfma_f32_16x16x32_bf16 v[92:95], v[152:155], v[202:205], v[92:95]
	v_mfma_f32_16x16x32_bf16 v[88:91], v[160:163], v[202:205], v[88:91]
	v_mfma_f32_16x16x32_bf16 v[76:79], v[152:155], v[210:213], v[76:79]
	v_mfma_f32_16x16x32_bf16 v[72:75], v[160:163], v[210:213], v[72:75]
	v_mfma_f32_16x16x32_bf16 v[124:127], v[156:159], v[190:193], v[124:127]
	v_mfma_f32_16x16x32_bf16 v[120:123], v[164:167], v[190:193], v[120:123]
	v_mfma_f32_16x16x32_bf16 v[108:111], v[156:159], v[198:201], v[108:111]
	v_mfma_f32_16x16x32_bf16 v[104:107], v[164:167], v[198:201], v[104:107]
	v_mfma_f32_16x16x32_bf16 v[92:95], v[156:159], v[206:209], v[92:95]
	v_mfma_f32_16x16x32_bf16 v[88:91], v[164:167], v[206:209], v[88:91]
	v_mfma_f32_16x16x32_bf16 v[76:79], v[156:159], v[214:217], v[76:79]
	v_mfma_f32_16x16x32_bf16 v[72:75], v[164:167], v[214:217], v[72:75]
	v_mfma_f32_16x16x32_bf16 v[116:119], v[168:171], v[184:187], v[116:119]
	v_mfma_f32_16x16x32_bf16 v[112:115], v[176:179], v[184:187], v[112:115]
	v_mfma_f32_16x16x32_bf16 v[100:103], v[168:171], v[194:197], v[100:103]
	v_mfma_f32_16x16x32_bf16 v[96:99], v[176:179], v[194:197], v[96:99]
	v_mfma_f32_16x16x32_bf16 v[84:87], v[168:171], v[202:205], v[84:87]
	v_mfma_f32_16x16x32_bf16 v[80:83], v[176:179], v[202:205], v[80:83]
	v_mfma_f32_16x16x32_bf16 v[68:71], v[168:171], v[210:213], v[68:71]
	v_mfma_f32_16x16x32_bf16 v[64:67], v[176:179], v[210:213], v[64:67]
	v_mfma_f32_16x16x32_bf16 v[116:119], v[172:175], v[190:193], v[116:119]
	v_mfma_f32_16x16x32_bf16 v[112:115], v[180:183], v[190:193], v[112:115]
	v_mfma_f32_16x16x32_bf16 v[100:103], v[172:175], v[198:201], v[100:103]
	v_mfma_f32_16x16x32_bf16 v[96:99], v[180:183], v[198:201], v[96:99]
	v_mfma_f32_16x16x32_bf16 v[84:87], v[172:175], v[206:209], v[84:87]
	v_mfma_f32_16x16x32_bf16 v[80:83], v[180:183], v[206:209], v[80:83]
	v_mfma_f32_16x16x32_bf16 v[68:71], v[172:175], v[214:217], v[68:71]
	v_mfma_f32_16x16x32_bf16 v[64:67], v[180:183], v[214:217], v[64:67]
	s_setprio 0
	s_barrier
	s_add_i32 s28, s70, s41
	s_add_i32 m0, s28, 0xffffff80
	ds_read_b128 v[184:187], v150 offset:49152
	ds_read_b128 v[190:193], v150 offset:50176
	ds_read_b128 v[194:197], v150 offset:51200
	ds_read_b128 v[198:201], v150 offset:52224
	global_load_lds_dwordx4 v128, s[26:27] offset:128
	s_add_i32 m0, s28, 0x1f80
	s_mov_b64 s[100:101], s[26:27]
	s_add_u32 s26, s26, 0xb0080
	s_addc_u32 s27, s27, 0
	s_add_i32 s28, s71, s41
	global_load_lds_dwordx4 v130, s[100:101] offset:128
	s_mov_b32 m0, s28
	ds_read_b128 v[214:217], v150 offset:56320
	global_load_lds_dwordx4 v128, s[26:27]
	s_add_i32 m0, s28, 0x2000
	ds_read_b128 v[210:213], v150 offset:55296
	global_load_lds_dwordx4 v130, s[26:27]
	s_add_i32 m0, s49, 0xffffff80
	ds_read_b128 v[206:209], v150 offset:54272
	global_load_lds_dwordx4 v128, vcc offset:128
	s_add_i32 m0, s50, 0xffffff80
	ds_read_b128 v[202:205], v150 offset:53248
	global_load_lds_dwordx4 v130, vcc offset:128
	s_waitcnt vmcnt(8) lgkmcnt(0)
	s_barrier
	s_setprio 1
	v_mfma_f32_16x16x32_bf16 v[60:63], v[152:155], v[184:187], v[60:63]
	v_mfma_f32_16x16x32_bf16 v[56:59], v[160:163], v[184:187], v[56:59]
	v_mfma_f32_16x16x32_bf16 v[44:47], v[152:155], v[194:197], v[44:47]
	v_mfma_f32_16x16x32_bf16 v[40:43], v[160:163], v[194:197], v[40:43]
	v_mfma_f32_16x16x32_bf16 v[28:31], v[152:155], v[202:205], v[28:31]
	v_mfma_f32_16x16x32_bf16 v[24:27], v[160:163], v[202:205], v[24:27]
	v_mfma_f32_16x16x32_bf16 v[12:15], v[152:155], v[210:213], v[12:15]
	v_mfma_f32_16x16x32_bf16 v[8:11], v[160:163], v[210:213], v[8:11]
	v_mfma_f32_16x16x32_bf16 v[60:63], v[156:159], v[190:193], v[60:63]
	v_mfma_f32_16x16x32_bf16 v[56:59], v[164:167], v[190:193], v[56:59]
	v_mfma_f32_16x16x32_bf16 v[44:47], v[156:159], v[198:201], v[44:47]
	v_mfma_f32_16x16x32_bf16 v[40:43], v[164:167], v[198:201], v[40:43]
	v_mfma_f32_16x16x32_bf16 v[28:31], v[156:159], v[206:209], v[28:31]
	v_mfma_f32_16x16x32_bf16 v[24:27], v[164:167], v[206:209], v[24:27]
	v_mfma_f32_16x16x32_bf16 v[12:15], v[156:159], v[214:217], v[12:15]
	v_mfma_f32_16x16x32_bf16 v[8:11], v[164:167], v[214:217], v[8:11]
	v_mfma_f32_16x16x32_bf16 v[52:55], v[168:171], v[184:187], v[52:55]
	v_mfma_f32_16x16x32_bf16 v[48:51], v[176:179], v[184:187], v[48:51]
	v_mfma_f32_16x16x32_bf16 v[36:39], v[168:171], v[194:197], v[36:39]
	v_mfma_f32_16x16x32_bf16 v[32:35], v[176:179], v[194:197], v[32:35]
	v_mfma_f32_16x16x32_bf16 v[20:23], v[168:171], v[202:205], v[20:23]
	v_mfma_f32_16x16x32_bf16 v[16:19], v[176:179], v[202:205], v[16:19]
	v_mfma_f32_16x16x32_bf16 v[4:7], v[168:171], v[210:213], v[4:7]
	v_mfma_f32_16x16x32_bf16 v[0:3], v[176:179], v[210:213], v[0:3]
	v_mfma_f32_16x16x32_bf16 v[52:55], v[172:175], v[190:193], v[52:55]
	v_mfma_f32_16x16x32_bf16 v[48:51], v[180:183], v[190:193], v[48:51]
	v_mfma_f32_16x16x32_bf16 v[36:39], v[172:175], v[198:201], v[36:39]
	v_mfma_f32_16x16x32_bf16 v[32:35], v[180:183], v[198:201], v[32:35]
	v_mfma_f32_16x16x32_bf16 v[20:23], v[172:175], v[206:209], v[20:23]
	v_mfma_f32_16x16x32_bf16 v[16:19], v[180:183], v[206:209], v[16:19]
	v_mfma_f32_16x16x32_bf16 v[4:7], v[172:175], v[214:217], v[4:7]
	v_mfma_f32_16x16x32_bf16 v[0:3], v[180:183], v[214:217], v[0:3]
	s_setprio 0
	s_barrier
	s_add_u32 s24, s24, 0x100
	s_addc_u32 s25, s25, 0
	s_add_u32 s67, s67, 0x100
	s_addc_u32 s68, s68, 0
	s_cmp_ge_i32 s69, s48
	s_mov_b32 s26, s69
	s_cbranch_scc0 .LBB0_1068

; #define PG8_STAGE(bufoff, gbase, voff) do { _Pragma("unroll") for (int _i = 0; _i < 2; ++_i) \
;         __builtin_amdgcn_global_load_lds((const unsigned*)((const char*)(gbase) + (voff)[_i]), (PG8_LAS unsigned*)(lds + (bufoff) + ldsw + _i * 8192), 16, 0, 0); } while (0)
; #define PG8_LDA(dst, b, h) do { _Pragma("unroll") for (int m = 0; m < 4; ++m) _Pragma("unroll") for (int k = 0; k < 2; ++k) dst[m][k] = *(const PG8_LAS bf16x8*)(lds + PG8_SA(b, h) + aoff + m * 2048 + k * 1024); } while (0)
; #define PG8_LDB(dst, b, h) do { _Pragma("unroll") for (int n = 0; n < 2; ++n) _Pragma("unroll") for (int k = 0; k < 2; ++k) dst[n][k] = *(const PG8_LAS bf16x8*)(lds + PG8_SB(b, h) + boff + n * 2048 + k * 1024); } while (0)
; #define PG8_MMA(ai, bj, At, Bt) do { __builtin_amdgcn_s_setprio(1); _Pragma("unroll") for (int m = 0; m < 4; ++m) _Pragma("unroll") for (int n = 0; n < 2; ++n) _Pragma("unroll") for (int k = 0; k < 2; ++k) \
;         acc[ai][bj][m][n] = __builtin_amdgcn_mfma_f32_16x16x32_bf16(Bt[n][k], At[m][k], acc[ai][bj][m][n], 0, 0, 0); __builtin_amdgcn_s_setprio(0); } while (0)
; #define PG8_WAIT_V(n) asm volatile("s_waitcnt vmcnt(" #n ")" ::: "memory")
; #define PG8_WAIT_L(n) asm volatile("s_waitcnt lgkmcnt(" #n ")" ::: "memory")
; #define PG8_BAR __builtin_amdgcn_s_barrier()
; #define PG8_SCHED __builtin_amdgcn_sched_barrier(0)
; template <class Epi, class Sched, bool ALIGN_EPI = false, bool SP2 = false>
; __device__ __forceinline__ void gemm_phase(PG8_LAS unsigned char* lds, const Gemm g, const Sched& S, const Epi& E) {
;     ...
;             const char* a1 = cA + (size_t)(t + 1) * kstep;
;             const char* a2 = last ? nA : cA + (size_t)(t + 2) * kstep; const char* b2 = last ? nB : cB + (size_t)(t + 2) * kstep;
;             const char* a3 = a2 + kstep; const char* b3 = b2 + kstep;
;             if (last && has_next) S.a_ready(nxt);
;             if constexpr (SP2) {
;             PG8_LDB(B0, 0, 0); PG8_LDB(B1, 0, 1); PG8_SCHED; PG8_LDA(At, 0, 0); PG8_STAGE(PG8_SA(1, 1), a1 + hstepA, voffA);
;             PG8_WAIT_V(8); PG8_WAIT_L(0); PG8_BAR; PG8_MMA(0, 0, At, B0); PG8_MMA(0, 1, At, B1); PG8_BAR; PG8_SCHED;
;             PG8_LDA(At, 0, 1); PG8_STAGE(PG8_SB(0, 0), b2, voffB); PG8_STAGE(PG8_SB(0, 1), b2 + hstep, voffB); PG8_STAGE(PG8_SA(0, 0), a2, voffA);
.LBB0_1098:
	ds_read_b128 v[148:151], v138
	ds_read_b128 v[152:155], v138 offset:1024
	ds_read_b128 v[156:159], v138 offset:2048
	ds_read_b128 v[160:163], v138 offset:3072
	ds_read_b128 v[164:167], v139
	ds_read_b128 v[168:171], v139 offset:1024
	ds_read_b128 v[172:175], v139 offset:2048
	ds_read_b128 v[176:179], v139 offset:3072
	s_add_i32 s65, s26, 2
	s_add_u32 s27, s24, 0xfff50080
	s_addc_u32 s28, s25, -1
	s_cmp_eq_u32 s30, s26
	s_cselect_b32 s26, s6, s63
	s_cselect_b32 s29, s23, s28
	s_cselect_b32 s28, s22, s27
	s_cselect_b32 s27, s7, s64
	v_lshl_add_u64 v[144:145], s[24:25], 0, v[136:137]
	s_add_i32 m0, s39, 0xc000
	ds_read_b128 v[180:183], v140
	ds_read_b128 v[184:187], v140 offset:1024
	ds_read_b128 v[190:193], v140 offset:2048
	ds_read_b128 v[194:197], v140 offset:3072
	ds_read_b128 v[198:201], v140 offset:4096
	ds_read_b128 v[202:205], v140 offset:5120
	ds_read_b128 v[206:209], v140 offset:6144
	ds_read_b128 v[210:213], v140 offset:7168
	global_load_lds_dwordx4 v[144:145], off
	v_lshl_add_u64 v[144:145], s[24:25], 0, v[132:133]
	s_add_i32 m0, s39, 0xe000
	s_nop 0
	global_load_lds_dwordx4 v[144:145], off
	s_waitcnt vmcnt(8) lgkmcnt(0)
	s_barrier
	s_setprio 1
	s_waitcnt lgkmcnt(0)
	v_mfma_f32_16x16x32_bf16 v[124:127], v[148:151], v[180:183], v[124:127]
	v_mfma_f32_16x16x32_bf16 v[120:123], v[156:159], v[180:183], v[120:123]
	v_mfma_f32_16x16x32_bf16 v[108:111], v[148:151], v[190:193], v[108:111]
	v_mfma_f32_16x16x32_bf16 v[104:107], v[156:159], v[190:193], v[104:107]
	v_mfma_f32_16x16x32_bf16 v[92:95], v[148:151], v[198:201], v[92:95]
	v_mfma_f32_16x16x32_bf16 v[88:91], v[156:159], v[198:201], v[88:91]
	v_mfma_f32_16x16x32_bf16 v[76:79], v[148:151], v[206:209], v[76:79]
	v_mfma_f32_16x16x32_bf16 v[72:75], v[156:159], v[206:209], v[72:75]
	v_mfma_f32_16x16x32_bf16 v[124:127], v[152:155], v[184:187], v[124:127]
	v_mfma_f32_16x16x32_bf16 v[120:123], v[160:163], v[184:187], v[120:123]
	v_mfma_f32_16x16x32_bf16 v[108:111], v[152:155], v[194:197], v[108:111]
	v_mfma_f32_16x16x32_bf16 v[104:107], v[160:163], v[194:197], v[104:107]
	v_mfma_f32_16x16x32_bf16 v[92:95], v[152:155], v[202:205], v[92:95]
	v_mfma_f32_16x16x32_bf16 v[88:91], v[160:163], v[202:205], v[88:91]
	v_mfma_f32_16x16x32_bf16 v[76:79], v[152:155], v[210:213], v[76:79]
	v_mfma_f32_16x16x32_bf16 v[72:75], v[160:163], v[210:213], v[72:75]
	s_setprio 0
	s_setprio 1
	v_mfma_f32_16x16x32_bf16 v[116:119], v[164:167], v[180:183], v[116:119]
	v_mfma_f32_16x16x32_bf16 v[112:115], v[172:175], v[180:183], v[112:115]
	v_mfma_f32_16x16x32_bf16 v[100:103], v[164:167], v[190:193], v[100:103]
	v_mfma_f32_16x16x32_bf16 v[96:99], v[172:175], v[190:193], v[96:99]
	v_mfma_f32_16x16x32_bf16 v[84:87], v[164:167], v[198:201], v[84:87]
	v_mfma_f32_16x16x32_bf16 v[80:83], v[172:175], v[198:201], v[80:83]
	v_mfma_f32_16x16x32_bf16 v[68:71], v[164:167], v[206:209], v[68:71]
	v_mfma_f32_16x16x32_bf16 v[64:67], v[172:175], v[206:209], v[64:67]
	v_mfma_f32_16x16x32_bf16 v[116:119], v[168:171], v[184:187], v[116:119]
	v_mfma_f32_16x16x32_bf16 v[112:115], v[176:179], v[184:187], v[112:115]
	v_mfma_f32_16x16x32_bf16 v[100:103], v[168:171], v[194:197], v[100:103]
	v_mfma_f32_16x16x32_bf16 v[96:99], v[176:179], v[194:197], v[96:99]
	v_mfma_f32_16x16x32_bf16 v[84:87], v[168:171], v[202:205], v[84:87]
	v_mfma_f32_16x16x32_bf16 v[80:83], v[176:179], v[202:205], v[80:83]
	v_mfma_f32_16x16x32_bf16 v[68:71], v[168:171], v[210:213], v[68:71]
	v_mfma_f32_16x16x32_bf16 v[64:67], v[176:179], v[210:213], v[64:67]
	s_setprio 0
	s_barrier
	s_add_i32 s66, s48, s38
	v_lshl_add_u64 v[144:145], s[26:27], 0, v[128:129]
	s_mov_b32 m0, s66
	ds_read_b128 v[180:183], v140 offset:16384
	ds_read_b128 v[184:187], v140 offset:17408
	ds_read_b128 v[190:193], v140 offset:18432
	ds_read_b128 v[194:197], v140 offset:19456
	ds_read_b128 v[198:201], v140 offset:20480
	ds_read_b128 v[202:205], v140 offset:21504
	ds_read_b128 v[206:209], v140 offset:22528
	ds_read_b128 v[210:213], v140 offset:23552
	global_load_lds_dwordx4 v[144:145], off
	s_add_i32 m0, s66, 0x2000
	s_add_u32 s66, s26, 0xb0000
	v_lshl_add_u64 v[214:215], s[26:27], 0, v[130:131]
	s_addc_u32 s67, s27, 0
	s_add_i32 s68, s49, s38
	global_load_lds_dwordx4 v[214:215], off
	v_lshl_add_u64 v[216:217], s[66:67], 0, v[128:129]
	s_mov_b32 m0, s68
	v_lshl_add_u64 v[218:219], s[28:29], 0, v[130:131]
	global_load_lds_dwordx4 v[216:217], off
	v_lshl_add_u64 v[216:217], s[66:67], 0, v[130:131]
	s_add_i32 m0, s68, 0x2000
	s_nop 0
	global_load_lds_dwordx4 v[216:217], off
	v_lshl_add_u64 v[216:217], s[28:29], 0, v[128:129]
	s_mov_b32 m0, s39
	s_nop 0
	global_load_lds_dwordx4 v[216:217], off
	s_mov_b32 m0, s40
	s_nop 0
	global_load_lds_dwordx4 v[218:219], off
	s_waitcnt vmcnt(8) lgkmcnt(0)
	s_barrier
; #define PG8_STAGE(bufoff, gbase, voff) do { _Pragma("unroll") for (int _i = 0; _i < 2; ++_i) \
;         __builtin_amdgcn_global_load_lds((const unsigned*)((const char*)(gbase) + (voff)[_i]), (PG8_LAS unsigned*)(lds + (bufoff) + ldsw + _i * 8192), 16, 0, 0); } while (0)
; #define PG8_LDA(dst, b, h) do { _Pragma("unroll") for (int m = 0; m < 4; ++m) _Pragma("unroll") for (int k = 0; k < 2; ++k) dst[m][k] = *(const PG8_LAS bf16x8*)(lds + PG8_SA(b, h) + aoff + m * 2048 + k * 1024); } while (0)
; #define PG8_LDB(dst, b, h) do { _Pragma("unroll") for (int n = 0; n < 2; ++n) _Pragma("unroll") for (int k = 0; k < 2; ++k) dst[n][k] = *(const PG8_LAS bf16x8*)(lds + PG8_SB(b, h) + boff + n * 2048 + k * 1024); } while (0)
; #define PG8_MMA(ai, bj, At, Bt) do { __builtin_amdgcn_s_setprio(1); _Pragma("unroll") for (int m = 0; m < 4; ++m) _Pragma("unroll") for (int n = 0; n < 2; ++n) _Pragma("unroll") for (int k = 0; k < 2; ++k) \
;         acc[ai][bj][m][n] = __builtin_amdgcn_mfma_f32_16x16x32_bf16(Bt[n][k], At[m][k], acc[ai][bj][m][n], 0, 0, 0); __builtin_amdgcn_s_setprio(0); } while (0)
; #define PG8_WAIT_V(n) asm volatile("s_waitcnt vmcnt(" #n ")" ::: "memory")
; #define PG8_WAIT_L(n) asm volatile("s_waitcnt lgkmcnt(" #n ")" ::: "memory")
; #define PG8_BAR __builtin_amdgcn_s_barrier()
; #define PG8_SCHED __builtin_amdgcn_sched_barrier(0)
; template <class Epi, class Sched, bool ALIGN_EPI = false, bool SP2 = false>
; __device__ __forceinline__ void gemm_phase(PG8_LAS unsigned char* lds, const Gemm g, const Sched& S, const Epi& E) {
;     ...
;             PG8_WAIT_V(8); PG8_WAIT_L(0); PG8_BAR; PG8_MMA(1, 0, At, B0); PG8_MMA(1, 1, At, B1); PG8_BAR; PG8_SCHED;
;             PG8_LDB(B0, 1, 0); PG8_LDB(B1, 1, 1); PG8_SCHED; PG8_LDA(At, 1, 0); PG8_STAGE(PG8_SA(0, 1), a2 + hstepA, voffA);
;             PG8_WAIT_V(8); PG8_WAIT_L(0); PG8_BAR; PG8_MMA(0, 0, At, B0); PG8_MMA(0, 1, At, B1); PG8_BAR; PG8_SCHED;
;             PG8_LDA(At, 1, 1); PG8_STAGE(PG8_SB(1, 0), b3, voffB); PG8_STAGE(PG8_SB(1, 1), b3 + hstep, voffB); PG8_STAGE(PG8_SA(1, 0), a3, voffA);
	s_setprio 1
	s_waitcnt lgkmcnt(0)
	v_mfma_f32_16x16x32_bf16 v[60:63], v[148:151], v[180:183], v[60:63]
	v_mfma_f32_16x16x32_bf16 v[56:59], v[156:159], v[180:183], v[56:59]
	v_mfma_f32_16x16x32_bf16 v[44:47], v[148:151], v[190:193], v[44:47]
	v_mfma_f32_16x16x32_bf16 v[40:43], v[156:159], v[190:193], v[40:43]
	v_mfma_f32_16x16x32_bf16 v[28:31], v[148:151], v[198:201], v[28:31]
	v_mfma_f32_16x16x32_bf16 v[24:27], v[156:159], v[198:201], v[24:27]
	v_mfma_f32_16x16x32_bf16 v[12:15], v[148:151], v[206:209], v[12:15]
	v_mfma_f32_16x16x32_bf16 v[8:11], v[156:159], v[206:209], v[8:11]
	v_mfma_f32_16x16x32_bf16 v[60:63], v[152:155], v[184:187], v[60:63]
	v_mfma_f32_16x16x32_bf16 v[56:59], v[160:163], v[184:187], v[56:59]
	v_mfma_f32_16x16x32_bf16 v[44:47], v[152:155], v[194:197], v[44:47]
	v_mfma_f32_16x16x32_bf16 v[40:43], v[160:163], v[194:197], v[40:43]
	v_mfma_f32_16x16x32_bf16 v[28:31], v[152:155], v[202:205], v[28:31]
	v_mfma_f32_16x16x32_bf16 v[24:27], v[160:163], v[202:205], v[24:27]
	v_mfma_f32_16x16x32_bf16 v[12:15], v[152:155], v[210:213], v[12:15]
	v_mfma_f32_16x16x32_bf16 v[8:11], v[160:163], v[210:213], v[8:11]
	s_setprio 0
	s_setprio 1
	v_mfma_f32_16x16x32_bf16 v[52:55], v[164:167], v[180:183], v[52:55]
	v_mfma_f32_16x16x32_bf16 v[48:51], v[172:175], v[180:183], v[48:51]
	v_mfma_f32_16x16x32_bf16 v[36:39], v[164:167], v[190:193], v[36:39]
	v_mfma_f32_16x16x32_bf16 v[32:35], v[172:175], v[190:193], v[32:35]
	v_mfma_f32_16x16x32_bf16 v[20:23], v[164:167], v[198:201], v[20:23]
	v_mfma_f32_16x16x32_bf16 v[16:19], v[172:175], v[198:201], v[16:19]
	v_mfma_f32_16x16x32_bf16 v[4:7], v[164:167], v[206:209], v[4:7]
	v_mfma_f32_16x16x32_bf16 v[0:3], v[172:175], v[206:209], v[0:3]
	v_mfma_f32_16x16x32_bf16 v[52:55], v[168:171], v[184:187], v[52:55]
	v_mfma_f32_16x16x32_bf16 v[48:51], v[176:179], v[184:187], v[48:51]
	v_mfma_f32_16x16x32_bf16 v[36:39], v[168:171], v[194:197], v[36:39]
	v_mfma_f32_16x16x32_bf16 v[32:35], v[176:179], v[194:197], v[32:35]
	v_mfma_f32_16x16x32_bf16 v[20:23], v[168:171], v[202:205], v[20:23]
	v_mfma_f32_16x16x32_bf16 v[16:19], v[176:179], v[202:205], v[16:19]
	v_mfma_f32_16x16x32_bf16 v[4:7], v[168:171], v[210:213], v[4:7]
	v_mfma_f32_16x16x32_bf16 v[0:3], v[176:179], v[210:213], v[0:3]
	s_setprio 0
	s_barrier
	s_add_i32 s66, 0, 0x18000
	v_add_u32_e32 v141, s66, v143
	s_add_i32 s67, 0, 0x1c000
	ds_read_b128 v[148:151], v141
	ds_read_b128 v[152:155], v141 offset:1024
	ds_read_b128 v[156:159], v141 offset:2048
	ds_read_b128 v[160:163], v141 offset:3072
	v_add_u32_e32 v141, s67, v143
	ds_read_b128 v[164:167], v141
	ds_read_b128 v[168:171], v141 offset:1024
	ds_read_b128 v[172:175], v141 offset:2048
	ds_read_b128 v[176:179], v141 offset:3072
	s_add_u32 s28, s28, 0xb0000
	s_addc_u32 s29, s29, 0
	s_mov_b32 m0, s41
	v_lshl_add_u64 v[220:221], s[28:29], 0, v[128:129]
	ds_read_b128 v[180:183], v140 offset:32768
	ds_read_b128 v[184:187], v140 offset:33792
	ds_read_b128 v[190:193], v140 offset:34816
	ds_read_b128 v[194:197], v140 offset:35840
	ds_read_b128 v[198:201], v140 offset:36864
	ds_read_b128 v[202:205], v140 offset:37888
	ds_read_b128 v[206:209], v140 offset:38912
	ds_read_b128 v[210:213], v140 offset:39936
	global_load_lds_dwordx4 v[220:221], off
	v_lshl_add_u64 v[220:221], s[28:29], 0, v[130:131]
	s_mov_b32 m0, s42
	s_nop 0
	global_load_lds_dwordx4 v[220:221], off
	s_waitcnt vmcnt(8) lgkmcnt(0)
	s_barrier
	s_setprio 1
	s_waitcnt lgkmcnt(0)
	v_mfma_f32_16x16x32_bf16 v[124:127], v[148:151], v[180:183], v[124:127]
	v_mfma_f32_16x16x32_bf16 v[120:123], v[156:159], v[180:183], v[120:123]
	v_mfma_f32_16x16x32_bf16 v[108:111], v[148:151], v[190:193], v[108:111]
	v_mfma_f32_16x16x32_bf16 v[104:107], v[156:159], v[190:193], v[104:107]
	v_mfma_f32_16x16x32_bf16 v[92:95], v[148:151], v[198:201], v[92:95]
	v_mfma_f32_16x16x32_bf16 v[88:91], v[156:159], v[198:201], v[88:91]
	v_mfma_f32_16x16x32_bf16 v[76:79], v[148:151], v[206:209], v[76:79]
	v_mfma_f32_16x16x32_bf16 v[72:75], v[156:159], v[206:209], v[72:75]
	v_mfma_f32_16x16x32_bf16 v[124:127], v[152:155], v[184:187], v[124:127]
	v_mfma_f32_16x16x32_bf16 v[120:123], v[160:163], v[184:187], v[120:123]
	v_mfma_f32_16x16x32_bf16 v[108:111], v[152:155], v[194:197], v[108:111]
	v_mfma_f32_16x16x32_bf16 v[104:107], v[160:163], v[194:197], v[104:107]
	v_mfma_f32_16x16x32_bf16 v[92:95], v[152:155], v[202:205], v[92:95]
	v_mfma_f32_16x16x32_bf16 v[88:91], v[160:163], v[202:205], v[88:91]
	v_mfma_f32_16x16x32_bf16 v[76:79], v[152:155], v[210:213], v[76:79]
	v_mfma_f32_16x16x32_bf16 v[72:75], v[160:163], v[210:213], v[72:75]
	s_setprio 0
	s_setprio 1
	v_mfma_f32_16x16x32_bf16 v[116:119], v[164:167], v[180:183], v[116:119]
	v_mfma_f32_16x16x32_bf16 v[112:115], v[172:175], v[180:183], v[112:115]
	v_mfma_f32_16x16x32_bf16 v[100:103], v[164:167], v[190:193], v[100:103]
	v_mfma_f32_16x16x32_bf16 v[96:99], v[172:175], v[190:193], v[96:99]
	v_mfma_f32_16x16x32_bf16 v[84:87], v[164:167], v[198:201], v[84:87]
	v_mfma_f32_16x16x32_bf16 v[80:83], v[172:175], v[198:201], v[80:83]
	v_mfma_f32_16x16x32_bf16 v[68:71], v[164:167], v[206:209], v[68:71]
	v_mfma_f32_16x16x32_bf16 v[64:67], v[172:175], v[206:209], v[64:67]
	v_mfma_f32_16x16x32_bf16 v[116:119], v[168:171], v[184:187], v[116:119]
	v_mfma_f32_16x16x32_bf16 v[112:115], v[176:179], v[184:187], v[112:115]
	v_mfma_f32_16x16x32_bf16 v[100:103], v[168:171], v[194:197], v[100:103]
	v_mfma_f32_16x16x32_bf16 v[96:99], v[176:179], v[194:197], v[96:99]
	v_mfma_f32_16x16x32_bf16 v[84:87], v[168:171], v[202:205], v[84:87]
	v_mfma_f32_16x16x32_bf16 v[80:83], v[176:179], v[202:205], v[80:83]
	v_mfma_f32_16x16x32_bf16 v[68:71], v[168:171], v[210:213], v[68:71]
	v_mfma_f32_16x16x32_bf16 v[64:67], v[176:179], v[210:213], v[64:67]
	s_setprio 0
	s_barrier
; #define PG8_STAGE(bufoff, gbase, voff) do { _Pragma("unroll") for (int _i = 0; _i < 2; ++_i) \
;         __builtin_amdgcn_global_load_lds((const unsigned*)((const char*)(gbase) + (voff)[_i]), (PG8_LAS unsigned*)(lds + (bufoff) + ldsw + _i * 8192), 16, 0, 0); } while (0)
; #define PG8_LDA(dst, b, h) do { _Pragma("unroll") for (int m = 0; m < 4; ++m) _Pragma("unroll") for (int k = 0; k < 2; ++k) dst[m][k] = *(const PG8_LAS bf16x8*)(lds + PG8_SA(b, h) + aoff + m * 2048 + k * 1024); } while (0)
; #define PG8_MMA(ai, bj, At, Bt) do { __builtin_amdgcn_s_setprio(1); _Pragma("unroll") for (int m = 0; m < 4; ++m) _Pragma("unroll") for (int n = 0; n < 2; ++n) _Pragma("unroll") for (int k = 0; k < 2; ++k) \
;         acc[ai][bj][m][n] = __builtin_amdgcn_mfma_f32_16x16x32_bf16(Bt[n][k], At[m][k], acc[ai][bj][m][n], 0, 0, 0); __builtin_amdgcn_s_setprio(0); } while (0)
; #define PG8_WAIT_V(n) asm volatile("s_waitcnt vmcnt(" #n ")" ::: "memory")
; #define PG8_WAIT_L(n) asm volatile("s_waitcnt lgkmcnt(" #n ")" ::: "memory")
; #define PG8_BAR __builtin_amdgcn_s_barrier()
; #define PG8_SCHED __builtin_amdgcn_sched_barrier(0)
; template <class Epi, class Sched, bool ALIGN_EPI = false, bool SP2 = false>
; __device__ __forceinline__ void gemm_phase(PG8_LAS unsigned char* lds, const Gemm g, const Sched& S, const Epi& E) {
;     ...
;         for (int t = 0; t < nt; t += 2) {
;     ...
;             PG8_LDA(At, 1, 1); PG8_STAGE(PG8_SB(1, 0), b3, voffB); PG8_STAGE(PG8_SB(1, 1), b3 + hstep, voffB); PG8_STAGE(PG8_SA(1, 0), a3, voffA);
;             PG8_WAIT_V(8); PG8_WAIT_L(0); PG8_BAR; PG8_MMA(1, 0, At, B0); PG8_MMA(1, 1, At, B1); PG8_BAR; PG8_SCHED;
	s_add_i32 s28, s66, s38
	v_lshl_add_u64 v[144:145], v[144:145], 0, s[14:15]
	s_mov_b32 m0, s28
	ds_read_b128 v[180:183], v140 offset:49152
	ds_read_b128 v[184:187], v140 offset:50176
	ds_read_b128 v[190:193], v140 offset:51200
	ds_read_b128 v[194:197], v140 offset:52224
	ds_read_b128 v[198:201], v140 offset:53248
	ds_read_b128 v[202:205], v140 offset:54272
	ds_read_b128 v[206:209], v140 offset:55296
	ds_read_b128 v[210:213], v140 offset:56320
	global_load_lds_dwordx4 v[144:145], off
	s_add_i32 m0, s28, 0x2000
	s_add_u32 s26, s26, 0xb0080
	v_lshl_add_u64 v[144:145], v[214:215], 0, s[14:15]
	s_addc_u32 s27, s27, 0
	s_add_i32 s28, s67, s38
	global_load_lds_dwordx4 v[144:145], off
	v_lshl_add_u64 v[144:145], s[26:27], 0, v[128:129]
	s_mov_b32 m0, s28
	s_nop 0
	global_load_lds_dwordx4 v[144:145], off
	v_lshl_add_u64 v[144:145], s[26:27], 0, v[130:131]
	s_add_i32 m0, s28, 0x2000
	s_nop 0
	global_load_lds_dwordx4 v[144:145], off
	v_lshl_add_u64 v[144:145], v[216:217], 0, s[14:15]
	s_mov_b32 m0, s45
	s_nop 0
	global_load_lds_dwordx4 v[144:145], off
	v_lshl_add_u64 v[144:145], v[218:219], 0, s[14:15]
	s_mov_b32 m0, s47
	s_nop 0
	global_load_lds_dwordx4 v[144:145], off
	s_waitcnt vmcnt(8) lgkmcnt(0)
	s_barrier
	s_setprio 1
	s_waitcnt lgkmcnt(0)
	v_mfma_f32_16x16x32_bf16 v[60:63], v[148:151], v[180:183], v[60:63]
	v_mfma_f32_16x16x32_bf16 v[56:59], v[156:159], v[180:183], v[56:59]
	v_mfma_f32_16x16x32_bf16 v[44:47], v[148:151], v[190:193], v[44:47]
	v_mfma_f32_16x16x32_bf16 v[40:43], v[156:159], v[190:193], v[40:43]
	v_mfma_f32_16x16x32_bf16 v[28:31], v[148:151], v[198:201], v[28:31]
	v_mfma_f32_16x16x32_bf16 v[24:27], v[156:159], v[198:201], v[24:27]
	v_mfma_f32_16x16x32_bf16 v[12:15], v[148:151], v[206:209], v[12:15]
	v_mfma_f32_16x16x32_bf16 v[8:11], v[156:159], v[206:209], v[8:11]
	v_mfma_f32_16x16x32_bf16 v[60:63], v[152:155], v[184:187], v[60:63]
	v_mfma_f32_16x16x32_bf16 v[56:59], v[160:163], v[184:187], v[56:59]
	v_mfma_f32_16x16x32_bf16 v[44:47], v[152:155], v[194:197], v[44:47]
	v_mfma_f32_16x16x32_bf16 v[40:43], v[160:163], v[194:197], v[40:43]
	v_mfma_f32_16x16x32_bf16 v[28:31], v[152:155], v[202:205], v[28:31]
	v_mfma_f32_16x16x32_bf16 v[24:27], v[160:163], v[202:205], v[24:27]
	v_mfma_f32_16x16x32_bf16 v[12:15], v[152:155], v[210:213], v[12:15]
	v_mfma_f32_16x16x32_bf16 v[8:11], v[160:163], v[210:213], v[8:11]
	s_setprio 0
	s_setprio 1
	v_mfma_f32_16x16x32_bf16 v[52:55], v[164:167], v[180:183], v[52:55]
	v_mfma_f32_16x16x32_bf16 v[48:51], v[172:175], v[180:183], v[48:51]
	v_mfma_f32_16x16x32_bf16 v[36:39], v[164:167], v[190:193], v[36:39]
	v_mfma_f32_16x16x32_bf16 v[32:35], v[172:175], v[190:193], v[32:35]
	v_mfma_f32_16x16x32_bf16 v[20:23], v[164:167], v[198:201], v[20:23]
	v_mfma_f32_16x16x32_bf16 v[16:19], v[172:175], v[198:201], v[16:19]
	v_mfma_f32_16x16x32_bf16 v[4:7], v[164:167], v[206:209], v[4:7]
	v_mfma_f32_16x16x32_bf16 v[0:3], v[172:175], v[206:209], v[0:3]
	v_mfma_f32_16x16x32_bf16 v[52:55], v[168:171], v[184:187], v[52:55]
	v_mfma_f32_16x16x32_bf16 v[48:51], v[176:179], v[184:187], v[48:51]
	v_mfma_f32_16x16x32_bf16 v[36:39], v[168:171], v[194:197], v[36:39]
	v_mfma_f32_16x16x32_bf16 v[32:35], v[176:179], v[194:197], v[32:35]
	v_mfma_f32_16x16x32_bf16 v[20:23], v[168:171], v[202:205], v[20:23]
	v_mfma_f32_16x16x32_bf16 v[16:19], v[176:179], v[202:205], v[16:19]
	v_mfma_f32_16x16x32_bf16 v[4:7], v[168:171], v[210:213], v[4:7]
	v_mfma_f32_16x16x32_bf16 v[0:3], v[176:179], v[210:213], v[0:3]
	s_setprio 0
	s_barrier
	s_add_u32 s63, s63, 0x100
	s_addc_u32 s64, s64, 0
	s_add_u32 s24, s24, 0x100
	s_addc_u32 s25, s25, 0
	s_cmp_lt_i32 s65, s44
	s_mov_b32 s26, s65
	s_cbranch_scc1 .LBB0_1098

; __device__ __forceinline__ unsigned xb_add(unsigned* p, unsigned v) { return __hip_atomic_fetch_add(p, v, __ATOMIC_RELAXED, __HIP_MEMORY_SCOPE_AGENT); }
; __device__ __forceinline__ void xcd_barrier(const XcdBarrier& b) {
;     ...
;             __builtin_amdgcn_fence(__ATOMIC_RELEASE, "agent");
;             asm volatile("s_waitcnt vmcnt(0)" ::: "memory");
;             const unsigned og = xb_add(&bar[XB_TOP], 1u);
;             const unsigned tg = og / nx;
;             if (og + 1u == (tg + 1u) * nx) xb_add(&bar[XB_TOPGEN], 1u);
.LBB0_1141:
	s_andn2_saveexec_b64 s[6:7], s[90:91]
	s_cbranch_execz .LBB0_1161
	s_mov_b64 s[6:7], exec
	buffer_wbl2 sc1
	s_waitcnt vmcnt(0) lgkmcnt(0)
	v_mbcnt_lo_u32_b32 v1, s6, 0
	v_mbcnt_hi_u32_b32 v1, s7, v1
	v_cmp_eq_u32_e32 vcc, 0, v1
	s_and_saveexec_b64 s[8:9], vcc
	s_cbranch_execz .LBB0_1144
	s_bcnt1_i32_b64 s6, s[6:7]
	v_mov_b32_e32 v2, 0
	v_mov_b32_e32 v3, s6
	global_atomic_add v2, v2, v3, s[48:49] sc0

; __device__ __forceinline__ unsigned xb_add(unsigned* p, unsigned v) { return __hip_atomic_fetch_add(p, v, __ATOMIC_RELAXED, __HIP_MEMORY_SCOPE_AGENT); }
; __device__ __forceinline__ void xcd_barrier(const XcdBarrier& b) {
;     ...
;             __builtin_amdgcn_fence(__ATOMIC_RELEASE, "agent");
;             asm volatile("s_waitcnt vmcnt(0)" ::: "memory");
;             const unsigned og = xb_add(&bar[XB_TOP], 1u);
;             const unsigned tg = og / nx;
;             if (og + 1u == (tg + 1u) * nx) xb_add(&bar[XB_TOPGEN], 1u);
.LBB0_1200:
	s_andn2_saveexec_b64 s[6:7], s[6:7]
	s_cbranch_execz .LBB0_1220
	s_mov_b64 s[6:7], exec
	buffer_wbl2 sc1
	s_waitcnt vmcnt(0) lgkmcnt(0)
	v_mbcnt_lo_u32_b32 v1, s6, 0
	v_mbcnt_hi_u32_b32 v1, s7, v1
	v_cmp_eq_u32_e32 vcc, 0, v1
	s_and_saveexec_b64 s[8:9], vcc
	s_cbranch_execz .LBB0_1203
	s_bcnt1_i32_b64 s3, s[6:7]
	v_mov_b32_e32 v2, 0
	v_mov_b32_e32 v3, s3
	global_atomic_add v2, v2, v3, s[48:49] sc0

; #define PG8_STAGE(bufoff, gbase, voff) do { _Pragma("unroll") for (int _i = 0; _i < 2; ++_i) \
;         __builtin_amdgcn_global_load_lds((const unsigned*)((const char*)(gbase) + (voff)[_i]), (PG8_LAS unsigned*)(lds + (bufoff) + ldsw + _i * 8192), 16, 0, 0); } while (0)
; #define PG8_LDA(dst, b, h) do { _Pragma("unroll") for (int m = 0; m < 4; ++m) _Pragma("unroll") for (int k = 0; k < 2; ++k) dst[m][k] = *(const PG8_LAS bf16x8*)(lds + PG8_SA(b, h) + aoff + m * 2048 + k * 1024); } while (0)
; #define PG8_LDB(dst, b, h) do { _Pragma("unroll") for (int n = 0; n < 2; ++n) _Pragma("unroll") for (int k = 0; k < 2; ++k) dst[n][k] = *(const PG8_LAS bf16x8*)(lds + PG8_SB(b, h) + boff + n * 2048 + k * 1024); } while (0)
; #define PG8_MMA(ai, bj, At, Bt) do { __builtin_amdgcn_s_setprio(1); _Pragma("unroll") for (int m = 0; m < 4; ++m) _Pragma("unroll") for (int n = 0; n < 2; ++n) _Pragma("unroll") for (int k = 0; k < 2; ++k) \
;         acc[ai][bj][m][n] = __builtin_amdgcn_mfma_f32_16x16x32_bf16(Bt[n][k], At[m][k], acc[ai][bj][m][n], 0, 0, 0); __builtin_amdgcn_s_setprio(0); } while (0)
; #define PG8_WAIT_V(n) asm volatile("s_waitcnt vmcnt(" #n ")" ::: "memory")
; #define PG8_BAR __builtin_amdgcn_s_barrier()
; template <class Epi, class Sched, bool ALIGN_EPI = false, bool SP2 = false>
; __device__ __forceinline__ void gemm_phase(PG8_LAS unsigned char* lds, const Gemm g, const Sched& S, const Epi& E) {
;     ...
;         for (int t = 0; t < nt; t += 2) {
;             const bool last = (t == nt - 2);
;             const char* a1 = cA + (size_t)(t + 1) * kstep;
;             const char* a2 = last ? nA : cA + (size_t)(t + 2) * kstep; const char* b2 = last ? nB : cB + (size_t)(t + 2) * kstep;
;             const char* a3 = a2 + kstep; const char* b3 = b2 + kstep;
;             if (last && has_next) S.a_ready(nxt);
;             if constexpr (SP2) {
;             PG8_LDB(B0, 0, 0); PG8_LDB(B1, 0, 1); PG8_SCHED; PG8_LDA(At, 0, 0); PG8_STAGE(PG8_SA(1, 1), a1 + hstepA, voffA);
;             PG8_WAIT_V(8); PG8_WAIT_L(0); PG8_BAR; PG8_MMA(0, 0, At, B0); PG8_MMA(0, 1, At, B1); PG8_BAR; PG8_SCHED;
;             PG8_LDA(At, 0, 1); PG8_STAGE(PG8_SB(0, 0), b2, voffB); PG8_STAGE(PG8_SB(0, 1), b2 + hstep, voffB); PG8_STAGE(PG8_SA(0, 0), a2, voffA);
;             PG8_WAIT_V(8); PG8_WAIT_L(0); PG8_BAR; PG8_MMA(1, 0, At, B0); PG8_MMA(1, 1, At, B1); PG8_BAR; PG8_SCHED;
.LBB0_1236:
	ds_read_b128 v[150:153], v147
	ds_read_b128 v[154:157], v147 offset:1024
	ds_read_b128 v[158:161], v147 offset:2048
	ds_read_b128 v[162:165], v147 offset:3072
	ds_read_b128 v[166:169], v148
	ds_read_b128 v[170:173], v148 offset:1024
	ds_read_b128 v[174:177], v148 offset:2048
	ds_read_b128 v[178:181], v148 offset:3072
	s_add_i32 s68, s40, 2
	s_add_u32 s69, s8, 0xfffc0080
	s_addc_u32 s41, s9, -1
	s_cmp_eq_u32 s59, s40
	s_cselect_b32 s40, s67, s69
	s_cselect_b32 s41, s35, s41
	s_cselect_b32 s71, s37, s43
	s_cselect_b32 s70, s36, s42
	s_add_i32 m0, s31, 0xc000
	ds_read_b128 v[182:185], v149
	ds_read_b128 v[190:193], v149 offset:1024
	ds_read_b128 v[194:197], v149 offset:2048
	ds_read_b128 v[198:201], v149 offset:3072
	ds_read_b128 v[202:205], v149 offset:4096
	ds_read_b128 v[206:209], v149 offset:5120
	ds_read_b128 v[210:213], v149 offset:6144
	global_load_lds_dwordx4 v136, s[8:9]
	s_add_i32 m0, s31, 0xe000
	ds_read_b128 v[214:217], v149 offset:7168
	global_load_lds_dwordx4 v138, s[8:9]
	s_waitcnt vmcnt(8) lgkmcnt(0)
	s_barrier
	s_setprio 1
	v_mfma_f32_16x16x32_bf16 v[120:123], v[150:153], v[182:185], v[120:123]
	v_mfma_f32_16x16x32_bf16 v[124:127], v[158:161], v[182:185], v[124:127]
	v_mfma_f32_16x16x32_bf16 v[108:111], v[150:153], v[194:197], v[108:111]
	v_mfma_f32_16x16x32_bf16 v[104:107], v[158:161], v[194:197], v[104:107]
	v_mfma_f32_16x16x32_bf16 v[92:95], v[150:153], v[202:205], v[92:95]
	v_mfma_f32_16x16x32_bf16 v[88:91], v[158:161], v[202:205], v[88:91]
	v_mfma_f32_16x16x32_bf16 v[76:79], v[150:153], v[210:213], v[76:79]
	v_mfma_f32_16x16x32_bf16 v[72:75], v[158:161], v[210:213], v[72:75]
	v_mfma_f32_16x16x32_bf16 v[120:123], v[154:157], v[190:193], v[120:123]
	v_mfma_f32_16x16x32_bf16 v[124:127], v[162:165], v[190:193], v[124:127]
	v_mfma_f32_16x16x32_bf16 v[108:111], v[154:157], v[198:201], v[108:111]
	v_mfma_f32_16x16x32_bf16 v[104:107], v[162:165], v[198:201], v[104:107]
	v_mfma_f32_16x16x32_bf16 v[92:95], v[154:157], v[206:209], v[92:95]
	v_mfma_f32_16x16x32_bf16 v[88:91], v[162:165], v[206:209], v[88:91]
	v_mfma_f32_16x16x32_bf16 v[76:79], v[154:157], v[214:217], v[76:79]
	v_mfma_f32_16x16x32_bf16 v[72:75], v[162:165], v[214:217], v[72:75]
	v_mfma_f32_16x16x32_bf16 v[116:119], v[166:169], v[182:185], v[116:119]
	v_mfma_f32_16x16x32_bf16 v[112:115], v[174:177], v[182:185], v[112:115]
	v_mfma_f32_16x16x32_bf16 v[100:103], v[166:169], v[194:197], v[100:103]
	v_mfma_f32_16x16x32_bf16 v[96:99], v[174:177], v[194:197], v[96:99]
	v_mfma_f32_16x16x32_bf16 v[84:87], v[166:169], v[202:205], v[84:87]
	v_mfma_f32_16x16x32_bf16 v[80:83], v[174:177], v[202:205], v[80:83]
	v_mfma_f32_16x16x32_bf16 v[68:71], v[166:169], v[210:213], v[68:71]
	v_mfma_f32_16x16x32_bf16 v[64:67], v[174:177], v[210:213], v[64:67]
	v_mfma_f32_16x16x32_bf16 v[116:119], v[170:173], v[190:193], v[116:119]
	v_mfma_f32_16x16x32_bf16 v[112:115], v[178:181], v[190:193], v[112:115]
	v_mfma_f32_16x16x32_bf16 v[100:103], v[170:173], v[198:201], v[100:103]
	v_mfma_f32_16x16x32_bf16 v[96:99], v[178:181], v[198:201], v[96:99]
	v_mfma_f32_16x16x32_bf16 v[84:87], v[170:173], v[206:209], v[84:87]
	v_mfma_f32_16x16x32_bf16 v[80:83], v[178:181], v[206:209], v[80:83]
	v_mfma_f32_16x16x32_bf16 v[68:71], v[170:173], v[214:217], v[68:71]
	v_mfma_f32_16x16x32_bf16 v[64:67], v[178:181], v[214:217], v[64:67]
	s_setprio 0
	s_barrier
	s_add_i32 s69, s60, s47
	s_mov_b32 m0, s69
	ds_read_b128 v[182:185], v149 offset:16384
	ds_read_b128 v[190:193], v149 offset:17408
	ds_read_b128 v[194:197], v149 offset:18432
	ds_read_b128 v[198:201], v149 offset:19456
	global_load_lds_dwordx4 v134, s[70:71]
	s_add_i32 m0, s69, 0x2000
	s_mov_b64 s[100:101], s[70:71]
	s_add_i32 s69, s61, s47
	global_load_lds_dwordx4 v132, s[70:71]
	s_add_u32 s70, s70, s4
	s_addc_u32 s71, s71, s5
	s_mov_b32 m0, s69
	ds_read_b128 v[214:217], v149 offset:23552
	global_load_lds_dwordx4 v134, s[70:71]
	s_add_i32 m0, s69, 0x2000
	ds_read_b128 v[210:213], v149 offset:22528
	global_load_lds_dwordx4 v132, s[70:71]
	s_mov_b32 m0, s31
	ds_read_b128 v[206:209], v149 offset:21504
	global_load_lds_dwordx4 v128, s[40:41]
	s_mov_b32 m0, s50
	ds_read_b128 v[202:205], v149 offset:20480
	global_load_lds_dwordx4 v130, s[40:41]
	s_waitcnt vmcnt(8) lgkmcnt(0)
	s_barrier
	s_setprio 1
	v_mfma_f32_16x16x32_bf16 v[60:63], v[150:153], v[182:185], v[60:63]
	v_mfma_f32_16x16x32_bf16 v[56:59], v[158:161], v[182:185], v[56:59]
	v_mfma_f32_16x16x32_bf16 v[44:47], v[150:153], v[194:197], v[44:47]
	v_mfma_f32_16x16x32_bf16 v[40:43], v[158:161], v[194:197], v[40:43]
	v_mfma_f32_16x16x32_bf16 v[28:31], v[150:153], v[202:205], v[28:31]
	v_mfma_f32_16x16x32_bf16 v[24:27], v[158:161], v[202:205], v[24:27]
	v_mfma_f32_16x16x32_bf16 v[12:15], v[150:153], v[210:213], v[12:15]
	v_mfma_f32_16x16x32_bf16 v[8:11], v[158:161], v[210:213], v[8:11]
	v_mfma_f32_16x16x32_bf16 v[60:63], v[154:157], v[190:193], v[60:63]
	v_mfma_f32_16x16x32_bf16 v[56:59], v[162:165], v[190:193], v[56:59]
	v_mfma_f32_16x16x32_bf16 v[44:47], v[154:157], v[198:201], v[44:47]
	v_mfma_f32_16x16x32_bf16 v[40:43], v[162:165], v[198:201], v[40:43]
	v_mfma_f32_16x16x32_bf16 v[28:31], v[154:157], v[206:209], v[28:31]
	v_mfma_f32_16x16x32_bf16 v[24:27], v[162:165], v[206:209], v[24:27]
	v_mfma_f32_16x16x32_bf16 v[12:15], v[154:157], v[214:217], v[12:15]
	v_mfma_f32_16x16x32_bf16 v[8:11], v[162:165], v[214:217], v[8:11]
	v_mfma_f32_16x16x32_bf16 v[52:55], v[166:169], v[182:185], v[52:55]
	v_mfma_f32_16x16x32_bf16 v[48:51], v[174:177], v[182:185], v[48:51]
	v_mfma_f32_16x16x32_bf16 v[36:39], v[166:169], v[194:197], v[36:39]
	v_mfma_f32_16x16x32_bf16 v[32:35], v[174:177], v[194:197], v[32:35]
	v_mfma_f32_16x16x32_bf16 v[20:23], v[166:169], v[202:205], v[20:23]
	v_mfma_f32_16x16x32_bf16 v[16:19], v[174:177], v[202:205], v[16:19]
	v_mfma_f32_16x16x32_bf16 v[4:7], v[166:169], v[210:213], v[4:7]
	v_mfma_f32_16x16x32_bf16 v[0:3], v[174:177], v[210:213], v[0:3]
	v_mfma_f32_16x16x32_bf16 v[52:55], v[170:173], v[190:193], v[52:55]
	v_mfma_f32_16x16x32_bf16 v[48:51], v[178:181], v[190:193], v[48:51]
	v_mfma_f32_16x16x32_bf16 v[36:39], v[170:173], v[198:201], v[36:39]
	v_mfma_f32_16x16x32_bf16 v[32:35], v[178:181], v[198:201], v[32:35]
	v_mfma_f32_16x16x32_bf16 v[20:23], v[170:173], v[206:209], v[20:23]
	v_mfma_f32_16x16x32_bf16 v[16:19], v[178:181], v[206:209], v[16:19]
	v_mfma_f32_16x16x32_bf16 v[4:7], v[170:173], v[214:217], v[4:7]
	v_mfma_f32_16x16x32_bf16 v[0:3], v[178:181], v[214:217], v[0:3]
	s_setprio 0
	s_barrier
; #define PG8_STAGE(bufoff, gbase, voff) do { _Pragma("unroll") for (int _i = 0; _i < 2; ++_i) \
;         __builtin_amdgcn_global_load_lds((const unsigned*)((const char*)(gbase) + (voff)[_i]), (PG8_LAS unsigned*)(lds + (bufoff) + ldsw + _i * 8192), 16, 0, 0); } while (0)
; #define PG8_LDA(dst, b, h) do { _Pragma("unroll") for (int m = 0; m < 4; ++m) _Pragma("unroll") for (int k = 0; k < 2; ++k) dst[m][k] = *(const PG8_LAS bf16x8*)(lds + PG8_SA(b, h) + aoff + m * 2048 + k * 1024); } while (0)
; #define PG8_LDB(dst, b, h) do { _Pragma("unroll") for (int n = 0; n < 2; ++n) _Pragma("unroll") for (int k = 0; k < 2; ++k) dst[n][k] = *(const PG8_LAS bf16x8*)(lds + PG8_SB(b, h) + boff + n * 2048 + k * 1024); } while (0)
; #define PG8_MMA(ai, bj, At, Bt) do { __builtin_amdgcn_s_setprio(1); _Pragma("unroll") for (int m = 0; m < 4; ++m) _Pragma("unroll") for (int n = 0; n < 2; ++n) _Pragma("unroll") for (int k = 0; k < 2; ++k) \
;         acc[ai][bj][m][n] = __builtin_amdgcn_mfma_f32_16x16x32_bf16(Bt[n][k], At[m][k], acc[ai][bj][m][n], 0, 0, 0); __builtin_amdgcn_s_setprio(0); } while (0)
; #define PG8_WAIT_V(n) asm volatile("s_waitcnt vmcnt(" #n ")" ::: "memory")
; #define PG8_WAIT_L(n) asm volatile("s_waitcnt lgkmcnt(" #n ")" ::: "memory")
; #define PG8_BAR __builtin_amdgcn_s_barrier()
; template <class Epi, class Sched, bool ALIGN_EPI = false, bool SP2 = false>
; __device__ __forceinline__ void gemm_phase(PG8_LAS unsigned char* lds, const Gemm g, const Sched& S, const Epi& E) {
;     ...
;         for (int t = 0; t < nt; t += 2) {
;             const bool last = (t == nt - 2);
;             const char* a1 = cA + (size_t)(t + 1) * kstep;
;             const char* a2 = last ? nA : cA + (size_t)(t + 2) * kstep; const char* b2 = last ? nB : cB + (size_t)(t + 2) * kstep;
;             const char* a3 = a2 + kstep; const char* b3 = b2 + kstep;
;     ...
;             PG8_LDB(B0, 1, 0); PG8_LDB(B1, 1, 1); PG8_SCHED; PG8_LDA(At, 1, 0); PG8_STAGE(PG8_SA(0, 1), a2 + hstepA, voffA);
;             PG8_WAIT_V(8); PG8_WAIT_L(0); PG8_BAR; PG8_MMA(0, 0, At, B0); PG8_MMA(0, 1, At, B1); PG8_BAR; PG8_SCHED;
;             PG8_LDA(At, 1, 1); PG8_STAGE(PG8_SB(1, 0), b3, voffB); PG8_STAGE(PG8_SB(1, 1), b3 + hstep, voffB); PG8_STAGE(PG8_SA(1, 0), a3, voffA);
;             PG8_WAIT_V(8); PG8_WAIT_L(0); PG8_BAR; PG8_MMA(1, 0, At, B0); PG8_MMA(1, 1, At, B1); PG8_BAR; PG8_SCHED;
	s_add_i32 s69, 0, 0x18000
	s_add_i32 s70, 0, 0x1c000
	v_add_u32_e32 v162, s69, v145
	v_add_u32_e32 v178, s70, v145
	ds_read_b128 v[150:153], v162
	ds_read_b128 v[154:157], v162 offset:1024
	ds_read_b128 v[158:161], v162 offset:2048
	ds_read_b128 v[162:165], v162 offset:3072
	ds_read_b128 v[166:169], v178
	ds_read_b128 v[170:173], v178 offset:1024
	ds_read_b128 v[174:177], v178 offset:2048
	ds_read_b128 v[178:181], v178 offset:3072
	s_mov_b64 vcc, s[40:41]
	s_add_u32 s40, s40, 0x40000
	s_addc_u32 s41, s41, 0
	s_mov_b32 m0, s51
	ds_read_b128 v[182:185], v149 offset:32768
	ds_read_b128 v[190:193], v149 offset:33792
	ds_read_b128 v[194:197], v149 offset:34816
	ds_read_b128 v[198:201], v149 offset:35840
	ds_read_b128 v[202:205], v149 offset:36864
	ds_read_b128 v[206:209], v149 offset:37888
	ds_read_b128 v[210:213], v149 offset:38912
	global_load_lds_dwordx4 v128, s[40:41]
	s_mov_b32 m0, s52
	ds_read_b128 v[214:217], v149 offset:39936
	global_load_lds_dwordx4 v130, s[40:41]
	s_waitcnt vmcnt(8) lgkmcnt(0)
	s_barrier
	s_setprio 1
	v_mfma_f32_16x16x32_bf16 v[120:123], v[150:153], v[182:185], v[120:123]
	v_mfma_f32_16x16x32_bf16 v[124:127], v[158:161], v[182:185], v[124:127]
	v_mfma_f32_16x16x32_bf16 v[108:111], v[150:153], v[194:197], v[108:111]
	v_mfma_f32_16x16x32_bf16 v[104:107], v[158:161], v[194:197], v[104:107]
	v_mfma_f32_16x16x32_bf16 v[92:95], v[150:153], v[202:205], v[92:95]
	v_mfma_f32_16x16x32_bf16 v[88:91], v[158:161], v[202:205], v[88:91]
	v_mfma_f32_16x16x32_bf16 v[76:79], v[150:153], v[210:213], v[76:79]
	v_mfma_f32_16x16x32_bf16 v[72:75], v[158:161], v[210:213], v[72:75]
	v_mfma_f32_16x16x32_bf16 v[120:123], v[154:157], v[190:193], v[120:123]
	v_mfma_f32_16x16x32_bf16 v[124:127], v[162:165], v[190:193], v[124:127]
	v_mfma_f32_16x16x32_bf16 v[108:111], v[154:157], v[198:201], v[108:111]
	v_mfma_f32_16x16x32_bf16 v[104:107], v[162:165], v[198:201], v[104:107]
	v_mfma_f32_16x16x32_bf16 v[92:95], v[154:157], v[206:209], v[92:95]
	v_mfma_f32_16x16x32_bf16 v[88:91], v[162:165], v[206:209], v[88:91]
	v_mfma_f32_16x16x32_bf16 v[76:79], v[154:157], v[214:217], v[76:79]
	v_mfma_f32_16x16x32_bf16 v[72:75], v[162:165], v[214:217], v[72:75]
	v_mfma_f32_16x16x32_bf16 v[116:119], v[166:169], v[182:185], v[116:119]
	v_mfma_f32_16x16x32_bf16 v[112:115], v[174:177], v[182:185], v[112:115]
	v_mfma_f32_16x16x32_bf16 v[100:103], v[166:169], v[194:197], v[100:103]
	v_mfma_f32_16x16x32_bf16 v[96:99], v[174:177], v[194:197], v[96:99]
	v_mfma_f32_16x16x32_bf16 v[84:87], v[166:169], v[202:205], v[84:87]
	v_mfma_f32_16x16x32_bf16 v[80:83], v[174:177], v[202:205], v[80:83]
	v_mfma_f32_16x16x32_bf16 v[68:71], v[166:169], v[210:213], v[68:71]
	v_mfma_f32_16x16x32_bf16 v[64:67], v[174:177], v[210:213], v[64:67]
	v_mfma_f32_16x16x32_bf16 v[116:119], v[170:173], v[190:193], v[116:119]
	v_mfma_f32_16x16x32_bf16 v[112:115], v[178:181], v[190:193], v[112:115]
	v_mfma_f32_16x16x32_bf16 v[100:103], v[170:173], v[198:201], v[100:103]
	v_mfma_f32_16x16x32_bf16 v[96:99], v[178:181], v[198:201], v[96:99]
	v_mfma_f32_16x16x32_bf16 v[84:87], v[170:173], v[206:209], v[84:87]
	v_mfma_f32_16x16x32_bf16 v[80:83], v[178:181], v[206:209], v[80:83]
	v_mfma_f32_16x16x32_bf16 v[68:71], v[170:173], v[214:217], v[68:71]
	v_mfma_f32_16x16x32_bf16 v[64:67], v[178:181], v[214:217], v[64:67]
	s_setprio 0
	s_barrier
	s_add_i32 s40, s69, s47
	s_add_i32 m0, s40, 0xffffff80
	ds_read_b128 v[182:185], v149 offset:49152
	ds_read_b128 v[190:193], v149 offset:50176
	ds_read_b128 v[194:197], v149 offset:51200
	ds_read_b128 v[198:201], v149 offset:52224
	global_load_lds_dwordx4 v134, s[100:101] offset:128
	s_add_i32 m0, s40, 0x1f80
	s_add_i32 s40, s70, s47
	global_load_lds_dwordx4 v132, s[100:101] offset:128
	s_add_u32 s100, s100, s4
	s_addc_u32 s101, s101, s5
	s_add_i32 m0, s40, 0xffffff80
	ds_read_b128 v[214:217], v149 offset:56320
	global_load_lds_dwordx4 v134, s[100:101] offset:128
	s_add_i32 m0, s40, 0x1f80
	ds_read_b128 v[210:213], v149 offset:55296
	global_load_lds_dwordx4 v132, s[100:101] offset:128
	s_add_i32 m0, s55, 0xffffff80
	ds_read_b128 v[206:209], v149 offset:54272
	global_load_lds_dwordx4 v128, vcc offset:128
	s_add_i32 m0, s56, 0xffffff80
	ds_read_b128 v[202:205], v149 offset:53248
	global_load_lds_dwordx4 v130, vcc offset:128
	s_waitcnt vmcnt(8) lgkmcnt(0)
	s_barrier
	s_setprio 1
	v_mfma_f32_16x16x32_bf16 v[60:63], v[150:153], v[182:185], v[60:63]
	v_mfma_f32_16x16x32_bf16 v[56:59], v[158:161], v[182:185], v[56:59]
	v_mfma_f32_16x16x32_bf16 v[44:47], v[150:153], v[194:197], v[44:47]
	v_mfma_f32_16x16x32_bf16 v[40:43], v[158:161], v[194:197], v[40:43]
	v_mfma_f32_16x16x32_bf16 v[28:31], v[150:153], v[202:205], v[28:31]
	v_mfma_f32_16x16x32_bf16 v[24:27], v[158:161], v[202:205], v[24:27]
	v_mfma_f32_16x16x32_bf16 v[12:15], v[150:153], v[210:213], v[12:15]
	v_mfma_f32_16x16x32_bf16 v[8:11], v[158:161], v[210:213], v[8:11]
	v_mfma_f32_16x16x32_bf16 v[60:63], v[154:157], v[190:193], v[60:63]
	v_mfma_f32_16x16x32_bf16 v[56:59], v[162:165], v[190:193], v[56:59]
	v_mfma_f32_16x16x32_bf16 v[44:47], v[154:157], v[198:201], v[44:47]
	v_mfma_f32_16x16x32_bf16 v[40:43], v[162:165], v[198:201], v[40:43]
	v_mfma_f32_16x16x32_bf16 v[28:31], v[154:157], v[206:209], v[28:31]
	v_mfma_f32_16x16x32_bf16 v[24:27], v[162:165], v[206:209], v[24:27]
	v_mfma_f32_16x16x32_bf16 v[12:15], v[154:157], v[214:217], v[12:15]
	v_mfma_f32_16x16x32_bf16 v[8:11], v[162:165], v[214:217], v[8:11]
	v_mfma_f32_16x16x32_bf16 v[52:55], v[166:169], v[182:185], v[52:55]
	v_mfma_f32_16x16x32_bf16 v[48:51], v[174:177], v[182:185], v[48:51]
	v_mfma_f32_16x16x32_bf16 v[36:39], v[166:169], v[194:197], v[36:39]
	v_mfma_f32_16x16x32_bf16 v[32:35], v[174:177], v[194:197], v[32:35]
	v_mfma_f32_16x16x32_bf16 v[20:23], v[166:169], v[202:205], v[20:23]
	v_mfma_f32_16x16x32_bf16 v[16:19], v[174:177], v[202:205], v[16:19]
	v_mfma_f32_16x16x32_bf16 v[4:7], v[166:169], v[210:213], v[4:7]
	v_mfma_f32_16x16x32_bf16 v[0:3], v[174:177], v[210:213], v[0:3]
	v_mfma_f32_16x16x32_bf16 v[52:55], v[170:173], v[190:193], v[52:55]
	v_mfma_f32_16x16x32_bf16 v[48:51], v[178:181], v[190:193], v[48:51]
	v_mfma_f32_16x16x32_bf16 v[36:39], v[170:173], v[198:201], v[36:39]
	v_mfma_f32_16x16x32_bf16 v[32:35], v[178:181], v[198:201], v[32:35]
	v_mfma_f32_16x16x32_bf16 v[20:23], v[170:173], v[206:209], v[20:23]
	v_mfma_f32_16x16x32_bf16 v[16:19], v[178:181], v[206:209], v[16:19]
	v_mfma_f32_16x16x32_bf16 v[4:7], v[170:173], v[214:217], v[4:7]
	v_mfma_f32_16x16x32_bf16 v[0:3], v[178:181], v[214:217], v[0:3]
	s_setprio 0
	s_barrier
	s_add_u32 s8, s8, 0x100
	s_addc_u32 s9, s9, 0
	s_add_u32 s42, s42, 0x100
	s_addc_u32 s43, s43, 0
	s_cmp_ge_i32 s68, s58
	s_mov_b32 s40, s68
	s_cbranch_scc0 .LBB0_1236

; #define PG8_STAGE(bufoff, gbase, voff) do { _Pragma("unroll") for (int _i = 0; _i < 2; ++_i) \
;         __builtin_amdgcn_global_load_lds((const unsigned*)((const char*)(gbase) + (voff)[_i]), (PG8_LAS unsigned*)(lds + (bufoff) + ldsw + _i * 8192), 16, 0, 0); } while (0)
; #define PG8_LDA(dst, b, h) do { _Pragma("unroll") for (int m = 0; m < 4; ++m) _Pragma("unroll") for (int k = 0; k < 2; ++k) dst[m][k] = *(const PG8_LAS bf16x8*)(lds + PG8_SA(b, h) + aoff + m * 2048 + k * 1024); } while (0)
; #define PG8_LDB(dst, b, h) do { _Pragma("unroll") for (int n = 0; n < 2; ++n) _Pragma("unroll") for (int k = 0; k < 2; ++k) dst[n][k] = *(const PG8_LAS bf16x8*)(lds + PG8_SB(b, h) + boff + n * 2048 + k * 1024); } while (0)
; #define PG8_MMA(ai, bj, At, Bt) do { __builtin_amdgcn_s_setprio(1); _Pragma("unroll") for (int m = 0; m < 4; ++m) _Pragma("unroll") for (int n = 0; n < 2; ++n) _Pragma("unroll") for (int k = 0; k < 2; ++k) \
;         acc[ai][bj][m][n] = __builtin_amdgcn_mfma_f32_16x16x32_bf16(Bt[n][k], At[m][k], acc[ai][bj][m][n], 0, 0, 0); __builtin_amdgcn_s_setprio(0); } while (0)
; #define PG8_WAIT_V(n) asm volatile("s_waitcnt vmcnt(" #n ")" ::: "memory")
; #define PG8_BAR __builtin_amdgcn_s_barrier()
; template <class Epi, class Sched, bool ALIGN_EPI = false, bool SP2 = false>
; __device__ __forceinline__ void gemm_phase(PG8_LAS unsigned char* lds, const Gemm g, const Sched& S, const Epi& E) {
;     ...
;         for (int t = 0; t < nt; t += 2) {
;             const bool last = (t == nt - 2);
;             const char* a1 = cA + (size_t)(t + 1) * kstep;
;             const char* a2 = last ? nA : cA + (size_t)(t + 2) * kstep; const char* b2 = last ? nB : cB + (size_t)(t + 2) * kstep;
;             const char* a3 = a2 + kstep; const char* b3 = b2 + kstep;
;             if (last && has_next) S.a_ready(nxt);
;             if constexpr (SP2) {
;             PG8_LDB(B0, 0, 0); PG8_LDB(B1, 0, 1); PG8_SCHED; PG8_LDA(At, 0, 0); PG8_STAGE(PG8_SA(1, 1), a1 + hstepA, voffA);
;             PG8_WAIT_V(8); PG8_WAIT_L(0); PG8_BAR; PG8_MMA(0, 0, At, B0); PG8_MMA(0, 1, At, B1); PG8_BAR; PG8_SCHED;
;             PG8_LDA(At, 0, 1); PG8_STAGE(PG8_SB(0, 0), b2, voffB); PG8_STAGE(PG8_SB(0, 1), b2 + hstep, voffB); PG8_STAGE(PG8_SA(0, 0), a2, voffA);
;             PG8_WAIT_V(8); PG8_WAIT_L(0); PG8_BAR; PG8_MMA(1, 0, At, B0); PG8_MMA(1, 1, At, B1); PG8_BAR; PG8_SCHED;
.LBB0_1480:
	ds_read_b128 v[162:165], v159
	ds_read_b128 v[166:169], v159 offset:1024
	ds_read_b128 v[170:173], v159 offset:2048
	ds_read_b128 v[174:177], v159 offset:3072
	ds_read_b128 v[178:181], v160
	ds_read_b128 v[182:185], v160 offset:1024
	ds_read_b128 v[190:193], v160 offset:2048
	ds_read_b128 v[194:197], v160 offset:3072
	s_add_i32 s63, s36, 2
	s_add_u32 s64, s10, 0xfffe0080
	s_addc_u32 s37, s11, -1
	s_cmp_eq_u32 s56, s36
	s_cselect_b32 s36, s62, s64
	s_cselect_b32 s37, s29, s37
	s_cselect_b32 s65, s31, s39
	s_cselect_b32 s64, s30, s38
	s_add_i32 m0, s27, 0xc000
	ds_read_b128 v[198:201], v161
	ds_read_b128 v[202:205], v161 offset:1024
	ds_read_b128 v[206:209], v161 offset:2048
	ds_read_b128 v[210:213], v161 offset:3072
	ds_read_b128 v[214:217], v161 offset:4096
	ds_read_b128 v[218:221], v161 offset:5120
	ds_read_b128 v[222:225], v161 offset:6144
	global_load_lds_dwordx4 v138, s[10:11]
	s_add_i32 m0, s27, 0xe000
	ds_read_b128 v[226:229], v161 offset:7168
	global_load_lds_dwordx4 v140, s[10:11]
	s_waitcnt vmcnt(8) lgkmcnt(0)
	s_barrier
	s_setprio 1
	v_mfma_f32_16x16x32_bf16 v[124:127], v[162:165], v[198:201], v[124:127]
	v_mfma_f32_16x16x32_bf16 v[120:123], v[170:173], v[198:201], v[120:123]
	v_mfma_f32_16x16x32_bf16 v[108:111], v[162:165], v[206:209], v[108:111]
	v_mfma_f32_16x16x32_bf16 v[104:107], v[170:173], v[206:209], v[104:107]
	v_mfma_f32_16x16x32_bf16 v[92:95], v[162:165], v[214:217], v[92:95]
	v_mfma_f32_16x16x32_bf16 v[88:91], v[170:173], v[214:217], v[88:91]
	v_mfma_f32_16x16x32_bf16 v[76:79], v[162:165], v[222:225], v[76:79]
	v_mfma_f32_16x16x32_bf16 v[72:75], v[170:173], v[222:225], v[72:75]
	v_mfma_f32_16x16x32_bf16 v[124:127], v[166:169], v[202:205], v[124:127]
	v_mfma_f32_16x16x32_bf16 v[120:123], v[174:177], v[202:205], v[120:123]
	v_mfma_f32_16x16x32_bf16 v[108:111], v[166:169], v[210:213], v[108:111]
	v_mfma_f32_16x16x32_bf16 v[104:107], v[174:177], v[210:213], v[104:107]
	v_mfma_f32_16x16x32_bf16 v[92:95], v[166:169], v[218:221], v[92:95]
	v_mfma_f32_16x16x32_bf16 v[88:91], v[174:177], v[218:221], v[88:91]
	v_mfma_f32_16x16x32_bf16 v[76:79], v[166:169], v[226:229], v[76:79]
	v_mfma_f32_16x16x32_bf16 v[72:75], v[174:177], v[226:229], v[72:75]
	v_mfma_f32_16x16x32_bf16 v[116:119], v[178:181], v[198:201], v[116:119]
	v_mfma_f32_16x16x32_bf16 v[112:115], v[190:193], v[198:201], v[112:115]
	v_mfma_f32_16x16x32_bf16 v[100:103], v[178:181], v[206:209], v[100:103]
	v_mfma_f32_16x16x32_bf16 v[96:99], v[190:193], v[206:209], v[96:99]
	v_mfma_f32_16x16x32_bf16 v[84:87], v[178:181], v[214:217], v[84:87]
	v_mfma_f32_16x16x32_bf16 v[80:83], v[190:193], v[214:217], v[80:83]
	v_mfma_f32_16x16x32_bf16 v[68:71], v[178:181], v[222:225], v[68:71]
	v_mfma_f32_16x16x32_bf16 v[64:67], v[190:193], v[222:225], v[64:67]
	v_mfma_f32_16x16x32_bf16 v[116:119], v[182:185], v[202:205], v[116:119]
	v_mfma_f32_16x16x32_bf16 v[112:115], v[194:197], v[202:205], v[112:115]
	v_mfma_f32_16x16x32_bf16 v[100:103], v[182:185], v[210:213], v[100:103]
	v_mfma_f32_16x16x32_bf16 v[96:99], v[194:197], v[210:213], v[96:99]
	v_mfma_f32_16x16x32_bf16 v[84:87], v[182:185], v[218:221], v[84:87]
	v_mfma_f32_16x16x32_bf16 v[80:83], v[194:197], v[218:221], v[80:83]
	v_mfma_f32_16x16x32_bf16 v[68:71], v[182:185], v[226:229], v[68:71]
	v_mfma_f32_16x16x32_bf16 v[64:67], v[194:197], v[226:229], v[64:67]
	s_setprio 0
	s_barrier
	s_add_i32 s66, s57, s47
	s_mov_b32 m0, s66
	ds_read_b128 v[198:201], v161 offset:16384
	ds_read_b128 v[202:205], v161 offset:17408
	ds_read_b128 v[206:209], v161 offset:18432
	ds_read_b128 v[210:213], v161 offset:19456
	global_load_lds_dwordx4 v136, s[64:65]
	s_add_i32 m0, s66, 0x2000
	s_mov_b64 s[100:101], s[64:65]
	s_add_i32 s66, s58, s47
	global_load_lds_dwordx4 v134, s[64:65]
	s_add_u32 s64, s64, s16
	s_addc_u32 s65, s65, s17
	s_mov_b32 m0, s66
	ds_read_b128 v[226:229], v161 offset:23552
	global_load_lds_dwordx4 v136, s[64:65]
	s_add_i32 m0, s66, 0x2000
	ds_read_b128 v[222:225], v161 offset:22528
	global_load_lds_dwordx4 v134, s[64:65]
	s_mov_b32 m0, s27
	ds_read_b128 v[218:221], v161 offset:21504
	global_load_lds_dwordx4 v130, s[36:37]
	s_mov_b32 m0, s48
	ds_read_b128 v[214:217], v161 offset:20480
	global_load_lds_dwordx4 v132, s[36:37]
	s_waitcnt vmcnt(8) lgkmcnt(0)
	s_barrier
	s_setprio 1
	v_mfma_f32_16x16x32_bf16 v[60:63], v[162:165], v[198:201], v[60:63]
	v_mfma_f32_16x16x32_bf16 v[56:59], v[170:173], v[198:201], v[56:59]
	v_mfma_f32_16x16x32_bf16 v[44:47], v[162:165], v[206:209], v[44:47]
	v_mfma_f32_16x16x32_bf16 v[40:43], v[170:173], v[206:209], v[40:43]
	v_mfma_f32_16x16x32_bf16 v[28:31], v[162:165], v[214:217], v[28:31]
	v_mfma_f32_16x16x32_bf16 v[24:27], v[170:173], v[214:217], v[24:27]
	v_mfma_f32_16x16x32_bf16 v[12:15], v[162:165], v[222:225], v[12:15]
	v_mfma_f32_16x16x32_bf16 v[8:11], v[170:173], v[222:225], v[8:11]
	v_mfma_f32_16x16x32_bf16 v[60:63], v[166:169], v[202:205], v[60:63]
	v_mfma_f32_16x16x32_bf16 v[56:59], v[174:177], v[202:205], v[56:59]
	v_mfma_f32_16x16x32_bf16 v[44:47], v[166:169], v[210:213], v[44:47]
	v_mfma_f32_16x16x32_bf16 v[40:43], v[174:177], v[210:213], v[40:43]
	v_mfma_f32_16x16x32_bf16 v[28:31], v[166:169], v[218:221], v[28:31]
	v_mfma_f32_16x16x32_bf16 v[24:27], v[174:177], v[218:221], v[24:27]
	v_mfma_f32_16x16x32_bf16 v[12:15], v[166:169], v[226:229], v[12:15]
	v_mfma_f32_16x16x32_bf16 v[8:11], v[174:177], v[226:229], v[8:11]
	v_mfma_f32_16x16x32_bf16 v[52:55], v[178:181], v[198:201], v[52:55]
	v_mfma_f32_16x16x32_bf16 v[48:51], v[190:193], v[198:201], v[48:51]
	v_mfma_f32_16x16x32_bf16 v[36:39], v[178:181], v[206:209], v[36:39]
	v_mfma_f32_16x16x32_bf16 v[32:35], v[190:193], v[206:209], v[32:35]
	v_mfma_f32_16x16x32_bf16 v[20:23], v[178:181], v[214:217], v[20:23]
	v_mfma_f32_16x16x32_bf16 v[16:19], v[190:193], v[214:217], v[16:19]
	v_mfma_f32_16x16x32_bf16 v[4:7], v[178:181], v[222:225], v[4:7]
	v_mfma_f32_16x16x32_bf16 v[0:3], v[190:193], v[222:225], v[0:3]
	v_mfma_f32_16x16x32_bf16 v[52:55], v[182:185], v[202:205], v[52:55]
	v_mfma_f32_16x16x32_bf16 v[48:51], v[194:197], v[202:205], v[48:51]
	v_mfma_f32_16x16x32_bf16 v[36:39], v[182:185], v[210:213], v[36:39]
	v_mfma_f32_16x16x32_bf16 v[32:35], v[194:197], v[210:213], v[32:35]
	v_mfma_f32_16x16x32_bf16 v[20:23], v[182:185], v[218:221], v[20:23]
	v_mfma_f32_16x16x32_bf16 v[16:19], v[194:197], v[218:221], v[16:19]
	v_mfma_f32_16x16x32_bf16 v[4:7], v[182:185], v[226:229], v[4:7]
	v_mfma_f32_16x16x32_bf16 v[0:3], v[194:197], v[226:229], v[0:3]
	s_setprio 0
	s_barrier
; #define PG8_STAGE(bufoff, gbase, voff) do { _Pragma("unroll") for (int _i = 0; _i < 2; ++_i) \
;         __builtin_amdgcn_global_load_lds((const unsigned*)((const char*)(gbase) + (voff)[_i]), (PG8_LAS unsigned*)(lds + (bufoff) + ldsw + _i * 8192), 16, 0, 0); } while (0)
; #define PG8_LDA(dst, b, h) do { _Pragma("unroll") for (int m = 0; m < 4; ++m) _Pragma("unroll") for (int k = 0; k < 2; ++k) dst[m][k] = *(const PG8_LAS bf16x8*)(lds + PG8_SA(b, h) + aoff + m * 2048 + k * 1024); } while (0)
; #define PG8_LDB(dst, b, h) do { _Pragma("unroll") for (int n = 0; n < 2; ++n) _Pragma("unroll") for (int k = 0; k < 2; ++k) dst[n][k] = *(const PG8_LAS bf16x8*)(lds + PG8_SB(b, h) + boff + n * 2048 + k * 1024); } while (0)
; #define PG8_MMA(ai, bj, At, Bt) do { __builtin_amdgcn_s_setprio(1); _Pragma("unroll") for (int m = 0; m < 4; ++m) _Pragma("unroll") for (int n = 0; n < 2; ++n) _Pragma("unroll") for (int k = 0; k < 2; ++k) \
;         acc[ai][bj][m][n] = __builtin_amdgcn_mfma_f32_16x16x32_bf16(Bt[n][k], At[m][k], acc[ai][bj][m][n], 0, 0, 0); __builtin_amdgcn_s_setprio(0); } while (0)
; #define PG8_WAIT_V(n) asm volatile("s_waitcnt vmcnt(" #n ")" ::: "memory")
; #define PG8_WAIT_L(n) asm volatile("s_waitcnt lgkmcnt(" #n ")" ::: "memory")
; #define PG8_BAR __builtin_amdgcn_s_barrier()
; template <class Epi, class Sched, bool ALIGN_EPI = false, bool SP2 = false>
; __device__ __forceinline__ void gemm_phase(PG8_LAS unsigned char* lds, const Gemm g, const Sched& S, const Epi& E) {
;     ...
;         for (int t = 0; t < nt; t += 2) {
;             const bool last = (t == nt - 2);
;             const char* a1 = cA + (size_t)(t + 1) * kstep;
;             const char* a2 = last ? nA : cA + (size_t)(t + 2) * kstep; const char* b2 = last ? nB : cB + (size_t)(t + 2) * kstep;
;             const char* a3 = a2 + kstep; const char* b3 = b2 + kstep;
;     ...
;             PG8_LDB(B0, 1, 0); PG8_LDB(B1, 1, 1); PG8_SCHED; PG8_LDA(At, 1, 0); PG8_STAGE(PG8_SA(0, 1), a2 + hstepA, voffA);
;             PG8_WAIT_V(8); PG8_WAIT_L(0); PG8_BAR; PG8_MMA(0, 0, At, B0); PG8_MMA(0, 1, At, B1); PG8_BAR; PG8_SCHED;
;             PG8_LDA(At, 1, 1); PG8_STAGE(PG8_SB(1, 0), b3, voffB); PG8_STAGE(PG8_SB(1, 1), b3 + hstep, voffB); PG8_STAGE(PG8_SA(1, 0), a3, voffA);
;             PG8_WAIT_V(8); PG8_WAIT_L(0); PG8_BAR; PG8_MMA(1, 0, At, B0); PG8_MMA(1, 1, At, B1); PG8_BAR; PG8_SCHED;
	s_add_i32 s64, 0, 0x18000
	s_add_i32 s65, 0, 0x1c000
	v_add_u32_e32 v174, s64, v157
	v_add_u32_e32 v194, s65, v157
	ds_read_b128 v[162:165], v174
	ds_read_b128 v[166:169], v174 offset:1024
	ds_read_b128 v[170:173], v174 offset:2048
	ds_read_b128 v[174:177], v174 offset:3072
	ds_read_b128 v[178:181], v194
	ds_read_b128 v[182:185], v194 offset:1024
	ds_read_b128 v[190:193], v194 offset:2048
	ds_read_b128 v[194:197], v194 offset:3072
	s_mov_b64 vcc, s[36:37]
	s_add_u32 s36, s36, 0x20000
	s_addc_u32 s37, s37, 0
	s_mov_b32 m0, s49
	ds_read_b128 v[198:201], v161 offset:32768
	ds_read_b128 v[202:205], v161 offset:33792
	ds_read_b128 v[206:209], v161 offset:34816
	ds_read_b128 v[210:213], v161 offset:35840
	ds_read_b128 v[214:217], v161 offset:36864
	ds_read_b128 v[218:221], v161 offset:37888
	ds_read_b128 v[222:225], v161 offset:38912
	global_load_lds_dwordx4 v130, s[36:37]
	s_mov_b32 m0, s50
	ds_read_b128 v[226:229], v161 offset:39936
	global_load_lds_dwordx4 v132, s[36:37]
	s_waitcnt vmcnt(8) lgkmcnt(0)
	s_barrier
	s_setprio 1
	v_mfma_f32_16x16x32_bf16 v[124:127], v[162:165], v[198:201], v[124:127]
	v_mfma_f32_16x16x32_bf16 v[120:123], v[170:173], v[198:201], v[120:123]
	v_mfma_f32_16x16x32_bf16 v[108:111], v[162:165], v[206:209], v[108:111]
	v_mfma_f32_16x16x32_bf16 v[104:107], v[170:173], v[206:209], v[104:107]
	v_mfma_f32_16x16x32_bf16 v[92:95], v[162:165], v[214:217], v[92:95]
	v_mfma_f32_16x16x32_bf16 v[88:91], v[170:173], v[214:217], v[88:91]
	v_mfma_f32_16x16x32_bf16 v[76:79], v[162:165], v[222:225], v[76:79]
	v_mfma_f32_16x16x32_bf16 v[72:75], v[170:173], v[222:225], v[72:75]
	v_mfma_f32_16x16x32_bf16 v[124:127], v[166:169], v[202:205], v[124:127]
	v_mfma_f32_16x16x32_bf16 v[120:123], v[174:177], v[202:205], v[120:123]
	v_mfma_f32_16x16x32_bf16 v[108:111], v[166:169], v[210:213], v[108:111]
	v_mfma_f32_16x16x32_bf16 v[104:107], v[174:177], v[210:213], v[104:107]
	v_mfma_f32_16x16x32_bf16 v[92:95], v[166:169], v[218:221], v[92:95]
	v_mfma_f32_16x16x32_bf16 v[88:91], v[174:177], v[218:221], v[88:91]
	v_mfma_f32_16x16x32_bf16 v[76:79], v[166:169], v[226:229], v[76:79]
	v_mfma_f32_16x16x32_bf16 v[72:75], v[174:177], v[226:229], v[72:75]
	v_mfma_f32_16x16x32_bf16 v[116:119], v[178:181], v[198:201], v[116:119]
	v_mfma_f32_16x16x32_bf16 v[112:115], v[190:193], v[198:201], v[112:115]
	v_mfma_f32_16x16x32_bf16 v[100:103], v[178:181], v[206:209], v[100:103]
	v_mfma_f32_16x16x32_bf16 v[96:99], v[190:193], v[206:209], v[96:99]
	v_mfma_f32_16x16x32_bf16 v[84:87], v[178:181], v[214:217], v[84:87]
	v_mfma_f32_16x16x32_bf16 v[80:83], v[190:193], v[214:217], v[80:83]
	v_mfma_f32_16x16x32_bf16 v[68:71], v[178:181], v[222:225], v[68:71]
	v_mfma_f32_16x16x32_bf16 v[64:67], v[190:193], v[222:225], v[64:67]
	v_mfma_f32_16x16x32_bf16 v[116:119], v[182:185], v[202:205], v[116:119]
	v_mfma_f32_16x16x32_bf16 v[112:115], v[194:197], v[202:205], v[112:115]
	v_mfma_f32_16x16x32_bf16 v[100:103], v[182:185], v[210:213], v[100:103]
	v_mfma_f32_16x16x32_bf16 v[96:99], v[194:197], v[210:213], v[96:99]
	v_mfma_f32_16x16x32_bf16 v[84:87], v[182:185], v[218:221], v[84:87]
	v_mfma_f32_16x16x32_bf16 v[80:83], v[194:197], v[218:221], v[80:83]
	v_mfma_f32_16x16x32_bf16 v[68:71], v[182:185], v[226:229], v[68:71]
	v_mfma_f32_16x16x32_bf16 v[64:67], v[194:197], v[226:229], v[64:67]
	s_setprio 0
	s_barrier
	s_add_i32 s36, s64, s47
	s_add_i32 m0, s36, 0xffffff80
	ds_read_b128 v[198:201], v161 offset:49152
	ds_read_b128 v[202:205], v161 offset:50176
	ds_read_b128 v[206:209], v161 offset:51200
	ds_read_b128 v[210:213], v161 offset:52224
	global_load_lds_dwordx4 v136, s[100:101] offset:128
	s_add_i32 m0, s36, 0x1f80
	s_add_i32 s36, s65, s47
	global_load_lds_dwordx4 v134, s[100:101] offset:128
	s_add_u32 s100, s100, s16
	s_addc_u32 s101, s101, s17
	s_add_i32 m0, s36, 0xffffff80
	ds_read_b128 v[226:229], v161 offset:56320
	global_load_lds_dwordx4 v136, s[100:101] offset:128
	s_add_i32 m0, s36, 0x1f80
	ds_read_b128 v[222:225], v161 offset:55296
	global_load_lds_dwordx4 v134, s[100:101] offset:128
	s_add_i32 m0, s51, 0xffffff80
	ds_read_b128 v[218:221], v161 offset:54272
	global_load_lds_dwordx4 v130, vcc offset:128
	s_add_i32 m0, s52, 0xffffff80
	ds_read_b128 v[214:217], v161 offset:53248
	global_load_lds_dwordx4 v132, vcc offset:128
	s_waitcnt vmcnt(8) lgkmcnt(0)
	s_barrier
	s_setprio 1
	v_mfma_f32_16x16x32_bf16 v[60:63], v[162:165], v[198:201], v[60:63]
	v_mfma_f32_16x16x32_bf16 v[56:59], v[170:173], v[198:201], v[56:59]
	v_mfma_f32_16x16x32_bf16 v[44:47], v[162:165], v[206:209], v[44:47]
	v_mfma_f32_16x16x32_bf16 v[40:43], v[170:173], v[206:209], v[40:43]
	v_mfma_f32_16x16x32_bf16 v[28:31], v[162:165], v[214:217], v[28:31]
	v_mfma_f32_16x16x32_bf16 v[24:27], v[170:173], v[214:217], v[24:27]
	v_mfma_f32_16x16x32_bf16 v[12:15], v[162:165], v[222:225], v[12:15]
	v_mfma_f32_16x16x32_bf16 v[8:11], v[170:173], v[222:225], v[8:11]
	v_mfma_f32_16x16x32_bf16 v[60:63], v[166:169], v[202:205], v[60:63]
	v_mfma_f32_16x16x32_bf16 v[56:59], v[174:177], v[202:205], v[56:59]
	v_mfma_f32_16x16x32_bf16 v[44:47], v[166:169], v[210:213], v[44:47]
	v_mfma_f32_16x16x32_bf16 v[40:43], v[174:177], v[210:213], v[40:43]
	v_mfma_f32_16x16x32_bf16 v[28:31], v[166:169], v[218:221], v[28:31]
	v_mfma_f32_16x16x32_bf16 v[24:27], v[174:177], v[218:221], v[24:27]
	v_mfma_f32_16x16x32_bf16 v[12:15], v[166:169], v[226:229], v[12:15]
	v_mfma_f32_16x16x32_bf16 v[8:11], v[174:177], v[226:229], v[8:11]
	v_mfma_f32_16x16x32_bf16 v[52:55], v[178:181], v[198:201], v[52:55]
	v_mfma_f32_16x16x32_bf16 v[48:51], v[190:193], v[198:201], v[48:51]
	v_mfma_f32_16x16x32_bf16 v[36:39], v[178:181], v[206:209], v[36:39]
	v_mfma_f32_16x16x32_bf16 v[32:35], v[190:193], v[206:209], v[32:35]
	v_mfma_f32_16x16x32_bf16 v[20:23], v[178:181], v[214:217], v[20:23]
	v_mfma_f32_16x16x32_bf16 v[16:19], v[190:193], v[214:217], v[16:19]
	v_mfma_f32_16x16x32_bf16 v[4:7], v[178:181], v[222:225], v[4:7]
	v_mfma_f32_16x16x32_bf16 v[0:3], v[190:193], v[222:225], v[0:3]
	v_mfma_f32_16x16x32_bf16 v[52:55], v[182:185], v[202:205], v[52:55]
	v_mfma_f32_16x16x32_bf16 v[48:51], v[194:197], v[202:205], v[48:51]
	v_mfma_f32_16x16x32_bf16 v[36:39], v[182:185], v[210:213], v[36:39]
	v_mfma_f32_16x16x32_bf16 v[32:35], v[194:197], v[210:213], v[32:35]
	v_mfma_f32_16x16x32_bf16 v[20:23], v[182:185], v[218:221], v[20:23]
	v_mfma_f32_16x16x32_bf16 v[16:19], v[194:197], v[218:221], v[16:19]
	v_mfma_f32_16x16x32_bf16 v[4:7], v[182:185], v[226:229], v[4:7]
	v_mfma_f32_16x16x32_bf16 v[0:3], v[194:197], v[226:229], v[0:3]
	s_setprio 0
	s_barrier
	s_add_u32 s10, s10, 0x100
	s_addc_u32 s11, s11, 0
	s_add_u32 s38, s38, 0x100
	s_addc_u32 s39, s39, 0
	s_cmp_ge_i32 s63, s53
	s_mov_b32 s36, s63
	s_cbranch_scc0 .LBB0_1480

; #define PG8_STAGE(bufoff, gbase, voff) do { _Pragma("unroll") for (int _i = 0; _i < 2; ++_i) \
;         __builtin_amdgcn_global_load_lds((const unsigned*)((const char*)(gbase) + (voff)[_i]), (PG8_LAS unsigned*)(lds + (bufoff) + ldsw + _i * 8192), 16, 0, 0); } while (0)
; #define PG8_LDA(dst, b, h) do { _Pragma("unroll") for (int m = 0; m < 4; ++m) _Pragma("unroll") for (int k = 0; k < 2; ++k) dst[m][k] = *(const PG8_LAS bf16x8*)(lds + PG8_SA(b, h) + aoff + m * 2048 + k * 1024); } while (0)
; #define PG8_LDB(dst, b, h) do { _Pragma("unroll") for (int n = 0; n < 2; ++n) _Pragma("unroll") for (int k = 0; k < 2; ++k) dst[n][k] = *(const PG8_LAS bf16x8*)(lds + PG8_SB(b, h) + boff + n * 2048 + k * 1024); } while (0)
; #define PG8_MMA(ai, bj, At, Bt) do { __builtin_amdgcn_s_setprio(1); _Pragma("unroll") for (int m = 0; m < 4; ++m) _Pragma("unroll") for (int n = 0; n < 2; ++n) _Pragma("unroll") for (int k = 0; k < 2; ++k) \
;         acc[ai][bj][m][n] = __builtin_amdgcn_mfma_f32_16x16x32_bf16(Bt[n][k], At[m][k], acc[ai][bj][m][n], 0, 0, 0); __builtin_amdgcn_s_setprio(0); } while (0)
; #define PG8_WAIT_V(n) asm volatile("s_waitcnt vmcnt(" #n ")" ::: "memory")
; #define PG8_BAR __builtin_amdgcn_s_barrier()
; template <class Epi, class Sched, bool ALIGN_EPI = false, bool SP2 = false>
; __device__ __forceinline__ void gemm_phase(PG8_LAS unsigned char* lds, const Gemm g, const Sched& S, const Epi& E) {
;     ...
;         for (int t = 0; t < nt; t += 2) {
;             const bool last = (t == nt - 2);
;             const char* a1 = cA + (size_t)(t + 1) * kstep;
;             const char* a2 = last ? nA : cA + (size_t)(t + 2) * kstep; const char* b2 = last ? nB : cB + (size_t)(t + 2) * kstep;
;             const char* a3 = a2 + kstep; const char* b3 = b2 + kstep;
;             if (last && has_next) S.a_ready(nxt);
;             if constexpr (SP2) {
;             PG8_LDB(B0, 0, 0); PG8_LDB(B1, 0, 1); PG8_SCHED; PG8_LDA(At, 0, 0); PG8_STAGE(PG8_SA(1, 1), a1 + hstepA, voffA);
;             PG8_WAIT_V(8); PG8_WAIT_L(0); PG8_BAR; PG8_MMA(0, 0, At, B0); PG8_MMA(0, 1, At, B1); PG8_BAR; PG8_SCHED;
;             PG8_LDA(At, 0, 1); PG8_STAGE(PG8_SB(0, 0), b2, voffB); PG8_STAGE(PG8_SB(0, 1), b2 + hstep, voffB); PG8_STAGE(PG8_SA(0, 0), a2, voffA);
;             PG8_WAIT_V(8); PG8_WAIT_L(0); PG8_BAR; PG8_MMA(1, 0, At, B0); PG8_MMA(1, 1, At, B1); PG8_BAR; PG8_SCHED;
.LBB0_1501:
	ds_read_b128 v[68:71], v196
	ds_read_b128 v[72:75], v196 offset:1024
	ds_read_b128 v[76:79], v196 offset:2048
	ds_read_b128 v[80:83], v196 offset:3072
	ds_read_b128 v[84:87], v197
	ds_read_b128 v[88:91], v197 offset:1024
	ds_read_b128 v[182:185], v197 offset:2048
	ds_read_b128 v[202:205], v197 offset:3072
	s_add_i32 s38, s14, 2
	s_add_u32 s39, s4, 0xffff0080
	s_addc_u32 s15, s5, -1
	s_cmp_eq_u32 s58, s14
	s_cselect_b32 s14, s35, s39
	s_cselect_b32 s15, s27, s15
	s_cselect_b32 s73, s29, s37
	s_cselect_b32 s72, s28, s36
	s_add_i32 m0, s47, 0xc000
	ds_read_b128 v[206:209], v198
	ds_read_b128 v[210:213], v198 offset:1024
	ds_read_b128 v[214:217], v198 offset:2048
	ds_read_b128 v[218:221], v198 offset:3072
	ds_read_b128 v[222:225], v198 offset:4096
	ds_read_b128 v[226:229], v198 offset:5120
	ds_read_b128 v[230:233], v198 offset:6144
	global_load_lds_dwordx4 v174, s[4:5]
	s_add_i32 m0, s47, 0xe000
	ds_read_b128 v[234:237], v198 offset:7168
	global_load_lds_dwordx4 v176, s[4:5]
	s_waitcnt vmcnt(8) lgkmcnt(0)
	s_barrier
	s_setprio 1
	v_mfma_f32_16x16x32_bf16 v[152:155], v[68:71], v[206:209], v[152:155]
	v_mfma_f32_16x16x32_bf16 v[148:151], v[76:79], v[206:209], v[148:151]
	v_mfma_f32_16x16x32_bf16 v[136:139], v[68:71], v[214:217], v[136:139]
	v_mfma_f32_16x16x32_bf16 v[132:135], v[76:79], v[214:217], v[132:135]
	v_mfma_f32_16x16x32_bf16 v[120:123], v[68:71], v[222:225], v[120:123]
	v_mfma_f32_16x16x32_bf16 v[116:119], v[76:79], v[222:225], v[116:119]
	v_mfma_f32_16x16x32_bf16 v[104:107], v[68:71], v[230:233], v[104:107]
	v_mfma_f32_16x16x32_bf16 v[100:103], v[76:79], v[230:233], v[100:103]
	v_mfma_f32_16x16x32_bf16 v[152:155], v[72:75], v[210:213], v[152:155]
	v_mfma_f32_16x16x32_bf16 v[148:151], v[80:83], v[210:213], v[148:151]
	v_mfma_f32_16x16x32_bf16 v[136:139], v[72:75], v[218:221], v[136:139]
	v_mfma_f32_16x16x32_bf16 v[132:135], v[80:83], v[218:221], v[132:135]
	v_mfma_f32_16x16x32_bf16 v[120:123], v[72:75], v[226:229], v[120:123]
	v_mfma_f32_16x16x32_bf16 v[116:119], v[80:83], v[226:229], v[116:119]
	v_mfma_f32_16x16x32_bf16 v[104:107], v[72:75], v[234:237], v[104:107]
	v_mfma_f32_16x16x32_bf16 v[100:103], v[80:83], v[234:237], v[100:103]
	v_mfma_f32_16x16x32_bf16 v[144:147], v[84:87], v[206:209], v[144:147]
	v_mfma_f32_16x16x32_bf16 v[140:143], v[182:185], v[206:209], v[140:143]
	v_mfma_f32_16x16x32_bf16 v[128:131], v[84:87], v[214:217], v[128:131]
	v_mfma_f32_16x16x32_bf16 v[124:127], v[182:185], v[214:217], v[124:127]
	v_mfma_f32_16x16x32_bf16 v[112:115], v[84:87], v[222:225], v[112:115]
	v_mfma_f32_16x16x32_bf16 v[108:111], v[182:185], v[222:225], v[108:111]
	v_mfma_f32_16x16x32_bf16 v[96:99], v[84:87], v[230:233], v[96:99]
	v_mfma_f32_16x16x32_bf16 v[92:95], v[182:185], v[230:233], v[92:95]
	v_mfma_f32_16x16x32_bf16 v[144:147], v[88:91], v[210:213], v[144:147]
	v_mfma_f32_16x16x32_bf16 v[140:143], v[202:205], v[210:213], v[140:143]
	v_mfma_f32_16x16x32_bf16 v[128:131], v[88:91], v[218:221], v[128:131]
	v_mfma_f32_16x16x32_bf16 v[124:127], v[202:205], v[218:221], v[124:127]
	v_mfma_f32_16x16x32_bf16 v[112:115], v[88:91], v[226:229], v[112:115]
	v_mfma_f32_16x16x32_bf16 v[108:111], v[202:205], v[226:229], v[108:111]
	v_mfma_f32_16x16x32_bf16 v[96:99], v[88:91], v[234:237], v[96:99]
	v_mfma_f32_16x16x32_bf16 v[92:95], v[202:205], v[234:237], v[92:95]
	s_setprio 0
	s_barrier
	s_add_i32 s39, s61, s45
	s_mov_b32 m0, s39
	ds_read_b128 v[206:209], v198 offset:16384
	ds_read_b128 v[210:213], v198 offset:17408
	ds_read_b128 v[214:217], v198 offset:18432
	ds_read_b128 v[218:221], v198 offset:19456
	global_load_lds_dwordx4 v156, s[72:73]
	s_add_i32 m0, s39, 0x2000
	s_mov_b64 s[100:101], s[72:73]
	s_add_i32 s39, s62, s45
	global_load_lds_dwordx4 v158, s[72:73]
	s_add_u32 s72, s72, s16
	s_addc_u32 s73, s73, s17
	s_mov_b32 m0, s39
	ds_read_b128 v[234:237], v198 offset:23552
	global_load_lds_dwordx4 v156, s[72:73]
	s_add_i32 m0, s39, 0x2000
	ds_read_b128 v[230:233], v198 offset:22528
	global_load_lds_dwordx4 v158, s[72:73]
	s_mov_b32 m0, s47
	ds_read_b128 v[226:229], v198 offset:21504
	global_load_lds_dwordx4 v160, s[14:15]
	s_mov_b32 m0, s48
	ds_read_b128 v[222:225], v198 offset:20480
	global_load_lds_dwordx4 v162, s[14:15]
	s_waitcnt vmcnt(8) lgkmcnt(0)
	s_barrier
	s_setprio 1
	v_mfma_f32_16x16x32_bf16 v[64:67], v[68:71], v[206:209], v[64:67]
	v_mfma_f32_16x16x32_bf16 v[60:63], v[76:79], v[206:209], v[60:63]
	v_mfma_f32_16x16x32_bf16 v[48:51], v[68:71], v[214:217], v[48:51]
	v_mfma_f32_16x16x32_bf16 v[44:47], v[76:79], v[214:217], v[44:47]
	v_mfma_f32_16x16x32_bf16 v[32:35], v[68:71], v[222:225], v[32:35]
	v_mfma_f32_16x16x32_bf16 v[28:31], v[76:79], v[222:225], v[28:31]
	v_mfma_f32_16x16x32_bf16 v[16:19], v[68:71], v[230:233], v[16:19]
	v_mfma_f32_16x16x32_bf16 v[12:15], v[76:79], v[230:233], v[12:15]
	v_mfma_f32_16x16x32_bf16 v[64:67], v[72:75], v[210:213], v[64:67]
	v_mfma_f32_16x16x32_bf16 v[60:63], v[80:83], v[210:213], v[60:63]
	v_mfma_f32_16x16x32_bf16 v[48:51], v[72:75], v[218:221], v[48:51]
	v_mfma_f32_16x16x32_bf16 v[44:47], v[80:83], v[218:221], v[44:47]
	v_mfma_f32_16x16x32_bf16 v[32:35], v[72:75], v[226:229], v[32:35]
	v_mfma_f32_16x16x32_bf16 v[28:31], v[80:83], v[226:229], v[28:31]
	v_mfma_f32_16x16x32_bf16 v[16:19], v[72:75], v[234:237], v[16:19]
	v_mfma_f32_16x16x32_bf16 v[12:15], v[80:83], v[234:237], v[12:15]
	v_mfma_f32_16x16x32_bf16 v[56:59], v[84:87], v[206:209], v[56:59]
	v_mfma_f32_16x16x32_bf16 v[52:55], v[182:185], v[206:209], v[52:55]
	v_mfma_f32_16x16x32_bf16 v[40:43], v[84:87], v[214:217], v[40:43]
	v_mfma_f32_16x16x32_bf16 v[36:39], v[182:185], v[214:217], v[36:39]
	v_mfma_f32_16x16x32_bf16 v[24:27], v[84:87], v[222:225], v[24:27]
	v_mfma_f32_16x16x32_bf16 v[20:23], v[182:185], v[222:225], v[20:23]
	v_mfma_f32_16x16x32_bf16 v[8:11], v[84:87], v[230:233], v[8:11]
	v_mfma_f32_16x16x32_bf16 v[4:7], v[182:185], v[230:233], v[4:7]
	v_mfma_f32_16x16x32_bf16 v[56:59], v[88:91], v[210:213], v[56:59]
	v_mfma_f32_16x16x32_bf16 v[52:55], v[202:205], v[210:213], v[52:55]
	v_mfma_f32_16x16x32_bf16 v[40:43], v[88:91], v[218:221], v[40:43]
	v_mfma_f32_16x16x32_bf16 v[36:39], v[202:205], v[218:221], v[36:39]
	v_mfma_f32_16x16x32_bf16 v[24:27], v[88:91], v[226:229], v[24:27]
	v_mfma_f32_16x16x32_bf16 v[20:23], v[202:205], v[226:229], v[20:23]
	v_mfma_f32_16x16x32_bf16 v[8:11], v[88:91], v[234:237], v[8:11]
	v_mfma_f32_16x16x32_bf16 v[4:7], v[202:205], v[234:237], v[4:7]
	s_setprio 0
	s_barrier
; #define PG8_STAGE(bufoff, gbase, voff) do { _Pragma("unroll") for (int _i = 0; _i < 2; ++_i) \
;         __builtin_amdgcn_global_load_lds((const unsigned*)((const char*)(gbase) + (voff)[_i]), (PG8_LAS unsigned*)(lds + (bufoff) + ldsw + _i * 8192), 16, 0, 0); } while (0)
; #define PG8_LDA(dst, b, h) do { _Pragma("unroll") for (int m = 0; m < 4; ++m) _Pragma("unroll") for (int k = 0; k < 2; ++k) dst[m][k] = *(const PG8_LAS bf16x8*)(lds + PG8_SA(b, h) + aoff + m * 2048 + k * 1024); } while (0)
; #define PG8_LDB(dst, b, h) do { _Pragma("unroll") for (int n = 0; n < 2; ++n) _Pragma("unroll") for (int k = 0; k < 2; ++k) dst[n][k] = *(const PG8_LAS bf16x8*)(lds + PG8_SB(b, h) + boff + n * 2048 + k * 1024); } while (0)
; #define PG8_MMA(ai, bj, At, Bt) do { __builtin_amdgcn_s_setprio(1); _Pragma("unroll") for (int m = 0; m < 4; ++m) _Pragma("unroll") for (int n = 0; n < 2; ++n) _Pragma("unroll") for (int k = 0; k < 2; ++k) \
;         acc[ai][bj][m][n] = __builtin_amdgcn_mfma_f32_16x16x32_bf16(Bt[n][k], At[m][k], acc[ai][bj][m][n], 0, 0, 0); __builtin_amdgcn_s_setprio(0); } while (0)
; #define PG8_WAIT_V(n) asm volatile("s_waitcnt vmcnt(" #n ")" ::: "memory")
; #define PG8_WAIT_L(n) asm volatile("s_waitcnt lgkmcnt(" #n ")" ::: "memory")
; #define PG8_BAR __builtin_amdgcn_s_barrier()
; template <class Epi, class Sched, bool ALIGN_EPI = false, bool SP2 = false>
; __device__ __forceinline__ void gemm_phase(PG8_LAS unsigned char* lds, const Gemm g, const Sched& S, const Epi& E) {
;     ...
;         for (int t = 0; t < nt; t += 2) {
;             const bool last = (t == nt - 2);
;             const char* a1 = cA + (size_t)(t + 1) * kstep;
;             const char* a2 = last ? nA : cA + (size_t)(t + 2) * kstep; const char* b2 = last ? nB : cB + (size_t)(t + 2) * kstep;
;             const char* a3 = a2 + kstep; const char* b3 = b2 + kstep;
;     ...
;             PG8_LDB(B0, 1, 0); PG8_LDB(B1, 1, 1); PG8_SCHED; PG8_LDA(At, 1, 0); PG8_STAGE(PG8_SA(0, 1), a2 + hstepA, voffA);
;             PG8_WAIT_V(8); PG8_WAIT_L(0); PG8_BAR; PG8_MMA(0, 0, At, B0); PG8_MMA(0, 1, At, B1); PG8_BAR; PG8_SCHED;
;             PG8_LDA(At, 1, 1); PG8_STAGE(PG8_SB(1, 0), b3, voffB); PG8_STAGE(PG8_SB(1, 1), b3 + hstep, voffB); PG8_STAGE(PG8_SA(1, 0), a3, voffA);
;             PG8_WAIT_V(8); PG8_WAIT_L(0); PG8_BAR; PG8_MMA(1, 0, At, B0); PG8_MMA(1, 1, At, B1); PG8_BAR; PG8_SCHED;
	s_add_i32 s39, 0, 0x18000
	s_add_i32 s71, 0, 0x1c000
	v_add_u32_e32 v80, s39, v191
	v_add_u32_e32 v164, s71, v191
	ds_read_b128 v[68:71], v80
	ds_read_b128 v[72:75], v80 offset:1024
	ds_read_b128 v[76:79], v80 offset:2048
	ds_read_b128 v[80:83], v80 offset:3072
	ds_read_b128 v[84:87], v164
	ds_read_b128 v[88:91], v164 offset:1024
	ds_read_b128 v[182:185], v164 offset:2048
	ds_read_b128 v[202:205], v164 offset:3072
	s_mov_b64 vcc, s[14:15]
	s_add_u32 s14, s14, 0x10000
	s_addc_u32 s15, s15, 0
	s_mov_b32 m0, s49
	ds_read_b128 v[206:209], v198 offset:32768
	ds_read_b128 v[210:213], v198 offset:33792
	ds_read_b128 v[214:217], v198 offset:34816
	ds_read_b128 v[218:221], v198 offset:35840
	ds_read_b128 v[222:225], v198 offset:36864
	ds_read_b128 v[226:229], v198 offset:37888
	ds_read_b128 v[230:233], v198 offset:38912
	global_load_lds_dwordx4 v160, s[14:15]
	s_mov_b32 m0, s50
	ds_read_b128 v[234:237], v198 offset:39936
	global_load_lds_dwordx4 v162, s[14:15]
	s_waitcnt vmcnt(8) lgkmcnt(0)
	s_barrier
	s_setprio 1
	v_mfma_f32_16x16x32_bf16 v[152:155], v[68:71], v[206:209], v[152:155]
	v_mfma_f32_16x16x32_bf16 v[148:151], v[76:79], v[206:209], v[148:151]
	v_mfma_f32_16x16x32_bf16 v[136:139], v[68:71], v[214:217], v[136:139]
	v_mfma_f32_16x16x32_bf16 v[132:135], v[76:79], v[214:217], v[132:135]
	v_mfma_f32_16x16x32_bf16 v[120:123], v[68:71], v[222:225], v[120:123]
	v_mfma_f32_16x16x32_bf16 v[116:119], v[76:79], v[222:225], v[116:119]
	v_mfma_f32_16x16x32_bf16 v[104:107], v[68:71], v[230:233], v[104:107]
	v_mfma_f32_16x16x32_bf16 v[100:103], v[76:79], v[230:233], v[100:103]
	v_mfma_f32_16x16x32_bf16 v[152:155], v[72:75], v[210:213], v[152:155]
	v_mfma_f32_16x16x32_bf16 v[148:151], v[80:83], v[210:213], v[148:151]
	v_mfma_f32_16x16x32_bf16 v[136:139], v[72:75], v[218:221], v[136:139]
	v_mfma_f32_16x16x32_bf16 v[132:135], v[80:83], v[218:221], v[132:135]
	v_mfma_f32_16x16x32_bf16 v[120:123], v[72:75], v[226:229], v[120:123]
	v_mfma_f32_16x16x32_bf16 v[116:119], v[80:83], v[226:229], v[116:119]
	v_mfma_f32_16x16x32_bf16 v[104:107], v[72:75], v[234:237], v[104:107]
	v_mfma_f32_16x16x32_bf16 v[100:103], v[80:83], v[234:237], v[100:103]
	v_mfma_f32_16x16x32_bf16 v[144:147], v[84:87], v[206:209], v[144:147]
	v_mfma_f32_16x16x32_bf16 v[140:143], v[182:185], v[206:209], v[140:143]
	v_mfma_f32_16x16x32_bf16 v[128:131], v[84:87], v[214:217], v[128:131]
	v_mfma_f32_16x16x32_bf16 v[124:127], v[182:185], v[214:217], v[124:127]
	v_mfma_f32_16x16x32_bf16 v[112:115], v[84:87], v[222:225], v[112:115]
	v_mfma_f32_16x16x32_bf16 v[108:111], v[182:185], v[222:225], v[108:111]
	v_mfma_f32_16x16x32_bf16 v[96:99], v[84:87], v[230:233], v[96:99]
	v_mfma_f32_16x16x32_bf16 v[92:95], v[182:185], v[230:233], v[92:95]
	v_mfma_f32_16x16x32_bf16 v[144:147], v[88:91], v[210:213], v[144:147]
	v_mfma_f32_16x16x32_bf16 v[140:143], v[202:205], v[210:213], v[140:143]
	v_mfma_f32_16x16x32_bf16 v[128:131], v[88:91], v[218:221], v[128:131]
	v_mfma_f32_16x16x32_bf16 v[124:127], v[202:205], v[218:221], v[124:127]
	v_mfma_f32_16x16x32_bf16 v[112:115], v[88:91], v[226:229], v[112:115]
	v_mfma_f32_16x16x32_bf16 v[108:111], v[202:205], v[226:229], v[108:111]
	v_mfma_f32_16x16x32_bf16 v[96:99], v[88:91], v[234:237], v[96:99]
	v_mfma_f32_16x16x32_bf16 v[92:95], v[202:205], v[234:237], v[92:95]
	s_setprio 0
	s_barrier
	s_add_i32 s14, s39, s45
	s_add_i32 m0, s14, 0xffffff80
	ds_read_b128 v[206:209], v198 offset:49152
	ds_read_b128 v[210:213], v198 offset:50176
	ds_read_b128 v[214:217], v198 offset:51200
	ds_read_b128 v[218:221], v198 offset:52224
	global_load_lds_dwordx4 v156, s[100:101] offset:128
	s_add_i32 m0, s14, 0x1f80
	s_add_i32 s14, s71, s45
	global_load_lds_dwordx4 v158, s[100:101] offset:128
	s_add_i32 m0, s14, 0xffffff80
	ds_read_b128 v[234:237], v198 offset:56320
	global_load_lds_dwordx4 v156, s[72:73] offset:128
	s_add_i32 m0, s14, 0x1f80
	ds_read_b128 v[230:233], v198 offset:55296
	global_load_lds_dwordx4 v158, s[72:73] offset:128
	s_add_i32 m0, s56, 0xffffff80
	ds_read_b128 v[226:229], v198 offset:54272
	global_load_lds_dwordx4 v160, vcc offset:128
	s_add_i32 m0, s57, 0xffffff80
	ds_read_b128 v[222:225], v198 offset:53248
	global_load_lds_dwordx4 v162, vcc offset:128
	s_waitcnt vmcnt(8) lgkmcnt(0)
	s_barrier
	s_setprio 1
	v_mfma_f32_16x16x32_bf16 v[64:67], v[68:71], v[206:209], v[64:67]
	v_mfma_f32_16x16x32_bf16 v[60:63], v[76:79], v[206:209], v[60:63]
	v_mfma_f32_16x16x32_bf16 v[48:51], v[68:71], v[214:217], v[48:51]
	v_mfma_f32_16x16x32_bf16 v[44:47], v[76:79], v[214:217], v[44:47]
	v_mfma_f32_16x16x32_bf16 v[32:35], v[68:71], v[222:225], v[32:35]
	v_mfma_f32_16x16x32_bf16 v[28:31], v[76:79], v[222:225], v[28:31]
	v_mfma_f32_16x16x32_bf16 v[16:19], v[68:71], v[230:233], v[16:19]
	v_mfma_f32_16x16x32_bf16 v[12:15], v[76:79], v[230:233], v[12:15]
	v_mfma_f32_16x16x32_bf16 v[64:67], v[72:75], v[210:213], v[64:67]
	v_mfma_f32_16x16x32_bf16 v[60:63], v[80:83], v[210:213], v[60:63]
	v_mfma_f32_16x16x32_bf16 v[48:51], v[72:75], v[218:221], v[48:51]
	v_mfma_f32_16x16x32_bf16 v[44:47], v[80:83], v[218:221], v[44:47]
	v_mfma_f32_16x16x32_bf16 v[32:35], v[72:75], v[226:229], v[32:35]
	v_mfma_f32_16x16x32_bf16 v[28:31], v[80:83], v[226:229], v[28:31]
	v_mfma_f32_16x16x32_bf16 v[16:19], v[72:75], v[234:237], v[16:19]
	v_mfma_f32_16x16x32_bf16 v[12:15], v[80:83], v[234:237], v[12:15]
	v_mfma_f32_16x16x32_bf16 v[56:59], v[84:87], v[206:209], v[56:59]
	v_mfma_f32_16x16x32_bf16 v[52:55], v[182:185], v[206:209], v[52:55]
	v_mfma_f32_16x16x32_bf16 v[40:43], v[84:87], v[214:217], v[40:43]
	v_mfma_f32_16x16x32_bf16 v[36:39], v[182:185], v[214:217], v[36:39]
	v_mfma_f32_16x16x32_bf16 v[24:27], v[84:87], v[222:225], v[24:27]
	v_mfma_f32_16x16x32_bf16 v[20:23], v[182:185], v[222:225], v[20:23]
	v_mfma_f32_16x16x32_bf16 v[8:11], v[84:87], v[230:233], v[8:11]
	v_mfma_f32_16x16x32_bf16 v[4:7], v[182:185], v[230:233], v[4:7]
	v_mfma_f32_16x16x32_bf16 v[56:59], v[88:91], v[210:213], v[56:59]
	v_mfma_f32_16x16x32_bf16 v[52:55], v[202:205], v[210:213], v[52:55]
	v_mfma_f32_16x16x32_bf16 v[40:43], v[88:91], v[218:221], v[40:43]
	v_mfma_f32_16x16x32_bf16 v[36:39], v[202:205], v[218:221], v[36:39]
	v_mfma_f32_16x16x32_bf16 v[24:27], v[88:91], v[226:229], v[24:27]
	v_mfma_f32_16x16x32_bf16 v[20:23], v[202:205], v[226:229], v[20:23]
	v_mfma_f32_16x16x32_bf16 v[8:11], v[88:91], v[234:237], v[8:11]
	v_mfma_f32_16x16x32_bf16 v[4:7], v[202:205], v[234:237], v[4:7]
	s_setprio 0
	s_barrier
	s_add_u32 s4, s4, 0x100
	s_addc_u32 s5, s5, 0
	s_add_u32 s36, s36, 0x100
	s_addc_u32 s37, s37, 0
	s_cmp_ge_i32 s38, s54
	s_mov_b32 s14, s38
	s_cbranch_scc0 .LBB0_1501

; template <bool SHIFT> __device__ __forceinline__ void attn_dense_body(const bf16* __restrict__ Qb, const bf16* __restrict__ Kh, const bf16* __restrict__ Vh, bf16* __restrict__ Ob, int seq, char* lds, LAS unsigned char* ldsl, float negB, const float* __restrict__ gq, int qpos0) {
;     ...
;   f32x16 pA0, pA1, pB0, pB1; bf16x8 pa0, pa1, pa2, pa3; const int NT = seq / KVBLK;
;   DMA(0, 0); asm volatile("s_waitcnt vmcnt(0)" ::: "memory"); __syncthreads();
;   DMA(1, KVBLK);
;   qkt<SHIFT ? 7 : 6>(pA0, pA1, K_lds, qr, r32, hi); partialSM(pA0);
;   asm volatile("s_waitcnt vmcnt(0)" ::: "memory"); __syncthreads();
;   int bv = 0, bk = 1, bw = 2;
.LBB0_1594:
	s_or_b64 exec, exec, s[4:5]
	v_readfirstlane_b32 s60, v109
	s_add_u32 s56, s10, s50
	s_addc_u32 s57, s11, s51
	s_lshl_b32 s60, s60, 11
	s_add_u32 s56, s56, 0x12c00000
	s_addc_u32 s57, s57, 0
	s_add_u32 s58, s10, s52
	s_addc_u32 s59, s11, s53
	s_add_u32 s58, s58, 0x1bc00000
	s_addc_u32 s59, s59, 0
	v_add_u32_e32 v134, 0xc000, v115
	s_add_i32 m0, s60, 0x0
	s_nop 0
	global_load_lds_dwordx4 v124, s[56:57]
	global_load_lds_dwordx4 v126, s[56:57] offset:1024
	s_add_u32 s56, s56, 0x4000
	s_addc_u32 s57, s57, 0
	s_add_i32 m0, s60, 0x4000
	s_nop 0
	global_load_lds_dwordx4 v124, s[56:57]
	global_load_lds_dwordx4 v126, s[56:57] offset:1024
	s_add_u32 s56, s56, 0x4000
	s_addc_u32 s57, s57, 0
	s_add_i32 m0, s60, 0xc000
	s_nop 0
	global_load_lds_dwordx4 v128, s[58:59]
	s_add_u32 s58, s58, 0x2000
	s_addc_u32 s59, s59, 0
	s_add_i32 m0, s60, 0x8000
	s_nop 0
	global_load_lds_dwordx4 v124, s[56:57]
	global_load_lds_dwordx4 v126, s[56:57] offset:1024
	s_add_u32 s56, s56, 0x4000
	s_addc_u32 s57, s57, 0
	s_add_i32 m0, s60, 0x10000
	s_nop 0
	global_load_lds_dwordx4 v128, s[58:59]
	s_add_u32 s58, s58, 0x2000
	s_addc_u32 s59, s59, 0
	v_mov_b32_e32 v0, 0
	v_mov_b32_e32 v1, 0
	v_mov_b32_e32 v2, 0
	v_mov_b32_e32 v3, 0
	v_mov_b32_e32 v4, 0
	v_mov_b32_e32 v5, 0
	v_mov_b32_e32 v6, 0
	v_mov_b32_e32 v7, 0
	v_mov_b32_e32 v8, 0
	v_mov_b32_e32 v9, 0
	v_mov_b32_e32 v10, 0
	v_mov_b32_e32 v11, 0
	v_mov_b32_e32 v12, 0
	v_mov_b32_e32 v13, 0
	v_mov_b32_e32 v14, 0
	v_mov_b32_e32 v15, 0
	v_mov_b32_e32 v16, 0
	v_mov_b32_e32 v17, 0
	v_mov_b32_e32 v18, 0
	v_mov_b32_e32 v19, 0
	v_mov_b32_e32 v20, 0
	v_mov_b32_e32 v21, 0
	v_mov_b32_e32 v22, 0
	v_mov_b32_e32 v23, 0
	v_mov_b32_e32 v24, 0
	v_mov_b32_e32 v25, 0
	v_mov_b32_e32 v26, 0
	v_mov_b32_e32 v27, 0
	v_mov_b32_e32 v28, 0
	v_mov_b32_e32 v29, 0
	v_mov_b32_e32 v30, 0
	v_mov_b32_e32 v31, 0
	v_mov_b32_e32 v133, 0
	v_mov_b32_e32 v135, 0
	s_waitcnt vmcnt(6)
	s_barrier
	ds_read_b128 v[156:159], v146 offset:0
	ds_read_b128 v[160:163], v146 offset:8192
	ds_read_b128 v[164:167], v147 offset:0
	ds_read_b128 v[168:171], v147 offset:8192
	ds_read_b128 v[172:175], v148 offset:0
	ds_read_b128 v[176:179], v148 offset:8192
	ds_read_b128 v[180:183], v149 offset:0
	ds_read_b128 v[184:187], v149 offset:8192
	ds_read_b128 v[64:67], v150 offset:0
	ds_read_b128 v[68:71], v150 offset:8192
	ds_read_b128 v[72:75], v151 offset:0
	ds_read_b128 v[76:79], v151 offset:8192
	s_waitcnt lgkmcnt(0)
	v_mfma_f32_32x32x16_bf16 v[32:47], v[156:159], v[86:89], 0
	v_mfma_f32_32x32x16_bf16 v[48:63], v[160:163], v[86:89], 0
	v_mfma_f32_32x32x16_bf16 v[32:47], v[164:167], v[82:85], v[32:47]
	v_mfma_f32_32x32x16_bf16 v[48:63], v[168:171], v[82:85], v[48:63]
	v_mfma_f32_32x32x16_bf16 v[32:47], v[172:175], v[90:93], v[32:47]
	v_mfma_f32_32x32x16_bf16 v[48:63], v[176:179], v[90:93], v[48:63]
	v_mfma_f32_32x32x16_bf16 v[32:47], v[180:183], v[94:97], v[32:47]
	v_mfma_f32_32x32x16_bf16 v[48:63], v[184:187], v[94:97], v[48:63]
	v_mfma_f32_32x32x16_bf16 v[32:47], v[64:67], v[98:101], v[32:47]
	v_mfma_f32_32x32x16_bf16 v[48:63], v[68:71], v[98:101], v[48:63]
	v_mfma_f32_32x32x16_bf16 v[32:47], v[72:75], v[102:105], v[32:47]
	v_mfma_f32_32x32x16_bf16 v[48:63], v[76:79], v[102:105], v[48:63]
	s_waitcnt vmcnt(3) lgkmcnt(0)
	s_barrier
	ds_read_b128 v[156:159], v146 offset:16384
	ds_read_b128 v[160:163], v146 offset:24576
	ds_read_b128 v[164:167], v147 offset:16384
	ds_read_b128 v[168:171], v147 offset:24576
	ds_read_b128 v[172:175], v148 offset:16384
	ds_read_b128 v[176:179], v148 offset:24576
	ds_read_b128 v[180:183], v149 offset:16384
	ds_read_b128 v[184:187], v149 offset:24576
	ds_read_b128 v[64:67], v150 offset:16384
	ds_read_b128 v[68:71], v150 offset:24576
	ds_read_b128 v[72:75], v151 offset:16384
	ds_read_b128 v[76:79], v151 offset:24576
	v_exp_f32_e32 v32, v32
	v_exp_f32_e32 v33, v33
	v_exp_f32_e32 v34, v34
	v_exp_f32_e32 v35, v35
	v_exp_f32_e32 v36, v36
	v_exp_f32_e32 v37, v37
	v_exp_f32_e32 v38, v38
	v_exp_f32_e32 v39, v39
	v_exp_f32_e32 v40, v40
	v_exp_f32_e32 v41, v41
	v_exp_f32_e32 v42, v42
	v_exp_f32_e32 v43, v43
	v_exp_f32_e32 v44, v44
	v_exp_f32_e32 v45, v45
	v_exp_f32_e32 v46, v46
	v_exp_f32_e32 v47, v47
	s_add_i32 m0, s60, 0x0
	s_nop 0
	global_load_lds_dwordx4 v124, s[56:57]
	global_load_lds_dwordx4 v126, s[56:57] offset:1024
	s_add_u32 s56, s56, 0x4000
	s_addc_u32 s57, s57, 0
	s_add_i32 m0, s60, 0x14000
	s_nop 0
	global_load_lds_dwordx4 v128, s[58:59]
	s_add_u32 s58, s58, 0x2000
	s_addc_u32 s59, s59, 0
	s_mov_b32 s33, 10
; #define SBAR() __builtin_amdgcn_sched_barrier(0)
; #define ROT() do { const int t_ = bv; bv = bk; bk = bw; bw = t_; } while (0)
; __device__ __forceinline__ void partialSM(f32x16& p0) {
; #pragma unroll
;   for (int r = 0; r < 16; ++r) p0[r] = __builtin_amdgcn_exp2f(p0[r]);
; }
; __device__ __forceinline__ void finishSM(f32x16& p0, f32x16& p1, float& l_reg, bf16x8& pa0, bf16x8& pa1, bf16x8& pa2, bf16x8& pa3) {
; #pragma unroll
;   for (int r = 0; r < 16; ++r) p1[r] = __builtin_amdgcn_exp2f(p1[r]);
;   float ps = 0;
; #pragma unroll
;   for (int r = 0; r < 16; ++r) ps += p0[r];
; #pragma unroll
;   for (int r = 0; r < 16; ++r) ps += p1[r];
;   l_reg += ps;
;     ...
;   PK4(p0, 0, pa0); PK4(p0, 8, pa1); PK4(p1, 0, pa2); PK4(p1, 8, pa3);
;     ...
; }
; template <int ND> __device__ __forceinline__ void qkt(f32x16& p0, f32x16& p1, const bf16* Ks, const bf16x8* qr, int r32, int hi) {
;   p0 = f32x16{}; p1 = f32x16{};
; #pragma unroll
;   for (int d0 = 0; d0 < ND; ++d0) { int cb = (d0 * 16 + hi * 8) * 2;
;     bf16x8 b0 = *reinterpret_cast<const bf16x8*>((const char*)Ks + KSWZ(r32, cb));
;     bf16x8 b1 = *reinterpret_cast<const bf16x8*>((const char*)Ks + KSWZ(32 + r32, cb));
;     p0 = __builtin_amdgcn_mfma_f32_32x32x16_bf16(b0, qr[d0], p0, 0, 0, 0);
;     p1 = __builtin_amdgcn_mfma_f32_32x32x16_bf16(b1, qr[d0], p1, 0, 0, 0); }
; }
; template <bool SHIFT> __device__ __forceinline__ void attn_dense_body(const bf16* __restrict__ Qb, const bf16* __restrict__ Kh, const bf16* __restrict__ Vh, bf16* __restrict__ Ob, int seq, char* lds, LAS unsigned char* ldsl, float negB, const float* __restrict__ gq, int qpos0) {
;     ...
;   for (int j = 1; j + 1 < NT; j += 2) {
;     DMA(bw, (j + 1) * KVBLK);
;     SBAR(); qkt<SHIFT ? 7 : 6>(pB0, pB1, (bf16*)((char*)K_lds + bk * SHM_K), qr, r32, hi);
;     finishSM(pA0, pA1, l_reg, pa0, pa1, pa2, pa3); SBAR();
;     pv_d0(o, vb0 + bv * (int)SHM_V, pa0, pa1, pa2, pa3); partialSM(pB0);
;     asm volatile("s_waitcnt vmcnt(0)" ::: "memory"); __syncthreads(); ROT();
;     DMA(bw, (j + 2) * KVBLK);
;     SBAR(); qkt<SHIFT ? 7 : 6>(pA0, pA1, (bf16*)((char*)K_lds + bk * SHM_K), qr, r32, hi);
;     finishSM(pB0, pB1, l_reg, pa0, pa1, pa2, pa3); SBAR();
;     pv_d0(o, vb0 + bv * (int)SHM_V, pa0, pa1, pa2, pa3); partialSM(pA0);
;     asm volatile("s_waitcnt vmcnt(0)" ::: "memory"); __syncthreads(); ROT();
;   }
.Latt_loop:
	s_waitcnt lgkmcnt(0)
	ds_read_b64_tr_b16 v[222:223], v134 offset:0
	ds_read_b64_tr_b16 v[224:225], v134 offset:2048
	ds_read_b64_tr_b16 v[226:227], v134 offset:4096
	ds_read_b64_tr_b16 v[228:229], v134 offset:6144
	ds_read_b64_tr_b16 v[230:231], v134 offset:8192
	ds_read_b64_tr_b16 v[232:233], v134 offset:10240
	ds_read_b64_tr_b16 v[234:235], v134 offset:12288
	ds_read_b64_tr_b16 v[236:237], v134 offset:14336
	v_mfma_f32_32x32x16_bf16 v[190:205], v[156:159], v[86:89], 0
	v_exp_f32_e32 v48, v48
	v_add_f32_e32 v133, v133, v32
	v_exp_f32_e32 v49, v49
	v_add_f32_e32 v135, v135, v33
	v_exp_f32_e32 v50, v50
	v_mfma_f32_32x32x16_bf16 v[206:221], v[160:163], v[86:89], 0
	v_add_f32_e32 v133, v133, v34
	v_exp_f32_e32 v51, v51
	v_add_f32_e32 v135, v135, v35
	v_exp_f32_e32 v52, v52
	v_add_f32_e32 v133, v133, v36
	v_mfma_f32_32x32x16_bf16 v[190:205], v[164:167], v[82:85], v[190:205]
	v_exp_f32_e32 v53, v53
	v_add_f32_e32 v135, v135, v37
	v_exp_f32_e32 v54, v54
	v_add_f32_e32 v133, v133, v38
	v_exp_f32_e32 v55, v55
	v_add_f32_e32 v135, v135, v39
	v_mfma_f32_32x32x16_bf16 v[206:221], v[168:171], v[82:85], v[206:221]
	s_waitcnt lgkmcnt(7)
	ds_read_b64_tr_b16 v[238:239], v134 offset:512
	ds_read_b64_tr_b16 v[240:241], v134 offset:2560
	ds_read_b64_tr_b16 v[242:243], v134 offset:4608
	ds_read_b64_tr_b16 v[244:245], v134 offset:6656
	ds_read_b64_tr_b16 v[246:247], v134 offset:8704
	ds_read_b64_tr_b16 v[248:249], v134 offset:10752
	ds_read_b64_tr_b16 v[140:141], v134 offset:12800
	ds_read_b64_tr_b16 v[142:143], v134 offset:14848
	v_exp_f32_e32 v56, v56
	v_add_f32_e32 v133, v133, v40
	v_exp_f32_e32 v57, v57
	v_add_f32_e32 v135, v135, v41
	v_exp_f32_e32 v58, v58
	v_mfma_f32_32x32x16_bf16 v[190:205], v[172:175], v[90:93], v[190:205]
	v_add_f32_e32 v133, v133, v42
	v_exp_f32_e32 v59, v59
	v_add_f32_e32 v135, v135, v43
	v_exp_f32_e32 v60, v60
	v_add_f32_e32 v133, v133, v44
	v_mfma_f32_32x32x16_bf16 v[206:221], v[176:179], v[90:93], v[206:221]
	v_exp_f32_e32 v61, v61
	v_add_f32_e32 v135, v135, v45
	v_exp_f32_e32 v62, v62
	v_add_f32_e32 v133, v133, v46
	v_exp_f32_e32 v63, v63
	v_add_f32_e32 v135, v135, v47
	v_mfma_f32_32x32x16_bf16 v[190:205], v[180:183], v[94:97], v[190:205]
	v_add_f32_e32 v133, v133, v48
	v_add_f32_e32 v135, v135, v49
	v_add_f32_e32 v133, v133, v50
	v_add_f32_e32 v135, v135, v51
	v_add_f32_e32 v133, v133, v52
	v_mfma_f32_32x32x16_bf16 v[206:221], v[184:187], v[94:97], v[206:221]
	v_add_f32_e32 v135, v135, v53
	v_add_f32_e32 v133, v133, v54
	v_add_f32_e32 v135, v135, v55
	v_add_f32_e32 v133, v133, v56
	v_add_f32_e32 v135, v135, v57
	v_mfma_f32_32x32x16_bf16 v[190:205], v[64:67], v[98:101], v[190:205]
	v_add_f32_e32 v133, v133, v58
	v_add_f32_e32 v135, v135, v59
	v_add_f32_e32 v133, v133, v60
	v_add_f32_e32 v135, v135, v61
	v_add_f32_e32 v133, v133, v62
	v_add_f32_e32 v135, v135, v63
	v_mfma_f32_32x32x16_bf16 v[206:221], v[68:71], v[98:101], v[206:221]
	v_cvt_pk_bf16_f32 v32, v32, v33
	v_cvt_pk_bf16_f32 v33, v34, v35
	v_cvt_pk_bf16_f32 v34, v36, v37
	v_cvt_pk_bf16_f32 v35, v38, v39
	v_cvt_pk_bf16_f32 v36, v40, v41
	v_mfma_f32_32x32x16_bf16 v[190:205], v[72:75], v[102:105], v[190:205]
	v_cvt_pk_bf16_f32 v37, v42, v43
	v_cvt_pk_bf16_f32 v38, v44, v45
	v_cvt_pk_bf16_f32 v39, v46, v47
	v_cvt_pk_bf16_f32 v48, v48, v49
	v_cvt_pk_bf16_f32 v49, v50, v51
	v_mfma_f32_32x32x16_bf16 v[206:221], v[76:79], v[102:105], v[206:221]
	v_cvt_pk_bf16_f32 v50, v52, v53
	v_cvt_pk_bf16_f32 v51, v54, v55
	v_cvt_pk_bf16_f32 v52, v56, v57
	v_cvt_pk_bf16_f32 v53, v58, v59
	v_cvt_pk_bf16_f32 v54, v60, v61
	v_cvt_pk_bf16_f32 v55, v62, v63
	s_waitcnt vmcnt(3) lgkmcnt(0)
	s_barrier
	ds_read_b128 v[156:159], v146 offset:32768
	ds_read_b128 v[160:163], v146 offset:40960
	ds_read_b128 v[164:167], v147 offset:32768
	ds_read_b128 v[168:171], v147 offset:40960
	ds_read_b128 v[172:175], v148 offset:32768
	ds_read_b128 v[176:179], v148 offset:40960
	ds_read_b128 v[180:183], v149 offset:32768
	ds_read_b128 v[184:187], v149 offset:40960
	ds_read_b128 v[64:67], v150 offset:32768
	ds_read_b128 v[68:71], v150 offset:40960
	ds_read_b128 v[72:75], v151 offset:32768
	ds_read_b128 v[76:79], v151 offset:40960
	v_mfma_f32_32x32x16_bf16 v[0:15], v[32:35], v[222:225], v[0:15]
	s_add_i32 m0, s60, 0x4000
	v_exp_f32_e32 v190, v190
	v_exp_f32_e32 v191, v191
	v_mfma_f32_32x32x16_bf16 v[0:15], v[36:39], v[226:229], v[0:15]
	global_load_lds_dwordx4 v124, s[56:57]
	global_load_lds_dwordx4 v126, s[56:57] offset:1024
	v_exp_f32_e32 v192, v192
	v_exp_f32_e32 v193, v193
	v_mfma_f32_32x32x16_bf16 v[0:15], v[48:51], v[230:233], v[0:15]
	s_add_u32 s56, s56, 0x4000
	s_addc_u32 s57, s57, 0
	v_exp_f32_e32 v194, v194
	v_exp_f32_e32 v195, v195
	v_mfma_f32_32x32x16_bf16 v[0:15], v[52:55], v[234:237], v[0:15]
	s_add_i32 m0, s60, 0xc000
	v_exp_f32_e32 v196, v196
	v_exp_f32_e32 v197, v197
	v_mfma_f32_32x32x16_bf16 v[16:31], v[32:35], v[238:241], v[16:31]
	global_load_lds_dwordx4 v128, s[58:59]
	v_exp_f32_e32 v198, v198
	v_exp_f32_e32 v199, v199
	v_mfma_f32_32x32x16_bf16 v[16:31], v[36:39], v[242:245], v[16:31]
	s_add_u32 s58, s58, 0x2000
	s_addc_u32 s59, s59, 0
	v_exp_f32_e32 v200, v200
	v_exp_f32_e32 v201, v201
	v_mfma_f32_32x32x16_bf16 v[16:31], v[48:51], v[246:249], v[16:31]
	v_exp_f32_e32 v202, v202
	v_exp_f32_e32 v203, v203
	v_mfma_f32_32x32x16_bf16 v[16:31], v[52:55], v[140:143], v[16:31]
	v_exp_f32_e32 v204, v204
	v_exp_f32_e32 v205, v205
	s_waitcnt lgkmcnt(0)
; #define SBAR() __builtin_amdgcn_sched_barrier(0)
; #define ROT() do { const int t_ = bv; bv = bk; bk = bw; bw = t_; } while (0)
; __device__ __forceinline__ void partialSM(f32x16& p0) {
; #pragma unroll
;   for (int r = 0; r < 16; ++r) p0[r] = __builtin_amdgcn_exp2f(p0[r]);
; }
; __device__ __forceinline__ void finishSM(f32x16& p0, f32x16& p1, float& l_reg, bf16x8& pa0, bf16x8& pa1, bf16x8& pa2, bf16x8& pa3) {
; #pragma unroll
;   for (int r = 0; r < 16; ++r) p1[r] = __builtin_amdgcn_exp2f(p1[r]);
;   float ps = 0;
; #pragma unroll
;   for (int r = 0; r < 16; ++r) ps += p0[r];
; #pragma unroll
;   for (int r = 0; r < 16; ++r) ps += p1[r];
;   l_reg += ps;
;     ...
;   PK4(p0, 0, pa0); PK4(p0, 8, pa1); PK4(p1, 0, pa2); PK4(p1, 8, pa3);
;     ...
; }
; template <int ND> __device__ __forceinline__ void qkt(f32x16& p0, f32x16& p1, const bf16* Ks, const bf16x8* qr, int r32, int hi) {
;   p0 = f32x16{}; p1 = f32x16{};
; #pragma unroll
;   for (int d0 = 0; d0 < ND; ++d0) { int cb = (d0 * 16 + hi * 8) * 2;
;     bf16x8 b0 = *reinterpret_cast<const bf16x8*>((const char*)Ks + KSWZ(r32, cb));
;     bf16x8 b1 = *reinterpret_cast<const bf16x8*>((const char*)Ks + KSWZ(32 + r32, cb));
;     p0 = __builtin_amdgcn_mfma_f32_32x32x16_bf16(b0, qr[d0], p0, 0, 0, 0);
;     p1 = __builtin_amdgcn_mfma_f32_32x32x16_bf16(b1, qr[d0], p1, 0, 0, 0); }
; }
; template <bool SHIFT> __device__ __forceinline__ void attn_dense_body(const bf16* __restrict__ Qb, const bf16* __restrict__ Kh, const bf16* __restrict__ Vh, bf16* __restrict__ Ob, int seq, char* lds, LAS unsigned char* ldsl, float negB, const float* __restrict__ gq, int qpos0) {
;     ...
;   for (int j = 1; j + 1 < NT; j += 2) {
;     DMA(bw, (j + 1) * KVBLK);
;     SBAR(); qkt<SHIFT ? 7 : 6>(pB0, pB1, (bf16*)((char*)K_lds + bk * SHM_K), qr, r32, hi);
;     finishSM(pA0, pA1, l_reg, pa0, pa1, pa2, pa3); SBAR();
;     pv_d0(o, vb0 + bv * (int)SHM_V, pa0, pa1, pa2, pa3); partialSM(pB0);
;     asm volatile("s_waitcnt vmcnt(0)" ::: "memory"); __syncthreads(); ROT();
;     DMA(bw, (j + 2) * KVBLK);
;     SBAR(); qkt<SHIFT ? 7 : 6>(pA0, pA1, (bf16*)((char*)K_lds + bk * SHM_K), qr, r32, hi);
;     finishSM(pB0, pB1, l_reg, pa0, pa1, pa2, pa3); SBAR();
;     pv_d0(o, vb0 + bv * (int)SHM_V, pa0, pa1, pa2, pa3); partialSM(pA0);
;     asm volatile("s_waitcnt vmcnt(0)" ::: "memory"); __syncthreads(); ROT();
;   }
	ds_read_b64_tr_b16 v[222:223], v134 offset:16384
	ds_read_b64_tr_b16 v[224:225], v134 offset:18432
	ds_read_b64_tr_b16 v[226:227], v134 offset:20480
	ds_read_b64_tr_b16 v[228:229], v134 offset:22528
	ds_read_b64_tr_b16 v[230:231], v134 offset:24576
	ds_read_b64_tr_b16 v[232:233], v134 offset:26624
	ds_read_b64_tr_b16 v[234:235], v134 offset:28672
	ds_read_b64_tr_b16 v[236:237], v134 offset:30720
	v_mfma_f32_32x32x16_bf16 v[32:47], v[156:159], v[86:89], 0
	v_exp_f32_e32 v206, v206
	v_add_f32_e32 v133, v133, v190
	v_exp_f32_e32 v207, v207
	v_add_f32_e32 v135, v135, v191
	v_exp_f32_e32 v208, v208
	v_mfma_f32_32x32x16_bf16 v[48:63], v[160:163], v[86:89], 0
	v_add_f32_e32 v133, v133, v192
	v_exp_f32_e32 v209, v209
	v_add_f32_e32 v135, v135, v193
	v_exp_f32_e32 v210, v210
	v_add_f32_e32 v133, v133, v194
	v_mfma_f32_32x32x16_bf16 v[32:47], v[164:167], v[82:85], v[32:47]
	v_exp_f32_e32 v211, v211
	v_add_f32_e32 v135, v135, v195
	v_exp_f32_e32 v212, v212
	v_add_f32_e32 v133, v133, v196
	v_exp_f32_e32 v213, v213
	v_add_f32_e32 v135, v135, v197
	v_mfma_f32_32x32x16_bf16 v[48:63], v[168:171], v[82:85], v[48:63]
	s_waitcnt lgkmcnt(7)
	ds_read_b64_tr_b16 v[238:239], v134 offset:16896
	ds_read_b64_tr_b16 v[240:241], v134 offset:18944
	ds_read_b64_tr_b16 v[242:243], v134 offset:20992
	ds_read_b64_tr_b16 v[244:245], v134 offset:23040
	ds_read_b64_tr_b16 v[246:247], v134 offset:25088
	ds_read_b64_tr_b16 v[248:249], v134 offset:27136
	ds_read_b64_tr_b16 v[140:141], v134 offset:29184
	ds_read_b64_tr_b16 v[142:143], v134 offset:31232
	v_exp_f32_e32 v214, v214
	v_add_f32_e32 v133, v133, v198
	v_exp_f32_e32 v215, v215
	v_add_f32_e32 v135, v135, v199
	v_exp_f32_e32 v216, v216
	v_mfma_f32_32x32x16_bf16 v[32:47], v[172:175], v[90:93], v[32:47]
	v_add_f32_e32 v133, v133, v200
	v_exp_f32_e32 v217, v217
	v_add_f32_e32 v135, v135, v201
	v_exp_f32_e32 v218, v218
	v_add_f32_e32 v133, v133, v202
	v_mfma_f32_32x32x16_bf16 v[48:63], v[176:179], v[90:93], v[48:63]
	v_exp_f32_e32 v219, v219
	v_add_f32_e32 v135, v135, v203
	v_exp_f32_e32 v220, v220
	v_add_f32_e32 v133, v133, v204
	v_exp_f32_e32 v221, v221
	v_add_f32_e32 v135, v135, v205
	v_mfma_f32_32x32x16_bf16 v[32:47], v[180:183], v[94:97], v[32:47]
	v_add_f32_e32 v133, v133, v206
	v_add_f32_e32 v135, v135, v207
	v_add_f32_e32 v133, v133, v208
	v_add_f32_e32 v135, v135, v209
	v_add_f32_e32 v133, v133, v210
	v_mfma_f32_32x32x16_bf16 v[48:63], v[184:187], v[94:97], v[48:63]
	v_add_f32_e32 v135, v135, v211
	v_add_f32_e32 v133, v133, v212
	v_add_f32_e32 v135, v135, v213
	v_add_f32_e32 v133, v133, v214
	v_add_f32_e32 v135, v135, v215
	v_mfma_f32_32x32x16_bf16 v[32:47], v[64:67], v[98:101], v[32:47]
	v_add_f32_e32 v133, v133, v216
	v_add_f32_e32 v135, v135, v217
	v_add_f32_e32 v133, v133, v218
	v_add_f32_e32 v135, v135, v219
	v_add_f32_e32 v133, v133, v220
	v_add_f32_e32 v135, v135, v221
	v_mfma_f32_32x32x16_bf16 v[48:63], v[68:71], v[98:101], v[48:63]
	v_cvt_pk_bf16_f32 v190, v190, v191
	v_cvt_pk_bf16_f32 v191, v192, v193
	v_cvt_pk_bf16_f32 v192, v194, v195
	v_cvt_pk_bf16_f32 v193, v196, v197
	v_cvt_pk_bf16_f32 v194, v198, v199
	v_mfma_f32_32x32x16_bf16 v[32:47], v[72:75], v[102:105], v[32:47]
	v_cvt_pk_bf16_f32 v195, v200, v201
	v_cvt_pk_bf16_f32 v196, v202, v203
	v_cvt_pk_bf16_f32 v197, v204, v205
	v_cvt_pk_bf16_f32 v206, v206, v207
	v_cvt_pk_bf16_f32 v207, v208, v209
	v_mfma_f32_32x32x16_bf16 v[48:63], v[76:79], v[102:105], v[48:63]
	v_cvt_pk_bf16_f32 v208, v210, v211
	v_cvt_pk_bf16_f32 v209, v212, v213
	v_cvt_pk_bf16_f32 v210, v214, v215
	v_cvt_pk_bf16_f32 v211, v216, v217
	v_cvt_pk_bf16_f32 v212, v218, v219
	v_cvt_pk_bf16_f32 v213, v220, v221
	s_waitcnt vmcnt(3) lgkmcnt(0)
	s_barrier
	ds_read_b128 v[156:159], v146 offset:0
	ds_read_b128 v[160:163], v146 offset:8192
	ds_read_b128 v[164:167], v147 offset:0
	ds_read_b128 v[168:171], v147 offset:8192
	ds_read_b128 v[172:175], v148 offset:0
	ds_read_b128 v[176:179], v148 offset:8192
	ds_read_b128 v[180:183], v149 offset:0
	ds_read_b128 v[184:187], v149 offset:8192
	ds_read_b128 v[64:67], v150 offset:0
	ds_read_b128 v[68:71], v150 offset:8192
	ds_read_b128 v[72:75], v151 offset:0
	ds_read_b128 v[76:79], v151 offset:8192
	v_mfma_f32_32x32x16_bf16 v[0:15], v[190:193], v[222:225], v[0:15]
	s_add_i32 m0, s60, 0x8000
	v_exp_f32_e32 v32, v32
	v_exp_f32_e32 v33, v33
	v_mfma_f32_32x32x16_bf16 v[0:15], v[194:197], v[226:229], v[0:15]
	global_load_lds_dwordx4 v124, s[56:57]
	global_load_lds_dwordx4 v126, s[56:57] offset:1024
	v_exp_f32_e32 v34, v34
	v_exp_f32_e32 v35, v35
	v_mfma_f32_32x32x16_bf16 v[0:15], v[206:209], v[230:233], v[0:15]
	s_add_u32 s56, s56, 0x4000
	s_addc_u32 s57, s57, 0
	v_exp_f32_e32 v36, v36
	v_exp_f32_e32 v37, v37
	v_mfma_f32_32x32x16_bf16 v[0:15], v[210:213], v[234:237], v[0:15]
	s_add_i32 m0, s60, 0x10000
	v_exp_f32_e32 v38, v38
	v_exp_f32_e32 v39, v39
	v_mfma_f32_32x32x16_bf16 v[16:31], v[190:193], v[238:241], v[16:31]
	global_load_lds_dwordx4 v128, s[58:59]
	v_exp_f32_e32 v40, v40
	v_exp_f32_e32 v41, v41
	v_mfma_f32_32x32x16_bf16 v[16:31], v[194:197], v[242:245], v[16:31]
	s_add_u32 s58, s58, 0x2000
	s_addc_u32 s59, s59, 0
	v_exp_f32_e32 v42, v42
	v_exp_f32_e32 v43, v43
	v_mfma_f32_32x32x16_bf16 v[16:31], v[206:209], v[246:249], v[16:31]
	v_exp_f32_e32 v44, v44
	v_exp_f32_e32 v45, v45
	v_mfma_f32_32x32x16_bf16 v[16:31], v[210:213], v[140:143], v[16:31]
	v_exp_f32_e32 v46, v46
	v_exp_f32_e32 v47, v47
	s_waitcnt lgkmcnt(0)
; #define SBAR() __builtin_amdgcn_sched_barrier(0)
; #define ROT() do { const int t_ = bv; bv = bk; bk = bw; bw = t_; } while (0)
; __device__ __forceinline__ void partialSM(f32x16& p0) {
; #pragma unroll
;   for (int r = 0; r < 16; ++r) p0[r] = __builtin_amdgcn_exp2f(p0[r]);
; }
; __device__ __forceinline__ void finishSM(f32x16& p0, f32x16& p1, float& l_reg, bf16x8& pa0, bf16x8& pa1, bf16x8& pa2, bf16x8& pa3) {
; #pragma unroll
;   for (int r = 0; r < 16; ++r) p1[r] = __builtin_amdgcn_exp2f(p1[r]);
;   float ps = 0;
; #pragma unroll
;   for (int r = 0; r < 16; ++r) ps += p0[r];
; #pragma unroll
;   for (int r = 0; r < 16; ++r) ps += p1[r];
;   l_reg += ps;
;     ...
;   PK4(p0, 0, pa0); PK4(p0, 8, pa1); PK4(p1, 0, pa2); PK4(p1, 8, pa3);
;     ...
; }
; template <int ND> __device__ __forceinline__ void qkt(f32x16& p0, f32x16& p1, const bf16* Ks, const bf16x8* qr, int r32, int hi) {
;   p0 = f32x16{}; p1 = f32x16{};
; #pragma unroll
;   for (int d0 = 0; d0 < ND; ++d0) { int cb = (d0 * 16 + hi * 8) * 2;
;     bf16x8 b0 = *reinterpret_cast<const bf16x8*>((const char*)Ks + KSWZ(r32, cb));
;     bf16x8 b1 = *reinterpret_cast<const bf16x8*>((const char*)Ks + KSWZ(32 + r32, cb));
;     p0 = __builtin_amdgcn_mfma_f32_32x32x16_bf16(b0, qr[d0], p0, 0, 0, 0);
;     p1 = __builtin_amdgcn_mfma_f32_32x32x16_bf16(b1, qr[d0], p1, 0, 0, 0); }
; }
; template <bool SHIFT> __device__ __forceinline__ void attn_dense_body(const bf16* __restrict__ Qb, const bf16* __restrict__ Kh, const bf16* __restrict__ Vh, bf16* __restrict__ Ob, int seq, char* lds, LAS unsigned char* ldsl, float negB, const float* __restrict__ gq, int qpos0) {
;     ...
;   for (int j = 1; j + 1 < NT; j += 2) {
;     DMA(bw, (j + 1) * KVBLK);
;     SBAR(); qkt<SHIFT ? 7 : 6>(pB0, pB1, (bf16*)((char*)K_lds + bk * SHM_K), qr, r32, hi);
;     finishSM(pA0, pA1, l_reg, pa0, pa1, pa2, pa3); SBAR();
;     pv_d0(o, vb0 + bv * (int)SHM_V, pa0, pa1, pa2, pa3); partialSM(pB0);
;     asm volatile("s_waitcnt vmcnt(0)" ::: "memory"); __syncthreads(); ROT();
;     DMA(bw, (j + 2) * KVBLK);
;     SBAR(); qkt<SHIFT ? 7 : 6>(pA0, pA1, (bf16*)((char*)K_lds + bk * SHM_K), qr, r32, hi);
;     finishSM(pB0, pB1, l_reg, pa0, pa1, pa2, pa3); SBAR();
;     pv_d0(o, vb0 + bv * (int)SHM_V, pa0, pa1, pa2, pa3); partialSM(pA0);
;     asm volatile("s_waitcnt vmcnt(0)" ::: "memory"); __syncthreads(); ROT();
;   }
	ds_read_b64_tr_b16 v[222:223], v134 offset:32768
	ds_read_b64_tr_b16 v[224:225], v134 offset:34816
	ds_read_b64_tr_b16 v[226:227], v134 offset:36864
	ds_read_b64_tr_b16 v[228:229], v134 offset:38912
	ds_read_b64_tr_b16 v[230:231], v134 offset:40960
	ds_read_b64_tr_b16 v[232:233], v134 offset:43008
	ds_read_b64_tr_b16 v[234:235], v134 offset:45056
	ds_read_b64_tr_b16 v[236:237], v134 offset:47104
	v_mfma_f32_32x32x16_bf16 v[190:205], v[156:159], v[86:89], 0
	v_exp_f32_e32 v48, v48
	v_add_f32_e32 v133, v133, v32
	v_exp_f32_e32 v49, v49
	v_add_f32_e32 v135, v135, v33
	v_exp_f32_e32 v50, v50
	v_mfma_f32_32x32x16_bf16 v[206:221], v[160:163], v[86:89], 0
	v_add_f32_e32 v133, v133, v34
	v_exp_f32_e32 v51, v51
	v_add_f32_e32 v135, v135, v35
	v_exp_f32_e32 v52, v52
	v_add_f32_e32 v133, v133, v36
	v_mfma_f32_32x32x16_bf16 v[190:205], v[164:167], v[82:85], v[190:205]
	v_exp_f32_e32 v53, v53
	v_add_f32_e32 v135, v135, v37
	v_exp_f32_e32 v54, v54
	v_add_f32_e32 v133, v133, v38
	v_exp_f32_e32 v55, v55
	v_add_f32_e32 v135, v135, v39
	v_mfma_f32_32x32x16_bf16 v[206:221], v[168:171], v[82:85], v[206:221]
	s_waitcnt lgkmcnt(7)
	ds_read_b64_tr_b16 v[238:239], v134 offset:33280
	ds_read_b64_tr_b16 v[240:241], v134 offset:35328
	ds_read_b64_tr_b16 v[242:243], v134 offset:37376
	ds_read_b64_tr_b16 v[244:245], v134 offset:39424
	ds_read_b64_tr_b16 v[246:247], v134 offset:41472
	ds_read_b64_tr_b16 v[248:249], v134 offset:43520
	ds_read_b64_tr_b16 v[140:141], v134 offset:45568
	ds_read_b64_tr_b16 v[142:143], v134 offset:47616
	v_exp_f32_e32 v56, v56
	v_add_f32_e32 v133, v133, v40
	v_exp_f32_e32 v57, v57
	v_add_f32_e32 v135, v135, v41
	v_exp_f32_e32 v58, v58
	v_mfma_f32_32x32x16_bf16 v[190:205], v[172:175], v[90:93], v[190:205]
	v_add_f32_e32 v133, v133, v42
	v_exp_f32_e32 v59, v59
	v_add_f32_e32 v135, v135, v43
	v_exp_f32_e32 v60, v60
	v_add_f32_e32 v133, v133, v44
	v_mfma_f32_32x32x16_bf16 v[206:221], v[176:179], v[90:93], v[206:221]
	v_exp_f32_e32 v61, v61
	v_add_f32_e32 v135, v135, v45
	v_exp_f32_e32 v62, v62
	v_add_f32_e32 v133, v133, v46
	v_exp_f32_e32 v63, v63
	v_add_f32_e32 v135, v135, v47
	v_mfma_f32_32x32x16_bf16 v[190:205], v[180:183], v[94:97], v[190:205]
	v_add_f32_e32 v133, v133, v48
	v_add_f32_e32 v135, v135, v49
	v_add_f32_e32 v133, v133, v50
	v_add_f32_e32 v135, v135, v51
	v_add_f32_e32 v133, v133, v52
	v_mfma_f32_32x32x16_bf16 v[206:221], v[184:187], v[94:97], v[206:221]
	v_add_f32_e32 v135, v135, v53
	v_add_f32_e32 v133, v133, v54
	v_add_f32_e32 v135, v135, v55
	v_add_f32_e32 v133, v133, v56
	v_add_f32_e32 v135, v135, v57
	v_mfma_f32_32x32x16_bf16 v[190:205], v[64:67], v[98:101], v[190:205]
	v_add_f32_e32 v133, v133, v58
	v_add_f32_e32 v135, v135, v59
	v_add_f32_e32 v133, v133, v60
	v_add_f32_e32 v135, v135, v61
	v_add_f32_e32 v133, v133, v62
	v_add_f32_e32 v135, v135, v63
	v_mfma_f32_32x32x16_bf16 v[206:221], v[68:71], v[98:101], v[206:221]
	v_cvt_pk_bf16_f32 v32, v32, v33
	v_cvt_pk_bf16_f32 v33, v34, v35
	v_cvt_pk_bf16_f32 v34, v36, v37
	v_cvt_pk_bf16_f32 v35, v38, v39
	v_cvt_pk_bf16_f32 v36, v40, v41
	v_mfma_f32_32x32x16_bf16 v[190:205], v[72:75], v[102:105], v[190:205]
	v_cvt_pk_bf16_f32 v37, v42, v43
	v_cvt_pk_bf16_f32 v38, v44, v45
	v_cvt_pk_bf16_f32 v39, v46, v47
	v_cvt_pk_bf16_f32 v48, v48, v49
	v_cvt_pk_bf16_f32 v49, v50, v51
	v_mfma_f32_32x32x16_bf16 v[206:221], v[76:79], v[102:105], v[206:221]
	v_cvt_pk_bf16_f32 v50, v52, v53
	v_cvt_pk_bf16_f32 v51, v54, v55
	v_cvt_pk_bf16_f32 v52, v56, v57
	v_cvt_pk_bf16_f32 v53, v58, v59
	v_cvt_pk_bf16_f32 v54, v60, v61
	v_cvt_pk_bf16_f32 v55, v62, v63
	s_waitcnt vmcnt(3) lgkmcnt(0)
	s_barrier
	ds_read_b128 v[156:159], v146 offset:16384
	ds_read_b128 v[160:163], v146 offset:24576
	ds_read_b128 v[164:167], v147 offset:16384
	ds_read_b128 v[168:171], v147 offset:24576
	ds_read_b128 v[172:175], v148 offset:16384
	ds_read_b128 v[176:179], v148 offset:24576
	ds_read_b128 v[180:183], v149 offset:16384
	ds_read_b128 v[184:187], v149 offset:24576
	ds_read_b128 v[64:67], v150 offset:16384
	ds_read_b128 v[68:71], v150 offset:24576
	ds_read_b128 v[72:75], v151 offset:16384
	ds_read_b128 v[76:79], v151 offset:24576
	v_mfma_f32_32x32x16_bf16 v[0:15], v[32:35], v[222:225], v[0:15]
	s_add_i32 m0, s60, 0x0
	v_exp_f32_e32 v190, v190
	v_exp_f32_e32 v191, v191
	v_mfma_f32_32x32x16_bf16 v[0:15], v[36:39], v[226:229], v[0:15]
	global_load_lds_dwordx4 v124, s[56:57]
	global_load_lds_dwordx4 v126, s[56:57] offset:1024
	v_exp_f32_e32 v192, v192
	v_exp_f32_e32 v193, v193
	v_mfma_f32_32x32x16_bf16 v[0:15], v[48:51], v[230:233], v[0:15]
	s_add_u32 s56, s56, 0x4000
	s_addc_u32 s57, s57, 0
	v_exp_f32_e32 v194, v194
	v_exp_f32_e32 v195, v195
	v_mfma_f32_32x32x16_bf16 v[0:15], v[52:55], v[234:237], v[0:15]
	s_add_i32 m0, s60, 0x14000
	v_exp_f32_e32 v196, v196
	v_exp_f32_e32 v197, v197
	v_mfma_f32_32x32x16_bf16 v[16:31], v[32:35], v[238:241], v[16:31]
	global_load_lds_dwordx4 v128, s[58:59]
	v_exp_f32_e32 v198, v198
	v_exp_f32_e32 v199, v199
	v_mfma_f32_32x32x16_bf16 v[16:31], v[36:39], v[242:245], v[16:31]
	s_add_u32 s58, s58, 0x2000
	s_addc_u32 s59, s59, 0
	v_exp_f32_e32 v200, v200
	v_exp_f32_e32 v201, v201
	v_mfma_f32_32x32x16_bf16 v[16:31], v[48:51], v[246:249], v[16:31]
	v_exp_f32_e32 v202, v202
	v_exp_f32_e32 v203, v203
	v_mfma_f32_32x32x16_bf16 v[16:31], v[52:55], v[140:143], v[16:31]
	v_exp_f32_e32 v204, v204
	v_exp_f32_e32 v205, v205
	s_waitcnt lgkmcnt(0)
; #define SBAR() __builtin_amdgcn_sched_barrier(0)
; #define ROT() do { const int t_ = bv; bv = bk; bk = bw; bw = t_; } while (0)
; __device__ __forceinline__ void partialSM(f32x16& p0) {
; #pragma unroll
;   for (int r = 0; r < 16; ++r) p0[r] = __builtin_amdgcn_exp2f(p0[r]);
; }
; __device__ __forceinline__ void finishSM(f32x16& p0, f32x16& p1, float& l_reg, bf16x8& pa0, bf16x8& pa1, bf16x8& pa2, bf16x8& pa3) {
; #pragma unroll
;   for (int r = 0; r < 16; ++r) p1[r] = __builtin_amdgcn_exp2f(p1[r]);
;   float ps = 0;
; #pragma unroll
;   for (int r = 0; r < 16; ++r) ps += p0[r];
; #pragma unroll
;   for (int r = 0; r < 16; ++r) ps += p1[r];
;   l_reg += ps;
;     ...
;   PK4(p0, 0, pa0); PK4(p0, 8, pa1); PK4(p1, 0, pa2); PK4(p1, 8, pa3);
;     ...
; }
; template <int ND> __device__ __forceinline__ void qkt(f32x16& p0, f32x16& p1, const bf16* Ks, const bf16x8* qr, int r32, int hi) {
;   p0 = f32x16{}; p1 = f32x16{};
; #pragma unroll
;   for (int d0 = 0; d0 < ND; ++d0) { int cb = (d0 * 16 + hi * 8) * 2;
;     bf16x8 b0 = *reinterpret_cast<const bf16x8*>((const char*)Ks + KSWZ(r32, cb));
;     bf16x8 b1 = *reinterpret_cast<const bf16x8*>((const char*)Ks + KSWZ(32 + r32, cb));
;     p0 = __builtin_amdgcn_mfma_f32_32x32x16_bf16(b0, qr[d0], p0, 0, 0, 0);
;     p1 = __builtin_amdgcn_mfma_f32_32x32x16_bf16(b1, qr[d0], p1, 0, 0, 0); }
; }
; template <bool SHIFT> __device__ __forceinline__ void attn_dense_body(const bf16* __restrict__ Qb, const bf16* __restrict__ Kh, const bf16* __restrict__ Vh, bf16* __restrict__ Ob, int seq, char* lds, LAS unsigned char* ldsl, float negB, const float* __restrict__ gq, int qpos0) {
;     ...
;   for (int j = 1; j + 1 < NT; j += 2) {
;     DMA(bw, (j + 1) * KVBLK);
;     SBAR(); qkt<SHIFT ? 7 : 6>(pB0, pB1, (bf16*)((char*)K_lds + bk * SHM_K), qr, r32, hi);
;     finishSM(pA0, pA1, l_reg, pa0, pa1, pa2, pa3); SBAR();
;     pv_d0(o, vb0 + bv * (int)SHM_V, pa0, pa1, pa2, pa3); partialSM(pB0);
;     asm volatile("s_waitcnt vmcnt(0)" ::: "memory"); __syncthreads(); ROT();
;     DMA(bw, (j + 2) * KVBLK);
;     SBAR(); qkt<SHIFT ? 7 : 6>(pA0, pA1, (bf16*)((char*)K_lds + bk * SHM_K), qr, r32, hi);
;     finishSM(pB0, pB1, l_reg, pa0, pa1, pa2, pa3); SBAR();
;     pv_d0(o, vb0 + bv * (int)SHM_V, pa0, pa1, pa2, pa3); partialSM(pA0);
;     asm volatile("s_waitcnt vmcnt(0)" ::: "memory"); __syncthreads(); ROT();
;   }
	ds_read_b64_tr_b16 v[222:223], v134 offset:0
	ds_read_b64_tr_b16 v[224:225], v134 offset:2048
	ds_read_b64_tr_b16 v[226:227], v134 offset:4096
	ds_read_b64_tr_b16 v[228:229], v134 offset:6144
	ds_read_b64_tr_b16 v[230:231], v134 offset:8192
	ds_read_b64_tr_b16 v[232:233], v134 offset:10240
	ds_read_b64_tr_b16 v[234:235], v134 offset:12288
	ds_read_b64_tr_b16 v[236:237], v134 offset:14336
	v_mfma_f32_32x32x16_bf16 v[32:47], v[156:159], v[86:89], 0
	v_exp_f32_e32 v206, v206
	v_add_f32_e32 v133, v133, v190
	v_exp_f32_e32 v207, v207
	v_add_f32_e32 v135, v135, v191
	v_exp_f32_e32 v208, v208
	v_mfma_f32_32x32x16_bf16 v[48:63], v[160:163], v[86:89], 0
	v_add_f32_e32 v133, v133, v192
	v_exp_f32_e32 v209, v209
	v_add_f32_e32 v135, v135, v193
	v_exp_f32_e32 v210, v210
	v_add_f32_e32 v133, v133, v194
	v_mfma_f32_32x32x16_bf16 v[32:47], v[164:167], v[82:85], v[32:47]
	v_exp_f32_e32 v211, v211
	v_add_f32_e32 v135, v135, v195
	v_exp_f32_e32 v212, v212
	v_add_f32_e32 v133, v133, v196
	v_exp_f32_e32 v213, v213
	v_add_f32_e32 v135, v135, v197
	v_mfma_f32_32x32x16_bf16 v[48:63], v[168:171], v[82:85], v[48:63]
	s_waitcnt lgkmcnt(7)
	ds_read_b64_tr_b16 v[238:239], v134 offset:512
	ds_read_b64_tr_b16 v[240:241], v134 offset:2560
	ds_read_b64_tr_b16 v[242:243], v134 offset:4608
	ds_read_b64_tr_b16 v[244:245], v134 offset:6656
	ds_read_b64_tr_b16 v[246:247], v134 offset:8704
	ds_read_b64_tr_b16 v[248:249], v134 offset:10752
	ds_read_b64_tr_b16 v[140:141], v134 offset:12800
	ds_read_b64_tr_b16 v[142:143], v134 offset:14848
	v_exp_f32_e32 v214, v214
	v_add_f32_e32 v133, v133, v198
	v_exp_f32_e32 v215, v215
	v_add_f32_e32 v135, v135, v199
	v_exp_f32_e32 v216, v216
	v_mfma_f32_32x32x16_bf16 v[32:47], v[172:175], v[90:93], v[32:47]
	v_add_f32_e32 v133, v133, v200
	v_exp_f32_e32 v217, v217
	v_add_f32_e32 v135, v135, v201
	v_exp_f32_e32 v218, v218
	v_add_f32_e32 v133, v133, v202
	v_mfma_f32_32x32x16_bf16 v[48:63], v[176:179], v[90:93], v[48:63]
	v_exp_f32_e32 v219, v219
	v_add_f32_e32 v135, v135, v203
	v_exp_f32_e32 v220, v220
	v_add_f32_e32 v133, v133, v204
	v_exp_f32_e32 v221, v221
	v_add_f32_e32 v135, v135, v205
	v_mfma_f32_32x32x16_bf16 v[32:47], v[180:183], v[94:97], v[32:47]
	v_add_f32_e32 v133, v133, v206
	v_add_f32_e32 v135, v135, v207
	v_add_f32_e32 v133, v133, v208
	v_add_f32_e32 v135, v135, v209
	v_add_f32_e32 v133, v133, v210
	v_mfma_f32_32x32x16_bf16 v[48:63], v[184:187], v[94:97], v[48:63]
	v_add_f32_e32 v135, v135, v211
	v_add_f32_e32 v133, v133, v212
	v_add_f32_e32 v135, v135, v213
	v_add_f32_e32 v133, v133, v214
	v_add_f32_e32 v135, v135, v215
	v_mfma_f32_32x32x16_bf16 v[32:47], v[64:67], v[98:101], v[32:47]
	v_add_f32_e32 v133, v133, v216
	v_add_f32_e32 v135, v135, v217
	v_add_f32_e32 v133, v133, v218
	v_add_f32_e32 v135, v135, v219
	v_add_f32_e32 v133, v133, v220
	v_add_f32_e32 v135, v135, v221
	v_mfma_f32_32x32x16_bf16 v[48:63], v[68:71], v[98:101], v[48:63]
	v_cvt_pk_bf16_f32 v190, v190, v191
	v_cvt_pk_bf16_f32 v191, v192, v193
	v_cvt_pk_bf16_f32 v192, v194, v195
	v_cvt_pk_bf16_f32 v193, v196, v197
	v_cvt_pk_bf16_f32 v194, v198, v199
	v_mfma_f32_32x32x16_bf16 v[32:47], v[72:75], v[102:105], v[32:47]
	v_cvt_pk_bf16_f32 v195, v200, v201
	v_cvt_pk_bf16_f32 v196, v202, v203
	v_cvt_pk_bf16_f32 v197, v204, v205
	v_cvt_pk_bf16_f32 v206, v206, v207
	v_cvt_pk_bf16_f32 v207, v208, v209
	v_mfma_f32_32x32x16_bf16 v[48:63], v[76:79], v[102:105], v[48:63]
	v_cvt_pk_bf16_f32 v208, v210, v211
	v_cvt_pk_bf16_f32 v209, v212, v213
	v_cvt_pk_bf16_f32 v210, v214, v215
	v_cvt_pk_bf16_f32 v211, v216, v217
	v_cvt_pk_bf16_f32 v212, v218, v219
	v_cvt_pk_bf16_f32 v213, v220, v221
	s_waitcnt vmcnt(3) lgkmcnt(0)
	s_barrier
	ds_read_b128 v[156:159], v146 offset:32768
	ds_read_b128 v[160:163], v146 offset:40960
	ds_read_b128 v[164:167], v147 offset:32768
	ds_read_b128 v[168:171], v147 offset:40960
	ds_read_b128 v[172:175], v148 offset:32768
	ds_read_b128 v[176:179], v148 offset:40960
	ds_read_b128 v[180:183], v149 offset:32768
	ds_read_b128 v[184:187], v149 offset:40960
	ds_read_b128 v[64:67], v150 offset:32768
	ds_read_b128 v[68:71], v150 offset:40960
	ds_read_b128 v[72:75], v151 offset:32768
	ds_read_b128 v[76:79], v151 offset:40960
	v_mfma_f32_32x32x16_bf16 v[0:15], v[190:193], v[222:225], v[0:15]
	s_add_i32 m0, s60, 0x4000
	v_exp_f32_e32 v32, v32
	v_exp_f32_e32 v33, v33
	v_mfma_f32_32x32x16_bf16 v[0:15], v[194:197], v[226:229], v[0:15]
	global_load_lds_dwordx4 v124, s[56:57]
	global_load_lds_dwordx4 v126, s[56:57] offset:1024
	v_exp_f32_e32 v34, v34
	v_exp_f32_e32 v35, v35
	v_mfma_f32_32x32x16_bf16 v[0:15], v[206:209], v[230:233], v[0:15]
	s_add_u32 s56, s56, 0x4000
	s_addc_u32 s57, s57, 0
	v_exp_f32_e32 v36, v36
	v_exp_f32_e32 v37, v37
	v_mfma_f32_32x32x16_bf16 v[0:15], v[210:213], v[234:237], v[0:15]
	s_add_i32 m0, s60, 0xc000
	v_exp_f32_e32 v38, v38
	v_exp_f32_e32 v39, v39
	v_mfma_f32_32x32x16_bf16 v[16:31], v[190:193], v[238:241], v[16:31]
	global_load_lds_dwordx4 v128, s[58:59]
	v_exp_f32_e32 v40, v40
	v_exp_f32_e32 v41, v41
	v_mfma_f32_32x32x16_bf16 v[16:31], v[194:197], v[242:245], v[16:31]
	s_add_u32 s58, s58, 0x2000
	s_addc_u32 s59, s59, 0
	v_exp_f32_e32 v42, v42
	v_exp_f32_e32 v43, v43
	v_mfma_f32_32x32x16_bf16 v[16:31], v[206:209], v[246:249], v[16:31]
	v_exp_f32_e32 v44, v44
	v_exp_f32_e32 v45, v45
	v_mfma_f32_32x32x16_bf16 v[16:31], v[210:213], v[140:143], v[16:31]
	v_exp_f32_e32 v46, v46
	v_exp_f32_e32 v47, v47
	s_waitcnt lgkmcnt(0)
; __device__ __forceinline__ void finishSM(f32x16& p0, f32x16& p1, float& l_reg, bf16x8& pa0, bf16x8& pa1, bf16x8& pa2, bf16x8& pa3) {
; #pragma unroll
;   for (int r = 0; r < 16; ++r) p1[r] = __builtin_amdgcn_exp2f(p1[r]);
;   float ps = 0;
; #pragma unroll
;   for (int r = 0; r < 16; ++r) ps += p0[r];
; #pragma unroll
;   for (int r = 0; r < 16; ++r) ps += p1[r];
;   l_reg += ps;
;     ...
;   PK4(p0, 0, pa0); PK4(p0, 8, pa1); PK4(p1, 0, pa2); PK4(p1, 8, pa3);
;     ...
; }
; template <int ND> __device__ __forceinline__ void qkt(f32x16& p0, f32x16& p1, const bf16* Ks, const bf16x8* qr, int r32, int hi) {
;   p0 = f32x16{}; p1 = f32x16{};
; #pragma unroll
;   for (int d0 = 0; d0 < ND; ++d0) { int cb = (d0 * 16 + hi * 8) * 2;
;     bf16x8 b0 = *reinterpret_cast<const bf16x8*>((const char*)Ks + KSWZ(r32, cb));
;     bf16x8 b1 = *reinterpret_cast<const bf16x8*>((const char*)Ks + KSWZ(32 + r32, cb));
;     p0 = __builtin_amdgcn_mfma_f32_32x32x16_bf16(b0, qr[d0], p0, 0, 0, 0);
;     p1 = __builtin_amdgcn_mfma_f32_32x32x16_bf16(b1, qr[d0], p1, 0, 0, 0); }
; }
; __device__ __forceinline__ int v_st(int k, int c) { const int kk = (k & ~0xC) | ((k & 4) << 1) | ((k & 8) >> 1); return ((kk >> 3) * 4 + (c >> 5)) * 512 + ((kk & 7) * 32 + (c & 31)) * 2; }
; __device__ __forceinline__ int v_rd_base(int lane) { return ((lane & 3) << 3) | (((lane >> 2) & 3) << 6) | (((lane >> 4) & 1) << 5) | (((lane >> 5) & 1) << 8); }
; template <int OFF> __device__ __forceinline__ s16x4 tr_read(int vb) {
;   s16x4 r; asm volatile("ds_read_b64_tr_b16 %0, %1 offset:%2" : "=&v"(r) : "v"(vb), "i"(OFF) : "memory"); return r;
; }
; template <int D0> __device__ __forceinline__ void pv_one(f32x16& od, int vb, bf16x8 pa0, bf16x8 pa1, bf16x8 pa2, bf16x8 pa3) {
;   const s16x4 l0 = tr_read<v_rd_off(D0, 0, 0)>(vb), h0 = tr_read<v_rd_off(D0, 0, 1)>(vb), l1 = tr_read<v_rd_off(D0, 1, 0)>(vb), h1 = tr_read<v_rd_off(D0, 1, 1)>(vb);
;   const s16x4 l2 = tr_read<v_rd_off(D0, 2, 0)>(vb), h2 = tr_read<v_rd_off(D0, 2, 1)>(vb), l3 = tr_read<v_rd_off(D0, 3, 0)>(vb), h3 = tr_read<v_rd_off(D0, 3, 1)>(vb);
;   asm volatile("s_waitcnt lgkmcnt(0)" ::: "memory"); SBAR();
;     ...
;   od = __builtin_amdgcn_mfma_f32_32x32x16_bf16(pa0, PK(l0, h0), od, 0, 0, 0);
;   od = __builtin_amdgcn_mfma_f32_32x32x16_bf16(pa1, PK(l1, h1), od, 0, 0, 0);
;   od = __builtin_amdgcn_mfma_f32_32x32x16_bf16(pa2, PK(l2, h2), od, 0, 0, 0);
	ds_read_b64_tr_b16 v[222:223], v134 offset:16384
	ds_read_b64_tr_b16 v[224:225], v134 offset:18432
	ds_read_b64_tr_b16 v[226:227], v134 offset:20480
	ds_read_b64_tr_b16 v[228:229], v134 offset:22528
	ds_read_b64_tr_b16 v[230:231], v134 offset:24576
	ds_read_b64_tr_b16 v[232:233], v134 offset:26624
	ds_read_b64_tr_b16 v[234:235], v134 offset:28672
	ds_read_b64_tr_b16 v[236:237], v134 offset:30720
	v_mfma_f32_32x32x16_bf16 v[190:205], v[156:159], v[86:89], 0
	v_exp_f32_e32 v48, v48
	v_add_f32_e32 v133, v133, v32
	v_exp_f32_e32 v49, v49
	v_add_f32_e32 v135, v135, v33
	v_exp_f32_e32 v50, v50
	v_mfma_f32_32x32x16_bf16 v[206:221], v[160:163], v[86:89], 0
	v_add_f32_e32 v133, v133, v34
	v_exp_f32_e32 v51, v51
	v_add_f32_e32 v135, v135, v35
	v_exp_f32_e32 v52, v52
	v_add_f32_e32 v133, v133, v36
	v_mfma_f32_32x32x16_bf16 v[190:205], v[164:167], v[82:85], v[190:205]
	v_exp_f32_e32 v53, v53
	v_add_f32_e32 v135, v135, v37
	v_exp_f32_e32 v54, v54
	v_add_f32_e32 v133, v133, v38
	v_exp_f32_e32 v55, v55
	v_add_f32_e32 v135, v135, v39
	v_mfma_f32_32x32x16_bf16 v[206:221], v[168:171], v[82:85], v[206:221]
	s_waitcnt lgkmcnt(7)
	ds_read_b64_tr_b16 v[238:239], v134 offset:16896
	ds_read_b64_tr_b16 v[240:241], v134 offset:18944
	ds_read_b64_tr_b16 v[242:243], v134 offset:20992
	ds_read_b64_tr_b16 v[244:245], v134 offset:23040
	ds_read_b64_tr_b16 v[246:247], v134 offset:25088
	ds_read_b64_tr_b16 v[248:249], v134 offset:27136
	ds_read_b64_tr_b16 v[140:141], v134 offset:29184
	ds_read_b64_tr_b16 v[142:143], v134 offset:31232
	v_exp_f32_e32 v56, v56
	v_add_f32_e32 v133, v133, v40
	v_exp_f32_e32 v57, v57
	v_add_f32_e32 v135, v135, v41
	v_exp_f32_e32 v58, v58
	v_mfma_f32_32x32x16_bf16 v[190:205], v[172:175], v[90:93], v[190:205]
	v_add_f32_e32 v133, v133, v42
	v_exp_f32_e32 v59, v59
	v_add_f32_e32 v135, v135, v43
	v_exp_f32_e32 v60, v60
	v_add_f32_e32 v133, v133, v44
	v_mfma_f32_32x32x16_bf16 v[206:221], v[176:179], v[90:93], v[206:221]
	v_exp_f32_e32 v61, v61
	v_add_f32_e32 v135, v135, v45
	v_exp_f32_e32 v62, v62
	v_add_f32_e32 v133, v133, v46
	v_exp_f32_e32 v63, v63
	v_add_f32_e32 v135, v135, v47
	v_mfma_f32_32x32x16_bf16 v[190:205], v[180:183], v[94:97], v[190:205]
	v_add_f32_e32 v133, v133, v48
	v_add_f32_e32 v135, v135, v49
	v_add_f32_e32 v133, v133, v50
	v_add_f32_e32 v135, v135, v51
	v_add_f32_e32 v133, v133, v52
	v_mfma_f32_32x32x16_bf16 v[206:221], v[184:187], v[94:97], v[206:221]
	v_add_f32_e32 v135, v135, v53
	v_add_f32_e32 v133, v133, v54
	v_add_f32_e32 v135, v135, v55
	v_add_f32_e32 v133, v133, v56
	v_add_f32_e32 v135, v135, v57
	v_mfma_f32_32x32x16_bf16 v[190:205], v[64:67], v[98:101], v[190:205]
	v_add_f32_e32 v133, v133, v58
	v_add_f32_e32 v135, v135, v59
	v_add_f32_e32 v133, v133, v60
	v_add_f32_e32 v135, v135, v61
	v_add_f32_e32 v133, v133, v62
	v_add_f32_e32 v135, v135, v63
	v_mfma_f32_32x32x16_bf16 v[206:221], v[68:71], v[98:101], v[206:221]
	v_cvt_pk_bf16_f32 v32, v32, v33
	v_cvt_pk_bf16_f32 v33, v34, v35
	v_cvt_pk_bf16_f32 v34, v36, v37
	v_cvt_pk_bf16_f32 v35, v38, v39
	v_cvt_pk_bf16_f32 v36, v40, v41
	v_mfma_f32_32x32x16_bf16 v[190:205], v[72:75], v[102:105], v[190:205]
	v_cvt_pk_bf16_f32 v37, v42, v43
	v_cvt_pk_bf16_f32 v38, v44, v45
	v_cvt_pk_bf16_f32 v39, v46, v47
	v_cvt_pk_bf16_f32 v48, v48, v49
	v_cvt_pk_bf16_f32 v49, v50, v51
	v_mfma_f32_32x32x16_bf16 v[206:221], v[76:79], v[102:105], v[206:221]
	v_cvt_pk_bf16_f32 v50, v52, v53
	v_cvt_pk_bf16_f32 v51, v54, v55
	v_cvt_pk_bf16_f32 v52, v56, v57
	v_cvt_pk_bf16_f32 v53, v58, v59
	v_cvt_pk_bf16_f32 v54, v60, v61
	v_cvt_pk_bf16_f32 v55, v62, v63
	s_waitcnt vmcnt(3) lgkmcnt(0)
	s_barrier
	ds_read_b128 v[156:159], v146 offset:0
	ds_read_b128 v[160:163], v146 offset:8192
	ds_read_b128 v[164:167], v147 offset:0
	ds_read_b128 v[168:171], v147 offset:8192
	ds_read_b128 v[172:175], v148 offset:0
	ds_read_b128 v[176:179], v148 offset:8192
	ds_read_b128 v[180:183], v149 offset:0
	ds_read_b128 v[184:187], v149 offset:8192
	ds_read_b128 v[64:67], v150 offset:0
	ds_read_b128 v[68:71], v150 offset:8192
	ds_read_b128 v[72:75], v151 offset:0
	ds_read_b128 v[76:79], v151 offset:8192
	v_mfma_f32_32x32x16_bf16 v[0:15], v[32:35], v[222:225], v[0:15]
	s_add_i32 m0, s60, 0x8000
	v_exp_f32_e32 v190, v190
	v_exp_f32_e32 v191, v191
	v_mfma_f32_32x32x16_bf16 v[0:15], v[36:39], v[226:229], v[0:15]
	global_load_lds_dwordx4 v124, s[56:57]
	global_load_lds_dwordx4 v126, s[56:57] offset:1024
	v_exp_f32_e32 v192, v192
	v_exp_f32_e32 v193, v193
	v_mfma_f32_32x32x16_bf16 v[0:15], v[48:51], v[230:233], v[0:15]
	s_add_u32 s56, s56, 0x4000
	s_addc_u32 s57, s57, 0
	v_exp_f32_e32 v194, v194
	v_exp_f32_e32 v195, v195
	v_mfma_f32_32x32x16_bf16 v[0:15], v[52:55], v[234:237], v[0:15]
	s_add_i32 m0, s60, 0x10000
	v_exp_f32_e32 v196, v196
	v_exp_f32_e32 v197, v197
	v_mfma_f32_32x32x16_bf16 v[16:31], v[32:35], v[238:241], v[16:31]
	global_load_lds_dwordx4 v128, s[58:59]
	v_exp_f32_e32 v198, v198
	v_exp_f32_e32 v199, v199
	v_mfma_f32_32x32x16_bf16 v[16:31], v[36:39], v[242:245], v[16:31]
	s_add_u32 s58, s58, 0x2000
	s_addc_u32 s59, s59, 0
	v_exp_f32_e32 v200, v200
	v_exp_f32_e32 v201, v201
	v_mfma_f32_32x32x16_bf16 v[16:31], v[48:51], v[246:249], v[16:31]
	v_exp_f32_e32 v202, v202
	v_exp_f32_e32 v203, v203
	v_mfma_f32_32x32x16_bf16 v[16:31], v[52:55], v[140:143], v[16:31]
	v_exp_f32_e32 v204, v204
	v_exp_f32_e32 v205, v205
	s_waitcnt lgkmcnt(0)
; __device__ __forceinline__ void finishSM(f32x16& p0, f32x16& p1, float& l_reg, bf16x8& pa0, bf16x8& pa1, bf16x8& pa2, bf16x8& pa3) {
; #pragma unroll
;   for (int r = 0; r < 16; ++r) p1[r] = __builtin_amdgcn_exp2f(p1[r]);
;   float ps = 0;
; #pragma unroll
;   for (int r = 0; r < 16; ++r) ps += p0[r];
; #pragma unroll
;   for (int r = 0; r < 16; ++r) ps += p1[r];
;   l_reg += ps;
;     ...
;   PK4(p0, 0, pa0); PK4(p0, 8, pa1); PK4(p1, 0, pa2); PK4(p1, 8, pa3);
;     ...
; }
; template <int ND> __device__ __forceinline__ void qkt(f32x16& p0, f32x16& p1, const bf16* Ks, const bf16x8* qr, int r32, int hi) {
;   p0 = f32x16{}; p1 = f32x16{};
; #pragma unroll
;   for (int d0 = 0; d0 < ND; ++d0) { int cb = (d0 * 16 + hi * 8) * 2;
;     bf16x8 b0 = *reinterpret_cast<const bf16x8*>((const char*)Ks + KSWZ(r32, cb));
;     bf16x8 b1 = *reinterpret_cast<const bf16x8*>((const char*)Ks + KSWZ(32 + r32, cb));
;     p0 = __builtin_amdgcn_mfma_f32_32x32x16_bf16(b0, qr[d0], p0, 0, 0, 0);
;     p1 = __builtin_amdgcn_mfma_f32_32x32x16_bf16(b1, qr[d0], p1, 0, 0, 0); }
; }
; __device__ __forceinline__ int v_st(int k, int c) { const int kk = (k & ~0xC) | ((k & 4) << 1) | ((k & 8) >> 1); return ((kk >> 3) * 4 + (c >> 5)) * 512 + ((kk & 7) * 32 + (c & 31)) * 2; }
; __device__ __forceinline__ int v_rd_base(int lane) { return ((lane & 3) << 3) | (((lane >> 2) & 3) << 6) | (((lane >> 4) & 1) << 5) | (((lane >> 5) & 1) << 8); }
; template <int OFF> __device__ __forceinline__ s16x4 tr_read(int vb) {
;   s16x4 r; asm volatile("ds_read_b64_tr_b16 %0, %1 offset:%2" : "=&v"(r) : "v"(vb), "i"(OFF) : "memory"); return r;
; }
; template <int D0> __device__ __forceinline__ void pv_one(f32x16& od, int vb, bf16x8 pa0, bf16x8 pa1, bf16x8 pa2, bf16x8 pa3) {
;   const s16x4 l0 = tr_read<v_rd_off(D0, 0, 0)>(vb), h0 = tr_read<v_rd_off(D0, 0, 1)>(vb), l1 = tr_read<v_rd_off(D0, 1, 0)>(vb), h1 = tr_read<v_rd_off(D0, 1, 1)>(vb);
;   const s16x4 l2 = tr_read<v_rd_off(D0, 2, 0)>(vb), h2 = tr_read<v_rd_off(D0, 2, 1)>(vb), l3 = tr_read<v_rd_off(D0, 3, 0)>(vb), h3 = tr_read<v_rd_off(D0, 3, 1)>(vb);
;   asm volatile("s_waitcnt lgkmcnt(0)" ::: "memory"); SBAR();
;     ...
;   od = __builtin_amdgcn_mfma_f32_32x32x16_bf16(pa0, PK(l0, h0), od, 0, 0, 0);
;   od = __builtin_amdgcn_mfma_f32_32x32x16_bf16(pa1, PK(l1, h1), od, 0, 0, 0);
;   od = __builtin_amdgcn_mfma_f32_32x32x16_bf16(pa2, PK(l2, h2), od, 0, 0, 0);
	ds_read_b64_tr_b16 v[222:223], v134 offset:32768
	ds_read_b64_tr_b16 v[224:225], v134 offset:34816
	ds_read_b64_tr_b16 v[226:227], v134 offset:36864
	ds_read_b64_tr_b16 v[228:229], v134 offset:38912
	ds_read_b64_tr_b16 v[230:231], v134 offset:40960
	ds_read_b64_tr_b16 v[232:233], v134 offset:43008
	ds_read_b64_tr_b16 v[234:235], v134 offset:45056
	ds_read_b64_tr_b16 v[236:237], v134 offset:47104
	v_mfma_f32_32x32x16_bf16 v[32:47], v[156:159], v[86:89], 0
	v_exp_f32_e32 v206, v206
	v_add_f32_e32 v133, v133, v190
	v_exp_f32_e32 v207, v207
	v_add_f32_e32 v135, v135, v191
	v_exp_f32_e32 v208, v208
	v_mfma_f32_32x32x16_bf16 v[48:63], v[160:163], v[86:89], 0
	v_add_f32_e32 v133, v133, v192
	v_exp_f32_e32 v209, v209
	v_add_f32_e32 v135, v135, v193
	v_exp_f32_e32 v210, v210
	v_add_f32_e32 v133, v133, v194
	v_mfma_f32_32x32x16_bf16 v[32:47], v[164:167], v[82:85], v[32:47]
	v_exp_f32_e32 v211, v211
	v_add_f32_e32 v135, v135, v195
	v_exp_f32_e32 v212, v212
	v_add_f32_e32 v133, v133, v196
	v_exp_f32_e32 v213, v213
	v_add_f32_e32 v135, v135, v197
	v_mfma_f32_32x32x16_bf16 v[48:63], v[168:171], v[82:85], v[48:63]
	s_waitcnt lgkmcnt(7)
	ds_read_b64_tr_b16 v[238:239], v134 offset:33280
	ds_read_b64_tr_b16 v[240:241], v134 offset:35328
	ds_read_b64_tr_b16 v[242:243], v134 offset:37376
	ds_read_b64_tr_b16 v[244:245], v134 offset:39424
	ds_read_b64_tr_b16 v[246:247], v134 offset:41472
	ds_read_b64_tr_b16 v[248:249], v134 offset:43520
	ds_read_b64_tr_b16 v[140:141], v134 offset:45568
	ds_read_b64_tr_b16 v[142:143], v134 offset:47616
	v_exp_f32_e32 v214, v214
	v_add_f32_e32 v133, v133, v198
	v_exp_f32_e32 v215, v215
	v_add_f32_e32 v135, v135, v199
	v_exp_f32_e32 v216, v216
	v_mfma_f32_32x32x16_bf16 v[32:47], v[172:175], v[90:93], v[32:47]
	v_add_f32_e32 v133, v133, v200
	v_exp_f32_e32 v217, v217
	v_add_f32_e32 v135, v135, v201
	v_exp_f32_e32 v218, v218
	v_add_f32_e32 v133, v133, v202
	v_mfma_f32_32x32x16_bf16 v[48:63], v[176:179], v[90:93], v[48:63]
	v_exp_f32_e32 v219, v219
	v_add_f32_e32 v135, v135, v203
	v_exp_f32_e32 v220, v220
	v_add_f32_e32 v133, v133, v204
	v_exp_f32_e32 v221, v221
	v_add_f32_e32 v135, v135, v205
	v_mfma_f32_32x32x16_bf16 v[32:47], v[180:183], v[94:97], v[32:47]
	v_add_f32_e32 v133, v133, v206
	v_add_f32_e32 v135, v135, v207
	v_add_f32_e32 v133, v133, v208
	v_add_f32_e32 v135, v135, v209
	v_add_f32_e32 v133, v133, v210
	v_mfma_f32_32x32x16_bf16 v[48:63], v[184:187], v[94:97], v[48:63]
	v_add_f32_e32 v135, v135, v211
	v_add_f32_e32 v133, v133, v212
	v_add_f32_e32 v135, v135, v213
	v_add_f32_e32 v133, v133, v214
	v_add_f32_e32 v135, v135, v215
	v_mfma_f32_32x32x16_bf16 v[32:47], v[64:67], v[98:101], v[32:47]
	v_add_f32_e32 v133, v133, v216
	v_add_f32_e32 v135, v135, v217
	v_add_f32_e32 v133, v133, v218
	v_add_f32_e32 v135, v135, v219
	v_add_f32_e32 v133, v133, v220
	v_add_f32_e32 v135, v135, v221
	v_mfma_f32_32x32x16_bf16 v[48:63], v[68:71], v[98:101], v[48:63]
	v_cvt_pk_bf16_f32 v190, v190, v191
	v_cvt_pk_bf16_f32 v191, v192, v193
	v_cvt_pk_bf16_f32 v192, v194, v195
	v_cvt_pk_bf16_f32 v193, v196, v197
	v_cvt_pk_bf16_f32 v194, v198, v199
	v_mfma_f32_32x32x16_bf16 v[32:47], v[72:75], v[102:105], v[32:47]
	v_cvt_pk_bf16_f32 v195, v200, v201
	v_cvt_pk_bf16_f32 v196, v202, v203
	v_cvt_pk_bf16_f32 v197, v204, v205
	v_cvt_pk_bf16_f32 v206, v206, v207
	v_cvt_pk_bf16_f32 v207, v208, v209
	v_mfma_f32_32x32x16_bf16 v[48:63], v[76:79], v[102:105], v[48:63]
	v_cvt_pk_bf16_f32 v208, v210, v211
	v_cvt_pk_bf16_f32 v209, v212, v213
	v_cvt_pk_bf16_f32 v210, v214, v215
	v_cvt_pk_bf16_f32 v211, v216, v217
	v_cvt_pk_bf16_f32 v212, v218, v219
	v_cvt_pk_bf16_f32 v213, v220, v221
	s_waitcnt vmcnt(3) lgkmcnt(0)
	s_barrier
	ds_read_b128 v[156:159], v146 offset:16384
	ds_read_b128 v[160:163], v146 offset:24576
	ds_read_b128 v[164:167], v147 offset:16384
	ds_read_b128 v[168:171], v147 offset:24576
	ds_read_b128 v[172:175], v148 offset:16384
	ds_read_b128 v[176:179], v148 offset:24576
	ds_read_b128 v[180:183], v149 offset:16384
	ds_read_b128 v[184:187], v149 offset:24576
	ds_read_b128 v[64:67], v150 offset:16384
	ds_read_b128 v[68:71], v150 offset:24576
	ds_read_b128 v[72:75], v151 offset:16384
	ds_read_b128 v[76:79], v151 offset:24576
	v_mfma_f32_32x32x16_bf16 v[0:15], v[190:193], v[222:225], v[0:15]
	s_add_i32 m0, s60, 0x0
	v_exp_f32_e32 v32, v32
	v_exp_f32_e32 v33, v33
	v_mfma_f32_32x32x16_bf16 v[0:15], v[194:197], v[226:229], v[0:15]
	global_load_lds_dwordx4 v124, s[56:57]
	global_load_lds_dwordx4 v126, s[56:57] offset:1024
	v_exp_f32_e32 v34, v34
	v_exp_f32_e32 v35, v35
	v_mfma_f32_32x32x16_bf16 v[0:15], v[206:209], v[230:233], v[0:15]
	s_add_u32 s56, s56, 0x4000
	s_addc_u32 s57, s57, 0
	v_exp_f32_e32 v36, v36
	v_exp_f32_e32 v37, v37
	v_mfma_f32_32x32x16_bf16 v[0:15], v[210:213], v[234:237], v[0:15]
	s_add_i32 m0, s60, 0x14000
	v_exp_f32_e32 v38, v38
	v_exp_f32_e32 v39, v39
	v_mfma_f32_32x32x16_bf16 v[16:31], v[190:193], v[238:241], v[16:31]
	global_load_lds_dwordx4 v128, s[58:59]
	v_exp_f32_e32 v40, v40
	v_exp_f32_e32 v41, v41
	v_mfma_f32_32x32x16_bf16 v[16:31], v[194:197], v[242:245], v[16:31]
	s_add_u32 s58, s58, 0x2000
	s_addc_u32 s59, s59, 0
	v_exp_f32_e32 v42, v42
	v_exp_f32_e32 v43, v43
	v_mfma_f32_32x32x16_bf16 v[16:31], v[206:209], v[246:249], v[16:31]
	v_exp_f32_e32 v44, v44
	v_exp_f32_e32 v45, v45
	v_mfma_f32_32x32x16_bf16 v[16:31], v[210:213], v[140:143], v[16:31]
	v_exp_f32_e32 v46, v46
	v_exp_f32_e32 v47, v47
	s_sub_u32 s33, s33, 1
	s_cmp_lg_u32 s33, 0
	s_cbranch_scc1 .Latt_loop
; __device__ __forceinline__ void finishSM(f32x16& p0, f32x16& p1, float& l_reg, bf16x8& pa0, bf16x8& pa1, bf16x8& pa2, bf16x8& pa3) {
; #pragma unroll
;   for (int r = 0; r < 16; ++r) p1[r] = __builtin_amdgcn_exp2f(p1[r]);
;   float ps = 0;
; #pragma unroll
;   for (int r = 0; r < 16; ++r) ps += p0[r];
; #pragma unroll
;   for (int r = 0; r < 16; ++r) ps += p1[r];
;   l_reg += ps;
;     ...
;   PK4(p0, 0, pa0); PK4(p0, 8, pa1); PK4(p1, 0, pa2); PK4(p1, 8, pa3);
;     ...
; }
; template <int ND> __device__ __forceinline__ void qkt(f32x16& p0, f32x16& p1, const bf16* Ks, const bf16x8* qr, int r32, int hi) {
;   p0 = f32x16{}; p1 = f32x16{};
; #pragma unroll
;   for (int d0 = 0; d0 < ND; ++d0) { int cb = (d0 * 16 + hi * 8) * 2;
;     bf16x8 b0 = *reinterpret_cast<const bf16x8*>((const char*)Ks + KSWZ(r32, cb));
;     bf16x8 b1 = *reinterpret_cast<const bf16x8*>((const char*)Ks + KSWZ(32 + r32, cb));
;     p0 = __builtin_amdgcn_mfma_f32_32x32x16_bf16(b0, qr[d0], p0, 0, 0, 0);
;     p1 = __builtin_amdgcn_mfma_f32_32x32x16_bf16(b1, qr[d0], p1, 0, 0, 0); }
; }
; __device__ __forceinline__ int v_st(int k, int c) { const int kk = (k & ~0xC) | ((k & 4) << 1) | ((k & 8) >> 1); return ((kk >> 3) * 4 + (c >> 5)) * 512 + ((kk & 7) * 32 + (c & 31)) * 2; }
; __device__ __forceinline__ int v_rd_base(int lane) { return ((lane & 3) << 3) | (((lane >> 2) & 3) << 6) | (((lane >> 4) & 1) << 5) | (((lane >> 5) & 1) << 8); }
; template <int OFF> __device__ __forceinline__ s16x4 tr_read(int vb) {
;   s16x4 r; asm volatile("ds_read_b64_tr_b16 %0, %1 offset:%2" : "=&v"(r) : "v"(vb), "i"(OFF) : "memory"); return r;
; }
; template <int D0> __device__ __forceinline__ void pv_one(f32x16& od, int vb, bf16x8 pa0, bf16x8 pa1, bf16x8 pa2, bf16x8 pa3) {
;   const s16x4 l0 = tr_read<v_rd_off(D0, 0, 0)>(vb), h0 = tr_read<v_rd_off(D0, 0, 1)>(vb), l1 = tr_read<v_rd_off(D0, 1, 0)>(vb), h1 = tr_read<v_rd_off(D0, 1, 1)>(vb);
;   const s16x4 l2 = tr_read<v_rd_off(D0, 2, 0)>(vb), h2 = tr_read<v_rd_off(D0, 2, 1)>(vb), l3 = tr_read<v_rd_off(D0, 3, 0)>(vb), h3 = tr_read<v_rd_off(D0, 3, 1)>(vb);
;   asm volatile("s_waitcnt lgkmcnt(0)" ::: "memory"); SBAR();
;     ...
;   od = __builtin_amdgcn_mfma_f32_32x32x16_bf16(pa0, PK(l0, h0), od, 0, 0, 0);
;   od = __builtin_amdgcn_mfma_f32_32x32x16_bf16(pa1, PK(l1, h1), od, 0, 0, 0);
;   od = __builtin_amdgcn_mfma_f32_32x32x16_bf16(pa2, PK(l2, h2), od, 0, 0, 0);
	s_waitcnt lgkmcnt(0)
	ds_read_b64_tr_b16 v[222:223], v134 offset:0
	ds_read_b64_tr_b16 v[224:225], v134 offset:2048
	ds_read_b64_tr_b16 v[226:227], v134 offset:4096
	ds_read_b64_tr_b16 v[228:229], v134 offset:6144
	ds_read_b64_tr_b16 v[230:231], v134 offset:8192
	ds_read_b64_tr_b16 v[232:233], v134 offset:10240
	ds_read_b64_tr_b16 v[234:235], v134 offset:12288
	ds_read_b64_tr_b16 v[236:237], v134 offset:14336
	v_mfma_f32_32x32x16_bf16 v[190:205], v[156:159], v[86:89], 0
	v_exp_f32_e32 v48, v48
	v_add_f32_e32 v133, v133, v32
	v_exp_f32_e32 v49, v49
	v_add_f32_e32 v135, v135, v33
	v_exp_f32_e32 v50, v50
	v_mfma_f32_32x32x16_bf16 v[206:221], v[160:163], v[86:89], 0
	v_add_f32_e32 v133, v133, v34
	v_exp_f32_e32 v51, v51
	v_add_f32_e32 v135, v135, v35
	v_exp_f32_e32 v52, v52
	v_add_f32_e32 v133, v133, v36
	v_mfma_f32_32x32x16_bf16 v[190:205], v[164:167], v[82:85], v[190:205]
	v_exp_f32_e32 v53, v53
	v_add_f32_e32 v135, v135, v37
	v_exp_f32_e32 v54, v54
	v_add_f32_e32 v133, v133, v38
	v_exp_f32_e32 v55, v55
	v_add_f32_e32 v135, v135, v39
	v_mfma_f32_32x32x16_bf16 v[206:221], v[168:171], v[82:85], v[206:221]
	s_waitcnt lgkmcnt(7)
	ds_read_b64_tr_b16 v[238:239], v134 offset:512
	ds_read_b64_tr_b16 v[240:241], v134 offset:2560
	ds_read_b64_tr_b16 v[242:243], v134 offset:4608
	ds_read_b64_tr_b16 v[244:245], v134 offset:6656
	ds_read_b64_tr_b16 v[246:247], v134 offset:8704
	ds_read_b64_tr_b16 v[248:249], v134 offset:10752
	ds_read_b64_tr_b16 v[140:141], v134 offset:12800
	ds_read_b64_tr_b16 v[142:143], v134 offset:14848
	v_exp_f32_e32 v56, v56
	v_add_f32_e32 v133, v133, v40
	v_exp_f32_e32 v57, v57
	v_add_f32_e32 v135, v135, v41
	v_exp_f32_e32 v58, v58
	v_mfma_f32_32x32x16_bf16 v[190:205], v[172:175], v[90:93], v[190:205]
	v_add_f32_e32 v133, v133, v42
	v_exp_f32_e32 v59, v59
	v_add_f32_e32 v135, v135, v43
	v_exp_f32_e32 v60, v60
	v_add_f32_e32 v133, v133, v44
	v_mfma_f32_32x32x16_bf16 v[206:221], v[176:179], v[90:93], v[206:221]
	v_exp_f32_e32 v61, v61
	v_add_f32_e32 v135, v135, v45
	v_exp_f32_e32 v62, v62
	v_add_f32_e32 v133, v133, v46
	v_exp_f32_e32 v63, v63
	v_add_f32_e32 v135, v135, v47
	v_mfma_f32_32x32x16_bf16 v[190:205], v[180:183], v[94:97], v[190:205]
	v_add_f32_e32 v133, v133, v48
	v_add_f32_e32 v135, v135, v49
	v_add_f32_e32 v133, v133, v50
	v_add_f32_e32 v135, v135, v51
	v_add_f32_e32 v133, v133, v52
	v_mfma_f32_32x32x16_bf16 v[206:221], v[184:187], v[94:97], v[206:221]
	v_add_f32_e32 v135, v135, v53
	v_add_f32_e32 v133, v133, v54
	v_add_f32_e32 v135, v135, v55
	v_add_f32_e32 v133, v133, v56
	v_add_f32_e32 v135, v135, v57
	v_mfma_f32_32x32x16_bf16 v[190:205], v[64:67], v[98:101], v[190:205]
	v_add_f32_e32 v133, v133, v58
	v_add_f32_e32 v135, v135, v59
	v_add_f32_e32 v133, v133, v60
	v_add_f32_e32 v135, v135, v61
	v_add_f32_e32 v133, v133, v62
	v_add_f32_e32 v135, v135, v63
	v_mfma_f32_32x32x16_bf16 v[206:221], v[68:71], v[98:101], v[206:221]
	v_cvt_pk_bf16_f32 v32, v32, v33
	v_cvt_pk_bf16_f32 v33, v34, v35
	v_cvt_pk_bf16_f32 v34, v36, v37
	v_cvt_pk_bf16_f32 v35, v38, v39
	v_cvt_pk_bf16_f32 v36, v40, v41
	v_mfma_f32_32x32x16_bf16 v[190:205], v[72:75], v[102:105], v[190:205]
	v_cvt_pk_bf16_f32 v37, v42, v43
	v_cvt_pk_bf16_f32 v38, v44, v45
	v_cvt_pk_bf16_f32 v39, v46, v47
	v_cvt_pk_bf16_f32 v48, v48, v49
	v_cvt_pk_bf16_f32 v49, v50, v51
	v_mfma_f32_32x32x16_bf16 v[206:221], v[76:79], v[102:105], v[206:221]
	v_cvt_pk_bf16_f32 v50, v52, v53
	v_cvt_pk_bf16_f32 v51, v54, v55
	v_cvt_pk_bf16_f32 v52, v56, v57
	v_cvt_pk_bf16_f32 v53, v58, v59
	v_cvt_pk_bf16_f32 v54, v60, v61
	v_cvt_pk_bf16_f32 v55, v62, v63
	s_waitcnt vmcnt(3) lgkmcnt(0)
	s_barrier
	ds_read_b128 v[156:159], v146 offset:32768
	ds_read_b128 v[160:163], v146 offset:40960
	ds_read_b128 v[164:167], v147 offset:32768
	ds_read_b128 v[168:171], v147 offset:40960
	ds_read_b128 v[172:175], v148 offset:32768
	ds_read_b128 v[176:179], v148 offset:40960
	ds_read_b128 v[180:183], v149 offset:32768
	ds_read_b128 v[184:187], v149 offset:40960
	ds_read_b128 v[64:67], v150 offset:32768
	ds_read_b128 v[68:71], v150 offset:40960
	ds_read_b128 v[72:75], v151 offset:32768
	ds_read_b128 v[76:79], v151 offset:40960
	v_mfma_f32_32x32x16_bf16 v[0:15], v[32:35], v[222:225], v[0:15]
	s_add_i32 m0, s60, 0x4000
	v_exp_f32_e32 v190, v190
	v_exp_f32_e32 v191, v191
	v_mfma_f32_32x32x16_bf16 v[0:15], v[36:39], v[226:229], v[0:15]
	global_load_lds_dwordx4 v124, s[56:57]
	global_load_lds_dwordx4 v126, s[56:57] offset:1024
	v_exp_f32_e32 v192, v192
	v_exp_f32_e32 v193, v193
	v_mfma_f32_32x32x16_bf16 v[0:15], v[48:51], v[230:233], v[0:15]
	s_add_u32 s56, s56, 0x4000
	s_addc_u32 s57, s57, 0
	v_exp_f32_e32 v194, v194
	v_exp_f32_e32 v195, v195
	v_mfma_f32_32x32x16_bf16 v[0:15], v[52:55], v[234:237], v[0:15]
	s_add_i32 m0, s60, 0xc000
	v_exp_f32_e32 v196, v196
	v_exp_f32_e32 v197, v197
	v_mfma_f32_32x32x16_bf16 v[16:31], v[32:35], v[238:241], v[16:31]
	global_load_lds_dwordx4 v128, s[58:59]
	v_exp_f32_e32 v198, v198
	v_exp_f32_e32 v199, v199
	v_mfma_f32_32x32x16_bf16 v[16:31], v[36:39], v[242:245], v[16:31]
	s_add_u32 s58, s58, 0x2000
	s_addc_u32 s59, s59, 0
	v_exp_f32_e32 v200, v200
	v_exp_f32_e32 v201, v201
	v_mfma_f32_32x32x16_bf16 v[16:31], v[48:51], v[246:249], v[16:31]
	v_exp_f32_e32 v202, v202
	v_exp_f32_e32 v203, v203
	v_mfma_f32_32x32x16_bf16 v[16:31], v[52:55], v[140:143], v[16:31]
	v_exp_f32_e32 v204, v204
	v_exp_f32_e32 v205, v205
	s_waitcnt lgkmcnt(0)
; __device__ __forceinline__ void finishSM(f32x16& p0, f32x16& p1, float& l_reg, bf16x8& pa0, bf16x8& pa1, bf16x8& pa2, bf16x8& pa3) {
; #pragma unroll
;   for (int r = 0; r < 16; ++r) p1[r] = __builtin_amdgcn_exp2f(p1[r]);
;   float ps = 0;
; #pragma unroll
;   for (int r = 0; r < 16; ++r) ps += p0[r];
; #pragma unroll
;   for (int r = 0; r < 16; ++r) ps += p1[r];
;   l_reg += ps;
;     ...
;   PK4(p0, 0, pa0); PK4(p0, 8, pa1); PK4(p1, 0, pa2); PK4(p1, 8, pa3);
;     ...
; }
; template <int ND> __device__ __forceinline__ void qkt(f32x16& p0, f32x16& p1, const bf16* Ks, const bf16x8* qr, int r32, int hi) {
;   p0 = f32x16{}; p1 = f32x16{};
; #pragma unroll
;   for (int d0 = 0; d0 < ND; ++d0) { int cb = (d0 * 16 + hi * 8) * 2;
;     bf16x8 b0 = *reinterpret_cast<const bf16x8*>((const char*)Ks + KSWZ(r32, cb));
;     bf16x8 b1 = *reinterpret_cast<const bf16x8*>((const char*)Ks + KSWZ(32 + r32, cb));
;     p0 = __builtin_amdgcn_mfma_f32_32x32x16_bf16(b0, qr[d0], p0, 0, 0, 0);
;     p1 = __builtin_amdgcn_mfma_f32_32x32x16_bf16(b1, qr[d0], p1, 0, 0, 0); }
; }
; __device__ __forceinline__ int v_st(int k, int c) { const int kk = (k & ~0xC) | ((k & 4) << 1) | ((k & 8) >> 1); return ((kk >> 3) * 4 + (c >> 5)) * 512 + ((kk & 7) * 32 + (c & 31)) * 2; }
; __device__ __forceinline__ int v_rd_base(int lane) { return ((lane & 3) << 3) | (((lane >> 2) & 3) << 6) | (((lane >> 4) & 1) << 5) | (((lane >> 5) & 1) << 8); }
; template <int OFF> __device__ __forceinline__ s16x4 tr_read(int vb) {
;   s16x4 r; asm volatile("ds_read_b64_tr_b16 %0, %1 offset:%2" : "=&v"(r) : "v"(vb), "i"(OFF) : "memory"); return r;
; }
; template <int D0> __device__ __forceinline__ void pv_one(f32x16& od, int vb, bf16x8 pa0, bf16x8 pa1, bf16x8 pa2, bf16x8 pa3) {
;   const s16x4 l0 = tr_read<v_rd_off(D0, 0, 0)>(vb), h0 = tr_read<v_rd_off(D0, 0, 1)>(vb), l1 = tr_read<v_rd_off(D0, 1, 0)>(vb), h1 = tr_read<v_rd_off(D0, 1, 1)>(vb);
;   const s16x4 l2 = tr_read<v_rd_off(D0, 2, 0)>(vb), h2 = tr_read<v_rd_off(D0, 2, 1)>(vb), l3 = tr_read<v_rd_off(D0, 3, 0)>(vb), h3 = tr_read<v_rd_off(D0, 3, 1)>(vb);
;   asm volatile("s_waitcnt lgkmcnt(0)" ::: "memory"); SBAR();
;     ...
;   od = __builtin_amdgcn_mfma_f32_32x32x16_bf16(pa0, PK(l0, h0), od, 0, 0, 0);
;   od = __builtin_amdgcn_mfma_f32_32x32x16_bf16(pa1, PK(l1, h1), od, 0, 0, 0);
;   od = __builtin_amdgcn_mfma_f32_32x32x16_bf16(pa2, PK(l2, h2), od, 0, 0, 0);
	ds_read_b64_tr_b16 v[222:223], v134 offset:16384
	ds_read_b64_tr_b16 v[224:225], v134 offset:18432
	ds_read_b64_tr_b16 v[226:227], v134 offset:20480
	ds_read_b64_tr_b16 v[228:229], v134 offset:22528
	ds_read_b64_tr_b16 v[230:231], v134 offset:24576
	ds_read_b64_tr_b16 v[232:233], v134 offset:26624
	ds_read_b64_tr_b16 v[234:235], v134 offset:28672
	ds_read_b64_tr_b16 v[236:237], v134 offset:30720
	v_mfma_f32_32x32x16_bf16 v[32:47], v[156:159], v[86:89], 0
	v_exp_f32_e32 v206, v206
	v_add_f32_e32 v133, v133, v190
	v_exp_f32_e32 v207, v207
	v_add_f32_e32 v135, v135, v191
	v_exp_f32_e32 v208, v208
	v_mfma_f32_32x32x16_bf16 v[48:63], v[160:163], v[86:89], 0
	v_add_f32_e32 v133, v133, v192
	v_exp_f32_e32 v209, v209
	v_add_f32_e32 v135, v135, v193
	v_exp_f32_e32 v210, v210
	v_add_f32_e32 v133, v133, v194
	v_mfma_f32_32x32x16_bf16 v[32:47], v[164:167], v[82:85], v[32:47]
	v_exp_f32_e32 v211, v211
	v_add_f32_e32 v135, v135, v195
	v_exp_f32_e32 v212, v212
	v_add_f32_e32 v133, v133, v196
	v_exp_f32_e32 v213, v213
	v_add_f32_e32 v135, v135, v197
	v_mfma_f32_32x32x16_bf16 v[48:63], v[168:171], v[82:85], v[48:63]
	s_waitcnt lgkmcnt(7)
	ds_read_b64_tr_b16 v[238:239], v134 offset:16896
	ds_read_b64_tr_b16 v[240:241], v134 offset:18944
	ds_read_b64_tr_b16 v[242:243], v134 offset:20992
	ds_read_b64_tr_b16 v[244:245], v134 offset:23040
	ds_read_b64_tr_b16 v[246:247], v134 offset:25088
	ds_read_b64_tr_b16 v[248:249], v134 offset:27136
	ds_read_b64_tr_b16 v[140:141], v134 offset:29184
	ds_read_b64_tr_b16 v[142:143], v134 offset:31232
	v_exp_f32_e32 v214, v214
	v_add_f32_e32 v133, v133, v198
	v_exp_f32_e32 v215, v215
	v_add_f32_e32 v135, v135, v199
	v_exp_f32_e32 v216, v216
	v_mfma_f32_32x32x16_bf16 v[32:47], v[172:175], v[90:93], v[32:47]
	v_add_f32_e32 v133, v133, v200
	v_exp_f32_e32 v217, v217
	v_add_f32_e32 v135, v135, v201
	v_exp_f32_e32 v218, v218
	v_add_f32_e32 v133, v133, v202
	v_mfma_f32_32x32x16_bf16 v[48:63], v[176:179], v[90:93], v[48:63]
	v_exp_f32_e32 v219, v219
	v_add_f32_e32 v135, v135, v203
	v_exp_f32_e32 v220, v220
	v_add_f32_e32 v133, v133, v204
	v_exp_f32_e32 v221, v221
	v_add_f32_e32 v135, v135, v205
	v_mfma_f32_32x32x16_bf16 v[32:47], v[180:183], v[94:97], v[32:47]
	v_add_f32_e32 v133, v133, v206
	v_add_f32_e32 v135, v135, v207
	v_add_f32_e32 v133, v133, v208
	v_add_f32_e32 v135, v135, v209
	v_add_f32_e32 v133, v133, v210
	v_mfma_f32_32x32x16_bf16 v[48:63], v[184:187], v[94:97], v[48:63]
	v_add_f32_e32 v135, v135, v211
	v_add_f32_e32 v133, v133, v212
	v_add_f32_e32 v135, v135, v213
	v_add_f32_e32 v133, v133, v214
	v_add_f32_e32 v135, v135, v215
	v_mfma_f32_32x32x16_bf16 v[32:47], v[64:67], v[98:101], v[32:47]
	v_add_f32_e32 v133, v133, v216
	v_add_f32_e32 v135, v135, v217
	v_add_f32_e32 v133, v133, v218
	v_add_f32_e32 v135, v135, v219
	v_add_f32_e32 v133, v133, v220
	v_add_f32_e32 v135, v135, v221
	v_mfma_f32_32x32x16_bf16 v[48:63], v[68:71], v[98:101], v[48:63]
	v_cvt_pk_bf16_f32 v190, v190, v191
	v_cvt_pk_bf16_f32 v191, v192, v193
	v_cvt_pk_bf16_f32 v192, v194, v195
	v_cvt_pk_bf16_f32 v193, v196, v197
	v_cvt_pk_bf16_f32 v194, v198, v199
	v_mfma_f32_32x32x16_bf16 v[32:47], v[72:75], v[102:105], v[32:47]
	v_cvt_pk_bf16_f32 v195, v200, v201
	v_cvt_pk_bf16_f32 v196, v202, v203
	v_cvt_pk_bf16_f32 v197, v204, v205
	v_cvt_pk_bf16_f32 v206, v206, v207
	v_cvt_pk_bf16_f32 v207, v208, v209
	v_mfma_f32_32x32x16_bf16 v[48:63], v[76:79], v[102:105], v[48:63]
	v_cvt_pk_bf16_f32 v208, v210, v211
	v_cvt_pk_bf16_f32 v209, v212, v213
	v_cvt_pk_bf16_f32 v210, v214, v215
	v_cvt_pk_bf16_f32 v211, v216, v217
	v_cvt_pk_bf16_f32 v212, v218, v219
	v_cvt_pk_bf16_f32 v213, v220, v221
	s_waitcnt vmcnt(3) lgkmcnt(0)
	s_barrier
	ds_read_b128 v[156:159], v146 offset:0
	ds_read_b128 v[160:163], v146 offset:8192
	ds_read_b128 v[164:167], v147 offset:0
	ds_read_b128 v[168:171], v147 offset:8192
	ds_read_b128 v[172:175], v148 offset:0
	ds_read_b128 v[176:179], v148 offset:8192
	ds_read_b128 v[180:183], v149 offset:0
	ds_read_b128 v[184:187], v149 offset:8192
	ds_read_b128 v[64:67], v150 offset:0
	ds_read_b128 v[68:71], v150 offset:8192
	ds_read_b128 v[72:75], v151 offset:0
	ds_read_b128 v[76:79], v151 offset:8192
	v_mfma_f32_32x32x16_bf16 v[0:15], v[190:193], v[222:225], v[0:15]
	s_add_i32 m0, s60, 0x8000
	v_exp_f32_e32 v32, v32
	v_exp_f32_e32 v33, v33
	v_mfma_f32_32x32x16_bf16 v[0:15], v[194:197], v[226:229], v[0:15]
	global_load_lds_dwordx4 v124, s[56:57]
	global_load_lds_dwordx4 v126, s[56:57] offset:1024
	v_exp_f32_e32 v34, v34
	v_exp_f32_e32 v35, v35
	v_mfma_f32_32x32x16_bf16 v[0:15], v[206:209], v[230:233], v[0:15]
	s_add_u32 s56, s56, 0x4000
	s_addc_u32 s57, s57, 0
	v_exp_f32_e32 v36, v36
	v_exp_f32_e32 v37, v37
	v_mfma_f32_32x32x16_bf16 v[0:15], v[210:213], v[234:237], v[0:15]
	s_add_i32 m0, s60, 0x10000
	v_exp_f32_e32 v38, v38
	v_exp_f32_e32 v39, v39
	v_mfma_f32_32x32x16_bf16 v[16:31], v[190:193], v[238:241], v[16:31]
	global_load_lds_dwordx4 v128, s[58:59]
	v_exp_f32_e32 v40, v40
	v_exp_f32_e32 v41, v41
	v_mfma_f32_32x32x16_bf16 v[16:31], v[194:197], v[242:245], v[16:31]
	s_add_u32 s58, s58, 0x2000
	s_addc_u32 s59, s59, 0
	v_exp_f32_e32 v42, v42
	v_exp_f32_e32 v43, v43
	v_mfma_f32_32x32x16_bf16 v[16:31], v[206:209], v[246:249], v[16:31]
	v_exp_f32_e32 v44, v44
	v_exp_f32_e32 v45, v45
	v_mfma_f32_32x32x16_bf16 v[16:31], v[210:213], v[140:143], v[16:31]
	v_exp_f32_e32 v46, v46
	v_exp_f32_e32 v47, v47
	s_waitcnt lgkmcnt(0)
; __device__ __forceinline__ void finishSM(f32x16& p0, f32x16& p1, float& l_reg, bf16x8& pa0, bf16x8& pa1, bf16x8& pa2, bf16x8& pa3) {
; #pragma unroll
;   for (int r = 0; r < 16; ++r) p1[r] = __builtin_amdgcn_exp2f(p1[r]);
;   float ps = 0;
; #pragma unroll
;   for (int r = 0; r < 16; ++r) ps += p0[r];
; #pragma unroll
;   for (int r = 0; r < 16; ++r) ps += p1[r];
;   l_reg += ps;
;     ...
;   PK4(p0, 0, pa0); PK4(p0, 8, pa1); PK4(p1, 0, pa2); PK4(p1, 8, pa3);
;     ...
; }
; template <int ND> __device__ __forceinline__ void qkt(f32x16& p0, f32x16& p1, const bf16* Ks, const bf16x8* qr, int r32, int hi) {
;   p0 = f32x16{}; p1 = f32x16{};
; #pragma unroll
;   for (int d0 = 0; d0 < ND; ++d0) { int cb = (d0 * 16 + hi * 8) * 2;
;     bf16x8 b0 = *reinterpret_cast<const bf16x8*>((const char*)Ks + KSWZ(r32, cb));
;     bf16x8 b1 = *reinterpret_cast<const bf16x8*>((const char*)Ks + KSWZ(32 + r32, cb));
;     p0 = __builtin_amdgcn_mfma_f32_32x32x16_bf16(b0, qr[d0], p0, 0, 0, 0);
;     p1 = __builtin_amdgcn_mfma_f32_32x32x16_bf16(b1, qr[d0], p1, 0, 0, 0); }
; }
; __device__ __forceinline__ int v_st(int k, int c) { const int kk = (k & ~0xC) | ((k & 4) << 1) | ((k & 8) >> 1); return ((kk >> 3) * 4 + (c >> 5)) * 512 + ((kk & 7) * 32 + (c & 31)) * 2; }
; __device__ __forceinline__ int v_rd_base(int lane) { return ((lane & 3) << 3) | (((lane >> 2) & 3) << 6) | (((lane >> 4) & 1) << 5) | (((lane >> 5) & 1) << 8); }
; template <int OFF> __device__ __forceinline__ s16x4 tr_read(int vb) {
;   s16x4 r; asm volatile("ds_read_b64_tr_b16 %0, %1 offset:%2" : "=&v"(r) : "v"(vb), "i"(OFF) : "memory"); return r;
; }
; template <int D0> __device__ __forceinline__ void pv_one(f32x16& od, int vb, bf16x8 pa0, bf16x8 pa1, bf16x8 pa2, bf16x8 pa3) {
;   const s16x4 l0 = tr_read<v_rd_off(D0, 0, 0)>(vb), h0 = tr_read<v_rd_off(D0, 0, 1)>(vb), l1 = tr_read<v_rd_off(D0, 1, 0)>(vb), h1 = tr_read<v_rd_off(D0, 1, 1)>(vb);
;   const s16x4 l2 = tr_read<v_rd_off(D0, 2, 0)>(vb), h2 = tr_read<v_rd_off(D0, 2, 1)>(vb), l3 = tr_read<v_rd_off(D0, 3, 0)>(vb), h3 = tr_read<v_rd_off(D0, 3, 1)>(vb);
;   asm volatile("s_waitcnt lgkmcnt(0)" ::: "memory"); SBAR();
;     ...
;   od = __builtin_amdgcn_mfma_f32_32x32x16_bf16(pa0, PK(l0, h0), od, 0, 0, 0);
;   od = __builtin_amdgcn_mfma_f32_32x32x16_bf16(pa1, PK(l1, h1), od, 0, 0, 0);
;   od = __builtin_amdgcn_mfma_f32_32x32x16_bf16(pa2, PK(l2, h2), od, 0, 0, 0);
	ds_read_b64_tr_b16 v[222:223], v134 offset:32768
	ds_read_b64_tr_b16 v[224:225], v134 offset:34816
	ds_read_b64_tr_b16 v[226:227], v134 offset:36864
	ds_read_b64_tr_b16 v[228:229], v134 offset:38912
	ds_read_b64_tr_b16 v[230:231], v134 offset:40960
	ds_read_b64_tr_b16 v[232:233], v134 offset:43008
	ds_read_b64_tr_b16 v[234:235], v134 offset:45056
	ds_read_b64_tr_b16 v[236:237], v134 offset:47104
	v_mfma_f32_32x32x16_bf16 v[190:205], v[156:159], v[86:89], 0
	v_exp_f32_e32 v48, v48
	v_add_f32_e32 v133, v133, v32
	v_exp_f32_e32 v49, v49
	v_add_f32_e32 v135, v135, v33
	v_exp_f32_e32 v50, v50
	v_mfma_f32_32x32x16_bf16 v[206:221], v[160:163], v[86:89], 0
	v_add_f32_e32 v133, v133, v34
	v_exp_f32_e32 v51, v51
	v_add_f32_e32 v135, v135, v35
	v_exp_f32_e32 v52, v52
	v_add_f32_e32 v133, v133, v36
	v_mfma_f32_32x32x16_bf16 v[190:205], v[164:167], v[82:85], v[190:205]
	v_exp_f32_e32 v53, v53
	v_add_f32_e32 v135, v135, v37
	v_exp_f32_e32 v54, v54
	v_add_f32_e32 v133, v133, v38
	v_exp_f32_e32 v55, v55
	v_add_f32_e32 v135, v135, v39
	v_mfma_f32_32x32x16_bf16 v[206:221], v[168:171], v[82:85], v[206:221]
	s_waitcnt lgkmcnt(7)
	ds_read_b64_tr_b16 v[238:239], v134 offset:33280
	ds_read_b64_tr_b16 v[240:241], v134 offset:35328
	ds_read_b64_tr_b16 v[242:243], v134 offset:37376
	ds_read_b64_tr_b16 v[244:245], v134 offset:39424
	ds_read_b64_tr_b16 v[246:247], v134 offset:41472
	ds_read_b64_tr_b16 v[248:249], v134 offset:43520
	ds_read_b64_tr_b16 v[140:141], v134 offset:45568
	ds_read_b64_tr_b16 v[142:143], v134 offset:47616
	v_exp_f32_e32 v56, v56
	v_add_f32_e32 v133, v133, v40
	v_exp_f32_e32 v57, v57
	v_add_f32_e32 v135, v135, v41
	v_exp_f32_e32 v58, v58
	v_mfma_f32_32x32x16_bf16 v[190:205], v[172:175], v[90:93], v[190:205]
	v_add_f32_e32 v133, v133, v42
	v_exp_f32_e32 v59, v59
	v_add_f32_e32 v135, v135, v43
	v_exp_f32_e32 v60, v60
	v_add_f32_e32 v133, v133, v44
	v_mfma_f32_32x32x16_bf16 v[206:221], v[176:179], v[90:93], v[206:221]
	v_exp_f32_e32 v61, v61
	v_add_f32_e32 v135, v135, v45
	v_exp_f32_e32 v62, v62
	v_add_f32_e32 v133, v133, v46
	v_exp_f32_e32 v63, v63
	v_add_f32_e32 v135, v135, v47
	v_mfma_f32_32x32x16_bf16 v[190:205], v[180:183], v[94:97], v[190:205]
	v_add_f32_e32 v133, v133, v48
	v_add_f32_e32 v135, v135, v49
	v_add_f32_e32 v133, v133, v50
	v_add_f32_e32 v135, v135, v51
	v_add_f32_e32 v133, v133, v52
	v_mfma_f32_32x32x16_bf16 v[206:221], v[184:187], v[94:97], v[206:221]
	v_add_f32_e32 v135, v135, v53
	v_add_f32_e32 v133, v133, v54
	v_add_f32_e32 v135, v135, v55
	v_add_f32_e32 v133, v133, v56
	v_add_f32_e32 v135, v135, v57
	v_mfma_f32_32x32x16_bf16 v[190:205], v[64:67], v[98:101], v[190:205]
	v_add_f32_e32 v133, v133, v58
	v_add_f32_e32 v135, v135, v59
	v_add_f32_e32 v133, v133, v60
	v_add_f32_e32 v135, v135, v61
	v_add_f32_e32 v133, v133, v62
	v_add_f32_e32 v135, v135, v63
	v_mfma_f32_32x32x16_bf16 v[206:221], v[68:71], v[98:101], v[206:221]
	v_cvt_pk_bf16_f32 v32, v32, v33
	v_cvt_pk_bf16_f32 v33, v34, v35
	v_cvt_pk_bf16_f32 v34, v36, v37
	v_cvt_pk_bf16_f32 v35, v38, v39
	v_cvt_pk_bf16_f32 v36, v40, v41
	v_mfma_f32_32x32x16_bf16 v[190:205], v[72:75], v[102:105], v[190:205]
	v_cvt_pk_bf16_f32 v37, v42, v43
	v_cvt_pk_bf16_f32 v38, v44, v45
	v_cvt_pk_bf16_f32 v39, v46, v47
	v_cvt_pk_bf16_f32 v48, v48, v49
	v_cvt_pk_bf16_f32 v49, v50, v51
	v_mfma_f32_32x32x16_bf16 v[206:221], v[76:79], v[102:105], v[206:221]
	v_cvt_pk_bf16_f32 v50, v52, v53
	v_cvt_pk_bf16_f32 v51, v54, v55
	v_cvt_pk_bf16_f32 v52, v56, v57
	v_cvt_pk_bf16_f32 v53, v58, v59
	v_cvt_pk_bf16_f32 v54, v60, v61
	v_cvt_pk_bf16_f32 v55, v62, v63
	s_waitcnt vmcnt(3) lgkmcnt(0)
	s_barrier
	ds_read_b128 v[156:159], v146 offset:16384
	ds_read_b128 v[160:163], v146 offset:24576
	ds_read_b128 v[164:167], v147 offset:16384
	ds_read_b128 v[168:171], v147 offset:24576
	ds_read_b128 v[172:175], v148 offset:16384
	ds_read_b128 v[176:179], v148 offset:24576
	ds_read_b128 v[180:183], v149 offset:16384
	ds_read_b128 v[184:187], v149 offset:24576
	ds_read_b128 v[64:67], v150 offset:16384
	ds_read_b128 v[68:71], v150 offset:24576
	ds_read_b128 v[72:75], v151 offset:16384
	ds_read_b128 v[76:79], v151 offset:24576
	v_mfma_f32_32x32x16_bf16 v[0:15], v[32:35], v[222:225], v[0:15]
	s_add_i32 m0, s60, 0x0
	v_exp_f32_e32 v190, v190
	v_exp_f32_e32 v191, v191
	v_mfma_f32_32x32x16_bf16 v[0:15], v[36:39], v[226:229], v[0:15]
	global_load_lds_dwordx4 v124, s[56:57]
	global_load_lds_dwordx4 v126, s[56:57] offset:1024
	v_exp_f32_e32 v192, v192
	v_exp_f32_e32 v193, v193
	v_mfma_f32_32x32x16_bf16 v[0:15], v[48:51], v[230:233], v[0:15]
	s_add_u32 s56, s56, 0x4000
	s_addc_u32 s57, s57, 0
	v_exp_f32_e32 v194, v194
	v_exp_f32_e32 v195, v195
	v_mfma_f32_32x32x16_bf16 v[0:15], v[52:55], v[234:237], v[0:15]
	s_add_i32 m0, s60, 0x14000
	v_exp_f32_e32 v196, v196
	v_exp_f32_e32 v197, v197
	v_mfma_f32_32x32x16_bf16 v[16:31], v[32:35], v[238:241], v[16:31]
	global_load_lds_dwordx4 v128, s[58:59]
	v_exp_f32_e32 v198, v198
	v_exp_f32_e32 v199, v199
	v_mfma_f32_32x32x16_bf16 v[16:31], v[36:39], v[242:245], v[16:31]
	s_add_u32 s58, s58, 0x2000
	s_addc_u32 s59, s59, 0
	v_exp_f32_e32 v200, v200
	v_exp_f32_e32 v201, v201
	v_mfma_f32_32x32x16_bf16 v[16:31], v[48:51], v[246:249], v[16:31]
	v_exp_f32_e32 v202, v202
	v_exp_f32_e32 v203, v203
	v_mfma_f32_32x32x16_bf16 v[16:31], v[52:55], v[140:143], v[16:31]
	v_exp_f32_e32 v204, v204
	v_exp_f32_e32 v205, v205
	s_waitcnt lgkmcnt(0)
; __device__ __forceinline__ void finishSM(f32x16& p0, f32x16& p1, float& l_reg, bf16x8& pa0, bf16x8& pa1, bf16x8& pa2, bf16x8& pa3) {
; #pragma unroll
;   for (int r = 0; r < 16; ++r) p1[r] = __builtin_amdgcn_exp2f(p1[r]);
;   float ps = 0;
; #pragma unroll
;   for (int r = 0; r < 16; ++r) ps += p0[r];
; #pragma unroll
;   for (int r = 0; r < 16; ++r) ps += p1[r];
;   l_reg += ps;
;     ...
;   PK4(p0, 0, pa0); PK4(p0, 8, pa1); PK4(p1, 0, pa2); PK4(p1, 8, pa3);
;     ...
; }
; template <int ND> __device__ __forceinline__ void qkt(f32x16& p0, f32x16& p1, const bf16* Ks, const bf16x8* qr, int r32, int hi) {
;   p0 = f32x16{}; p1 = f32x16{};
; #pragma unroll
;   for (int d0 = 0; d0 < ND; ++d0) { int cb = (d0 * 16 + hi * 8) * 2;
;     bf16x8 b0 = *reinterpret_cast<const bf16x8*>((const char*)Ks + KSWZ(r32, cb));
;     bf16x8 b1 = *reinterpret_cast<const bf16x8*>((const char*)Ks + KSWZ(32 + r32, cb));
;     p0 = __builtin_amdgcn_mfma_f32_32x32x16_bf16(b0, qr[d0], p0, 0, 0, 0);
;     p1 = __builtin_amdgcn_mfma_f32_32x32x16_bf16(b1, qr[d0], p1, 0, 0, 0); }
; }
; __device__ __forceinline__ int v_st(int k, int c) { const int kk = (k & ~0xC) | ((k & 4) << 1) | ((k & 8) >> 1); return ((kk >> 3) * 4 + (c >> 5)) * 512 + ((kk & 7) * 32 + (c & 31)) * 2; }
; __device__ __forceinline__ int v_rd_base(int lane) { return ((lane & 3) << 3) | (((lane >> 2) & 3) << 6) | (((lane >> 4) & 1) << 5) | (((lane >> 5) & 1) << 8); }
; template <int OFF> __device__ __forceinline__ s16x4 tr_read(int vb) {
;   s16x4 r; asm volatile("ds_read_b64_tr_b16 %0, %1 offset:%2" : "=&v"(r) : "v"(vb), "i"(OFF) : "memory"); return r;
; }
; template <int D0> __device__ __forceinline__ void pv_one(f32x16& od, int vb, bf16x8 pa0, bf16x8 pa1, bf16x8 pa2, bf16x8 pa3) {
;   const s16x4 l0 = tr_read<v_rd_off(D0, 0, 0)>(vb), h0 = tr_read<v_rd_off(D0, 0, 1)>(vb), l1 = tr_read<v_rd_off(D0, 1, 0)>(vb), h1 = tr_read<v_rd_off(D0, 1, 1)>(vb);
;   const s16x4 l2 = tr_read<v_rd_off(D0, 2, 0)>(vb), h2 = tr_read<v_rd_off(D0, 2, 1)>(vb), l3 = tr_read<v_rd_off(D0, 3, 0)>(vb), h3 = tr_read<v_rd_off(D0, 3, 1)>(vb);
;   asm volatile("s_waitcnt lgkmcnt(0)" ::: "memory"); SBAR();
;     ...
;   od = __builtin_amdgcn_mfma_f32_32x32x16_bf16(pa0, PK(l0, h0), od, 0, 0, 0);
;   od = __builtin_amdgcn_mfma_f32_32x32x16_bf16(pa1, PK(l1, h1), od, 0, 0, 0);
;   od = __builtin_amdgcn_mfma_f32_32x32x16_bf16(pa2, PK(l2, h2), od, 0, 0, 0);
	ds_read_b64_tr_b16 v[222:223], v134 offset:0
	ds_read_b64_tr_b16 v[224:225], v134 offset:2048
	ds_read_b64_tr_b16 v[226:227], v134 offset:4096
	ds_read_b64_tr_b16 v[228:229], v134 offset:6144
	ds_read_b64_tr_b16 v[230:231], v134 offset:8192
	ds_read_b64_tr_b16 v[232:233], v134 offset:10240
	ds_read_b64_tr_b16 v[234:235], v134 offset:12288
	ds_read_b64_tr_b16 v[236:237], v134 offset:14336
	v_mfma_f32_32x32x16_bf16 v[32:47], v[156:159], v[86:89], 0
	v_exp_f32_e32 v206, v206
	v_add_f32_e32 v133, v133, v190
	v_exp_f32_e32 v207, v207
	v_add_f32_e32 v135, v135, v191
	v_exp_f32_e32 v208, v208
	v_mfma_f32_32x32x16_bf16 v[48:63], v[160:163], v[86:89], 0
	v_add_f32_e32 v133, v133, v192
	v_exp_f32_e32 v209, v209
	v_add_f32_e32 v135, v135, v193
	v_exp_f32_e32 v210, v210
	v_add_f32_e32 v133, v133, v194
	v_mfma_f32_32x32x16_bf16 v[32:47], v[164:167], v[82:85], v[32:47]
	v_exp_f32_e32 v211, v211
	v_add_f32_e32 v135, v135, v195
	v_exp_f32_e32 v212, v212
	v_add_f32_e32 v133, v133, v196
	v_exp_f32_e32 v213, v213
	v_add_f32_e32 v135, v135, v197
	v_mfma_f32_32x32x16_bf16 v[48:63], v[168:171], v[82:85], v[48:63]
	s_waitcnt lgkmcnt(7)
	ds_read_b64_tr_b16 v[238:239], v134 offset:512
	ds_read_b64_tr_b16 v[240:241], v134 offset:2560
	ds_read_b64_tr_b16 v[242:243], v134 offset:4608
	ds_read_b64_tr_b16 v[244:245], v134 offset:6656
	ds_read_b64_tr_b16 v[246:247], v134 offset:8704
	ds_read_b64_tr_b16 v[248:249], v134 offset:10752
	ds_read_b64_tr_b16 v[140:141], v134 offset:12800
	ds_read_b64_tr_b16 v[142:143], v134 offset:14848
	v_exp_f32_e32 v214, v214
	v_add_f32_e32 v133, v133, v198
	v_exp_f32_e32 v215, v215
	v_add_f32_e32 v135, v135, v199
	v_exp_f32_e32 v216, v216
	v_mfma_f32_32x32x16_bf16 v[32:47], v[172:175], v[90:93], v[32:47]
	v_add_f32_e32 v133, v133, v200
	v_exp_f32_e32 v217, v217
	v_add_f32_e32 v135, v135, v201
	v_exp_f32_e32 v218, v218
	v_add_f32_e32 v133, v133, v202
	v_mfma_f32_32x32x16_bf16 v[48:63], v[176:179], v[90:93], v[48:63]
	v_exp_f32_e32 v219, v219
	v_add_f32_e32 v135, v135, v203
	v_exp_f32_e32 v220, v220
	v_add_f32_e32 v133, v133, v204
	v_exp_f32_e32 v221, v221
	v_add_f32_e32 v135, v135, v205
	v_mfma_f32_32x32x16_bf16 v[32:47], v[180:183], v[94:97], v[32:47]
	v_add_f32_e32 v133, v133, v206
	v_add_f32_e32 v135, v135, v207
	v_add_f32_e32 v133, v133, v208
	v_add_f32_e32 v135, v135, v209
	v_add_f32_e32 v133, v133, v210
	v_mfma_f32_32x32x16_bf16 v[48:63], v[184:187], v[94:97], v[48:63]
	v_add_f32_e32 v135, v135, v211
	v_add_f32_e32 v133, v133, v212
	v_add_f32_e32 v135, v135, v213
	v_add_f32_e32 v133, v133, v214
	v_add_f32_e32 v135, v135, v215
	v_mfma_f32_32x32x16_bf16 v[32:47], v[64:67], v[98:101], v[32:47]
	v_add_f32_e32 v133, v133, v216
	v_add_f32_e32 v135, v135, v217
	v_add_f32_e32 v133, v133, v218
	v_add_f32_e32 v135, v135, v219
	v_add_f32_e32 v133, v133, v220
	v_add_f32_e32 v135, v135, v221
	v_mfma_f32_32x32x16_bf16 v[48:63], v[68:71], v[98:101], v[48:63]
	v_cvt_pk_bf16_f32 v190, v190, v191
	v_cvt_pk_bf16_f32 v191, v192, v193
	v_cvt_pk_bf16_f32 v192, v194, v195
	v_cvt_pk_bf16_f32 v193, v196, v197
	v_cvt_pk_bf16_f32 v194, v198, v199
	v_mfma_f32_32x32x16_bf16 v[32:47], v[72:75], v[102:105], v[32:47]
	v_cvt_pk_bf16_f32 v195, v200, v201
	v_cvt_pk_bf16_f32 v196, v202, v203
	v_cvt_pk_bf16_f32 v197, v204, v205
	v_cvt_pk_bf16_f32 v206, v206, v207
	v_cvt_pk_bf16_f32 v207, v208, v209
	v_mfma_f32_32x32x16_bf16 v[48:63], v[76:79], v[102:105], v[48:63]
	v_cvt_pk_bf16_f32 v208, v210, v211
	v_cvt_pk_bf16_f32 v209, v212, v213
	v_cvt_pk_bf16_f32 v210, v214, v215
	v_cvt_pk_bf16_f32 v211, v216, v217
	v_cvt_pk_bf16_f32 v212, v218, v219
	v_cvt_pk_bf16_f32 v213, v220, v221
	s_waitcnt vmcnt(3) lgkmcnt(0)
	s_barrier
	ds_read_b128 v[156:159], v146 offset:32768
	ds_read_b128 v[160:163], v146 offset:40960
	ds_read_b128 v[164:167], v147 offset:32768
	ds_read_b128 v[168:171], v147 offset:40960
	ds_read_b128 v[172:175], v148 offset:32768
	ds_read_b128 v[176:179], v148 offset:40960
	ds_read_b128 v[180:183], v149 offset:32768
	ds_read_b128 v[184:187], v149 offset:40960
	ds_read_b128 v[64:67], v150 offset:32768
	ds_read_b128 v[68:71], v150 offset:40960
	ds_read_b128 v[72:75], v151 offset:32768
	ds_read_b128 v[76:79], v151 offset:40960
	v_mfma_f32_32x32x16_bf16 v[0:15], v[190:193], v[222:225], v[0:15]
	s_add_i32 m0, s60, 0x4000
	v_exp_f32_e32 v32, v32
	v_exp_f32_e32 v33, v33
	v_mfma_f32_32x32x16_bf16 v[0:15], v[194:197], v[226:229], v[0:15]
	global_load_lds_dwordx4 v124, s[56:57]
	global_load_lds_dwordx4 v126, s[56:57] offset:1024
	v_exp_f32_e32 v34, v34
	v_exp_f32_e32 v35, v35
	v_mfma_f32_32x32x16_bf16 v[0:15], v[206:209], v[230:233], v[0:15]
	s_add_u32 s56, s56, 0x4000
	s_addc_u32 s57, s57, 0
	v_exp_f32_e32 v36, v36
	v_exp_f32_e32 v37, v37
	v_mfma_f32_32x32x16_bf16 v[0:15], v[210:213], v[234:237], v[0:15]
	s_add_i32 m0, s60, 0xc000
	v_exp_f32_e32 v38, v38
	v_exp_f32_e32 v39, v39
	v_mfma_f32_32x32x16_bf16 v[16:31], v[190:193], v[238:241], v[16:31]
	global_load_lds_dwordx4 v128, s[58:59]
	v_exp_f32_e32 v40, v40
	v_exp_f32_e32 v41, v41
	v_mfma_f32_32x32x16_bf16 v[16:31], v[194:197], v[242:245], v[16:31]
	s_add_u32 s58, s58, 0x2000
	s_addc_u32 s59, s59, 0
	v_exp_f32_e32 v42, v42
	v_exp_f32_e32 v43, v43
	v_mfma_f32_32x32x16_bf16 v[16:31], v[206:209], v[246:249], v[16:31]
	v_exp_f32_e32 v44, v44
	v_exp_f32_e32 v45, v45
	v_mfma_f32_32x32x16_bf16 v[16:31], v[210:213], v[140:143], v[16:31]
	v_exp_f32_e32 v46, v46
	v_exp_f32_e32 v47, v47
	s_waitcnt lgkmcnt(0)
; __device__ __forceinline__ void finishSM(f32x16& p0, f32x16& p1, float& l_reg, bf16x8& pa0, bf16x8& pa1, bf16x8& pa2, bf16x8& pa3) {
; #pragma unroll
;   for (int r = 0; r < 16; ++r) p1[r] = __builtin_amdgcn_exp2f(p1[r]);
;   float ps = 0;
; #pragma unroll
;   for (int r = 0; r < 16; ++r) ps += p0[r];
; #pragma unroll
;   for (int r = 0; r < 16; ++r) ps += p1[r];
;   l_reg += ps;
;     ...
;   PK4(p0, 0, pa0); PK4(p0, 8, pa1); PK4(p1, 0, pa2); PK4(p1, 8, pa3);
;     ...
; }
; template <int ND> __device__ __forceinline__ void qkt(f32x16& p0, f32x16& p1, const bf16* Ks, const bf16x8* qr, int r32, int hi) {
;   p0 = f32x16{}; p1 = f32x16{};
; #pragma unroll
;   for (int d0 = 0; d0 < ND; ++d0) { int cb = (d0 * 16 + hi * 8) * 2;
;     bf16x8 b0 = *reinterpret_cast<const bf16x8*>((const char*)Ks + KSWZ(r32, cb));
;     bf16x8 b1 = *reinterpret_cast<const bf16x8*>((const char*)Ks + KSWZ(32 + r32, cb));
;     p0 = __builtin_amdgcn_mfma_f32_32x32x16_bf16(b0, qr[d0], p0, 0, 0, 0);
;     p1 = __builtin_amdgcn_mfma_f32_32x32x16_bf16(b1, qr[d0], p1, 0, 0, 0); }
; }
; __device__ __forceinline__ int v_st(int k, int c) { const int kk = (k & ~0xC) | ((k & 4) << 1) | ((k & 8) >> 1); return ((kk >> 3) * 4 + (c >> 5)) * 512 + ((kk & 7) * 32 + (c & 31)) * 2; }
; __device__ __forceinline__ int v_rd_base(int lane) { return ((lane & 3) << 3) | (((lane >> 2) & 3) << 6) | (((lane >> 4) & 1) << 5) | (((lane >> 5) & 1) << 8); }
; template <int OFF> __device__ __forceinline__ s16x4 tr_read(int vb) {
;   s16x4 r; asm volatile("ds_read_b64_tr_b16 %0, %1 offset:%2" : "=&v"(r) : "v"(vb), "i"(OFF) : "memory"); return r;
; }
; template <int D0> __device__ __forceinline__ void pv_one(f32x16& od, int vb, bf16x8 pa0, bf16x8 pa1, bf16x8 pa2, bf16x8 pa3) {
;   const s16x4 l0 = tr_read<v_rd_off(D0, 0, 0)>(vb), h0 = tr_read<v_rd_off(D0, 0, 1)>(vb), l1 = tr_read<v_rd_off(D0, 1, 0)>(vb), h1 = tr_read<v_rd_off(D0, 1, 1)>(vb);
;   const s16x4 l2 = tr_read<v_rd_off(D0, 2, 0)>(vb), h2 = tr_read<v_rd_off(D0, 2, 1)>(vb), l3 = tr_read<v_rd_off(D0, 3, 0)>(vb), h3 = tr_read<v_rd_off(D0, 3, 1)>(vb);
;   asm volatile("s_waitcnt lgkmcnt(0)" ::: "memory"); SBAR();
;     ...
;   od = __builtin_amdgcn_mfma_f32_32x32x16_bf16(pa0, PK(l0, h0), od, 0, 0, 0);
;   od = __builtin_amdgcn_mfma_f32_32x32x16_bf16(pa1, PK(l1, h1), od, 0, 0, 0);
;   od = __builtin_amdgcn_mfma_f32_32x32x16_bf16(pa2, PK(l2, h2), od, 0, 0, 0);
	ds_read_b64_tr_b16 v[222:223], v134 offset:16384
	ds_read_b64_tr_b16 v[224:225], v134 offset:18432
	ds_read_b64_tr_b16 v[226:227], v134 offset:20480
	ds_read_b64_tr_b16 v[228:229], v134 offset:22528
	ds_read_b64_tr_b16 v[230:231], v134 offset:24576
	ds_read_b64_tr_b16 v[232:233], v134 offset:26624
	ds_read_b64_tr_b16 v[234:235], v134 offset:28672
	ds_read_b64_tr_b16 v[236:237], v134 offset:30720
	v_mfma_f32_32x32x16_bf16 v[190:205], v[156:159], v[86:89], 0
	v_exp_f32_e32 v48, v48
	v_add_f32_e32 v133, v133, v32
	v_exp_f32_e32 v49, v49
	v_add_f32_e32 v135, v135, v33
	v_exp_f32_e32 v50, v50
	v_mfma_f32_32x32x16_bf16 v[206:221], v[160:163], v[86:89], 0
	v_add_f32_e32 v133, v133, v34
	v_exp_f32_e32 v51, v51
	v_add_f32_e32 v135, v135, v35
	v_exp_f32_e32 v52, v52
	v_add_f32_e32 v133, v133, v36
	v_mfma_f32_32x32x16_bf16 v[190:205], v[164:167], v[82:85], v[190:205]
	v_exp_f32_e32 v53, v53
	v_add_f32_e32 v135, v135, v37
	v_exp_f32_e32 v54, v54
	v_add_f32_e32 v133, v133, v38
	v_exp_f32_e32 v55, v55
	v_add_f32_e32 v135, v135, v39
	v_mfma_f32_32x32x16_bf16 v[206:221], v[168:171], v[82:85], v[206:221]
	s_waitcnt lgkmcnt(7)
	ds_read_b64_tr_b16 v[238:239], v134 offset:16896
	ds_read_b64_tr_b16 v[240:241], v134 offset:18944
	ds_read_b64_tr_b16 v[242:243], v134 offset:20992
	ds_read_b64_tr_b16 v[244:245], v134 offset:23040
	ds_read_b64_tr_b16 v[246:247], v134 offset:25088
	ds_read_b64_tr_b16 v[248:249], v134 offset:27136
	ds_read_b64_tr_b16 v[140:141], v134 offset:29184
	ds_read_b64_tr_b16 v[142:143], v134 offset:31232
	v_exp_f32_e32 v56, v56
	v_add_f32_e32 v133, v133, v40
	v_exp_f32_e32 v57, v57
	v_add_f32_e32 v135, v135, v41
	v_exp_f32_e32 v58, v58
	v_mfma_f32_32x32x16_bf16 v[190:205], v[172:175], v[90:93], v[190:205]
	v_add_f32_e32 v133, v133, v42
	v_exp_f32_e32 v59, v59
	v_add_f32_e32 v135, v135, v43
	v_exp_f32_e32 v60, v60
	v_add_f32_e32 v133, v133, v44
	v_mfma_f32_32x32x16_bf16 v[206:221], v[176:179], v[90:93], v[206:221]
	v_exp_f32_e32 v61, v61
	v_add_f32_e32 v135, v135, v45
	v_exp_f32_e32 v62, v62
	v_add_f32_e32 v133, v133, v46
	v_exp_f32_e32 v63, v63
	v_add_f32_e32 v135, v135, v47
	v_mfma_f32_32x32x16_bf16 v[190:205], v[180:183], v[94:97], v[190:205]
	v_add_f32_e32 v133, v133, v48
	v_add_f32_e32 v135, v135, v49
	v_add_f32_e32 v133, v133, v50
	v_add_f32_e32 v135, v135, v51
	v_add_f32_e32 v133, v133, v52
	v_mfma_f32_32x32x16_bf16 v[206:221], v[184:187], v[94:97], v[206:221]
	v_add_f32_e32 v135, v135, v53
	v_add_f32_e32 v133, v133, v54
	v_add_f32_e32 v135, v135, v55
	v_add_f32_e32 v133, v133, v56
	v_add_f32_e32 v135, v135, v57
	v_mfma_f32_32x32x16_bf16 v[190:205], v[64:67], v[98:101], v[190:205]
	v_add_f32_e32 v133, v133, v58
	v_add_f32_e32 v135, v135, v59
	v_add_f32_e32 v133, v133, v60
	v_add_f32_e32 v135, v135, v61
	v_add_f32_e32 v133, v133, v62
	v_add_f32_e32 v135, v135, v63
	v_mfma_f32_32x32x16_bf16 v[206:221], v[68:71], v[98:101], v[206:221]
	v_cvt_pk_bf16_f32 v32, v32, v33
	v_cvt_pk_bf16_f32 v33, v34, v35
	v_cvt_pk_bf16_f32 v34, v36, v37
	v_cvt_pk_bf16_f32 v35, v38, v39
	v_cvt_pk_bf16_f32 v36, v40, v41
	v_mfma_f32_32x32x16_bf16 v[190:205], v[72:75], v[102:105], v[190:205]
	v_cvt_pk_bf16_f32 v37, v42, v43
	v_cvt_pk_bf16_f32 v38, v44, v45
	v_cvt_pk_bf16_f32 v39, v46, v47
	v_cvt_pk_bf16_f32 v48, v48, v49
	v_cvt_pk_bf16_f32 v49, v50, v51
	v_mfma_f32_32x32x16_bf16 v[206:221], v[76:79], v[102:105], v[206:221]
	v_cvt_pk_bf16_f32 v50, v52, v53
	v_cvt_pk_bf16_f32 v51, v54, v55
	v_cvt_pk_bf16_f32 v52, v56, v57
	v_cvt_pk_bf16_f32 v53, v58, v59
	v_cvt_pk_bf16_f32 v54, v60, v61
	v_cvt_pk_bf16_f32 v55, v62, v63
	s_waitcnt vmcnt(3) lgkmcnt(0)
	s_barrier
	ds_read_b128 v[156:159], v146 offset:0
	ds_read_b128 v[160:163], v146 offset:8192
	ds_read_b128 v[164:167], v147 offset:0
	ds_read_b128 v[168:171], v147 offset:8192
	ds_read_b128 v[172:175], v148 offset:0
	ds_read_b128 v[176:179], v148 offset:8192
	ds_read_b128 v[180:183], v149 offset:0
	ds_read_b128 v[184:187], v149 offset:8192
	ds_read_b128 v[64:67], v150 offset:0
	ds_read_b128 v[68:71], v150 offset:8192
	ds_read_b128 v[72:75], v151 offset:0
	ds_read_b128 v[76:79], v151 offset:8192
	v_mfma_f32_32x32x16_bf16 v[0:15], v[32:35], v[222:225], v[0:15]
	s_add_i32 m0, s60, 0x10000
	v_exp_f32_e32 v190, v190
	v_exp_f32_e32 v191, v191
	v_mfma_f32_32x32x16_bf16 v[0:15], v[36:39], v[226:229], v[0:15]
	global_load_lds_dwordx4 v128, s[58:59]
	v_exp_f32_e32 v192, v192
	v_exp_f32_e32 v193, v193
	v_mfma_f32_32x32x16_bf16 v[0:15], v[48:51], v[230:233], v[0:15]
	s_add_u32 s58, s58, 0x2000
	s_addc_u32 s59, s59, 0
	v_exp_f32_e32 v194, v194
	v_exp_f32_e32 v195, v195
	v_mfma_f32_32x32x16_bf16 v[0:15], v[52:55], v[234:237], v[0:15]
	v_exp_f32_e32 v196, v196
	v_exp_f32_e32 v197, v197
	v_mfma_f32_32x32x16_bf16 v[16:31], v[32:35], v[238:241], v[16:31]
	v_exp_f32_e32 v198, v198
	v_exp_f32_e32 v199, v199
	v_mfma_f32_32x32x16_bf16 v[16:31], v[36:39], v[242:245], v[16:31]
	v_exp_f32_e32 v200, v200
	v_exp_f32_e32 v201, v201
	v_mfma_f32_32x32x16_bf16 v[16:31], v[48:51], v[246:249], v[16:31]
	v_exp_f32_e32 v202, v202
	v_exp_f32_e32 v203, v203
	v_mfma_f32_32x32x16_bf16 v[16:31], v[52:55], v[140:143], v[16:31]
	v_exp_f32_e32 v204, v204
	v_exp_f32_e32 v205, v205
	s_waitcnt lgkmcnt(0)
; __device__ __forceinline__ void finishSM(f32x16& p0, f32x16& p1, float& l_reg, bf16x8& pa0, bf16x8& pa1, bf16x8& pa2, bf16x8& pa3) {
; #pragma unroll
;   for (int r = 0; r < 16; ++r) p1[r] = __builtin_amdgcn_exp2f(p1[r]);
;   float ps = 0;
; #pragma unroll
;   for (int r = 0; r < 16; ++r) ps += p0[r];
; #pragma unroll
;   for (int r = 0; r < 16; ++r) ps += p1[r];
;   l_reg += ps;
;     ...
;   PK4(p0, 0, pa0); PK4(p0, 8, pa1); PK4(p1, 0, pa2); PK4(p1, 8, pa3);
;     ...
; }
; template <int ND> __device__ __forceinline__ void qkt(f32x16& p0, f32x16& p1, const bf16* Ks, const bf16x8* qr, int r32, int hi) {
;   p0 = f32x16{}; p1 = f32x16{};
; #pragma unroll
;   for (int d0 = 0; d0 < ND; ++d0) { int cb = (d0 * 16 + hi * 8) * 2;
;     bf16x8 b0 = *reinterpret_cast<const bf16x8*>((const char*)Ks + KSWZ(r32, cb));
;     bf16x8 b1 = *reinterpret_cast<const bf16x8*>((const char*)Ks + KSWZ(32 + r32, cb));
;     p0 = __builtin_amdgcn_mfma_f32_32x32x16_bf16(b0, qr[d0], p0, 0, 0, 0);
;     p1 = __builtin_amdgcn_mfma_f32_32x32x16_bf16(b1, qr[d0], p1, 0, 0, 0); }
; }
; __device__ __forceinline__ int v_st(int k, int c) { const int kk = (k & ~0xC) | ((k & 4) << 1) | ((k & 8) >> 1); return ((kk >> 3) * 4 + (c >> 5)) * 512 + ((kk & 7) * 32 + (c & 31)) * 2; }
; __device__ __forceinline__ int v_rd_base(int lane) { return ((lane & 3) << 3) | (((lane >> 2) & 3) << 6) | (((lane >> 4) & 1) << 5) | (((lane >> 5) & 1) << 8); }
; template <int OFF> __device__ __forceinline__ s16x4 tr_read(int vb) {
;   s16x4 r; asm volatile("ds_read_b64_tr_b16 %0, %1 offset:%2" : "=&v"(r) : "v"(vb), "i"(OFF) : "memory"); return r;
; }
; template <int D0> __device__ __forceinline__ void pv_one(f32x16& od, int vb, bf16x8 pa0, bf16x8 pa1, bf16x8 pa2, bf16x8 pa3) {
;   const s16x4 l0 = tr_read<v_rd_off(D0, 0, 0)>(vb), h0 = tr_read<v_rd_off(D0, 0, 1)>(vb), l1 = tr_read<v_rd_off(D0, 1, 0)>(vb), h1 = tr_read<v_rd_off(D0, 1, 1)>(vb);
;   const s16x4 l2 = tr_read<v_rd_off(D0, 2, 0)>(vb), h2 = tr_read<v_rd_off(D0, 2, 1)>(vb), l3 = tr_read<v_rd_off(D0, 3, 0)>(vb), h3 = tr_read<v_rd_off(D0, 3, 1)>(vb);
;   asm volatile("s_waitcnt lgkmcnt(0)" ::: "memory"); SBAR();
;     ...
;   od = __builtin_amdgcn_mfma_f32_32x32x16_bf16(pa0, PK(l0, h0), od, 0, 0, 0);
;   od = __builtin_amdgcn_mfma_f32_32x32x16_bf16(pa1, PK(l1, h1), od, 0, 0, 0);
;   od = __builtin_amdgcn_mfma_f32_32x32x16_bf16(pa2, PK(l2, h2), od, 0, 0, 0);
	ds_read_b64_tr_b16 v[222:223], v134 offset:32768
	ds_read_b64_tr_b16 v[224:225], v134 offset:34816
	ds_read_b64_tr_b16 v[226:227], v134 offset:36864
	ds_read_b64_tr_b16 v[228:229], v134 offset:38912
	ds_read_b64_tr_b16 v[230:231], v134 offset:40960
	ds_read_b64_tr_b16 v[232:233], v134 offset:43008
	ds_read_b64_tr_b16 v[234:235], v134 offset:45056
	ds_read_b64_tr_b16 v[236:237], v134 offset:47104
	v_mfma_f32_32x32x16_bf16 v[32:47], v[156:159], v[86:89], 0
	v_exp_f32_e32 v206, v206
	v_add_f32_e32 v133, v133, v190
	v_exp_f32_e32 v207, v207
	v_add_f32_e32 v135, v135, v191
	v_exp_f32_e32 v208, v208
	v_mfma_f32_32x32x16_bf16 v[48:63], v[160:163], v[86:89], 0
	v_add_f32_e32 v133, v133, v192
	v_exp_f32_e32 v209, v209
	v_add_f32_e32 v135, v135, v193
	v_exp_f32_e32 v210, v210
	v_add_f32_e32 v133, v133, v194
	v_mfma_f32_32x32x16_bf16 v[32:47], v[164:167], v[82:85], v[32:47]
	v_exp_f32_e32 v211, v211
	v_add_f32_e32 v135, v135, v195
	v_exp_f32_e32 v212, v212
	v_add_f32_e32 v133, v133, v196
	v_exp_f32_e32 v213, v213
	v_add_f32_e32 v135, v135, v197
	v_mfma_f32_32x32x16_bf16 v[48:63], v[168:171], v[82:85], v[48:63]
	s_waitcnt lgkmcnt(7)
	ds_read_b64_tr_b16 v[238:239], v134 offset:33280
	ds_read_b64_tr_b16 v[240:241], v134 offset:35328
	ds_read_b64_tr_b16 v[242:243], v134 offset:37376
	ds_read_b64_tr_b16 v[244:245], v134 offset:39424
	ds_read_b64_tr_b16 v[246:247], v134 offset:41472
	ds_read_b64_tr_b16 v[248:249], v134 offset:43520
	ds_read_b64_tr_b16 v[140:141], v134 offset:45568
	ds_read_b64_tr_b16 v[142:143], v134 offset:47616
	v_exp_f32_e32 v214, v214
	v_add_f32_e32 v133, v133, v198
	v_exp_f32_e32 v215, v215
	v_add_f32_e32 v135, v135, v199
	v_exp_f32_e32 v216, v216
	v_mfma_f32_32x32x16_bf16 v[32:47], v[172:175], v[90:93], v[32:47]
	v_add_f32_e32 v133, v133, v200
	v_exp_f32_e32 v217, v217
	v_add_f32_e32 v135, v135, v201
	v_exp_f32_e32 v218, v218
	v_add_f32_e32 v133, v133, v202
	v_mfma_f32_32x32x16_bf16 v[48:63], v[176:179], v[90:93], v[48:63]
	v_exp_f32_e32 v219, v219
	v_add_f32_e32 v135, v135, v203
	v_exp_f32_e32 v220, v220
	v_add_f32_e32 v133, v133, v204
	v_exp_f32_e32 v221, v221
	v_add_f32_e32 v135, v135, v205
	v_mfma_f32_32x32x16_bf16 v[32:47], v[180:183], v[94:97], v[32:47]
	v_add_f32_e32 v133, v133, v206
	v_add_f32_e32 v135, v135, v207
	v_add_f32_e32 v133, v133, v208
	v_add_f32_e32 v135, v135, v209
	v_add_f32_e32 v133, v133, v210
	v_mfma_f32_32x32x16_bf16 v[48:63], v[184:187], v[94:97], v[48:63]
	v_add_f32_e32 v135, v135, v211
	v_add_f32_e32 v133, v133, v212
	v_add_f32_e32 v135, v135, v213
	v_add_f32_e32 v133, v133, v214
	v_add_f32_e32 v135, v135, v215
	v_mfma_f32_32x32x16_bf16 v[32:47], v[64:67], v[98:101], v[32:47]
	v_add_f32_e32 v133, v133, v216
	v_add_f32_e32 v135, v135, v217
	v_add_f32_e32 v133, v133, v218
	v_add_f32_e32 v135, v135, v219
	v_add_f32_e32 v133, v133, v220
	v_add_f32_e32 v135, v135, v221
	v_mfma_f32_32x32x16_bf16 v[48:63], v[68:71], v[98:101], v[48:63]
	v_cvt_pk_bf16_f32 v190, v190, v191
	v_cvt_pk_bf16_f32 v191, v192, v193
	v_cvt_pk_bf16_f32 v192, v194, v195
	v_cvt_pk_bf16_f32 v193, v196, v197
	v_cvt_pk_bf16_f32 v194, v198, v199
	v_mfma_f32_32x32x16_bf16 v[32:47], v[72:75], v[102:105], v[32:47]
	v_cvt_pk_bf16_f32 v195, v200, v201
	v_cvt_pk_bf16_f32 v196, v202, v203
	v_cvt_pk_bf16_f32 v197, v204, v205
	v_cvt_pk_bf16_f32 v206, v206, v207
	v_cvt_pk_bf16_f32 v207, v208, v209
	v_mfma_f32_32x32x16_bf16 v[48:63], v[76:79], v[102:105], v[48:63]
	v_cvt_pk_bf16_f32 v208, v210, v211
	v_cvt_pk_bf16_f32 v209, v212, v213
	v_cvt_pk_bf16_f32 v210, v214, v215
	v_cvt_pk_bf16_f32 v211, v216, v217
	v_cvt_pk_bf16_f32 v212, v218, v219
	v_cvt_pk_bf16_f32 v213, v220, v221
	s_waitcnt vmcnt(1) lgkmcnt(0)
	s_barrier
	ds_read_b128 v[156:159], v146 offset:16384
	ds_read_b128 v[160:163], v146 offset:24576
	ds_read_b128 v[164:167], v147 offset:16384
	ds_read_b128 v[168:171], v147 offset:24576
	ds_read_b128 v[172:175], v148 offset:16384
	ds_read_b128 v[176:179], v148 offset:24576
	ds_read_b128 v[180:183], v149 offset:16384
	ds_read_b128 v[184:187], v149 offset:24576
	ds_read_b128 v[64:67], v150 offset:16384
	ds_read_b128 v[68:71], v150 offset:24576
	ds_read_b128 v[72:75], v151 offset:16384
	ds_read_b128 v[76:79], v151 offset:24576
	v_mfma_f32_32x32x16_bf16 v[0:15], v[190:193], v[222:225], v[0:15]
	v_exp_f32_e32 v32, v32
	v_exp_f32_e32 v33, v33
	v_mfma_f32_32x32x16_bf16 v[0:15], v[194:197], v[226:229], v[0:15]
	v_exp_f32_e32 v34, v34
	v_exp_f32_e32 v35, v35
	v_mfma_f32_32x32x16_bf16 v[0:15], v[206:209], v[230:233], v[0:15]
	v_exp_f32_e32 v36, v36
	v_exp_f32_e32 v37, v37
	v_mfma_f32_32x32x16_bf16 v[0:15], v[210:213], v[234:237], v[0:15]
	v_exp_f32_e32 v38, v38
	v_exp_f32_e32 v39, v39
	v_mfma_f32_32x32x16_bf16 v[16:31], v[190:193], v[238:241], v[16:31]
	v_exp_f32_e32 v40, v40
	v_exp_f32_e32 v41, v41
	v_mfma_f32_32x32x16_bf16 v[16:31], v[194:197], v[242:245], v[16:31]
	v_exp_f32_e32 v42, v42
	v_exp_f32_e32 v43, v43
	v_mfma_f32_32x32x16_bf16 v[16:31], v[206:209], v[246:249], v[16:31]
	v_exp_f32_e32 v44, v44
	v_exp_f32_e32 v45, v45
	v_mfma_f32_32x32x16_bf16 v[16:31], v[210:213], v[140:143], v[16:31]
	v_exp_f32_e32 v46, v46
	v_exp_f32_e32 v47, v47
	s_waitcnt lgkmcnt(0)
; __device__ __forceinline__ void finishSM(f32x16& p0, f32x16& p1, float& l_reg, bf16x8& pa0, bf16x8& pa1, bf16x8& pa2, bf16x8& pa3) {
; #pragma unroll
;   for (int r = 0; r < 16; ++r) p1[r] = __builtin_amdgcn_exp2f(p1[r]);
;   float ps = 0;
; #pragma unroll
;   for (int r = 0; r < 16; ++r) ps += p0[r];
; #pragma unroll
;   for (int r = 0; r < 16; ++r) ps += p1[r];
;   l_reg += ps;
;     ...
;   PK4(p0, 0, pa0); PK4(p0, 8, pa1); PK4(p1, 0, pa2); PK4(p1, 8, pa3);
;     ...
; }
; template <int ND> __device__ __forceinline__ void qkt(f32x16& p0, f32x16& p1, const bf16* Ks, const bf16x8* qr, int r32, int hi) {
;   p0 = f32x16{}; p1 = f32x16{};
; #pragma unroll
;   for (int d0 = 0; d0 < ND; ++d0) { int cb = (d0 * 16 + hi * 8) * 2;
;     bf16x8 b0 = *reinterpret_cast<const bf16x8*>((const char*)Ks + KSWZ(r32, cb));
;     bf16x8 b1 = *reinterpret_cast<const bf16x8*>((const char*)Ks + KSWZ(32 + r32, cb));
;     p0 = __builtin_amdgcn_mfma_f32_32x32x16_bf16(b0, qr[d0], p0, 0, 0, 0);
;     p1 = __builtin_amdgcn_mfma_f32_32x32x16_bf16(b1, qr[d0], p1, 0, 0, 0); }
; }
; __device__ __forceinline__ int v_st(int k, int c) { const int kk = (k & ~0xC) | ((k & 4) << 1) | ((k & 8) >> 1); return ((kk >> 3) * 4 + (c >> 5)) * 512 + ((kk & 7) * 32 + (c & 31)) * 2; }
; __device__ __forceinline__ int v_rd_base(int lane) { return ((lane & 3) << 3) | (((lane >> 2) & 3) << 6) | (((lane >> 4) & 1) << 5) | (((lane >> 5) & 1) << 8); }
; template <int OFF> __device__ __forceinline__ s16x4 tr_read(int vb) {
;   s16x4 r; asm volatile("ds_read_b64_tr_b16 %0, %1 offset:%2" : "=&v"(r) : "v"(vb), "i"(OFF) : "memory"); return r;
; }
; template <int D0> __device__ __forceinline__ void pv_one(f32x16& od, int vb, bf16x8 pa0, bf16x8 pa1, bf16x8 pa2, bf16x8 pa3) {
;   const s16x4 l0 = tr_read<v_rd_off(D0, 0, 0)>(vb), h0 = tr_read<v_rd_off(D0, 0, 1)>(vb), l1 = tr_read<v_rd_off(D0, 1, 0)>(vb), h1 = tr_read<v_rd_off(D0, 1, 1)>(vb);
;   const s16x4 l2 = tr_read<v_rd_off(D0, 2, 0)>(vb), h2 = tr_read<v_rd_off(D0, 2, 1)>(vb), l3 = tr_read<v_rd_off(D0, 3, 0)>(vb), h3 = tr_read<v_rd_off(D0, 3, 1)>(vb);
;   asm volatile("s_waitcnt lgkmcnt(0)" ::: "memory"); SBAR();
;     ...
;   od = __builtin_amdgcn_mfma_f32_32x32x16_bf16(pa0, PK(l0, h0), od, 0, 0, 0);
;   od = __builtin_amdgcn_mfma_f32_32x32x16_bf16(pa1, PK(l1, h1), od, 0, 0, 0);
;   od = __builtin_amdgcn_mfma_f32_32x32x16_bf16(pa2, PK(l2, h2), od, 0, 0, 0);
	ds_read_b64_tr_b16 v[222:223], v134 offset:0
	ds_read_b64_tr_b16 v[224:225], v134 offset:2048
	ds_read_b64_tr_b16 v[226:227], v134 offset:4096
	ds_read_b64_tr_b16 v[228:229], v134 offset:6144
	ds_read_b64_tr_b16 v[230:231], v134 offset:8192
	ds_read_b64_tr_b16 v[232:233], v134 offset:10240
	ds_read_b64_tr_b16 v[234:235], v134 offset:12288
	ds_read_b64_tr_b16 v[236:237], v134 offset:14336
	v_mfma_f32_32x32x16_bf16 v[190:205], v[156:159], v[86:89], 0
	v_exp_f32_e32 v48, v48
	v_add_f32_e32 v133, v133, v32
	v_exp_f32_e32 v49, v49
	v_add_f32_e32 v135, v135, v33
	v_exp_f32_e32 v50, v50
	v_mfma_f32_32x32x16_bf16 v[206:221], v[160:163], v[86:89], 0
	v_add_f32_e32 v133, v133, v34
	v_exp_f32_e32 v51, v51
	v_add_f32_e32 v135, v135, v35
	v_exp_f32_e32 v52, v52
	v_add_f32_e32 v133, v133, v36
	v_mfma_f32_32x32x16_bf16 v[190:205], v[164:167], v[82:85], v[190:205]
	v_exp_f32_e32 v53, v53
	v_add_f32_e32 v135, v135, v37
	v_exp_f32_e32 v54, v54
	v_add_f32_e32 v133, v133, v38
	v_exp_f32_e32 v55, v55
	v_add_f32_e32 v135, v135, v39
	v_mfma_f32_32x32x16_bf16 v[206:221], v[168:171], v[82:85], v[206:221]
	s_waitcnt lgkmcnt(7)
	ds_read_b64_tr_b16 v[238:239], v134 offset:512
	ds_read_b64_tr_b16 v[240:241], v134 offset:2560
	ds_read_b64_tr_b16 v[242:243], v134 offset:4608
	ds_read_b64_tr_b16 v[244:245], v134 offset:6656
	ds_read_b64_tr_b16 v[246:247], v134 offset:8704
	ds_read_b64_tr_b16 v[248:249], v134 offset:10752
	ds_read_b64_tr_b16 v[140:141], v134 offset:12800
	ds_read_b64_tr_b16 v[142:143], v134 offset:14848
	v_exp_f32_e32 v56, v56
	v_add_f32_e32 v133, v133, v40
	v_exp_f32_e32 v57, v57
	v_add_f32_e32 v135, v135, v41
	v_exp_f32_e32 v58, v58
	v_mfma_f32_32x32x16_bf16 v[190:205], v[172:175], v[90:93], v[190:205]
	v_add_f32_e32 v133, v133, v42
	v_exp_f32_e32 v59, v59
	v_add_f32_e32 v135, v135, v43
	v_exp_f32_e32 v60, v60
	v_add_f32_e32 v133, v133, v44
	v_mfma_f32_32x32x16_bf16 v[206:221], v[176:179], v[90:93], v[206:221]
	v_exp_f32_e32 v61, v61
	v_add_f32_e32 v135, v135, v45
	v_exp_f32_e32 v62, v62
	v_add_f32_e32 v133, v133, v46
	v_exp_f32_e32 v63, v63
	v_add_f32_e32 v135, v135, v47
	v_mfma_f32_32x32x16_bf16 v[190:205], v[180:183], v[94:97], v[190:205]
	v_add_f32_e32 v133, v133, v48
	v_add_f32_e32 v135, v135, v49
	v_add_f32_e32 v133, v133, v50
	v_add_f32_e32 v135, v135, v51
	v_add_f32_e32 v133, v133, v52
	v_mfma_f32_32x32x16_bf16 v[206:221], v[184:187], v[94:97], v[206:221]
	v_add_f32_e32 v135, v135, v53
	v_add_f32_e32 v133, v133, v54
	v_add_f32_e32 v135, v135, v55
	v_add_f32_e32 v133, v133, v56
	v_add_f32_e32 v135, v135, v57
	v_mfma_f32_32x32x16_bf16 v[190:205], v[64:67], v[98:101], v[190:205]
	v_add_f32_e32 v133, v133, v58
	v_add_f32_e32 v135, v135, v59
	v_add_f32_e32 v133, v133, v60
	v_add_f32_e32 v135, v135, v61
	v_add_f32_e32 v133, v133, v62
	v_add_f32_e32 v135, v135, v63
	v_mfma_f32_32x32x16_bf16 v[206:221], v[68:71], v[98:101], v[206:221]
	v_cvt_pk_bf16_f32 v32, v32, v33
	v_cvt_pk_bf16_f32 v33, v34, v35
	v_cvt_pk_bf16_f32 v34, v36, v37
	v_cvt_pk_bf16_f32 v35, v38, v39
	v_cvt_pk_bf16_f32 v36, v40, v41
	v_mfma_f32_32x32x16_bf16 v[190:205], v[72:75], v[102:105], v[190:205]
	v_cvt_pk_bf16_f32 v37, v42, v43
	v_cvt_pk_bf16_f32 v38, v44, v45
	v_cvt_pk_bf16_f32 v39, v46, v47
	v_cvt_pk_bf16_f32 v48, v48, v49
	v_cvt_pk_bf16_f32 v49, v50, v51
	v_mfma_f32_32x32x16_bf16 v[206:221], v[76:79], v[102:105], v[206:221]
	v_cvt_pk_bf16_f32 v50, v52, v53
	v_cvt_pk_bf16_f32 v51, v54, v55
	v_cvt_pk_bf16_f32 v52, v56, v57
	v_cvt_pk_bf16_f32 v53, v58, v59
	v_cvt_pk_bf16_f32 v54, v60, v61
	v_cvt_pk_bf16_f32 v55, v62, v63
	s_waitcnt vmcnt(0) lgkmcnt(0)
	s_barrier
	s_nop 7
	s_nop 3
	v_mfma_f32_32x32x16_bf16 v[0:15], v[32:35], v[222:225], v[0:15]
	v_exp_f32_e32 v190, v190
	v_exp_f32_e32 v191, v191
	v_mfma_f32_32x32x16_bf16 v[0:15], v[36:39], v[226:229], v[0:15]
	v_exp_f32_e32 v192, v192
	v_exp_f32_e32 v193, v193
	v_mfma_f32_32x32x16_bf16 v[0:15], v[48:51], v[230:233], v[0:15]
	v_exp_f32_e32 v194, v194
	v_exp_f32_e32 v195, v195
	v_mfma_f32_32x32x16_bf16 v[0:15], v[52:55], v[234:237], v[0:15]
	v_exp_f32_e32 v196, v196
	v_exp_f32_e32 v197, v197
	v_mfma_f32_32x32x16_bf16 v[16:31], v[32:35], v[238:241], v[16:31]
	v_exp_f32_e32 v198, v198
	v_exp_f32_e32 v199, v199
	v_mfma_f32_32x32x16_bf16 v[16:31], v[36:39], v[242:245], v[16:31]
	v_exp_f32_e32 v200, v200
	v_exp_f32_e32 v201, v201
	v_mfma_f32_32x32x16_bf16 v[16:31], v[48:51], v[246:249], v[16:31]
	v_exp_f32_e32 v202, v202
	v_exp_f32_e32 v203, v203
	v_mfma_f32_32x32x16_bf16 v[16:31], v[52:55], v[140:143], v[16:31]
	v_exp_f32_e32 v204, v204
	v_exp_f32_e32 v205, v205
	s_waitcnt lgkmcnt(0)
	ds_read_b64_tr_b16 v[222:223], v134 offset:16384
	ds_read_b64_tr_b16 v[224:225], v134 offset:18432
	ds_read_b64_tr_b16 v[226:227], v134 offset:20480
	ds_read_b64_tr_b16 v[228:229], v134 offset:22528
	ds_read_b64_tr_b16 v[230:231], v134 offset:24576
	ds_read_b64_tr_b16 v[232:233], v134 offset:26624
	ds_read_b64_tr_b16 v[234:235], v134 offset:28672
	ds_read_b64_tr_b16 v[236:237], v134 offset:30720
	s_nop 3
	s_waitcnt lgkmcnt(7)
; #define SBAR() __builtin_amdgcn_sched_barrier(0)
; __device__ __forceinline__ int crow(int r, int hi) { return (r & 3) + 8 * (r >> 2) + 4 * hi; }
; #define ROT() do { const int t_ = bv; bv = bk; bk = bw; bw = t_; } while (0)
; __device__ __forceinline__ void finishSM(f32x16& p0, f32x16& p1, float& l_reg, bf16x8& pa0, bf16x8& pa1, bf16x8& pa2, bf16x8& pa3) {
; #pragma unroll
;   for (int r = 0; r < 16; ++r) p1[r] = __builtin_amdgcn_exp2f(p1[r]);
;   float ps = 0;
; #pragma unroll
;   for (int r = 0; r < 16; ++r) ps += p0[r];
; #pragma unroll
;   for (int r = 0; r < 16; ++r) ps += p1[r];
;   l_reg += ps;
;     ...
;   PK4(p0, 0, pa0); PK4(p0, 8, pa1); PK4(p1, 0, pa2); PK4(p1, 8, pa3);
;     ...
; }
; template <bool SHIFT> __device__ __forceinline__ void attn_dense_body(const bf16* __restrict__ Qb, const bf16* __restrict__ Kh, const bf16* __restrict__ Vh, bf16* __restrict__ Ob, int seq, char* lds, LAS unsigned char* ldsl, float negB, const float* __restrict__ gq, int qpos0) {
;     ...
;   SBAR(); qkt<SHIFT ? 7 : 6>(pB0, pB1, (bf16*)((char*)K_lds + bk * SHM_K), qr, r32, hi);
;   finishSM(pA0, pA1, l_reg, pa0, pa1, pa2, pa3); SBAR();
;   pv_d0(o, vb0 + bv * (int)SHM_V, pa0, pa1, pa2, pa3); partialSM(pB0);
;   ROT();
;   finishSM(pB0, pB1, l_reg, pa0, pa1, pa2, pa3); SBAR();
;   pv_d0(o, vb0 + bv * (int)SHM_V, pa0, pa1, pa2, pa3);
;     ...
;   { auto rr = __builtin_amdgcn_permlane32_swap(__float_as_uint(l_reg), __float_as_uint(l_reg), false, false); l_reg = __uint_as_float(rr[0]) + __uint_as_float(rr[1]); }
;   if (hi == 0) li_l[r32] = l_reg; asm volatile("s_waitcnt lgkmcnt(0)" ::: "memory");
;   float rli[16];
; #pragma unroll
;   for (int r = 0; r < 16; ++r) rli[r] = __builtin_amdgcn_rcpf(li_l[crow(r, hi)]);
	ds_read_b64_tr_b16 v[238:239], v134 offset:16896
	ds_read_b64_tr_b16 v[240:241], v134 offset:18944
	ds_read_b64_tr_b16 v[242:243], v134 offset:20992
	ds_read_b64_tr_b16 v[244:245], v134 offset:23040
	ds_read_b64_tr_b16 v[246:247], v134 offset:25088
	ds_read_b64_tr_b16 v[248:249], v134 offset:27136
	ds_read_b64_tr_b16 v[140:141], v134 offset:29184
	ds_read_b64_tr_b16 v[142:143], v134 offset:31232
	v_exp_f32_e32 v206, v206
	v_add_f32_e32 v133, v133, v190
	v_exp_f32_e32 v207, v207
	v_add_f32_e32 v135, v135, v191
	v_exp_f32_e32 v208, v208
	v_add_f32_e32 v133, v133, v192
	v_exp_f32_e32 v209, v209
	v_add_f32_e32 v135, v135, v193
	v_exp_f32_e32 v210, v210
	v_add_f32_e32 v133, v133, v194
	v_exp_f32_e32 v211, v211
	v_add_f32_e32 v135, v135, v195
	v_exp_f32_e32 v212, v212
	v_add_f32_e32 v133, v133, v196
	v_exp_f32_e32 v213, v213
	v_add_f32_e32 v135, v135, v197
	v_exp_f32_e32 v214, v214
	v_add_f32_e32 v133, v133, v198
	v_exp_f32_e32 v215, v215
	v_add_f32_e32 v135, v135, v199
	v_exp_f32_e32 v216, v216
	v_add_f32_e32 v133, v133, v200
	v_exp_f32_e32 v217, v217
	v_add_f32_e32 v135, v135, v201
	v_exp_f32_e32 v218, v218
	v_add_f32_e32 v133, v133, v202
	v_exp_f32_e32 v219, v219
	v_add_f32_e32 v135, v135, v203
	v_exp_f32_e32 v220, v220
	v_add_f32_e32 v133, v133, v204
	v_exp_f32_e32 v221, v221
	v_add_f32_e32 v135, v135, v205
	v_add_f32_e32 v133, v133, v206
	v_add_f32_e32 v135, v135, v207
	v_add_f32_e32 v133, v133, v208
	v_add_f32_e32 v135, v135, v209
	v_add_f32_e32 v133, v133, v210
	v_add_f32_e32 v135, v135, v211
	v_add_f32_e32 v133, v133, v212
	v_add_f32_e32 v135, v135, v213
	v_add_f32_e32 v133, v133, v214
	v_add_f32_e32 v135, v135, v215
	v_add_f32_e32 v133, v133, v216
	v_add_f32_e32 v135, v135, v217
	v_add_f32_e32 v133, v133, v218
	v_add_f32_e32 v135, v135, v219
	v_add_f32_e32 v133, v133, v220
	v_add_f32_e32 v135, v135, v221
	v_cvt_pk_bf16_f32 v190, v190, v191
	v_cvt_pk_bf16_f32 v191, v192, v193
	v_cvt_pk_bf16_f32 v192, v194, v195
	v_cvt_pk_bf16_f32 v193, v196, v197
	v_cvt_pk_bf16_f32 v194, v198, v199
	v_cvt_pk_bf16_f32 v195, v200, v201
	v_cvt_pk_bf16_f32 v196, v202, v203
	v_cvt_pk_bf16_f32 v197, v204, v205
	v_cvt_pk_bf16_f32 v206, v206, v207
	v_cvt_pk_bf16_f32 v207, v208, v209
	v_cvt_pk_bf16_f32 v208, v210, v211
	v_cvt_pk_bf16_f32 v209, v212, v213
	v_cvt_pk_bf16_f32 v210, v214, v215
	v_cvt_pk_bf16_f32 v211, v216, v217
	v_cvt_pk_bf16_f32 v212, v218, v219
	v_cvt_pk_bf16_f32 v213, v220, v221
	s_waitcnt lgkmcnt(0)
	s_nop 7
	s_nop 3
	v_mfma_f32_32x32x16_bf16 v[0:15], v[190:193], v[222:225], v[0:15]
	v_mfma_f32_32x32x16_bf16 v[0:15], v[194:197], v[226:229], v[0:15]
	v_mfma_f32_32x32x16_bf16 v[0:15], v[206:209], v[230:233], v[0:15]
	v_mfma_f32_32x32x16_bf16 v[0:15], v[210:213], v[234:237], v[0:15]
	v_mfma_f32_32x32x16_bf16 v[16:31], v[190:193], v[238:241], v[16:31]
	v_mfma_f32_32x32x16_bf16 v[16:31], v[194:197], v[242:245], v[16:31]
	v_mfma_f32_32x32x16_bf16 v[16:31], v[206:209], v[246:249], v[16:31]
	v_mfma_f32_32x32x16_bf16 v[16:31], v[210:213], v[140:143], v[16:31]
	v_add_f32_e32 v32, v133, v135
	s_nop 0
	v_mov_b32_e32 v33, v32
	s_nop 1
	v_permlane32_swap_b32_e32 v32, v33
	s_and_saveexec_b64 s[4:5], s[6:7]
	v_add_f32_e32 v32, v32, v33
	ds_write_b32 v153, v32
	s_or_b64 exec, exec, s[4:5]
	s_waitcnt lgkmcnt(0)
	v_add_u32_e32 v40, v113, v117
	ds_read_b128 v[32:35], v40
	ds_read_b128 v[36:39], v40 offset:32
	s_waitcnt lgkmcnt(1)
	v_rcp_f32_e32 v41, v32
	v_rcp_f32_e32 v42, v33
	v_rcp_f32_e32 v43, v34
	v_rcp_f32_e32 v44, v35
	ds_read_b128 v[32:35], v40 offset:64
	s_waitcnt lgkmcnt(1)
	v_rcp_f32_e32 v45, v36
	v_rcp_f32_e32 v46, v37
	v_rcp_f32_e32 v47, v38
	v_rcp_f32_e32 v48, v39
	ds_read_b128 v[36:39], v40 offset:96
	s_waitcnt lgkmcnt(1)
; __device__ __forceinline__ int crow(int r, int hi) { return (r & 3) + 8 * (r >> 2) + 4 * hi; }
; __device__ __forceinline__ unsigned cvtpk(float lo, float hi) { unsigned r; asm volatile("v_cvt_pk_bf16_f32 %0, %1, %2" : "=v"(r) : "v"(lo), "v"(hi)); return r; }
; template <bool SHIFT> __device__ __forceinline__ void attn_dense_body(const bf16* __restrict__ Qb, const bf16* __restrict__ Kh, const bf16* __restrict__ Vh, bf16* __restrict__ Ob, int seq, char* lds, LAS unsigned char* ldsl, float negB, const float* __restrict__ gq, int qpos0) {
;     ...
;   float rli[16];
; #pragma unroll
;   for (int r = 0; r < 16; ++r) rli[r] = __builtin_amdgcn_rcpf(li_l[crow(r, hi)]);
;   bf16* Ow = Ob + (long)(wid * QBLK) * LDO;
; #pragma unroll
;   for (int r = 0; r < 16; ++r) { int orow = crow(r, hi);
; #pragma unroll
;     for (int d0 = 0; d0 < 2; ++d0) Ow[(long)orow * LDO + d0 * 32 + r32] = (bf16)(cvtpk(o[d0][r] * rli[r], 0.f) & 0xffffu); }
;   __syncthreads();
	v_rcp_f32_e32 v40, v32
	v_rcp_f32_e32 v49, v33
	v_lshlrev_b32_e32 v32, 1, v116
	v_mov_b32_e32 v33, v81
	v_rcp_f32_e32 v50, v34
	v_rcp_f32_e32 v51, v35
	v_lshl_add_u64 v[32:33], s[38:39], 0, v[32:33]
	v_lshlrev_b32_e32 v34, 1, v108
	v_mov_b32_e32 v35, v81
	v_lshl_add_u64 v[32:33], v[32:33], 0, v[34:35]
	v_mul_f32_e32 v0, v0, v41
	v_lshl_add_u64 v[32:33], v[32:33], 0, v[118:119]
	v_cvt_pk_bf16_f32 v0, v0, v81
	global_store_short v[32:33], v0, off
	v_mul_f32_e32 v0, v16, v41
	v_cvt_pk_bf16_f32 v0, v0, v81
	global_store_short v[32:33], v0, off offset:64
	v_mul_f32_e32 v0, v1, v42
	v_cvt_pk_bf16_f32 v0, v0, v81
	global_store_short v[32:33], v0, off offset:2048
	v_mul_f32_e32 v0, v17, v42
	v_cvt_pk_bf16_f32 v0, v0, v81
	global_store_short v[32:33], v0, off offset:2112
	v_mul_f32_e32 v0, v2, v43
	v_cvt_pk_bf16_f32 v2, v0, v81
	v_add_co_u32_e32 v0, vcc, s47, v32
	s_waitcnt lgkmcnt(0)
	v_rcp_f32_e32 v36, v36
	v_addc_co_u32_e32 v1, vcc, 0, v33, vcc
	global_store_short v[0:1], v2, off
	v_mul_f32_e32 v2, v18, v43
	v_cvt_pk_bf16_f32 v2, v2, v81
	global_store_short v[0:1], v2, off offset:64
	v_mul_f32_e32 v2, v3, v44
	v_cvt_pk_bf16_f32 v2, v2, v81
	global_store_short v[0:1], v2, off offset:2048
	v_mul_f32_e32 v2, v19, v44
	v_cvt_pk_bf16_f32 v2, v2, v81
	global_store_short v[0:1], v2, off offset:2112
	v_mul_f32_e32 v0, v4, v45
	v_cvt_pk_bf16_f32 v4, v0, v81
	v_add_co_u32_e32 v0, vcc, s41, v32
	v_rcp_f32_e32 v37, v37
	s_nop 0
	v_addc_co_u32_e32 v1, vcc, 0, v33, vcc
	v_add_co_u32_e32 v2, vcc, s48, v32
	v_rcp_f32_e32 v38, v38
	s_nop 0
	v_addc_co_u32_e32 v3, vcc, 0, v33, vcc
	global_store_short v[2:3], v4, off offset:-4096
	v_mul_f32_e32 v4, v20, v45
	v_cvt_pk_bf16_f32 v4, v4, v81
	global_store_short v[0:1], v4, off offset:64
	v_mul_f32_e32 v4, v5, v46
	v_cvt_pk_bf16_f32 v4, v4, v81
	global_store_short v[0:1], v4, off offset:2048
	v_mul_f32_e32 v4, v21, v46
	v_cvt_pk_bf16_f32 v4, v4, v81
	global_store_short v[0:1], v4, off offset:2112
	v_mul_f32_e32 v0, v6, v47
	v_cvt_pk_bf16_f32 v0, v0, v81
	global_store_short v[2:3], v0, off
	v_mul_f32_e32 v0, v22, v47
	v_cvt_pk_bf16_f32 v0, v0, v81
	global_store_short v[2:3], v0, off offset:64
	v_mul_f32_e32 v0, v7, v48
	v_cvt_pk_bf16_f32 v0, v0, v81
	global_store_short v[2:3], v0, off offset:2048
	v_mul_f32_e32 v0, v23, v48
	v_cvt_pk_bf16_f32 v0, v0, v81
	global_store_short v[2:3], v0, off offset:2112
	v_mul_f32_e32 v0, v8, v40
	v_cvt_pk_bf16_f32 v4, v0, v81
	v_add_co_u32_e32 v0, vcc, s49, v32
	v_rcp_f32_e32 v39, v39
	s_nop 0
	v_addc_co_u32_e32 v1, vcc, 0, v33, vcc
	v_add_co_u32_e32 v2, vcc, s54, v32
	s_nop 1
	v_addc_co_u32_e32 v3, vcc, 0, v33, vcc
	global_store_short v[2:3], v4, off offset:-4096
	v_mul_f32_e32 v4, v24, v40
	v_cvt_pk_bf16_f32 v4, v4, v81
	global_store_short v[0:1], v4, off offset:64
	v_mul_f32_e32 v4, v9, v49
	v_cvt_pk_bf16_f32 v4, v4, v81
	global_store_short v[0:1], v4, off offset:2048
	v_mul_f32_e32 v4, v25, v49
	v_cvt_pk_bf16_f32 v4, v4, v81
	global_store_short v[0:1], v4, off offset:2112
	v_mul_f32_e32 v0, v10, v50
	v_cvt_pk_bf16_f32 v0, v0, v81
	global_store_short v[2:3], v0, off
	v_mul_f32_e32 v0, v26, v50
	v_cvt_pk_bf16_f32 v0, v0, v81
	global_store_short v[2:3], v0, off offset:64
	v_mul_f32_e32 v0, v11, v51
	v_cvt_pk_bf16_f32 v0, v0, v81
	global_store_short v[2:3], v0, off offset:2048
	v_mul_f32_e32 v0, v27, v51
	v_cvt_pk_bf16_f32 v0, v0, v81
	global_store_short v[2:3], v0, off offset:2112
	v_mul_f32_e32 v0, v12, v36
	v_cvt_pk_bf16_f32 v4, v0, v81
	v_add_co_u32_e32 v0, vcc, s45, v32
	s_nop 1
	v_addc_co_u32_e32 v1, vcc, 0, v33, vcc
	v_add_co_u32_e32 v2, vcc, s55, v32
	s_nop 1
	v_addc_co_u32_e32 v3, vcc, 0, v33, vcc
	global_store_short v[2:3], v4, off offset:-4096
	v_mul_f32_e32 v4, v28, v36
	v_cvt_pk_bf16_f32 v4, v4, v81
	global_store_short v[0:1], v4, off offset:64
	v_mul_f32_e32 v4, v13, v37
	v_cvt_pk_bf16_f32 v4, v4, v81
	global_store_short v[0:1], v4, off offset:2048
	v_mul_f32_e32 v4, v29, v37
	v_cvt_pk_bf16_f32 v4, v4, v81
	global_store_short v[0:1], v4, off offset:2112
	v_mul_f32_e32 v0, v14, v38
	v_cvt_pk_bf16_f32 v0, v0, v81
	global_store_short v[2:3], v0, off
	v_mul_f32_e32 v0, v30, v38
	v_cvt_pk_bf16_f32 v0, v0, v81
	global_store_short v[2:3], v0, off offset:64
	v_mul_f32_e32 v0, v15, v39
	v_cvt_pk_bf16_f32 v0, v0, v81
	global_store_short v[2:3], v0, off offset:2048
	v_mul_f32_e32 v0, v31, v39
	v_cvt_pk_bf16_f32 v0, v0, v81
	global_store_short v[2:3], v0, off offset:2112
	s_barrier
	s_branch .LBB0_1590

; #define PG8_STAGE(bufoff, gbase, voff) do { _Pragma("unroll") for (int _i = 0; _i < 2; ++_i) \
;         __builtin_amdgcn_global_load_lds((const unsigned*)((const char*)(gbase) + (voff)[_i]), (PG8_LAS unsigned*)(lds + (bufoff) + ldsw + _i * 8192), 16, 0, 0); } while (0)
; #define PG8_LDA(dst, b, h) do { _Pragma("unroll") for (int m = 0; m < 4; ++m) _Pragma("unroll") for (int k = 0; k < 2; ++k) dst[m][k] = *(const PG8_LAS bf16x8*)(lds + PG8_SA(b, h) + aoff + m * 2048 + k * 1024); } while (0)
; #define PG8_LDB(dst, b, h) do { _Pragma("unroll") for (int n = 0; n < 2; ++n) _Pragma("unroll") for (int k = 0; k < 2; ++k) dst[n][k] = *(const PG8_LAS bf16x8*)(lds + PG8_SB(b, h) + boff + n * 2048 + k * 1024); } while (0)
; template <class Epi, class Sched, bool ALIGN_EPI = false, bool SP2 = false>
; __device__ __forceinline__ void gemm_phase(PG8_LAS unsigned char* lds, const Gemm g, const Sched& S, const Epi& E) {
;     ...
;         for (int t = 0; t < nt; t += 2) {
;             const bool last = (t == nt - 2);
;             const char* a1 = cA + (size_t)(t + 1) * kstep;
;             const char* a2 = last ? nA : cA + (size_t)(t + 2) * kstep; const char* b2 = last ? nB : cB + (size_t)(t + 2) * kstep;
;             const char* a3 = a2 + kstep; const char* b3 = b2 + kstep;
;             if (last && has_next) S.a_ready(nxt);
;             if constexpr (SP2) {
;             PG8_LDB(B0, 0, 0); PG8_LDB(B1, 0, 1); PG8_SCHED; PG8_LDA(At, 0, 0); PG8_STAGE(PG8_SA(1, 1), a1 + hstepA, voffA);
;             PG8_WAIT_V(8); PG8_WAIT_L(0); PG8_BAR; PG8_MMA(0, 0, At, B0); PG8_MMA(0, 1, At, B1); PG8_BAR; PG8_SCHED;
;             PG8_LDA(At, 0, 1); PG8_STAGE(PG8_SB(0, 0), b2, voffB); PG8_STAGE(PG8_SB(0, 1), b2 + hstep, voffB); PG8_STAGE(PG8_SA(0, 0), a2, voffA);
;             PG8_WAIT_V(8); PG8_WAIT_L(0); PG8_BAR; PG8_MMA(1, 0, At, B0); PG8_MMA(1, 1, At, B1); PG8_BAR; PG8_SCHED;
;             PG8_LDB(B0, 1, 0); PG8_LDB(B1, 1, 1); PG8_SCHED; PG8_LDA(At, 1, 0); PG8_STAGE(PG8_SA(0, 1), a2 + hstepA, voffA);
;             PG8_WAIT_V(8); PG8_WAIT_L(0); PG8_BAR; PG8_MMA(0, 0, At, B0); PG8_MMA(0, 1, At, B1); PG8_BAR; PG8_SCHED;
;             PG8_LDA(At, 1, 1); PG8_STAGE(PG8_SB(1, 0), b3, voffB); PG8_STAGE(PG8_SB(1, 1), b3 + hstep, voffB); PG8_STAGE(PG8_SA(1, 0), a3, voffA);
;             PG8_WAIT_V(8); PG8_WAIT_L(0); PG8_BAR; PG8_MMA(1, 0, At, B0); PG8_MMA(1, 1, At, B1); PG8_BAR; PG8_SCHED;
.LBB0_1679:
	ds_read_b128 v[120:123], v169
	ds_read_b128 v[128:131], v169 offset:1024
	ds_read_b128 v[136:139], v169 offset:2048
	ds_read_b128 v[140:143], v169 offset:3072
	ds_read_b128 v[160:163], v170
	ds_read_b128 v[172:175], v170 offset:1024
	ds_read_b128 v[176:179], v170 offset:2048
	ds_read_b128 v[180:183], v170 offset:3072
	s_add_i32 s90, s68, 2
	s_add_u32 s91, s8, 0xfffc0080
	s_addc_u32 s69, s9, -1
	s_cmp_eq_u32 s84, s68
	s_cselect_b32 s68, s89, s91
	s_cselect_b32 s69, s61, s69
	s_cselect_b32 s93, s63, s71
	s_cselect_b32 s92, s62, s70
	s_add_i32 m0, s67, 0xc000
	ds_read_b128 v[184:187], v171
	ds_read_b128 v[190:193], v171 offset:1024
	ds_read_b128 v[194:197], v171 offset:2048
	ds_read_b128 v[198:201], v171 offset:3072
	ds_read_b128 v[202:205], v171 offset:4096
	ds_read_b128 v[206:209], v171 offset:5120
	ds_read_b128 v[210:213], v171 offset:6144
	global_load_lds_dwordx4 v152, s[8:9]
	s_add_i32 m0, s67, 0xe000
	ds_read_b128 v[214:217], v171 offset:7168
	global_load_lds_dwordx4 v154, s[8:9]
	s_waitcnt vmcnt(8) lgkmcnt(0)
	s_barrier
	s_setprio 1
	v_mfma_f32_16x16x32_bf16 v[132:135], v[120:123], v[184:187], v[132:135]
	v_mfma_f32_16x16x32_bf16 v[124:127], v[136:139], v[184:187], v[124:127]
	v_mfma_f32_16x16x32_bf16 v[108:111], v[120:123], v[194:197], v[108:111]
	v_mfma_f32_16x16x32_bf16 v[104:107], v[136:139], v[194:197], v[104:107]
	v_mfma_f32_16x16x32_bf16 v[92:95], v[120:123], v[202:205], v[92:95]
	v_mfma_f32_16x16x32_bf16 v[88:91], v[136:139], v[202:205], v[88:91]
	v_mfma_f32_16x16x32_bf16 v[76:79], v[120:123], v[210:213], v[76:79]
	v_mfma_f32_16x16x32_bf16 v[72:75], v[136:139], v[210:213], v[72:75]
	v_mfma_f32_16x16x32_bf16 v[132:135], v[128:131], v[190:193], v[132:135]
	v_mfma_f32_16x16x32_bf16 v[124:127], v[140:143], v[190:193], v[124:127]
	v_mfma_f32_16x16x32_bf16 v[108:111], v[128:131], v[198:201], v[108:111]
	v_mfma_f32_16x16x32_bf16 v[104:107], v[140:143], v[198:201], v[104:107]
	v_mfma_f32_16x16x32_bf16 v[92:95], v[128:131], v[206:209], v[92:95]
	v_mfma_f32_16x16x32_bf16 v[88:91], v[140:143], v[206:209], v[88:91]
	v_mfma_f32_16x16x32_bf16 v[76:79], v[128:131], v[214:217], v[76:79]
	v_mfma_f32_16x16x32_bf16 v[72:75], v[140:143], v[214:217], v[72:75]
	v_mfma_f32_16x16x32_bf16 v[116:119], v[160:163], v[184:187], v[116:119]
	v_mfma_f32_16x16x32_bf16 v[112:115], v[176:179], v[184:187], v[112:115]
	v_mfma_f32_16x16x32_bf16 v[100:103], v[160:163], v[194:197], v[100:103]
	v_mfma_f32_16x16x32_bf16 v[96:99], v[176:179], v[194:197], v[96:99]
	v_mfma_f32_16x16x32_bf16 v[84:87], v[160:163], v[202:205], v[84:87]
	v_mfma_f32_16x16x32_bf16 v[80:83], v[176:179], v[202:205], v[80:83]
	v_mfma_f32_16x16x32_bf16 v[68:71], v[160:163], v[210:213], v[68:71]
	v_mfma_f32_16x16x32_bf16 v[64:67], v[176:179], v[210:213], v[64:67]
	v_mfma_f32_16x16x32_bf16 v[116:119], v[172:175], v[190:193], v[116:119]
	v_mfma_f32_16x16x32_bf16 v[112:115], v[180:183], v[190:193], v[112:115]
	v_mfma_f32_16x16x32_bf16 v[100:103], v[172:175], v[198:201], v[100:103]
	v_mfma_f32_16x16x32_bf16 v[96:99], v[180:183], v[198:201], v[96:99]
	v_mfma_f32_16x16x32_bf16 v[84:87], v[172:175], v[206:209], v[84:87]
	v_mfma_f32_16x16x32_bf16 v[80:83], v[180:183], v[206:209], v[80:83]
	v_mfma_f32_16x16x32_bf16 v[68:71], v[172:175], v[214:217], v[68:71]
	v_mfma_f32_16x16x32_bf16 v[64:67], v[180:183], v[214:217], v[64:67]
	s_setprio 0
	s_barrier
	s_add_i32 s91, s85, s73
	s_mov_b32 m0, s91
	ds_read_b128 v[184:187], v171 offset:16384
	ds_read_b128 v[190:193], v171 offset:17408
	ds_read_b128 v[194:197], v171 offset:18432
	ds_read_b128 v[198:201], v171 offset:19456
	global_load_lds_dwordx4 v150, s[92:93]
	s_add_i32 m0, s91, 0x2000
	s_mov_b64 s[100:101], s[92:93]
	s_add_i32 s91, s86, s73
	global_load_lds_dwordx4 v148, s[92:93]
	s_add_u32 s92, s92, s10
	s_addc_u32 s93, s93, s11
	s_mov_b32 m0, s91
	ds_read_b128 v[214:217], v171 offset:23552
	global_load_lds_dwordx4 v150, s[92:93]
	s_add_i32 m0, s91, 0x2000
	ds_read_b128 v[210:213], v171 offset:22528
	global_load_lds_dwordx4 v148, s[92:93]
	s_mov_b32 m0, s67
	ds_read_b128 v[206:209], v171 offset:21504
	global_load_lds_dwordx4 v144, s[68:69]
	s_mov_b32 m0, s75
	ds_read_b128 v[202:205], v171 offset:20480
	global_load_lds_dwordx4 v146, s[68:69]
	s_waitcnt vmcnt(8) lgkmcnt(0)
	s_barrier
	s_setprio 1
	v_mfma_f32_16x16x32_bf16 v[60:63], v[120:123], v[184:187], v[60:63]
	v_mfma_f32_16x16x32_bf16 v[56:59], v[136:139], v[184:187], v[56:59]
	v_mfma_f32_16x16x32_bf16 v[44:47], v[120:123], v[194:197], v[44:47]
	v_mfma_f32_16x16x32_bf16 v[40:43], v[136:139], v[194:197], v[40:43]
	v_mfma_f32_16x16x32_bf16 v[28:31], v[120:123], v[202:205], v[28:31]
	v_mfma_f32_16x16x32_bf16 v[24:27], v[136:139], v[202:205], v[24:27]
	v_mfma_f32_16x16x32_bf16 v[12:15], v[120:123], v[210:213], v[12:15]
	v_mfma_f32_16x16x32_bf16 v[8:11], v[136:139], v[210:213], v[8:11]
	v_mfma_f32_16x16x32_bf16 v[60:63], v[128:131], v[190:193], v[60:63]
	v_mfma_f32_16x16x32_bf16 v[56:59], v[140:143], v[190:193], v[56:59]
	v_mfma_f32_16x16x32_bf16 v[44:47], v[128:131], v[198:201], v[44:47]
	v_mfma_f32_16x16x32_bf16 v[40:43], v[140:143], v[198:201], v[40:43]
	v_mfma_f32_16x16x32_bf16 v[28:31], v[128:131], v[206:209], v[28:31]
	v_mfma_f32_16x16x32_bf16 v[24:27], v[140:143], v[206:209], v[24:27]
	v_mfma_f32_16x16x32_bf16 v[12:15], v[128:131], v[214:217], v[12:15]
	v_mfma_f32_16x16x32_bf16 v[8:11], v[140:143], v[214:217], v[8:11]
	v_mfma_f32_16x16x32_bf16 v[52:55], v[160:163], v[184:187], v[52:55]
	v_mfma_f32_16x16x32_bf16 v[48:51], v[176:179], v[184:187], v[48:51]
	v_mfma_f32_16x16x32_bf16 v[36:39], v[160:163], v[194:197], v[36:39]
	v_mfma_f32_16x16x32_bf16 v[32:35], v[176:179], v[194:197], v[32:35]
	v_mfma_f32_16x16x32_bf16 v[20:23], v[160:163], v[202:205], v[20:23]
	v_mfma_f32_16x16x32_bf16 v[16:19], v[176:179], v[202:205], v[16:19]
	v_mfma_f32_16x16x32_bf16 v[4:7], v[160:163], v[210:213], v[4:7]
	v_mfma_f32_16x16x32_bf16 v[0:3], v[176:179], v[210:213], v[0:3]
	v_mfma_f32_16x16x32_bf16 v[52:55], v[172:175], v[190:193], v[52:55]
	v_mfma_f32_16x16x32_bf16 v[48:51], v[180:183], v[190:193], v[48:51]
	v_mfma_f32_16x16x32_bf16 v[36:39], v[172:175], v[198:201], v[36:39]
	v_mfma_f32_16x16x32_bf16 v[32:35], v[180:183], v[198:201], v[32:35]
	v_mfma_f32_16x16x32_bf16 v[20:23], v[172:175], v[206:209], v[20:23]
	v_mfma_f32_16x16x32_bf16 v[16:19], v[180:183], v[206:209], v[16:19]
	v_mfma_f32_16x16x32_bf16 v[4:7], v[172:175], v[214:217], v[4:7]
	v_mfma_f32_16x16x32_bf16 v[0:3], v[180:183], v[214:217], v[0:3]
	s_setprio 0
	s_barrier
; #define PG8_STAGE(bufoff, gbase, voff) do { _Pragma("unroll") for (int _i = 0; _i < 2; ++_i) \
;         __builtin_amdgcn_global_load_lds((const unsigned*)((const char*)(gbase) + (voff)[_i]), (PG8_LAS unsigned*)(lds + (bufoff) + ldsw + _i * 8192), 16, 0, 0); } while (0)
; #define PG8_LDA(dst, b, h) do { _Pragma("unroll") for (int m = 0; m < 4; ++m) _Pragma("unroll") for (int k = 0; k < 2; ++k) dst[m][k] = *(const PG8_LAS bf16x8*)(lds + PG8_SA(b, h) + aoff + m * 2048 + k * 1024); } while (0)
; #define PG8_LDB(dst, b, h) do { _Pragma("unroll") for (int n = 0; n < 2; ++n) _Pragma("unroll") for (int k = 0; k < 2; ++k) dst[n][k] = *(const PG8_LAS bf16x8*)(lds + PG8_SB(b, h) + boff + n * 2048 + k * 1024); } while (0)
; template <class Epi, class Sched, bool ALIGN_EPI = false, bool SP2 = false>
; __device__ __forceinline__ void gemm_phase(PG8_LAS unsigned char* lds, const Gemm g, const Sched& S, const Epi& E) {
;     ...
;         for (int t = 0; t < nt; t += 2) {
;             const bool last = (t == nt - 2);
;             const char* a1 = cA + (size_t)(t + 1) * kstep;
;             const char* a2 = last ? nA : cA + (size_t)(t + 2) * kstep; const char* b2 = last ? nB : cB + (size_t)(t + 2) * kstep;
;             const char* a3 = a2 + kstep; const char* b3 = b2 + kstep;
;             if (last && has_next) S.a_ready(nxt);
;             if constexpr (SP2) {
;             PG8_LDB(B0, 0, 0); PG8_LDB(B1, 0, 1); PG8_SCHED; PG8_LDA(At, 0, 0); PG8_STAGE(PG8_SA(1, 1), a1 + hstepA, voffA);
;             PG8_WAIT_V(8); PG8_WAIT_L(0); PG8_BAR; PG8_MMA(0, 0, At, B0); PG8_MMA(0, 1, At, B1); PG8_BAR; PG8_SCHED;
;             PG8_LDA(At, 0, 1); PG8_STAGE(PG8_SB(0, 0), b2, voffB); PG8_STAGE(PG8_SB(0, 1), b2 + hstep, voffB); PG8_STAGE(PG8_SA(0, 0), a2, voffA);
;             PG8_WAIT_V(8); PG8_WAIT_L(0); PG8_BAR; PG8_MMA(1, 0, At, B0); PG8_MMA(1, 1, At, B1); PG8_BAR; PG8_SCHED;
;             PG8_LDB(B0, 1, 0); PG8_LDB(B1, 1, 1); PG8_SCHED; PG8_LDA(At, 1, 0); PG8_STAGE(PG8_SA(0, 1), a2 + hstepA, voffA);
;             PG8_WAIT_V(8); PG8_WAIT_L(0); PG8_BAR; PG8_MMA(0, 0, At, B0); PG8_MMA(0, 1, At, B1); PG8_BAR; PG8_SCHED;
;             PG8_LDA(At, 1, 1); PG8_STAGE(PG8_SB(1, 0), b3, voffB); PG8_STAGE(PG8_SB(1, 1), b3 + hstep, voffB); PG8_STAGE(PG8_SA(1, 0), a3, voffA);
;             PG8_WAIT_V(8); PG8_WAIT_L(0); PG8_BAR; PG8_MMA(1, 0, At, B0); PG8_MMA(1, 1, At, B1); PG8_BAR; PG8_SCHED;
	s_add_i32 s91, 0, 0x18000
	s_add_i32 s92, 0, 0x1c000
	v_add_u32_e32 v140, s91, v167
	v_add_u32_e32 v180, s92, v167
	ds_read_b128 v[120:123], v140
	ds_read_b128 v[128:131], v140 offset:1024
	ds_read_b128 v[136:139], v140 offset:2048
	ds_read_b128 v[140:143], v140 offset:3072
	ds_read_b128 v[160:163], v180
	ds_read_b128 v[172:175], v180 offset:1024
	ds_read_b128 v[176:179], v180 offset:2048
	ds_read_b128 v[180:183], v180 offset:3072
	s_mov_b64 vcc, s[68:69]
	s_add_u32 s68, s68, 0x40000
	s_addc_u32 s69, s69, 0
	s_mov_b32 m0, s76
	ds_read_b128 v[184:187], v171 offset:32768
	ds_read_b128 v[190:193], v171 offset:33792
	ds_read_b128 v[194:197], v171 offset:34816
	ds_read_b128 v[198:201], v171 offset:35840
	ds_read_b128 v[202:205], v171 offset:36864
	ds_read_b128 v[206:209], v171 offset:37888
	ds_read_b128 v[210:213], v171 offset:38912
	global_load_lds_dwordx4 v144, s[68:69]
	s_mov_b32 m0, s77
	ds_read_b128 v[214:217], v171 offset:39936
	global_load_lds_dwordx4 v146, s[68:69]
	s_waitcnt vmcnt(8) lgkmcnt(0)
	s_barrier
	s_setprio 1
	v_mfma_f32_16x16x32_bf16 v[132:135], v[120:123], v[184:187], v[132:135]
	v_mfma_f32_16x16x32_bf16 v[124:127], v[136:139], v[184:187], v[124:127]
	v_mfma_f32_16x16x32_bf16 v[108:111], v[120:123], v[194:197], v[108:111]
	v_mfma_f32_16x16x32_bf16 v[104:107], v[136:139], v[194:197], v[104:107]
	v_mfma_f32_16x16x32_bf16 v[92:95], v[120:123], v[202:205], v[92:95]
	v_mfma_f32_16x16x32_bf16 v[88:91], v[136:139], v[202:205], v[88:91]
	v_mfma_f32_16x16x32_bf16 v[76:79], v[120:123], v[210:213], v[76:79]
	v_mfma_f32_16x16x32_bf16 v[72:75], v[136:139], v[210:213], v[72:75]
	v_mfma_f32_16x16x32_bf16 v[132:135], v[128:131], v[190:193], v[132:135]
	v_mfma_f32_16x16x32_bf16 v[124:127], v[140:143], v[190:193], v[124:127]
	v_mfma_f32_16x16x32_bf16 v[108:111], v[128:131], v[198:201], v[108:111]
	v_mfma_f32_16x16x32_bf16 v[104:107], v[140:143], v[198:201], v[104:107]
	v_mfma_f32_16x16x32_bf16 v[92:95], v[128:131], v[206:209], v[92:95]
	v_mfma_f32_16x16x32_bf16 v[88:91], v[140:143], v[206:209], v[88:91]
	v_mfma_f32_16x16x32_bf16 v[76:79], v[128:131], v[214:217], v[76:79]
	v_mfma_f32_16x16x32_bf16 v[72:75], v[140:143], v[214:217], v[72:75]
	v_mfma_f32_16x16x32_bf16 v[116:119], v[160:163], v[184:187], v[116:119]
	v_mfma_f32_16x16x32_bf16 v[112:115], v[176:179], v[184:187], v[112:115]
	v_mfma_f32_16x16x32_bf16 v[100:103], v[160:163], v[194:197], v[100:103]
	v_mfma_f32_16x16x32_bf16 v[96:99], v[176:179], v[194:197], v[96:99]
	v_mfma_f32_16x16x32_bf16 v[84:87], v[160:163], v[202:205], v[84:87]
	v_mfma_f32_16x16x32_bf16 v[80:83], v[176:179], v[202:205], v[80:83]
	v_mfma_f32_16x16x32_bf16 v[68:71], v[160:163], v[210:213], v[68:71]
	v_mfma_f32_16x16x32_bf16 v[64:67], v[176:179], v[210:213], v[64:67]
	v_mfma_f32_16x16x32_bf16 v[116:119], v[172:175], v[190:193], v[116:119]
	v_mfma_f32_16x16x32_bf16 v[112:115], v[180:183], v[190:193], v[112:115]
	v_mfma_f32_16x16x32_bf16 v[100:103], v[172:175], v[198:201], v[100:103]
	v_mfma_f32_16x16x32_bf16 v[96:99], v[180:183], v[198:201], v[96:99]
	v_mfma_f32_16x16x32_bf16 v[84:87], v[172:175], v[206:209], v[84:87]
	v_mfma_f32_16x16x32_bf16 v[80:83], v[180:183], v[206:209], v[80:83]
	v_mfma_f32_16x16x32_bf16 v[68:71], v[172:175], v[214:217], v[68:71]
	v_mfma_f32_16x16x32_bf16 v[64:67], v[180:183], v[214:217], v[64:67]
	s_setprio 0
	s_barrier
	s_add_i32 s68, s91, s73
	s_add_i32 m0, s68, 0xffffff80
	ds_read_b128 v[184:187], v171 offset:49152
	ds_read_b128 v[190:193], v171 offset:50176
	ds_read_b128 v[194:197], v171 offset:51200
	ds_read_b128 v[198:201], v171 offset:52224
	global_load_lds_dwordx4 v150, s[100:101] offset:128
	s_add_i32 m0, s68, 0x1f80
	s_add_i32 s68, s92, s73
	global_load_lds_dwordx4 v148, s[100:101] offset:128
	s_add_u32 s100, s100, s10
	s_addc_u32 s101, s101, s11
	s_add_i32 m0, s68, 0xffffff80
	ds_read_b128 v[214:217], v171 offset:56320
	global_load_lds_dwordx4 v150, s[100:101] offset:128
	s_add_i32 m0, s68, 0x1f80
	ds_read_b128 v[210:213], v171 offset:55296
	global_load_lds_dwordx4 v148, s[100:101] offset:128
	s_add_i32 m0, s80, 0xffffff80
	ds_read_b128 v[206:209], v171 offset:54272
	global_load_lds_dwordx4 v144, vcc offset:128
	s_add_i32 m0, s81, 0xffffff80
	ds_read_b128 v[202:205], v171 offset:53248
	global_load_lds_dwordx4 v146, vcc offset:128
	s_waitcnt vmcnt(8) lgkmcnt(0)
	s_barrier
	s_setprio 1
	v_mfma_f32_16x16x32_bf16 v[60:63], v[120:123], v[184:187], v[60:63]
	v_mfma_f32_16x16x32_bf16 v[56:59], v[136:139], v[184:187], v[56:59]
	v_mfma_f32_16x16x32_bf16 v[44:47], v[120:123], v[194:197], v[44:47]
	v_mfma_f32_16x16x32_bf16 v[40:43], v[136:139], v[194:197], v[40:43]
	v_mfma_f32_16x16x32_bf16 v[28:31], v[120:123], v[202:205], v[28:31]
	v_mfma_f32_16x16x32_bf16 v[24:27], v[136:139], v[202:205], v[24:27]
	v_mfma_f32_16x16x32_bf16 v[12:15], v[120:123], v[210:213], v[12:15]
	v_mfma_f32_16x16x32_bf16 v[8:11], v[136:139], v[210:213], v[8:11]
	v_mfma_f32_16x16x32_bf16 v[60:63], v[128:131], v[190:193], v[60:63]
	v_mfma_f32_16x16x32_bf16 v[56:59], v[140:143], v[190:193], v[56:59]
	v_mfma_f32_16x16x32_bf16 v[44:47], v[128:131], v[198:201], v[44:47]
	v_mfma_f32_16x16x32_bf16 v[40:43], v[140:143], v[198:201], v[40:43]
	v_mfma_f32_16x16x32_bf16 v[28:31], v[128:131], v[206:209], v[28:31]
	v_mfma_f32_16x16x32_bf16 v[24:27], v[140:143], v[206:209], v[24:27]
	v_mfma_f32_16x16x32_bf16 v[12:15], v[128:131], v[214:217], v[12:15]
	v_mfma_f32_16x16x32_bf16 v[8:11], v[140:143], v[214:217], v[8:11]
	v_mfma_f32_16x16x32_bf16 v[52:55], v[160:163], v[184:187], v[52:55]
	v_mfma_f32_16x16x32_bf16 v[48:51], v[176:179], v[184:187], v[48:51]
	v_mfma_f32_16x16x32_bf16 v[36:39], v[160:163], v[194:197], v[36:39]
	v_mfma_f32_16x16x32_bf16 v[32:35], v[176:179], v[194:197], v[32:35]
	v_mfma_f32_16x16x32_bf16 v[20:23], v[160:163], v[202:205], v[20:23]
	v_mfma_f32_16x16x32_bf16 v[16:19], v[176:179], v[202:205], v[16:19]
	v_mfma_f32_16x16x32_bf16 v[4:7], v[160:163], v[210:213], v[4:7]
	v_mfma_f32_16x16x32_bf16 v[0:3], v[176:179], v[210:213], v[0:3]
	v_mfma_f32_16x16x32_bf16 v[52:55], v[172:175], v[190:193], v[52:55]
	v_mfma_f32_16x16x32_bf16 v[48:51], v[180:183], v[190:193], v[48:51]
	v_mfma_f32_16x16x32_bf16 v[36:39], v[172:175], v[198:201], v[36:39]
	v_mfma_f32_16x16x32_bf16 v[32:35], v[180:183], v[198:201], v[32:35]
	v_mfma_f32_16x16x32_bf16 v[20:23], v[172:175], v[206:209], v[20:23]
	v_mfma_f32_16x16x32_bf16 v[16:19], v[180:183], v[206:209], v[16:19]
	v_mfma_f32_16x16x32_bf16 v[4:7], v[172:175], v[214:217], v[4:7]
	v_mfma_f32_16x16x32_bf16 v[0:3], v[180:183], v[214:217], v[0:3]
	s_setprio 0
	s_barrier
	s_add_u32 s8, s8, 0x100
	s_addc_u32 s9, s9, 0
	s_add_u32 s70, s70, 0x100
	s_addc_u32 s71, s71, 0
	s_cmp_ge_i32 s90, s83
	s_mov_b32 s68, s90
	s_cbranch_scc0 .LBB0_1679

; #define PG8_STAGE(bufoff, gbase, voff) do { _Pragma("unroll") for (int _i = 0; _i < 2; ++_i) \
;         __builtin_amdgcn_global_load_lds((const unsigned*)((const char*)(gbase) + (voff)[_i]), (PG8_LAS unsigned*)(lds + (bufoff) + ldsw + _i * 8192), 16, 0, 0); } while (0)
; #define PG8_LDA(dst, b, h) do { _Pragma("unroll") for (int m = 0; m < 4; ++m) _Pragma("unroll") for (int k = 0; k < 2; ++k) dst[m][k] = *(const PG8_LAS bf16x8*)(lds + PG8_SA(b, h) + aoff + m * 2048 + k * 1024); } while (0)
; #define PG8_LDB(dst, b, h) do { _Pragma("unroll") for (int n = 0; n < 2; ++n) _Pragma("unroll") for (int k = 0; k < 2; ++k) dst[n][k] = *(const PG8_LAS bf16x8*)(lds + PG8_SB(b, h) + boff + n * 2048 + k * 1024); } while (0)
; template <class Epi, class Sched, bool ALIGN_EPI = false, bool SP2 = false>
; __device__ __forceinline__ void gemm_phase(PG8_LAS unsigned char* lds, const Gemm g, const Sched& S, const Epi& E) {
;     ...
;         for (int t = 0; t < nt; t += 2) {
;             const bool last = (t == nt - 2);
;             const char* a1 = cA + (size_t)(t + 1) * kstep;
;             const char* a2 = last ? nA : cA + (size_t)(t + 2) * kstep; const char* b2 = last ? nB : cB + (size_t)(t + 2) * kstep;
;             const char* a3 = a2 + kstep; const char* b3 = b2 + kstep;
;             if (last && has_next) S.a_ready(nxt);
;             if constexpr (SP2) {
;             PG8_LDB(B0, 0, 0); PG8_LDB(B1, 0, 1); PG8_SCHED; PG8_LDA(At, 0, 0); PG8_STAGE(PG8_SA(1, 1), a1 + hstepA, voffA);
;             PG8_WAIT_V(8); PG8_WAIT_L(0); PG8_BAR; PG8_MMA(0, 0, At, B0); PG8_MMA(0, 1, At, B1); PG8_BAR; PG8_SCHED;
;             PG8_LDA(At, 0, 1); PG8_STAGE(PG8_SB(0, 0), b2, voffB); PG8_STAGE(PG8_SB(0, 1), b2 + hstep, voffB); PG8_STAGE(PG8_SA(0, 0), a2, voffA);
;             PG8_WAIT_V(8); PG8_WAIT_L(0); PG8_BAR; PG8_MMA(1, 0, At, B0); PG8_MMA(1, 1, At, B1); PG8_BAR; PG8_SCHED;
;             PG8_LDB(B0, 1, 0); PG8_LDB(B1, 1, 1); PG8_SCHED; PG8_LDA(At, 1, 0); PG8_STAGE(PG8_SA(0, 1), a2 + hstepA, voffA);
;             PG8_WAIT_V(8); PG8_WAIT_L(0); PG8_BAR; PG8_MMA(0, 0, At, B0); PG8_MMA(0, 1, At, B1); PG8_BAR; PG8_SCHED;
;             PG8_LDA(At, 1, 1); PG8_STAGE(PG8_SB(1, 0), b3, voffB); PG8_STAGE(PG8_SB(1, 1), b3 + hstep, voffB); PG8_STAGE(PG8_SA(1, 0), a3, voffA);
;             PG8_WAIT_V(8); PG8_WAIT_L(0); PG8_BAR; PG8_MMA(1, 0, At, B0); PG8_MMA(1, 1, At, B1); PG8_BAR; PG8_SCHED;
.LBB0_1815:
	ds_read_b128 v[150:153], v147
	ds_read_b128 v[154:157], v147 offset:1024
	ds_read_b128 v[158:161], v147 offset:2048
	ds_read_b128 v[162:165], v147 offset:3072
	ds_read_b128 v[166:169], v148
	ds_read_b128 v[170:173], v148 offset:1024
	ds_read_b128 v[174:177], v148 offset:2048
	ds_read_b128 v[178:181], v148 offset:3072
	s_add_i32 s57, s30, 2
	s_add_u32 s58, s10, 0xfffc0080
	s_addc_u32 s31, s11, -1
	s_cmp_eq_u32 s50, s30
	s_cselect_b32 s30, s56, s58
	s_cselect_b32 s31, s23, s31
	s_cselect_b32 s59, s25, s35
	s_cselect_b32 s58, s24, s34
	s_add_i32 m0, s29, 0xc000
	ds_read_b128 v[182:185], v149
	ds_read_b128 v[190:193], v149 offset:1024
	ds_read_b128 v[194:197], v149 offset:2048
	ds_read_b128 v[198:201], v149 offset:3072
	ds_read_b128 v[202:205], v149 offset:4096
	ds_read_b128 v[206:209], v149 offset:5120
	ds_read_b128 v[210:213], v149 offset:6144
	global_load_lds_dwordx4 v136, s[10:11]
	s_add_i32 m0, s29, 0xe000
	ds_read_b128 v[214:217], v149 offset:7168
	global_load_lds_dwordx4 v138, s[10:11]
	s_waitcnt vmcnt(8) lgkmcnt(0)
	s_barrier
	s_setprio 1
	v_mfma_f32_16x16x32_bf16 v[124:127], v[150:153], v[182:185], v[124:127]
	v_mfma_f32_16x16x32_bf16 v[116:119], v[158:161], v[182:185], v[116:119]
	v_mfma_f32_16x16x32_bf16 v[108:111], v[150:153], v[194:197], v[108:111]
	v_mfma_f32_16x16x32_bf16 v[100:103], v[158:161], v[194:197], v[100:103]
	v_mfma_f32_16x16x32_bf16 v[92:95], v[150:153], v[202:205], v[92:95]
	v_mfma_f32_16x16x32_bf16 v[84:87], v[158:161], v[202:205], v[84:87]
	v_mfma_f32_16x16x32_bf16 v[76:79], v[150:153], v[210:213], v[76:79]
	v_mfma_f32_16x16x32_bf16 v[68:71], v[158:161], v[210:213], v[68:71]
	v_mfma_f32_16x16x32_bf16 v[124:127], v[154:157], v[190:193], v[124:127]
	v_mfma_f32_16x16x32_bf16 v[116:119], v[162:165], v[190:193], v[116:119]
	v_mfma_f32_16x16x32_bf16 v[108:111], v[154:157], v[198:201], v[108:111]
	v_mfma_f32_16x16x32_bf16 v[100:103], v[162:165], v[198:201], v[100:103]
	v_mfma_f32_16x16x32_bf16 v[92:95], v[154:157], v[206:209], v[92:95]
	v_mfma_f32_16x16x32_bf16 v[84:87], v[162:165], v[206:209], v[84:87]
	v_mfma_f32_16x16x32_bf16 v[76:79], v[154:157], v[214:217], v[76:79]
	v_mfma_f32_16x16x32_bf16 v[68:71], v[162:165], v[214:217], v[68:71]
	v_mfma_f32_16x16x32_bf16 v[120:123], v[166:169], v[182:185], v[120:123]
	v_mfma_f32_16x16x32_bf16 v[112:115], v[174:177], v[182:185], v[112:115]
	v_mfma_f32_16x16x32_bf16 v[104:107], v[166:169], v[194:197], v[104:107]
	v_mfma_f32_16x16x32_bf16 v[96:99], v[174:177], v[194:197], v[96:99]
	v_mfma_f32_16x16x32_bf16 v[88:91], v[166:169], v[202:205], v[88:91]
	v_mfma_f32_16x16x32_bf16 v[80:83], v[174:177], v[202:205], v[80:83]
	v_mfma_f32_16x16x32_bf16 v[72:75], v[166:169], v[210:213], v[72:75]
	v_mfma_f32_16x16x32_bf16 v[64:67], v[174:177], v[210:213], v[64:67]
	v_mfma_f32_16x16x32_bf16 v[120:123], v[170:173], v[190:193], v[120:123]
	v_mfma_f32_16x16x32_bf16 v[112:115], v[178:181], v[190:193], v[112:115]
	v_mfma_f32_16x16x32_bf16 v[104:107], v[170:173], v[198:201], v[104:107]
	v_mfma_f32_16x16x32_bf16 v[96:99], v[178:181], v[198:201], v[96:99]
	v_mfma_f32_16x16x32_bf16 v[88:91], v[170:173], v[206:209], v[88:91]
	v_mfma_f32_16x16x32_bf16 v[80:83], v[178:181], v[206:209], v[80:83]
	v_mfma_f32_16x16x32_bf16 v[72:75], v[170:173], v[214:217], v[72:75]
	v_mfma_f32_16x16x32_bf16 v[64:67], v[178:181], v[214:217], v[64:67]
	s_setprio 0
	s_barrier
	s_add_i32 s60, s51, s38
	s_mov_b32 m0, s60
	ds_read_b128 v[182:185], v149 offset:16384
	ds_read_b128 v[190:193], v149 offset:17408
	ds_read_b128 v[194:197], v149 offset:18432
	ds_read_b128 v[198:201], v149 offset:19456
	global_load_lds_dwordx4 v134, s[58:59]
	s_add_i32 m0, s60, 0x2000
	s_mov_b64 s[100:101], s[58:59]
	s_add_i32 s60, s52, s38
	global_load_lds_dwordx4 v132, s[58:59]
	s_add_u32 s58, s58, s4
	s_addc_u32 s59, s59, s5
	s_mov_b32 m0, s60
	ds_read_b128 v[214:217], v149 offset:23552
	global_load_lds_dwordx4 v134, s[58:59]
	s_add_i32 m0, s60, 0x2000
	ds_read_b128 v[210:213], v149 offset:22528
	global_load_lds_dwordx4 v132, s[58:59]
	s_mov_b32 m0, s29
	ds_read_b128 v[206:209], v149 offset:21504
	global_load_lds_dwordx4 v128, s[30:31]
	s_mov_b32 m0, s41
	ds_read_b128 v[202:205], v149 offset:20480
	global_load_lds_dwordx4 v130, s[30:31]
	s_waitcnt vmcnt(8) lgkmcnt(0)
	s_barrier
	s_setprio 1
	v_mfma_f32_16x16x32_bf16 v[60:63], v[150:153], v[182:185], v[60:63]
	v_mfma_f32_16x16x32_bf16 v[52:55], v[158:161], v[182:185], v[52:55]
	v_mfma_f32_16x16x32_bf16 v[44:47], v[150:153], v[194:197], v[44:47]
	v_mfma_f32_16x16x32_bf16 v[36:39], v[158:161], v[194:197], v[36:39]
	v_mfma_f32_16x16x32_bf16 v[28:31], v[150:153], v[202:205], v[28:31]
	v_mfma_f32_16x16x32_bf16 v[20:23], v[158:161], v[202:205], v[20:23]
	v_mfma_f32_16x16x32_bf16 v[12:15], v[150:153], v[210:213], v[12:15]
	v_mfma_f32_16x16x32_bf16 v[4:7], v[158:161], v[210:213], v[4:7]
	v_mfma_f32_16x16x32_bf16 v[60:63], v[154:157], v[190:193], v[60:63]
	v_mfma_f32_16x16x32_bf16 v[52:55], v[162:165], v[190:193], v[52:55]
	v_mfma_f32_16x16x32_bf16 v[44:47], v[154:157], v[198:201], v[44:47]
	v_mfma_f32_16x16x32_bf16 v[36:39], v[162:165], v[198:201], v[36:39]
	v_mfma_f32_16x16x32_bf16 v[28:31], v[154:157], v[206:209], v[28:31]
	v_mfma_f32_16x16x32_bf16 v[20:23], v[162:165], v[206:209], v[20:23]
	v_mfma_f32_16x16x32_bf16 v[12:15], v[154:157], v[214:217], v[12:15]
	v_mfma_f32_16x16x32_bf16 v[4:7], v[162:165], v[214:217], v[4:7]
	v_mfma_f32_16x16x32_bf16 v[56:59], v[166:169], v[182:185], v[56:59]
	v_mfma_f32_16x16x32_bf16 v[48:51], v[174:177], v[182:185], v[48:51]
	v_mfma_f32_16x16x32_bf16 v[40:43], v[166:169], v[194:197], v[40:43]
	v_mfma_f32_16x16x32_bf16 v[32:35], v[174:177], v[194:197], v[32:35]
	v_mfma_f32_16x16x32_bf16 v[24:27], v[166:169], v[202:205], v[24:27]
	v_mfma_f32_16x16x32_bf16 v[16:19], v[174:177], v[202:205], v[16:19]
	v_mfma_f32_16x16x32_bf16 v[8:11], v[166:169], v[210:213], v[8:11]
	v_mfma_f32_16x16x32_bf16 v[0:3], v[174:177], v[210:213], v[0:3]
	v_mfma_f32_16x16x32_bf16 v[56:59], v[170:173], v[190:193], v[56:59]
	v_mfma_f32_16x16x32_bf16 v[48:51], v[178:181], v[190:193], v[48:51]
	v_mfma_f32_16x16x32_bf16 v[40:43], v[170:173], v[198:201], v[40:43]
	v_mfma_f32_16x16x32_bf16 v[32:35], v[178:181], v[198:201], v[32:35]
	v_mfma_f32_16x16x32_bf16 v[24:27], v[170:173], v[206:209], v[24:27]
	v_mfma_f32_16x16x32_bf16 v[16:19], v[178:181], v[206:209], v[16:19]
	v_mfma_f32_16x16x32_bf16 v[8:11], v[170:173], v[214:217], v[8:11]
	v_mfma_f32_16x16x32_bf16 v[0:3], v[178:181], v[214:217], v[0:3]
	s_setprio 0
	s_barrier
; #define PG8_STAGE(bufoff, gbase, voff) do { _Pragma("unroll") for (int _i = 0; _i < 2; ++_i) \
;         __builtin_amdgcn_global_load_lds((const unsigned*)((const char*)(gbase) + (voff)[_i]), (PG8_LAS unsigned*)(lds + (bufoff) + ldsw + _i * 8192), 16, 0, 0); } while (0)
; #define PG8_LDA(dst, b, h) do { _Pragma("unroll") for (int m = 0; m < 4; ++m) _Pragma("unroll") for (int k = 0; k < 2; ++k) dst[m][k] = *(const PG8_LAS bf16x8*)(lds + PG8_SA(b, h) + aoff + m * 2048 + k * 1024); } while (0)
; #define PG8_LDB(dst, b, h) do { _Pragma("unroll") for (int n = 0; n < 2; ++n) _Pragma("unroll") for (int k = 0; k < 2; ++k) dst[n][k] = *(const PG8_LAS bf16x8*)(lds + PG8_SB(b, h) + boff + n * 2048 + k * 1024); } while (0)
; template <class Epi, class Sched, bool ALIGN_EPI = false, bool SP2 = false>
; __device__ __forceinline__ void gemm_phase(PG8_LAS unsigned char* lds, const Gemm g, const Sched& S, const Epi& E) {
;     ...
;         for (int t = 0; t < nt; t += 2) {
;             const bool last = (t == nt - 2);
;             const char* a1 = cA + (size_t)(t + 1) * kstep;
;             const char* a2 = last ? nA : cA + (size_t)(t + 2) * kstep; const char* b2 = last ? nB : cB + (size_t)(t + 2) * kstep;
;             const char* a3 = a2 + kstep; const char* b3 = b2 + kstep;
;             if (last && has_next) S.a_ready(nxt);
;             if constexpr (SP2) {
;             PG8_LDB(B0, 0, 0); PG8_LDB(B1, 0, 1); PG8_SCHED; PG8_LDA(At, 0, 0); PG8_STAGE(PG8_SA(1, 1), a1 + hstepA, voffA);
;             PG8_WAIT_V(8); PG8_WAIT_L(0); PG8_BAR; PG8_MMA(0, 0, At, B0); PG8_MMA(0, 1, At, B1); PG8_BAR; PG8_SCHED;
;             PG8_LDA(At, 0, 1); PG8_STAGE(PG8_SB(0, 0), b2, voffB); PG8_STAGE(PG8_SB(0, 1), b2 + hstep, voffB); PG8_STAGE(PG8_SA(0, 0), a2, voffA);
;             PG8_WAIT_V(8); PG8_WAIT_L(0); PG8_BAR; PG8_MMA(1, 0, At, B0); PG8_MMA(1, 1, At, B1); PG8_BAR; PG8_SCHED;
;             PG8_LDB(B0, 1, 0); PG8_LDB(B1, 1, 1); PG8_SCHED; PG8_LDA(At, 1, 0); PG8_STAGE(PG8_SA(0, 1), a2 + hstepA, voffA);
;             PG8_WAIT_V(8); PG8_WAIT_L(0); PG8_BAR; PG8_MMA(0, 0, At, B0); PG8_MMA(0, 1, At, B1); PG8_BAR; PG8_SCHED;
;             PG8_LDA(At, 1, 1); PG8_STAGE(PG8_SB(1, 0), b3, voffB); PG8_STAGE(PG8_SB(1, 1), b3 + hstep, voffB); PG8_STAGE(PG8_SA(1, 0), a3, voffA);
;             PG8_WAIT_V(8); PG8_WAIT_L(0); PG8_BAR; PG8_MMA(1, 0, At, B0); PG8_MMA(1, 1, At, B1); PG8_BAR; PG8_SCHED;
	s_add_i32 s58, 0, 0x18000
	s_add_i32 s59, 0, 0x1c000
	v_add_u32_e32 v162, s58, v145
	v_add_u32_e32 v178, s59, v145
	ds_read_b128 v[150:153], v162
	ds_read_b128 v[154:157], v162 offset:1024
	ds_read_b128 v[158:161], v162 offset:2048
	ds_read_b128 v[162:165], v162 offset:3072
	ds_read_b128 v[166:169], v178
	ds_read_b128 v[170:173], v178 offset:1024
	ds_read_b128 v[174:177], v178 offset:2048
	ds_read_b128 v[178:181], v178 offset:3072
	s_mov_b64 vcc, s[30:31]
	s_add_u32 s30, s30, 0x40000
	s_addc_u32 s31, s31, 0
	s_mov_b32 m0, s42
	ds_read_b128 v[182:185], v149 offset:32768
	ds_read_b128 v[190:193], v149 offset:33792
	ds_read_b128 v[194:197], v149 offset:34816
	ds_read_b128 v[198:201], v149 offset:35840
	ds_read_b128 v[202:205], v149 offset:36864
	ds_read_b128 v[206:209], v149 offset:37888
	ds_read_b128 v[210:213], v149 offset:38912
	global_load_lds_dwordx4 v128, s[30:31]
	s_mov_b32 m0, s43
	ds_read_b128 v[214:217], v149 offset:39936
	global_load_lds_dwordx4 v130, s[30:31]
	s_waitcnt vmcnt(8) lgkmcnt(0)
	s_barrier
	s_setprio 1
	v_mfma_f32_16x16x32_bf16 v[124:127], v[150:153], v[182:185], v[124:127]
	v_mfma_f32_16x16x32_bf16 v[116:119], v[158:161], v[182:185], v[116:119]
	v_mfma_f32_16x16x32_bf16 v[108:111], v[150:153], v[194:197], v[108:111]
	v_mfma_f32_16x16x32_bf16 v[100:103], v[158:161], v[194:197], v[100:103]
	v_mfma_f32_16x16x32_bf16 v[92:95], v[150:153], v[202:205], v[92:95]
	v_mfma_f32_16x16x32_bf16 v[84:87], v[158:161], v[202:205], v[84:87]
	v_mfma_f32_16x16x32_bf16 v[76:79], v[150:153], v[210:213], v[76:79]
	v_mfma_f32_16x16x32_bf16 v[68:71], v[158:161], v[210:213], v[68:71]
	v_mfma_f32_16x16x32_bf16 v[124:127], v[154:157], v[190:193], v[124:127]
	v_mfma_f32_16x16x32_bf16 v[116:119], v[162:165], v[190:193], v[116:119]
	v_mfma_f32_16x16x32_bf16 v[108:111], v[154:157], v[198:201], v[108:111]
	v_mfma_f32_16x16x32_bf16 v[100:103], v[162:165], v[198:201], v[100:103]
	v_mfma_f32_16x16x32_bf16 v[92:95], v[154:157], v[206:209], v[92:95]
	v_mfma_f32_16x16x32_bf16 v[84:87], v[162:165], v[206:209], v[84:87]
	v_mfma_f32_16x16x32_bf16 v[76:79], v[154:157], v[214:217], v[76:79]
	v_mfma_f32_16x16x32_bf16 v[68:71], v[162:165], v[214:217], v[68:71]
	v_mfma_f32_16x16x32_bf16 v[120:123], v[166:169], v[182:185], v[120:123]
	v_mfma_f32_16x16x32_bf16 v[112:115], v[174:177], v[182:185], v[112:115]
	v_mfma_f32_16x16x32_bf16 v[104:107], v[166:169], v[194:197], v[104:107]
	v_mfma_f32_16x16x32_bf16 v[96:99], v[174:177], v[194:197], v[96:99]
	v_mfma_f32_16x16x32_bf16 v[88:91], v[166:169], v[202:205], v[88:91]
	v_mfma_f32_16x16x32_bf16 v[80:83], v[174:177], v[202:205], v[80:83]
	v_mfma_f32_16x16x32_bf16 v[72:75], v[166:169], v[210:213], v[72:75]
	v_mfma_f32_16x16x32_bf16 v[64:67], v[174:177], v[210:213], v[64:67]
	v_mfma_f32_16x16x32_bf16 v[120:123], v[170:173], v[190:193], v[120:123]
	v_mfma_f32_16x16x32_bf16 v[112:115], v[178:181], v[190:193], v[112:115]
	v_mfma_f32_16x16x32_bf16 v[104:107], v[170:173], v[198:201], v[104:107]
	v_mfma_f32_16x16x32_bf16 v[96:99], v[178:181], v[198:201], v[96:99]
	v_mfma_f32_16x16x32_bf16 v[88:91], v[170:173], v[206:209], v[88:91]
	v_mfma_f32_16x16x32_bf16 v[80:83], v[178:181], v[206:209], v[80:83]
	v_mfma_f32_16x16x32_bf16 v[72:75], v[170:173], v[214:217], v[72:75]
	v_mfma_f32_16x16x32_bf16 v[64:67], v[178:181], v[214:217], v[64:67]
	s_setprio 0
	s_barrier
	s_add_i32 s30, s58, s38
	s_add_i32 m0, s30, 0xffffff80
	ds_read_b128 v[182:185], v149 offset:49152
	ds_read_b128 v[190:193], v149 offset:50176
	ds_read_b128 v[194:197], v149 offset:51200
	ds_read_b128 v[198:201], v149 offset:52224
	global_load_lds_dwordx4 v134, s[100:101] offset:128
	s_add_i32 m0, s30, 0x1f80
	s_add_i32 s30, s59, s38
	global_load_lds_dwordx4 v132, s[100:101] offset:128
	s_add_u32 s100, s100, s4
	s_addc_u32 s101, s101, s5
	s_add_i32 m0, s30, 0xffffff80
	ds_read_b128 v[214:217], v149 offset:56320
	global_load_lds_dwordx4 v134, s[100:101] offset:128
	s_add_i32 m0, s30, 0x1f80
	ds_read_b128 v[210:213], v149 offset:55296
	global_load_lds_dwordx4 v132, s[100:101] offset:128
	s_add_i32 m0, s46, 0xffffff80
	ds_read_b128 v[206:209], v149 offset:54272
	global_load_lds_dwordx4 v128, vcc offset:128
	s_add_i32 m0, s47, 0xffffff80
	ds_read_b128 v[202:205], v149 offset:53248
	global_load_lds_dwordx4 v130, vcc offset:128
	s_waitcnt vmcnt(8) lgkmcnt(0)
	s_barrier
	s_setprio 1
	v_mfma_f32_16x16x32_bf16 v[60:63], v[150:153], v[182:185], v[60:63]
	v_mfma_f32_16x16x32_bf16 v[52:55], v[158:161], v[182:185], v[52:55]
	v_mfma_f32_16x16x32_bf16 v[44:47], v[150:153], v[194:197], v[44:47]
	v_mfma_f32_16x16x32_bf16 v[36:39], v[158:161], v[194:197], v[36:39]
	v_mfma_f32_16x16x32_bf16 v[28:31], v[150:153], v[202:205], v[28:31]
	v_mfma_f32_16x16x32_bf16 v[20:23], v[158:161], v[202:205], v[20:23]
	v_mfma_f32_16x16x32_bf16 v[12:15], v[150:153], v[210:213], v[12:15]
	v_mfma_f32_16x16x32_bf16 v[4:7], v[158:161], v[210:213], v[4:7]
	v_mfma_f32_16x16x32_bf16 v[60:63], v[154:157], v[190:193], v[60:63]
	v_mfma_f32_16x16x32_bf16 v[52:55], v[162:165], v[190:193], v[52:55]
	v_mfma_f32_16x16x32_bf16 v[44:47], v[154:157], v[198:201], v[44:47]
	v_mfma_f32_16x16x32_bf16 v[36:39], v[162:165], v[198:201], v[36:39]
	v_mfma_f32_16x16x32_bf16 v[28:31], v[154:157], v[206:209], v[28:31]
	v_mfma_f32_16x16x32_bf16 v[20:23], v[162:165], v[206:209], v[20:23]
	v_mfma_f32_16x16x32_bf16 v[12:15], v[154:157], v[214:217], v[12:15]
	v_mfma_f32_16x16x32_bf16 v[4:7], v[162:165], v[214:217], v[4:7]
	v_mfma_f32_16x16x32_bf16 v[56:59], v[166:169], v[182:185], v[56:59]
	v_mfma_f32_16x16x32_bf16 v[48:51], v[174:177], v[182:185], v[48:51]
	v_mfma_f32_16x16x32_bf16 v[40:43], v[166:169], v[194:197], v[40:43]
	v_mfma_f32_16x16x32_bf16 v[32:35], v[174:177], v[194:197], v[32:35]
	v_mfma_f32_16x16x32_bf16 v[24:27], v[166:169], v[202:205], v[24:27]
	v_mfma_f32_16x16x32_bf16 v[16:19], v[174:177], v[202:205], v[16:19]
	v_mfma_f32_16x16x32_bf16 v[8:11], v[166:169], v[210:213], v[8:11]
	v_mfma_f32_16x16x32_bf16 v[0:3], v[174:177], v[210:213], v[0:3]
	v_mfma_f32_16x16x32_bf16 v[56:59], v[170:173], v[190:193], v[56:59]
	v_mfma_f32_16x16x32_bf16 v[48:51], v[178:181], v[190:193], v[48:51]
	v_mfma_f32_16x16x32_bf16 v[40:43], v[170:173], v[198:201], v[40:43]
	v_mfma_f32_16x16x32_bf16 v[32:35], v[178:181], v[198:201], v[32:35]
	v_mfma_f32_16x16x32_bf16 v[24:27], v[170:173], v[206:209], v[24:27]
	v_mfma_f32_16x16x32_bf16 v[16:19], v[178:181], v[206:209], v[16:19]
	v_mfma_f32_16x16x32_bf16 v[8:11], v[170:173], v[214:217], v[8:11]
	v_mfma_f32_16x16x32_bf16 v[0:3], v[178:181], v[214:217], v[0:3]
	s_setprio 0
	s_barrier
	s_add_u32 s10, s10, 0x100
	s_addc_u32 s11, s11, 0
	s_add_u32 s34, s34, 0x100
	s_addc_u32 s35, s35, 0
	s_cmp_ge_i32 s57, s49
	s_mov_b32 s30, s57
	s_cbranch_scc0 .LBB0_1815

; #define PG8_STAGE(bufoff, gbase, voff) do { _Pragma("unroll") for (int _i = 0; _i < 2; ++_i) \
;         __builtin_amdgcn_global_load_lds((const unsigned*)((const char*)(gbase) + (voff)[_i]), (PG8_LAS unsigned*)(lds + (bufoff) + ldsw + _i * 8192), 16, 0, 0); } while (0)
; #define PG8_LDA(dst, b, h) do { _Pragma("unroll") for (int m = 0; m < 4; ++m) _Pragma("unroll") for (int k = 0; k < 2; ++k) dst[m][k] = *(const PG8_LAS bf16x8*)(lds + PG8_SA(b, h) + aoff + m * 2048 + k * 1024); } while (0)
; #define PG8_LDB(dst, b, h) do { _Pragma("unroll") for (int n = 0; n < 2; ++n) _Pragma("unroll") for (int k = 0; k < 2; ++k) dst[n][k] = *(const PG8_LAS bf16x8*)(lds + PG8_SB(b, h) + boff + n * 2048 + k * 1024); } while (0)
; template <class Epi, class Sched, bool ALIGN_EPI = false, bool SP2 = false>
; __device__ __forceinline__ void gemm_phase(PG8_LAS unsigned char* lds, const Gemm g, const Sched& S, const Epi& E) {
;     ...
;         for (int t = 0; t < nt; t += 2) {
;             const bool last = (t == nt - 2);
;             const char* a1 = cA + (size_t)(t + 1) * kstep;
;             const char* a2 = last ? nA : cA + (size_t)(t + 2) * kstep; const char* b2 = last ? nB : cB + (size_t)(t + 2) * kstep;
;             const char* a3 = a2 + kstep; const char* b3 = b2 + kstep;
;             if (last && has_next) S.a_ready(nxt);
;             if constexpr (SP2) {
;             PG8_LDB(B0, 0, 0); PG8_LDB(B1, 0, 1); PG8_SCHED; PG8_LDA(At, 0, 0); PG8_STAGE(PG8_SA(1, 1), a1 + hstepA, voffA);
;             PG8_WAIT_V(8); PG8_WAIT_L(0); PG8_BAR; PG8_MMA(0, 0, At, B0); PG8_MMA(0, 1, At, B1); PG8_BAR; PG8_SCHED;
;             PG8_LDA(At, 0, 1); PG8_STAGE(PG8_SB(0, 0), b2, voffB); PG8_STAGE(PG8_SB(0, 1), b2 + hstep, voffB); PG8_STAGE(PG8_SA(0, 0), a2, voffA);
;             PG8_WAIT_V(8); PG8_WAIT_L(0); PG8_BAR; PG8_MMA(1, 0, At, B0); PG8_MMA(1, 1, At, B1); PG8_BAR; PG8_SCHED;
;             PG8_LDB(B0, 1, 0); PG8_LDB(B1, 1, 1); PG8_SCHED; PG8_LDA(At, 1, 0); PG8_STAGE(PG8_SA(0, 1), a2 + hstepA, voffA);
;             PG8_WAIT_V(8); PG8_WAIT_L(0); PG8_BAR; PG8_MMA(0, 0, At, B0); PG8_MMA(0, 1, At, B1); PG8_BAR; PG8_SCHED;
;             PG8_LDA(At, 1, 1); PG8_STAGE(PG8_SB(1, 0), b3, voffB); PG8_STAGE(PG8_SB(1, 1), b3 + hstep, voffB); PG8_STAGE(PG8_SA(1, 0), a3, voffA);
;             PG8_WAIT_V(8); PG8_WAIT_L(0); PG8_BAR; PG8_MMA(1, 0, At, B0); PG8_MMA(1, 1, At, B1); PG8_BAR; PG8_SCHED;
.LBB0_1897:
	ds_read_b128 v[128:131], v169
	ds_read_b128 v[132:135], v169 offset:1024
	ds_read_b128 v[136:139], v169 offset:2048
	ds_read_b128 v[140:143], v169 offset:3072
	ds_read_b128 v[160:163], v170
	ds_read_b128 v[172:175], v170 offset:1024
	ds_read_b128 v[176:179], v170 offset:2048
	ds_read_b128 v[180:183], v170 offset:3072
	s_add_i32 s63, s38, 2
	s_add_u32 s64, s36, 0xfff50080
	s_addc_u32 s39, s37, -1
	s_cmp_eq_u32 s53, s38
	s_cselect_b32 s38, s4, s64
	s_cselect_b32 s39, s5, s39
	s_cselect_b32 s65, s35, s62
	s_cselect_b32 s64, s34, s61
	s_add_i32 m0, s44, 0xc000
	ds_read_b128 v[184:187], v171
	ds_read_b128 v[188:191], v171 offset:1024
	ds_read_b128 v[192:195], v171 offset:2048
	ds_read_b128 v[196:199], v171 offset:3072
	ds_read_b128 v[200:203], v171 offset:4096
	ds_read_b128 v[204:207], v171 offset:5120
	ds_read_b128 v[208:211], v171 offset:6144
	global_load_lds_dwordx4 v152, s[36:37]
	s_add_i32 m0, s44, 0xe000
	ds_read_b128 v[212:215], v171 offset:7168
	global_load_lds_dwordx4 v154, s[36:37]
	s_waitcnt vmcnt(8) lgkmcnt(0)
	s_barrier
	s_setprio 1
	v_mfma_f32_16x16x32_bf16 v[124:127], v[128:131], v[184:187], v[124:127]
	v_mfma_f32_16x16x32_bf16 v[120:123], v[136:139], v[184:187], v[120:123]
	v_mfma_f32_16x16x32_bf16 v[108:111], v[128:131], v[192:195], v[108:111]
	v_mfma_f32_16x16x32_bf16 v[104:107], v[136:139], v[192:195], v[104:107]
	v_mfma_f32_16x16x32_bf16 v[92:95], v[128:131], v[200:203], v[92:95]
	v_mfma_f32_16x16x32_bf16 v[88:91], v[136:139], v[200:203], v[88:91]
	v_mfma_f32_16x16x32_bf16 v[76:79], v[128:131], v[208:211], v[76:79]
	v_mfma_f32_16x16x32_bf16 v[72:75], v[136:139], v[208:211], v[72:75]
	v_mfma_f32_16x16x32_bf16 v[124:127], v[132:135], v[188:191], v[124:127]
	v_mfma_f32_16x16x32_bf16 v[120:123], v[140:143], v[188:191], v[120:123]
	v_mfma_f32_16x16x32_bf16 v[108:111], v[132:135], v[196:199], v[108:111]
	v_mfma_f32_16x16x32_bf16 v[104:107], v[140:143], v[196:199], v[104:107]
	v_mfma_f32_16x16x32_bf16 v[92:95], v[132:135], v[204:207], v[92:95]
	v_mfma_f32_16x16x32_bf16 v[88:91], v[140:143], v[204:207], v[88:91]
	v_mfma_f32_16x16x32_bf16 v[76:79], v[132:135], v[212:215], v[76:79]
	v_mfma_f32_16x16x32_bf16 v[72:75], v[140:143], v[212:215], v[72:75]
	v_mfma_f32_16x16x32_bf16 v[116:119], v[160:163], v[184:187], v[116:119]
	v_mfma_f32_16x16x32_bf16 v[112:115], v[176:179], v[184:187], v[112:115]
	v_mfma_f32_16x16x32_bf16 v[100:103], v[160:163], v[192:195], v[100:103]
	v_mfma_f32_16x16x32_bf16 v[96:99], v[176:179], v[192:195], v[96:99]
	v_mfma_f32_16x16x32_bf16 v[84:87], v[160:163], v[200:203], v[84:87]
	v_mfma_f32_16x16x32_bf16 v[80:83], v[176:179], v[200:203], v[80:83]
	v_mfma_f32_16x16x32_bf16 v[68:71], v[160:163], v[208:211], v[68:71]
	v_mfma_f32_16x16x32_bf16 v[64:67], v[176:179], v[208:211], v[64:67]
	v_mfma_f32_16x16x32_bf16 v[116:119], v[172:175], v[188:191], v[116:119]
	v_mfma_f32_16x16x32_bf16 v[112:115], v[180:183], v[188:191], v[112:115]
	v_mfma_f32_16x16x32_bf16 v[100:103], v[172:175], v[196:199], v[100:103]
	v_mfma_f32_16x16x32_bf16 v[96:99], v[180:183], v[196:199], v[96:99]
	v_mfma_f32_16x16x32_bf16 v[84:87], v[172:175], v[204:207], v[84:87]
	v_mfma_f32_16x16x32_bf16 v[80:83], v[180:183], v[204:207], v[80:83]
	v_mfma_f32_16x16x32_bf16 v[68:71], v[172:175], v[212:215], v[68:71]
	v_mfma_f32_16x16x32_bf16 v[64:67], v[180:183], v[212:215], v[64:67]
	s_setprio 0
	s_barrier
	s_add_i32 s66, s54, s42
	s_mov_b32 m0, s66
	ds_read_b128 v[184:187], v171 offset:16384
	ds_read_b128 v[188:191], v171 offset:17408
	ds_read_b128 v[192:195], v171 offset:18432
	ds_read_b128 v[196:199], v171 offset:19456
	global_load_lds_dwordx4 v150, s[64:65]
	s_add_i32 m0, s66, 0x2000
	s_mov_b64 s[100:101], s[64:65]
	s_add_i32 s66, s55, s42
	global_load_lds_dwordx4 v148, s[64:65]
	s_add_u32 s64, s64, s6
	s_addc_u32 s65, s65, s7
	s_mov_b32 m0, s66
	ds_read_b128 v[212:215], v171 offset:23552
	global_load_lds_dwordx4 v150, s[64:65]
	s_add_i32 m0, s66, 0x2000
	ds_read_b128 v[208:211], v171 offset:22528
	global_load_lds_dwordx4 v148, s[64:65]
	s_mov_b32 m0, s44
	ds_read_b128 v[204:207], v171 offset:21504
	global_load_lds_dwordx4 v144, s[38:39]
	s_mov_b32 m0, s45
	ds_read_b128 v[200:203], v171 offset:20480
	global_load_lds_dwordx4 v146, s[38:39]
	s_waitcnt vmcnt(8) lgkmcnt(0)
	s_barrier
	s_setprio 1
	v_mfma_f32_16x16x32_bf16 v[60:63], v[128:131], v[184:187], v[60:63]
	v_mfma_f32_16x16x32_bf16 v[56:59], v[136:139], v[184:187], v[56:59]
	v_mfma_f32_16x16x32_bf16 v[44:47], v[128:131], v[192:195], v[44:47]
	v_mfma_f32_16x16x32_bf16 v[40:43], v[136:139], v[192:195], v[40:43]
	v_mfma_f32_16x16x32_bf16 v[28:31], v[128:131], v[200:203], v[28:31]
	v_mfma_f32_16x16x32_bf16 v[24:27], v[136:139], v[200:203], v[24:27]
	v_mfma_f32_16x16x32_bf16 v[12:15], v[128:131], v[208:211], v[12:15]
	v_mfma_f32_16x16x32_bf16 v[8:11], v[136:139], v[208:211], v[8:11]
	v_mfma_f32_16x16x32_bf16 v[60:63], v[132:135], v[188:191], v[60:63]
	v_mfma_f32_16x16x32_bf16 v[56:59], v[140:143], v[188:191], v[56:59]
	v_mfma_f32_16x16x32_bf16 v[44:47], v[132:135], v[196:199], v[44:47]
	v_mfma_f32_16x16x32_bf16 v[40:43], v[140:143], v[196:199], v[40:43]
	v_mfma_f32_16x16x32_bf16 v[28:31], v[132:135], v[204:207], v[28:31]
	v_mfma_f32_16x16x32_bf16 v[24:27], v[140:143], v[204:207], v[24:27]
	v_mfma_f32_16x16x32_bf16 v[12:15], v[132:135], v[212:215], v[12:15]
	v_mfma_f32_16x16x32_bf16 v[8:11], v[140:143], v[212:215], v[8:11]
	v_mfma_f32_16x16x32_bf16 v[52:55], v[160:163], v[184:187], v[52:55]
	v_mfma_f32_16x16x32_bf16 v[48:51], v[176:179], v[184:187], v[48:51]
	v_mfma_f32_16x16x32_bf16 v[36:39], v[160:163], v[192:195], v[36:39]
	v_mfma_f32_16x16x32_bf16 v[32:35], v[176:179], v[192:195], v[32:35]
	v_mfma_f32_16x16x32_bf16 v[20:23], v[160:163], v[200:203], v[20:23]
	v_mfma_f32_16x16x32_bf16 v[16:19], v[176:179], v[200:203], v[16:19]
	v_mfma_f32_16x16x32_bf16 v[4:7], v[160:163], v[208:211], v[4:7]
	v_mfma_f32_16x16x32_bf16 v[0:3], v[176:179], v[208:211], v[0:3]
	v_mfma_f32_16x16x32_bf16 v[52:55], v[172:175], v[188:191], v[52:55]
	v_mfma_f32_16x16x32_bf16 v[48:51], v[180:183], v[188:191], v[48:51]
	v_mfma_f32_16x16x32_bf16 v[36:39], v[172:175], v[196:199], v[36:39]
	v_mfma_f32_16x16x32_bf16 v[32:35], v[180:183], v[196:199], v[32:35]
	v_mfma_f32_16x16x32_bf16 v[20:23], v[172:175], v[204:207], v[20:23]
	v_mfma_f32_16x16x32_bf16 v[16:19], v[180:183], v[204:207], v[16:19]
	v_mfma_f32_16x16x32_bf16 v[4:7], v[172:175], v[212:215], v[4:7]
	v_mfma_f32_16x16x32_bf16 v[0:3], v[180:183], v[212:215], v[0:3]
	s_setprio 0
	s_barrier
; #define PG8_STAGE(bufoff, gbase, voff) do { _Pragma("unroll") for (int _i = 0; _i < 2; ++_i) \
;         __builtin_amdgcn_global_load_lds((const unsigned*)((const char*)(gbase) + (voff)[_i]), (PG8_LAS unsigned*)(lds + (bufoff) + ldsw + _i * 8192), 16, 0, 0); } while (0)
; #define PG8_LDA(dst, b, h) do { _Pragma("unroll") for (int m = 0; m < 4; ++m) _Pragma("unroll") for (int k = 0; k < 2; ++k) dst[m][k] = *(const PG8_LAS bf16x8*)(lds + PG8_SA(b, h) + aoff + m * 2048 + k * 1024); } while (0)
; #define PG8_LDB(dst, b, h) do { _Pragma("unroll") for (int n = 0; n < 2; ++n) _Pragma("unroll") for (int k = 0; k < 2; ++k) dst[n][k] = *(const PG8_LAS bf16x8*)(lds + PG8_SB(b, h) + boff + n * 2048 + k * 1024); } while (0)
; template <class Epi, class Sched, bool ALIGN_EPI = false, bool SP2 = false>
; __device__ __forceinline__ void gemm_phase(PG8_LAS unsigned char* lds, const Gemm g, const Sched& S, const Epi& E) {
;     ...
;         for (int t = 0; t < nt; t += 2) {
;             const bool last = (t == nt - 2);
;             const char* a1 = cA + (size_t)(t + 1) * kstep;
;             const char* a2 = last ? nA : cA + (size_t)(t + 2) * kstep; const char* b2 = last ? nB : cB + (size_t)(t + 2) * kstep;
;             const char* a3 = a2 + kstep; const char* b3 = b2 + kstep;
;             if (last && has_next) S.a_ready(nxt);
;             if constexpr (SP2) {
;             PG8_LDB(B0, 0, 0); PG8_LDB(B1, 0, 1); PG8_SCHED; PG8_LDA(At, 0, 0); PG8_STAGE(PG8_SA(1, 1), a1 + hstepA, voffA);
;             PG8_WAIT_V(8); PG8_WAIT_L(0); PG8_BAR; PG8_MMA(0, 0, At, B0); PG8_MMA(0, 1, At, B1); PG8_BAR; PG8_SCHED;
;             PG8_LDA(At, 0, 1); PG8_STAGE(PG8_SB(0, 0), b2, voffB); PG8_STAGE(PG8_SB(0, 1), b2 + hstep, voffB); PG8_STAGE(PG8_SA(0, 0), a2, voffA);
;             PG8_WAIT_V(8); PG8_WAIT_L(0); PG8_BAR; PG8_MMA(1, 0, At, B0); PG8_MMA(1, 1, At, B1); PG8_BAR; PG8_SCHED;
;             PG8_LDB(B0, 1, 0); PG8_LDB(B1, 1, 1); PG8_SCHED; PG8_LDA(At, 1, 0); PG8_STAGE(PG8_SA(0, 1), a2 + hstepA, voffA);
;             PG8_WAIT_V(8); PG8_WAIT_L(0); PG8_BAR; PG8_MMA(0, 0, At, B0); PG8_MMA(0, 1, At, B1); PG8_BAR; PG8_SCHED;
;             PG8_LDA(At, 1, 1); PG8_STAGE(PG8_SB(1, 0), b3, voffB); PG8_STAGE(PG8_SB(1, 1), b3 + hstep, voffB); PG8_STAGE(PG8_SA(1, 0), a3, voffA);
;             PG8_WAIT_V(8); PG8_WAIT_L(0); PG8_BAR; PG8_MMA(1, 0, At, B0); PG8_MMA(1, 1, At, B1); PG8_BAR; PG8_SCHED;
	s_add_i32 s64, 0, 0x18000
	s_add_i32 s65, 0, 0x1c000
	v_add_u32_e32 v140, s64, v167
	v_add_u32_e32 v180, s65, v167
	ds_read_b128 v[128:131], v140
	ds_read_b128 v[132:135], v140 offset:1024
	ds_read_b128 v[136:139], v140 offset:2048
	ds_read_b128 v[140:143], v140 offset:3072
	ds_read_b128 v[160:163], v180
	ds_read_b128 v[172:175], v180 offset:1024
	ds_read_b128 v[176:179], v180 offset:2048
	ds_read_b128 v[180:183], v180 offset:3072
	s_mov_b64 vcc, s[38:39]
	s_add_u32 s38, s38, 0xb0000
	s_addc_u32 s39, s39, 0
	s_mov_b32 m0, s46
	ds_read_b128 v[184:187], v171 offset:32768
	ds_read_b128 v[188:191], v171 offset:33792
	ds_read_b128 v[192:195], v171 offset:34816
	ds_read_b128 v[196:199], v171 offset:35840
	ds_read_b128 v[200:203], v171 offset:36864
	ds_read_b128 v[204:207], v171 offset:37888
	ds_read_b128 v[208:211], v171 offset:38912
	global_load_lds_dwordx4 v144, s[38:39]
	s_mov_b32 m0, s47
	ds_read_b128 v[212:215], v171 offset:39936
	global_load_lds_dwordx4 v146, s[38:39]
	s_waitcnt vmcnt(8) lgkmcnt(0)
	s_barrier
	s_setprio 1
	v_mfma_f32_16x16x32_bf16 v[124:127], v[128:131], v[184:187], v[124:127]
	v_mfma_f32_16x16x32_bf16 v[120:123], v[136:139], v[184:187], v[120:123]
	v_mfma_f32_16x16x32_bf16 v[108:111], v[128:131], v[192:195], v[108:111]
	v_mfma_f32_16x16x32_bf16 v[104:107], v[136:139], v[192:195], v[104:107]
	v_mfma_f32_16x16x32_bf16 v[92:95], v[128:131], v[200:203], v[92:95]
	v_mfma_f32_16x16x32_bf16 v[88:91], v[136:139], v[200:203], v[88:91]
	v_mfma_f32_16x16x32_bf16 v[76:79], v[128:131], v[208:211], v[76:79]
	v_mfma_f32_16x16x32_bf16 v[72:75], v[136:139], v[208:211], v[72:75]
	v_mfma_f32_16x16x32_bf16 v[124:127], v[132:135], v[188:191], v[124:127]
	v_mfma_f32_16x16x32_bf16 v[120:123], v[140:143], v[188:191], v[120:123]
	v_mfma_f32_16x16x32_bf16 v[108:111], v[132:135], v[196:199], v[108:111]
	v_mfma_f32_16x16x32_bf16 v[104:107], v[140:143], v[196:199], v[104:107]
	v_mfma_f32_16x16x32_bf16 v[92:95], v[132:135], v[204:207], v[92:95]
	v_mfma_f32_16x16x32_bf16 v[88:91], v[140:143], v[204:207], v[88:91]
	v_mfma_f32_16x16x32_bf16 v[76:79], v[132:135], v[212:215], v[76:79]
	v_mfma_f32_16x16x32_bf16 v[72:75], v[140:143], v[212:215], v[72:75]
	v_mfma_f32_16x16x32_bf16 v[116:119], v[160:163], v[184:187], v[116:119]
	v_mfma_f32_16x16x32_bf16 v[112:115], v[176:179], v[184:187], v[112:115]
	v_mfma_f32_16x16x32_bf16 v[100:103], v[160:163], v[192:195], v[100:103]
	v_mfma_f32_16x16x32_bf16 v[96:99], v[176:179], v[192:195], v[96:99]
	v_mfma_f32_16x16x32_bf16 v[84:87], v[160:163], v[200:203], v[84:87]
	v_mfma_f32_16x16x32_bf16 v[80:83], v[176:179], v[200:203], v[80:83]
	v_mfma_f32_16x16x32_bf16 v[68:71], v[160:163], v[208:211], v[68:71]
	v_mfma_f32_16x16x32_bf16 v[64:67], v[176:179], v[208:211], v[64:67]
	v_mfma_f32_16x16x32_bf16 v[116:119], v[172:175], v[188:191], v[116:119]
	v_mfma_f32_16x16x32_bf16 v[112:115], v[180:183], v[188:191], v[112:115]
	v_mfma_f32_16x16x32_bf16 v[100:103], v[172:175], v[196:199], v[100:103]
	v_mfma_f32_16x16x32_bf16 v[96:99], v[180:183], v[196:199], v[96:99]
	v_mfma_f32_16x16x32_bf16 v[84:87], v[172:175], v[204:207], v[84:87]
	v_mfma_f32_16x16x32_bf16 v[80:83], v[180:183], v[204:207], v[80:83]
	v_mfma_f32_16x16x32_bf16 v[68:71], v[172:175], v[212:215], v[68:71]
	v_mfma_f32_16x16x32_bf16 v[64:67], v[180:183], v[212:215], v[64:67]
	s_setprio 0
	s_barrier
	s_add_i32 s38, s64, s42
	s_add_i32 m0, s38, 0xffffff80
	ds_read_b128 v[184:187], v171 offset:49152
	ds_read_b128 v[188:191], v171 offset:50176
	ds_read_b128 v[192:195], v171 offset:51200
	ds_read_b128 v[196:199], v171 offset:52224
	global_load_lds_dwordx4 v150, s[100:101] offset:128
	s_add_i32 m0, s38, 0x1f80
	s_add_i32 s38, s65, s42
	global_load_lds_dwordx4 v148, s[100:101] offset:128
	s_add_u32 s100, s100, s6
	s_addc_u32 s101, s101, s7
	s_add_i32 m0, s38, 0xffffff80
	ds_read_b128 v[212:215], v171 offset:56320
	global_load_lds_dwordx4 v150, s[100:101] offset:128
	s_add_i32 m0, s38, 0x1f80
	ds_read_b128 v[208:211], v171 offset:55296
	global_load_lds_dwordx4 v148, s[100:101] offset:128
	s_add_i32 m0, s50, 0xffffff80
	ds_read_b128 v[204:207], v171 offset:54272
	global_load_lds_dwordx4 v144, vcc offset:128
	s_add_i32 m0, s51, 0xffffff80
	ds_read_b128 v[200:203], v171 offset:53248
	global_load_lds_dwordx4 v146, vcc offset:128
	s_waitcnt vmcnt(8) lgkmcnt(0)
	s_barrier
	s_setprio 1
	v_mfma_f32_16x16x32_bf16 v[60:63], v[128:131], v[184:187], v[60:63]
	v_mfma_f32_16x16x32_bf16 v[56:59], v[136:139], v[184:187], v[56:59]
	v_mfma_f32_16x16x32_bf16 v[44:47], v[128:131], v[192:195], v[44:47]
	v_mfma_f32_16x16x32_bf16 v[40:43], v[136:139], v[192:195], v[40:43]
	v_mfma_f32_16x16x32_bf16 v[28:31], v[128:131], v[200:203], v[28:31]
	v_mfma_f32_16x16x32_bf16 v[24:27], v[136:139], v[200:203], v[24:27]
	v_mfma_f32_16x16x32_bf16 v[12:15], v[128:131], v[208:211], v[12:15]
	v_mfma_f32_16x16x32_bf16 v[8:11], v[136:139], v[208:211], v[8:11]
	v_mfma_f32_16x16x32_bf16 v[60:63], v[132:135], v[188:191], v[60:63]
	v_mfma_f32_16x16x32_bf16 v[56:59], v[140:143], v[188:191], v[56:59]
	v_mfma_f32_16x16x32_bf16 v[44:47], v[132:135], v[196:199], v[44:47]
	v_mfma_f32_16x16x32_bf16 v[40:43], v[140:143], v[196:199], v[40:43]
	v_mfma_f32_16x16x32_bf16 v[28:31], v[132:135], v[204:207], v[28:31]
	v_mfma_f32_16x16x32_bf16 v[24:27], v[140:143], v[204:207], v[24:27]
	v_mfma_f32_16x16x32_bf16 v[12:15], v[132:135], v[212:215], v[12:15]
	v_mfma_f32_16x16x32_bf16 v[8:11], v[140:143], v[212:215], v[8:11]
	v_mfma_f32_16x16x32_bf16 v[52:55], v[160:163], v[184:187], v[52:55]
	v_mfma_f32_16x16x32_bf16 v[48:51], v[176:179], v[184:187], v[48:51]
	v_mfma_f32_16x16x32_bf16 v[36:39], v[160:163], v[192:195], v[36:39]
	v_mfma_f32_16x16x32_bf16 v[32:35], v[176:179], v[192:195], v[32:35]
	v_mfma_f32_16x16x32_bf16 v[20:23], v[160:163], v[200:203], v[20:23]
	v_mfma_f32_16x16x32_bf16 v[16:19], v[176:179], v[200:203], v[16:19]
	v_mfma_f32_16x16x32_bf16 v[4:7], v[160:163], v[208:211], v[4:7]
	v_mfma_f32_16x16x32_bf16 v[0:3], v[176:179], v[208:211], v[0:3]
	v_mfma_f32_16x16x32_bf16 v[52:55], v[172:175], v[188:191], v[52:55]
	v_mfma_f32_16x16x32_bf16 v[48:51], v[180:183], v[188:191], v[48:51]
	v_mfma_f32_16x16x32_bf16 v[36:39], v[172:175], v[196:199], v[36:39]
	v_mfma_f32_16x16x32_bf16 v[32:35], v[180:183], v[196:199], v[32:35]
	v_mfma_f32_16x16x32_bf16 v[20:23], v[172:175], v[204:207], v[20:23]
	v_mfma_f32_16x16x32_bf16 v[16:19], v[180:183], v[204:207], v[16:19]
	v_mfma_f32_16x16x32_bf16 v[4:7], v[172:175], v[212:215], v[4:7]
	v_mfma_f32_16x16x32_bf16 v[0:3], v[180:183], v[212:215], v[0:3]
	s_setprio 0
	s_barrier
	s_add_u32 s36, s36, 0x100
	s_addc_u32 s37, s37, 0
	s_add_u32 s61, s61, 0x100
	s_addc_u32 s62, s62, 0
	s_cmp_ge_i32 s63, s52
	s_mov_b32 s38, s63
	s_cbranch_scc0 .LBB0_1897
